# resid phases hand-written (X prefetch), barrier non-leaders poll top generation, write-through conv stores
# speedup vs baseline: 1.0429x; 1.0099x over previous
.LBB0_102:
	s_or_b64 exec, exec, s[10:11]
	v_cvt_f32_u32_e32 v4, v2
	s_waitcnt vmcnt(0)
	v_readfirstlane_b32 s2, v3
	v_sub_u32_e32 v3, 0, v2
	v_rcp_iflag_f32_e32 v4, v4
	v_add_u32_e32 v5, s2, v1
	v_mul_f32_e32 v4, 0x4f7ffffe, v4
	v_cvt_u32_f32_e32 v4, v4
	v_mul_lo_u32 v1, v3, v4
	v_mul_hi_u32 v1, v4, v1
	v_add_u32_e32 v1, v4, v1
	v_mul_hi_u32 v1, v5, v1
	v_mul_lo_u32 v3, v1, v2
	v_sub_u32_e32 v3, v5, v3
	v_add_u32_e32 v4, 1, v1
	v_cmp_ge_u32_e32 vcc, v3, v2
	s_nop 1
	v_cndmask_b32_e32 v1, v1, v4, vcc
	v_sub_u32_e32 v4, v3, v2
	v_cndmask_b32_e32 v3, v3, v4, vcc
	v_add_u32_e32 v4, 1, v1
	v_cmp_ge_u32_e32 vcc, v3, v2
	v_add_u32_e32 v3, 1, v5
	s_nop 0
	v_cndmask_b32_e32 v1, v1, v4, vcc
	v_mul_lo_u32 v4, v2, v1
	v_add_u32_e32 v2, v4, v2
	v_cmp_ne_u32_e32 vcc, v3, v2
	s_and_saveexec_b64 s[2:3], vcc
	s_xor_b64 s[8:9], exec, s[2:3]
	s_cbranch_execz .LBB0_116
	s_waitcnt lgkmcnt(0)
	v_mov_b32_e32 v0, 0x2000
	global_load_dword v0, v0, s[6:7] offset:1024 sc1
	s_add_u32 s14, s84, 0x3500
	s_addc_u32 s15, s85, 0
	s_waitcnt vmcnt(0)
	v_cmp_eq_u32_e32 vcc, v0, v1
	s_and_saveexec_b64 s[10:11], vcc
	s_cbranch_execz .LBB0_115
	s_add_u32 s12, s56, 0x1457a300
	s_addc_u32 s13, s57, 0
	s_mov_b32 s2, 1
	s_mov_b64 s[16:17], 0
	v_mov_b32_e32 v0, 0
	s_branch .LBB0_106

.Lcv3_rb:
	s_cmp_lt_u32 s3, 0x200
	s_cbranch_scc0 .Lcv3_end
	s_lshl_b32 s32, s3, 4
	s_cmp_lt_u32 s32, 0x1000
	s_mov_b32 s59, 0x3ff
	s_cselect_b32 s59, 0xff, s59
	s_and_b32 s65, s32, s59
	s_cmp_lg_u32 s65, 0
	s_cselect_b32 s62, -1, 0
	s_add_u32 s65, s65, 15
	s_cmp_lg_u32 s65, s59
	s_cselect_b32 s63, -1, 0
	s_lshl_b32 s65, s32, 12
	s_add_u32 s4, s14, 0xab7a100
	s_addc_u32 s5, s15, 0
	s_add_u32 s4, s4, s65
	s_addc_u32 s5, s5, 0
	s_sub_u32 s4, s4, 0x2000
	s_subb_u32 s5, s5, 0
	s_add_u32 s54, s14, 0x1037a100
	s_addc_u32 s55, s15, 0
	s_add_u32 s54, s54, s65
	s_addc_u32 s55, s55, 0
	global_load_dwordx4 v[76:79], v26, s[4:5]
	s_add_u32 s4, s4, 0x1000
	s_addc_u32 s5, s5, 0
	global_load_dwordx4 v[80:83], v26, s[4:5]
	s_add_u32 s4, s4, 0x1000
	s_addc_u32 s5, s5, 0
	global_load_dwordx4 v[84:87], v26, s[4:5]
	s_add_u32 s4, s4, 0x1000
	s_addc_u32 s5, s5, 0
	global_load_dwordx4 v[88:91], v26, s[4:5]
	s_add_u32 s4, s4, 0x1000
	s_addc_u32 s5, s5, 0
	global_load_dwordx4 v[92:95], v26, s[4:5]
	s_add_u32 s4, s4, 0x1000
	s_addc_u32 s5, s5, 0
	global_load_dwordx4 v[96:99], v26, s[4:5]
	s_add_u32 s4, s4, 0x1000
	s_addc_u32 s5, s5, 0
	global_load_dwordx4 v[100:103], v26, s[4:5]
	s_add_u32 s4, s4, 0x1000
	s_addc_u32 s5, s5, 0
	global_load_dwordx4 v[104:107], v26, s[4:5]
	s_add_u32 s4, s4, 0x1000
	s_addc_u32 s5, s5, 0
	global_load_dwordx4 v[108:111], v26, s[4:5]
	s_add_u32 s4, s4, 0x1000
	s_addc_u32 s5, s5, 0
	global_load_dwordx4 v[112:115], v26, s[4:5]
	s_add_u32 s4, s4, 0x1000
	s_addc_u32 s5, s5, 0
	global_load_dwordx4 v[116:119], v26, s[4:5]
	s_add_u32 s4, s4, 0x1000
	s_addc_u32 s5, s5, 0
	global_load_dwordx4 v[120:123], v26, s[4:5]
	s_add_u32 s4, s4, 0x1000
	s_addc_u32 s5, s5, 0
	global_load_dwordx4 v[124:127], v26, s[4:5]
	s_add_u32 s4, s4, 0x1000
	s_addc_u32 s5, s5, 0
	global_load_dwordx4 v[132:135], v26, s[4:5]
	s_add_u32 s4, s4, 0x1000
	s_addc_u32 s5, s5, 0
	global_load_dwordx4 v[136:139], v26, s[4:5]
	s_add_u32 s4, s4, 0x1000
	s_addc_u32 s5, s5, 0
	global_load_dwordx4 v[140:143], v26, s[4:5]
	s_add_u32 s4, s4, 0x1000
	s_addc_u32 s5, s5, 0
	global_load_dwordx4 v[144:147], v26, s[4:5]
	s_add_u32 s4, s4, 0x1000
	s_addc_u32 s5, s5, 0
	global_load_dwordx4 v[148:151], v26, s[4:5]
	s_add_u32 s4, s4, 0x1000
	s_addc_u32 s5, s5, 0
	global_load_dwordx4 v[152:155], v26, s[4:5]
	s_add_u32 s4, s4, 0x1000
	s_addc_u32 s5, s5, 0
	global_load_dwordx4 v[156:159], v26, s[4:5]
	s_waitcnt vmcnt(19)
	v_and_b32_e32 v76, s62, v76
	v_and_b32_e32 v77, s62, v77
	v_and_b32_e32 v78, s62, v78
	v_and_b32_e32 v79, s62, v79
	v_lshlrev_b32_e32 v172, 16, v76
	v_and_b32_e32 v173, 0xffff0000, v76
	v_lshlrev_b32_e32 v174, 16, v77
	v_and_b32_e32 v175, 0xffff0000, v77
	v_lshlrev_b32_e32 v176, 16, v78
	v_and_b32_e32 v177, 0xffff0000, v78
	v_lshlrev_b32_e32 v178, 16, v79
	v_and_b32_e32 v179, 0xffff0000, v79
	v_pk_fma_f32 v[180:181], v[28:29], v[172:173], v[68:69]
	v_pk_fma_f32 v[182:183], v[30:31], v[174:175], v[70:71]
	v_pk_fma_f32 v[184:185], v[32:33], v[176:177], v[72:73]
	v_pk_fma_f32 v[186:187], v[34:35], v[178:179], v[74:75]
	s_waitcnt vmcnt(18)
	v_and_b32_e32 v80, s62, v80
	v_and_b32_e32 v81, s62, v81
	v_and_b32_e32 v82, s62, v82
	v_and_b32_e32 v83, s62, v83
	v_lshlrev_b32_e32 v172, 16, v80
	v_and_b32_e32 v173, 0xffff0000, v80
	v_lshlrev_b32_e32 v174, 16, v81
	v_and_b32_e32 v175, 0xffff0000, v81
	v_lshlrev_b32_e32 v176, 16, v82
	v_and_b32_e32 v177, 0xffff0000, v82
	v_lshlrev_b32_e32 v178, 16, v83
	v_and_b32_e32 v179, 0xffff0000, v83
	v_pk_fma_f32 v[188:189], v[28:29], v[172:173], v[68:69]
	v_pk_fma_f32 v[190:191], v[30:31], v[174:175], v[70:71]
	v_pk_fma_f32 v[192:193], v[32:33], v[176:177], v[72:73]
	v_pk_fma_f32 v[194:195], v[34:35], v[178:179], v[74:75]
	v_pk_fma_f32 v[180:181], v[36:37], v[172:173], v[180:181]
	v_pk_fma_f32 v[182:183], v[38:39], v[174:175], v[182:183]
	v_pk_fma_f32 v[184:185], v[40:41], v[176:177], v[184:185]
	v_pk_fma_f32 v[186:187], v[42:43], v[178:179], v[186:187]
	s_waitcnt vmcnt(17)
	v_lshlrev_b32_e32 v172, 16, v84
	v_and_b32_e32 v173, 0xffff0000, v84
	v_lshlrev_b32_e32 v174, 16, v85
	v_and_b32_e32 v175, 0xffff0000, v85
	v_lshlrev_b32_e32 v176, 16, v86
	v_and_b32_e32 v177, 0xffff0000, v86
	v_lshlrev_b32_e32 v178, 16, v87
	v_and_b32_e32 v179, 0xffff0000, v87
	v_pk_fma_f32 v[196:197], v[28:29], v[172:173], v[68:69]
	v_pk_fma_f32 v[198:199], v[30:31], v[174:175], v[70:71]
	v_pk_fma_f32 v[200:201], v[32:33], v[176:177], v[72:73]
	v_pk_fma_f32 v[202:203], v[34:35], v[178:179], v[74:75]
	v_pk_fma_f32 v[188:189], v[36:37], v[172:173], v[188:189]
	v_pk_fma_f32 v[190:191], v[38:39], v[174:175], v[190:191]
	v_pk_fma_f32 v[192:193], v[40:41], v[176:177], v[192:193]
	v_pk_fma_f32 v[194:195], v[42:43], v[178:179], v[194:195]
	v_pk_fma_f32 v[180:181], v[44:45], v[172:173], v[180:181]
	v_pk_fma_f32 v[182:183], v[46:47], v[174:175], v[182:183]
	v_pk_fma_f32 v[184:185], v[48:49], v[176:177], v[184:185]
	v_pk_fma_f32 v[186:187], v[50:51], v[178:179], v[186:187]
	s_waitcnt vmcnt(16)
	v_lshlrev_b32_e32 v172, 16, v88
	v_and_b32_e32 v173, 0xffff0000, v88
	v_lshlrev_b32_e32 v174, 16, v89
	v_and_b32_e32 v175, 0xffff0000, v89
	v_lshlrev_b32_e32 v176, 16, v90
	v_and_b32_e32 v177, 0xffff0000, v90
	v_lshlrev_b32_e32 v178, 16, v91
	v_and_b32_e32 v179, 0xffff0000, v91
	v_pk_fma_f32 v[204:205], v[28:29], v[172:173], v[68:69]
	v_pk_fma_f32 v[206:207], v[30:31], v[174:175], v[70:71]
	v_pk_fma_f32 v[208:209], v[32:33], v[176:177], v[72:73]
	v_pk_fma_f32 v[210:211], v[34:35], v[178:179], v[74:75]
	v_pk_fma_f32 v[196:197], v[36:37], v[172:173], v[196:197]
	v_pk_fma_f32 v[198:199], v[38:39], v[174:175], v[198:199]
	v_pk_fma_f32 v[200:201], v[40:41], v[176:177], v[200:201]
	v_pk_fma_f32 v[202:203], v[42:43], v[178:179], v[202:203]
	v_pk_fma_f32 v[188:189], v[44:45], v[172:173], v[188:189]
	v_pk_fma_f32 v[190:191], v[46:47], v[174:175], v[190:191]
	v_pk_fma_f32 v[192:193], v[48:49], v[176:177], v[192:193]
	v_pk_fma_f32 v[194:195], v[50:51], v[178:179], v[194:195]
	v_pk_fma_f32 v[180:181], v[52:53], v[172:173], v[180:181]
	v_pk_fma_f32 v[182:183], v[54:55], v[174:175], v[182:183]
	v_pk_fma_f32 v[184:185], v[56:57], v[176:177], v[184:185]
	v_pk_fma_f32 v[186:187], v[58:59], v[178:179], v[186:187]
	s_waitcnt vmcnt(15)
	v_lshlrev_b32_e32 v172, 16, v92
	v_and_b32_e32 v173, 0xffff0000, v92
	v_lshlrev_b32_e32 v174, 16, v93
	v_and_b32_e32 v175, 0xffff0000, v93
	v_lshlrev_b32_e32 v176, 16, v94
	v_and_b32_e32 v177, 0xffff0000, v94
	v_lshlrev_b32_e32 v178, 16, v95
	v_and_b32_e32 v179, 0xffff0000, v95
	v_pk_fma_f32 v[212:213], v[28:29], v[172:173], v[68:69]
	v_pk_fma_f32 v[214:215], v[30:31], v[174:175], v[70:71]
	v_pk_fma_f32 v[216:217], v[32:33], v[176:177], v[72:73]
	v_pk_fma_f32 v[218:219], v[34:35], v[178:179], v[74:75]
	v_pk_fma_f32 v[204:205], v[36:37], v[172:173], v[204:205]
	v_pk_fma_f32 v[206:207], v[38:39], v[174:175], v[206:207]
	v_pk_fma_f32 v[208:209], v[40:41], v[176:177], v[208:209]
	v_pk_fma_f32 v[210:211], v[42:43], v[178:179], v[210:211]
	v_pk_fma_f32 v[196:197], v[44:45], v[172:173], v[196:197]
	v_pk_fma_f32 v[198:199], v[46:47], v[174:175], v[198:199]
	v_pk_fma_f32 v[200:201], v[48:49], v[176:177], v[200:201]
	v_pk_fma_f32 v[202:203], v[50:51], v[178:179], v[202:203]
	v_pk_fma_f32 v[188:189], v[52:53], v[172:173], v[188:189]
	v_pk_fma_f32 v[190:191], v[54:55], v[174:175], v[190:191]
	v_pk_fma_f32 v[192:193], v[56:57], v[176:177], v[192:193]
	v_pk_fma_f32 v[194:195], v[58:59], v[178:179], v[194:195]
	v_pk_fma_f32 v[180:181], v[60:61], v[172:173], v[180:181]
	v_pk_fma_f32 v[182:183], v[62:63], v[174:175], v[182:183]
	v_pk_fma_f32 v[184:185], v[64:65], v[176:177], v[184:185]
	v_pk_fma_f32 v[186:187], v[66:67], v[178:179], v[186:187]
	v_mul_f32_e32 v220, 0xbfb8aa3b, v180
	v_mul_f32_e32 v221, 0xbfb8aa3b, v181
	v_mul_f32_e32 v222, 0xbfb8aa3b, v182
	v_mul_f32_e32 v223, 0xbfb8aa3b, v183
	v_mul_f32_e32 v224, 0xbfb8aa3b, v184
	v_mul_f32_e32 v225, 0xbfb8aa3b, v185
	v_mul_f32_e32 v226, 0xbfb8aa3b, v186
	v_mul_f32_e32 v227, 0xbfb8aa3b, v187
	v_exp_f32_e32 v220, v220
	v_exp_f32_e32 v221, v221
	v_exp_f32_e32 v222, v222
	v_exp_f32_e32 v223, v223
	v_exp_f32_e32 v224, v224
	v_exp_f32_e32 v225, v225
	v_exp_f32_e32 v226, v226
	v_exp_f32_e32 v227, v227
	v_add_f32_e32 v220, 1.0, v220
	v_add_f32_e32 v221, 1.0, v221
	v_add_f32_e32 v222, 1.0, v222
	v_add_f32_e32 v223, 1.0, v223
	v_add_f32_e32 v224, 1.0, v224
	v_add_f32_e32 v225, 1.0, v225
	v_add_f32_e32 v226, 1.0, v226
	v_add_f32_e32 v227, 1.0, v227
	v_rcp_f32_e32 v220, v220
	v_rcp_f32_e32 v221, v221
	v_rcp_f32_e32 v222, v222
	v_rcp_f32_e32 v223, v223
	v_rcp_f32_e32 v224, v224
	v_rcp_f32_e32 v225, v225
	v_rcp_f32_e32 v226, v226
	v_rcp_f32_e32 v227, v227
	v_mul_f32_e32 v220, v180, v220
	v_mul_f32_e32 v221, v181, v221
	v_mul_f32_e32 v222, v182, v222
	v_mul_f32_e32 v223, v183, v223
	v_mul_f32_e32 v224, v184, v224
	v_mul_f32_e32 v225, v185, v225
	v_mul_f32_e32 v226, v186, v226
	v_mul_f32_e32 v227, v187, v227
	v_cvt_pk_bf16_f32 v180, v220, v221
	v_cvt_pk_bf16_f32 v181, v222, v223
	v_cvt_pk_bf16_f32 v182, v224, v225
	v_cvt_pk_bf16_f32 v183, v226, v227
	global_store_dwordx4 v26, v[180:183], s[54:55] sc1
	s_add_u32 s54, s54, 0x1000
	s_addc_u32 s55, s55, 0
	s_waitcnt vmcnt(15)
	v_lshlrev_b32_e32 v172, 16, v96
	v_and_b32_e32 v173, 0xffff0000, v96
	v_lshlrev_b32_e32 v174, 16, v97
	v_and_b32_e32 v175, 0xffff0000, v97
	v_lshlrev_b32_e32 v176, 16, v98
	v_and_b32_e32 v177, 0xffff0000, v98
	v_lshlrev_b32_e32 v178, 16, v99
	v_and_b32_e32 v179, 0xffff0000, v99
	v_pk_fma_f32 v[180:181], v[28:29], v[172:173], v[68:69]
	v_pk_fma_f32 v[182:183], v[30:31], v[174:175], v[70:71]
	v_pk_fma_f32 v[184:185], v[32:33], v[176:177], v[72:73]
	v_pk_fma_f32 v[186:187], v[34:35], v[178:179], v[74:75]
	v_pk_fma_f32 v[212:213], v[36:37], v[172:173], v[212:213]
	v_pk_fma_f32 v[214:215], v[38:39], v[174:175], v[214:215]
	v_pk_fma_f32 v[216:217], v[40:41], v[176:177], v[216:217]
	v_pk_fma_f32 v[218:219], v[42:43], v[178:179], v[218:219]
	v_pk_fma_f32 v[204:205], v[44:45], v[172:173], v[204:205]
	v_pk_fma_f32 v[206:207], v[46:47], v[174:175], v[206:207]
	v_pk_fma_f32 v[208:209], v[48:49], v[176:177], v[208:209]
	v_pk_fma_f32 v[210:211], v[50:51], v[178:179], v[210:211]
	v_pk_fma_f32 v[196:197], v[52:53], v[172:173], v[196:197]
	v_pk_fma_f32 v[198:199], v[54:55], v[174:175], v[198:199]
	v_pk_fma_f32 v[200:201], v[56:57], v[176:177], v[200:201]
	v_pk_fma_f32 v[202:203], v[58:59], v[178:179], v[202:203]
	v_pk_fma_f32 v[188:189], v[60:61], v[172:173], v[188:189]
	v_pk_fma_f32 v[190:191], v[62:63], v[174:175], v[190:191]
	v_pk_fma_f32 v[192:193], v[64:65], v[176:177], v[192:193]
	v_pk_fma_f32 v[194:195], v[66:67], v[178:179], v[194:195]
	v_mul_f32_e32 v220, 0xbfb8aa3b, v188
	v_mul_f32_e32 v221, 0xbfb8aa3b, v189
	v_mul_f32_e32 v222, 0xbfb8aa3b, v190
	v_mul_f32_e32 v223, 0xbfb8aa3b, v191
	v_mul_f32_e32 v224, 0xbfb8aa3b, v192
	v_mul_f32_e32 v225, 0xbfb8aa3b, v193
	v_mul_f32_e32 v226, 0xbfb8aa3b, v194
	v_mul_f32_e32 v227, 0xbfb8aa3b, v195
	v_exp_f32_e32 v220, v220
	v_exp_f32_e32 v221, v221
	v_exp_f32_e32 v222, v222
	v_exp_f32_e32 v223, v223
	v_exp_f32_e32 v224, v224
	v_exp_f32_e32 v225, v225
	v_exp_f32_e32 v226, v226
	v_exp_f32_e32 v227, v227
	v_add_f32_e32 v220, 1.0, v220
	v_add_f32_e32 v221, 1.0, v221
	v_add_f32_e32 v222, 1.0, v222
	v_add_f32_e32 v223, 1.0, v223
	v_add_f32_e32 v224, 1.0, v224
	v_add_f32_e32 v225, 1.0, v225
	v_add_f32_e32 v226, 1.0, v226
	v_add_f32_e32 v227, 1.0, v227
	v_rcp_f32_e32 v220, v220
	v_rcp_f32_e32 v221, v221
	v_rcp_f32_e32 v222, v222
	v_rcp_f32_e32 v223, v223
	v_rcp_f32_e32 v224, v224
	v_rcp_f32_e32 v225, v225
	v_rcp_f32_e32 v226, v226
	v_rcp_f32_e32 v227, v227
	v_mul_f32_e32 v220, v188, v220
	v_mul_f32_e32 v221, v189, v221
	v_mul_f32_e32 v222, v190, v222
	v_mul_f32_e32 v223, v191, v223
	v_mul_f32_e32 v224, v192, v224
	v_mul_f32_e32 v225, v193, v225
	v_mul_f32_e32 v226, v194, v226
	v_mul_f32_e32 v227, v195, v227
	v_cvt_pk_bf16_f32 v188, v220, v221
	v_cvt_pk_bf16_f32 v189, v222, v223
	v_cvt_pk_bf16_f32 v190, v224, v225
	v_cvt_pk_bf16_f32 v191, v226, v227
	global_store_dwordx4 v26, v[188:191], s[54:55] sc1
	s_add_u32 s54, s54, 0x1000
	s_addc_u32 s55, s55, 0
	s_waitcnt vmcnt(15)
	v_lshlrev_b32_e32 v172, 16, v100
	v_and_b32_e32 v173, 0xffff0000, v100
	v_lshlrev_b32_e32 v174, 16, v101
	v_and_b32_e32 v175, 0xffff0000, v101
	v_lshlrev_b32_e32 v176, 16, v102
	v_and_b32_e32 v177, 0xffff0000, v102
	v_lshlrev_b32_e32 v178, 16, v103
	v_and_b32_e32 v179, 0xffff0000, v103
	v_pk_fma_f32 v[188:189], v[28:29], v[172:173], v[68:69]
	v_pk_fma_f32 v[190:191], v[30:31], v[174:175], v[70:71]
	v_pk_fma_f32 v[192:193], v[32:33], v[176:177], v[72:73]
	v_pk_fma_f32 v[194:195], v[34:35], v[178:179], v[74:75]
	v_pk_fma_f32 v[180:181], v[36:37], v[172:173], v[180:181]
	v_pk_fma_f32 v[182:183], v[38:39], v[174:175], v[182:183]
	v_pk_fma_f32 v[184:185], v[40:41], v[176:177], v[184:185]
	v_pk_fma_f32 v[186:187], v[42:43], v[178:179], v[186:187]
	v_pk_fma_f32 v[212:213], v[44:45], v[172:173], v[212:213]
	v_pk_fma_f32 v[214:215], v[46:47], v[174:175], v[214:215]
	v_pk_fma_f32 v[216:217], v[48:49], v[176:177], v[216:217]
	v_pk_fma_f32 v[218:219], v[50:51], v[178:179], v[218:219]
	v_pk_fma_f32 v[204:205], v[52:53], v[172:173], v[204:205]
	v_pk_fma_f32 v[206:207], v[54:55], v[174:175], v[206:207]
	v_pk_fma_f32 v[208:209], v[56:57], v[176:177], v[208:209]
	v_pk_fma_f32 v[210:211], v[58:59], v[178:179], v[210:211]
	v_pk_fma_f32 v[196:197], v[60:61], v[172:173], v[196:197]
	v_pk_fma_f32 v[198:199], v[62:63], v[174:175], v[198:199]
	v_pk_fma_f32 v[200:201], v[64:65], v[176:177], v[200:201]
	v_pk_fma_f32 v[202:203], v[66:67], v[178:179], v[202:203]
	v_mul_f32_e32 v220, 0xbfb8aa3b, v196
	v_mul_f32_e32 v221, 0xbfb8aa3b, v197
	v_mul_f32_e32 v222, 0xbfb8aa3b, v198
	v_mul_f32_e32 v223, 0xbfb8aa3b, v199
	v_mul_f32_e32 v224, 0xbfb8aa3b, v200
	v_mul_f32_e32 v225, 0xbfb8aa3b, v201
	v_mul_f32_e32 v226, 0xbfb8aa3b, v202
	v_mul_f32_e32 v227, 0xbfb8aa3b, v203
	v_exp_f32_e32 v220, v220
	v_exp_f32_e32 v221, v221
	v_exp_f32_e32 v222, v222
	v_exp_f32_e32 v223, v223
	v_exp_f32_e32 v224, v224
	v_exp_f32_e32 v225, v225
	v_exp_f32_e32 v226, v226
	v_exp_f32_e32 v227, v227
	v_add_f32_e32 v220, 1.0, v220
	v_add_f32_e32 v221, 1.0, v221
	v_add_f32_e32 v222, 1.0, v222
	v_add_f32_e32 v223, 1.0, v223
	v_add_f32_e32 v224, 1.0, v224
	v_add_f32_e32 v225, 1.0, v225
	v_add_f32_e32 v226, 1.0, v226
	v_add_f32_e32 v227, 1.0, v227
	v_rcp_f32_e32 v220, v220
	v_rcp_f32_e32 v221, v221
	v_rcp_f32_e32 v222, v222
	v_rcp_f32_e32 v223, v223
	v_rcp_f32_e32 v224, v224
	v_rcp_f32_e32 v225, v225
	v_rcp_f32_e32 v226, v226
	v_rcp_f32_e32 v227, v227
	v_mul_f32_e32 v220, v196, v220
	v_mul_f32_e32 v221, v197, v221
	v_mul_f32_e32 v222, v198, v222
	v_mul_f32_e32 v223, v199, v223
	v_mul_f32_e32 v224, v200, v224
	v_mul_f32_e32 v225, v201, v225
	v_mul_f32_e32 v226, v202, v226
	v_mul_f32_e32 v227, v203, v227
	v_cvt_pk_bf16_f32 v196, v220, v221
	v_cvt_pk_bf16_f32 v197, v222, v223
	v_cvt_pk_bf16_f32 v198, v224, v225
	v_cvt_pk_bf16_f32 v199, v226, v227
	global_store_dwordx4 v26, v[196:199], s[54:55] sc1
	s_add_u32 s54, s54, 0x1000
	s_addc_u32 s55, s55, 0
	s_waitcnt vmcnt(15)
	v_lshlrev_b32_e32 v172, 16, v104
	v_and_b32_e32 v173, 0xffff0000, v104
	v_lshlrev_b32_e32 v174, 16, v105
	v_and_b32_e32 v175, 0xffff0000, v105
	v_lshlrev_b32_e32 v176, 16, v106
	v_and_b32_e32 v177, 0xffff0000, v106
	v_lshlrev_b32_e32 v178, 16, v107
	v_and_b32_e32 v179, 0xffff0000, v107
	v_pk_fma_f32 v[196:197], v[28:29], v[172:173], v[68:69]
	v_pk_fma_f32 v[198:199], v[30:31], v[174:175], v[70:71]
	v_pk_fma_f32 v[200:201], v[32:33], v[176:177], v[72:73]
	v_pk_fma_f32 v[202:203], v[34:35], v[178:179], v[74:75]
	v_pk_fma_f32 v[188:189], v[36:37], v[172:173], v[188:189]
	v_pk_fma_f32 v[190:191], v[38:39], v[174:175], v[190:191]
	v_pk_fma_f32 v[192:193], v[40:41], v[176:177], v[192:193]
	v_pk_fma_f32 v[194:195], v[42:43], v[178:179], v[194:195]
	v_pk_fma_f32 v[180:181], v[44:45], v[172:173], v[180:181]
	v_pk_fma_f32 v[182:183], v[46:47], v[174:175], v[182:183]
	v_pk_fma_f32 v[184:185], v[48:49], v[176:177], v[184:185]
	v_pk_fma_f32 v[186:187], v[50:51], v[178:179], v[186:187]
	v_pk_fma_f32 v[212:213], v[52:53], v[172:173], v[212:213]
	v_pk_fma_f32 v[214:215], v[54:55], v[174:175], v[214:215]
	v_pk_fma_f32 v[216:217], v[56:57], v[176:177], v[216:217]
	v_pk_fma_f32 v[218:219], v[58:59], v[178:179], v[218:219]
	v_pk_fma_f32 v[204:205], v[60:61], v[172:173], v[204:205]
	v_pk_fma_f32 v[206:207], v[62:63], v[174:175], v[206:207]
	v_pk_fma_f32 v[208:209], v[64:65], v[176:177], v[208:209]
	v_pk_fma_f32 v[210:211], v[66:67], v[178:179], v[210:211]
	v_mul_f32_e32 v220, 0xbfb8aa3b, v204
	v_mul_f32_e32 v221, 0xbfb8aa3b, v205
	v_mul_f32_e32 v222, 0xbfb8aa3b, v206
	v_mul_f32_e32 v223, 0xbfb8aa3b, v207
	v_mul_f32_e32 v224, 0xbfb8aa3b, v208
	v_mul_f32_e32 v225, 0xbfb8aa3b, v209
	v_mul_f32_e32 v226, 0xbfb8aa3b, v210
	v_mul_f32_e32 v227, 0xbfb8aa3b, v211
	v_exp_f32_e32 v220, v220
	v_exp_f32_e32 v221, v221
	v_exp_f32_e32 v222, v222
	v_exp_f32_e32 v223, v223
	v_exp_f32_e32 v224, v224
	v_exp_f32_e32 v225, v225
	v_exp_f32_e32 v226, v226
	v_exp_f32_e32 v227, v227
	v_add_f32_e32 v220, 1.0, v220
	v_add_f32_e32 v221, 1.0, v221
	v_add_f32_e32 v222, 1.0, v222
	v_add_f32_e32 v223, 1.0, v223
	v_add_f32_e32 v224, 1.0, v224
	v_add_f32_e32 v225, 1.0, v225
	v_add_f32_e32 v226, 1.0, v226
	v_add_f32_e32 v227, 1.0, v227
	v_rcp_f32_e32 v220, v220
	v_rcp_f32_e32 v221, v221
	v_rcp_f32_e32 v222, v222
	v_rcp_f32_e32 v223, v223
	v_rcp_f32_e32 v224, v224
	v_rcp_f32_e32 v225, v225
	v_rcp_f32_e32 v226, v226
	v_rcp_f32_e32 v227, v227
	v_mul_f32_e32 v220, v204, v220
	v_mul_f32_e32 v221, v205, v221
	v_mul_f32_e32 v222, v206, v222
	v_mul_f32_e32 v223, v207, v223
	v_mul_f32_e32 v224, v208, v224
	v_mul_f32_e32 v225, v209, v225
	v_mul_f32_e32 v226, v210, v226
	v_mul_f32_e32 v227, v211, v227
	v_cvt_pk_bf16_f32 v204, v220, v221
	v_cvt_pk_bf16_f32 v205, v222, v223
	v_cvt_pk_bf16_f32 v206, v224, v225
	v_cvt_pk_bf16_f32 v207, v226, v227
	global_store_dwordx4 v26, v[204:207], s[54:55] sc1
	s_add_u32 s54, s54, 0x1000
	s_addc_u32 s55, s55, 0
	s_waitcnt vmcnt(15)
	v_lshlrev_b32_e32 v172, 16, v108
	v_and_b32_e32 v173, 0xffff0000, v108
	v_lshlrev_b32_e32 v174, 16, v109
	v_and_b32_e32 v175, 0xffff0000, v109
	v_lshlrev_b32_e32 v176, 16, v110
	v_and_b32_e32 v177, 0xffff0000, v110
	v_lshlrev_b32_e32 v178, 16, v111
	v_and_b32_e32 v179, 0xffff0000, v111
	v_pk_fma_f32 v[204:205], v[28:29], v[172:173], v[68:69]
	v_pk_fma_f32 v[206:207], v[30:31], v[174:175], v[70:71]
	v_pk_fma_f32 v[208:209], v[32:33], v[176:177], v[72:73]
	v_pk_fma_f32 v[210:211], v[34:35], v[178:179], v[74:75]
	v_pk_fma_f32 v[196:197], v[36:37], v[172:173], v[196:197]
	v_pk_fma_f32 v[198:199], v[38:39], v[174:175], v[198:199]
	v_pk_fma_f32 v[200:201], v[40:41], v[176:177], v[200:201]
	v_pk_fma_f32 v[202:203], v[42:43], v[178:179], v[202:203]
	v_pk_fma_f32 v[188:189], v[44:45], v[172:173], v[188:189]
	v_pk_fma_f32 v[190:191], v[46:47], v[174:175], v[190:191]
	v_pk_fma_f32 v[192:193], v[48:49], v[176:177], v[192:193]
	v_pk_fma_f32 v[194:195], v[50:51], v[178:179], v[194:195]
	v_pk_fma_f32 v[180:181], v[52:53], v[172:173], v[180:181]
	v_pk_fma_f32 v[182:183], v[54:55], v[174:175], v[182:183]
	v_pk_fma_f32 v[184:185], v[56:57], v[176:177], v[184:185]
	v_pk_fma_f32 v[186:187], v[58:59], v[178:179], v[186:187]
	v_pk_fma_f32 v[212:213], v[60:61], v[172:173], v[212:213]
	v_pk_fma_f32 v[214:215], v[62:63], v[174:175], v[214:215]
	v_pk_fma_f32 v[216:217], v[64:65], v[176:177], v[216:217]
	v_pk_fma_f32 v[218:219], v[66:67], v[178:179], v[218:219]
	v_mul_f32_e32 v220, 0xbfb8aa3b, v212
	v_mul_f32_e32 v221, 0xbfb8aa3b, v213
	v_mul_f32_e32 v222, 0xbfb8aa3b, v214
	v_mul_f32_e32 v223, 0xbfb8aa3b, v215
	v_mul_f32_e32 v224, 0xbfb8aa3b, v216
	v_mul_f32_e32 v225, 0xbfb8aa3b, v217
	v_mul_f32_e32 v226, 0xbfb8aa3b, v218
	v_mul_f32_e32 v227, 0xbfb8aa3b, v219
	v_exp_f32_e32 v220, v220
	v_exp_f32_e32 v221, v221
	v_exp_f32_e32 v222, v222
	v_exp_f32_e32 v223, v223
	v_exp_f32_e32 v224, v224
	v_exp_f32_e32 v225, v225
	v_exp_f32_e32 v226, v226
	v_exp_f32_e32 v227, v227
	v_add_f32_e32 v220, 1.0, v220
	v_add_f32_e32 v221, 1.0, v221
	v_add_f32_e32 v222, 1.0, v222
	v_add_f32_e32 v223, 1.0, v223
	v_add_f32_e32 v224, 1.0, v224
	v_add_f32_e32 v225, 1.0, v225
	v_add_f32_e32 v226, 1.0, v226
	v_add_f32_e32 v227, 1.0, v227
	v_rcp_f32_e32 v220, v220
	v_rcp_f32_e32 v221, v221
	v_rcp_f32_e32 v222, v222
	v_rcp_f32_e32 v223, v223
	v_rcp_f32_e32 v224, v224
	v_rcp_f32_e32 v225, v225
	v_rcp_f32_e32 v226, v226
	v_rcp_f32_e32 v227, v227
	v_mul_f32_e32 v220, v212, v220
	v_mul_f32_e32 v221, v213, v221
	v_mul_f32_e32 v222, v214, v222
	v_mul_f32_e32 v223, v215, v223
	v_mul_f32_e32 v224, v216, v224
	v_mul_f32_e32 v225, v217, v225
	v_mul_f32_e32 v226, v218, v226
	v_mul_f32_e32 v227, v219, v227
	v_cvt_pk_bf16_f32 v212, v220, v221
	v_cvt_pk_bf16_f32 v213, v222, v223
	v_cvt_pk_bf16_f32 v214, v224, v225
	v_cvt_pk_bf16_f32 v215, v226, v227
	global_store_dwordx4 v26, v[212:215], s[54:55] sc1
	s_add_u32 s54, s54, 0x1000
	s_addc_u32 s55, s55, 0
	s_waitcnt vmcnt(15)
	v_lshlrev_b32_e32 v172, 16, v112
	v_and_b32_e32 v173, 0xffff0000, v112
	v_lshlrev_b32_e32 v174, 16, v113
	v_and_b32_e32 v175, 0xffff0000, v113
	v_lshlrev_b32_e32 v176, 16, v114
	v_and_b32_e32 v177, 0xffff0000, v114
	v_lshlrev_b32_e32 v178, 16, v115
	v_and_b32_e32 v179, 0xffff0000, v115
	v_pk_fma_f32 v[212:213], v[28:29], v[172:173], v[68:69]
	v_pk_fma_f32 v[214:215], v[30:31], v[174:175], v[70:71]
	v_pk_fma_f32 v[216:217], v[32:33], v[176:177], v[72:73]
	v_pk_fma_f32 v[218:219], v[34:35], v[178:179], v[74:75]
	v_pk_fma_f32 v[204:205], v[36:37], v[172:173], v[204:205]
	v_pk_fma_f32 v[206:207], v[38:39], v[174:175], v[206:207]
	v_pk_fma_f32 v[208:209], v[40:41], v[176:177], v[208:209]
	v_pk_fma_f32 v[210:211], v[42:43], v[178:179], v[210:211]
	v_pk_fma_f32 v[196:197], v[44:45], v[172:173], v[196:197]
	v_pk_fma_f32 v[198:199], v[46:47], v[174:175], v[198:199]
	v_pk_fma_f32 v[200:201], v[48:49], v[176:177], v[200:201]
	v_pk_fma_f32 v[202:203], v[50:51], v[178:179], v[202:203]
	v_pk_fma_f32 v[188:189], v[52:53], v[172:173], v[188:189]
	v_pk_fma_f32 v[190:191], v[54:55], v[174:175], v[190:191]
	v_pk_fma_f32 v[192:193], v[56:57], v[176:177], v[192:193]
	v_pk_fma_f32 v[194:195], v[58:59], v[178:179], v[194:195]
	v_pk_fma_f32 v[180:181], v[60:61], v[172:173], v[180:181]
	v_pk_fma_f32 v[182:183], v[62:63], v[174:175], v[182:183]
	v_pk_fma_f32 v[184:185], v[64:65], v[176:177], v[184:185]
	v_pk_fma_f32 v[186:187], v[66:67], v[178:179], v[186:187]
	v_mul_f32_e32 v220, 0xbfb8aa3b, v180
	v_mul_f32_e32 v221, 0xbfb8aa3b, v181
	v_mul_f32_e32 v222, 0xbfb8aa3b, v182
	v_mul_f32_e32 v223, 0xbfb8aa3b, v183
	v_mul_f32_e32 v224, 0xbfb8aa3b, v184
	v_mul_f32_e32 v225, 0xbfb8aa3b, v185
	v_mul_f32_e32 v226, 0xbfb8aa3b, v186
	v_mul_f32_e32 v227, 0xbfb8aa3b, v187
	v_exp_f32_e32 v220, v220
	v_exp_f32_e32 v221, v221
	v_exp_f32_e32 v222, v222
	v_exp_f32_e32 v223, v223
	v_exp_f32_e32 v224, v224
	v_exp_f32_e32 v225, v225
	v_exp_f32_e32 v226, v226
	v_exp_f32_e32 v227, v227
	v_add_f32_e32 v220, 1.0, v220
	v_add_f32_e32 v221, 1.0, v221
	v_add_f32_e32 v222, 1.0, v222
	v_add_f32_e32 v223, 1.0, v223
	v_add_f32_e32 v224, 1.0, v224
	v_add_f32_e32 v225, 1.0, v225
	v_add_f32_e32 v226, 1.0, v226
	v_add_f32_e32 v227, 1.0, v227
	v_rcp_f32_e32 v220, v220
	v_rcp_f32_e32 v221, v221
	v_rcp_f32_e32 v222, v222
	v_rcp_f32_e32 v223, v223
	v_rcp_f32_e32 v224, v224
	v_rcp_f32_e32 v225, v225
	v_rcp_f32_e32 v226, v226
	v_rcp_f32_e32 v227, v227
	v_mul_f32_e32 v220, v180, v220
	v_mul_f32_e32 v221, v181, v221
	v_mul_f32_e32 v222, v182, v222
	v_mul_f32_e32 v223, v183, v223
	v_mul_f32_e32 v224, v184, v224
	v_mul_f32_e32 v225, v185, v225
	v_mul_f32_e32 v226, v186, v226
	v_mul_f32_e32 v227, v187, v227
	v_cvt_pk_bf16_f32 v180, v220, v221
	v_cvt_pk_bf16_f32 v181, v222, v223
	v_cvt_pk_bf16_f32 v182, v224, v225
	v_cvt_pk_bf16_f32 v183, v226, v227
	global_store_dwordx4 v26, v[180:183], s[54:55] sc1
	s_add_u32 s54, s54, 0x1000
	s_addc_u32 s55, s55, 0
	s_waitcnt vmcnt(15)
	v_lshlrev_b32_e32 v172, 16, v116
	v_and_b32_e32 v173, 0xffff0000, v116
	v_lshlrev_b32_e32 v174, 16, v117
	v_and_b32_e32 v175, 0xffff0000, v117
	v_lshlrev_b32_e32 v176, 16, v118
	v_and_b32_e32 v177, 0xffff0000, v118
	v_lshlrev_b32_e32 v178, 16, v119
	v_and_b32_e32 v179, 0xffff0000, v119
	v_pk_fma_f32 v[180:181], v[28:29], v[172:173], v[68:69]
	v_pk_fma_f32 v[182:183], v[30:31], v[174:175], v[70:71]
	v_pk_fma_f32 v[184:185], v[32:33], v[176:177], v[72:73]
	v_pk_fma_f32 v[186:187], v[34:35], v[178:179], v[74:75]
	v_pk_fma_f32 v[212:213], v[36:37], v[172:173], v[212:213]
	v_pk_fma_f32 v[214:215], v[38:39], v[174:175], v[214:215]
	v_pk_fma_f32 v[216:217], v[40:41], v[176:177], v[216:217]
	v_pk_fma_f32 v[218:219], v[42:43], v[178:179], v[218:219]
	v_pk_fma_f32 v[204:205], v[44:45], v[172:173], v[204:205]
	v_pk_fma_f32 v[206:207], v[46:47], v[174:175], v[206:207]
	v_pk_fma_f32 v[208:209], v[48:49], v[176:177], v[208:209]
	v_pk_fma_f32 v[210:211], v[50:51], v[178:179], v[210:211]
	v_pk_fma_f32 v[196:197], v[52:53], v[172:173], v[196:197]
	v_pk_fma_f32 v[198:199], v[54:55], v[174:175], v[198:199]
	v_pk_fma_f32 v[200:201], v[56:57], v[176:177], v[200:201]
	v_pk_fma_f32 v[202:203], v[58:59], v[178:179], v[202:203]
	v_pk_fma_f32 v[188:189], v[60:61], v[172:173], v[188:189]
	v_pk_fma_f32 v[190:191], v[62:63], v[174:175], v[190:191]
	v_pk_fma_f32 v[192:193], v[64:65], v[176:177], v[192:193]
	v_pk_fma_f32 v[194:195], v[66:67], v[178:179], v[194:195]
	v_mul_f32_e32 v220, 0xbfb8aa3b, v188
	v_mul_f32_e32 v221, 0xbfb8aa3b, v189
	v_mul_f32_e32 v222, 0xbfb8aa3b, v190
	v_mul_f32_e32 v223, 0xbfb8aa3b, v191
	v_mul_f32_e32 v224, 0xbfb8aa3b, v192
	v_mul_f32_e32 v225, 0xbfb8aa3b, v193
	v_mul_f32_e32 v226, 0xbfb8aa3b, v194
	v_mul_f32_e32 v227, 0xbfb8aa3b, v195
	v_exp_f32_e32 v220, v220
	v_exp_f32_e32 v221, v221
	v_exp_f32_e32 v222, v222
	v_exp_f32_e32 v223, v223
	v_exp_f32_e32 v224, v224
	v_exp_f32_e32 v225, v225
	v_exp_f32_e32 v226, v226
	v_exp_f32_e32 v227, v227
	v_add_f32_e32 v220, 1.0, v220
	v_add_f32_e32 v221, 1.0, v221
	v_add_f32_e32 v222, 1.0, v222
	v_add_f32_e32 v223, 1.0, v223
	v_add_f32_e32 v224, 1.0, v224
	v_add_f32_e32 v225, 1.0, v225
	v_add_f32_e32 v226, 1.0, v226
	v_add_f32_e32 v227, 1.0, v227
	v_rcp_f32_e32 v220, v220
	v_rcp_f32_e32 v221, v221
	v_rcp_f32_e32 v222, v222
	v_rcp_f32_e32 v223, v223
	v_rcp_f32_e32 v224, v224
	v_rcp_f32_e32 v225, v225
	v_rcp_f32_e32 v226, v226
	v_rcp_f32_e32 v227, v227
	v_mul_f32_e32 v220, v188, v220
	v_mul_f32_e32 v221, v189, v221
	v_mul_f32_e32 v222, v190, v222
	v_mul_f32_e32 v223, v191, v223
	v_mul_f32_e32 v224, v192, v224
	v_mul_f32_e32 v225, v193, v225
	v_mul_f32_e32 v226, v194, v226
	v_mul_f32_e32 v227, v195, v227
	v_cvt_pk_bf16_f32 v188, v220, v221
	v_cvt_pk_bf16_f32 v189, v222, v223
	v_cvt_pk_bf16_f32 v190, v224, v225
	v_cvt_pk_bf16_f32 v191, v226, v227
	global_store_dwordx4 v26, v[188:191], s[54:55] sc1
	s_add_u32 s54, s54, 0x1000
	s_addc_u32 s55, s55, 0
	s_waitcnt vmcnt(15)
	v_lshlrev_b32_e32 v172, 16, v120
	v_and_b32_e32 v173, 0xffff0000, v120
	v_lshlrev_b32_e32 v174, 16, v121
	v_and_b32_e32 v175, 0xffff0000, v121
	v_lshlrev_b32_e32 v176, 16, v122
	v_and_b32_e32 v177, 0xffff0000, v122
	v_lshlrev_b32_e32 v178, 16, v123
	v_and_b32_e32 v179, 0xffff0000, v123
	v_pk_fma_f32 v[188:189], v[28:29], v[172:173], v[68:69]
	v_pk_fma_f32 v[190:191], v[30:31], v[174:175], v[70:71]
	v_pk_fma_f32 v[192:193], v[32:33], v[176:177], v[72:73]
	v_pk_fma_f32 v[194:195], v[34:35], v[178:179], v[74:75]
	v_pk_fma_f32 v[180:181], v[36:37], v[172:173], v[180:181]
	v_pk_fma_f32 v[182:183], v[38:39], v[174:175], v[182:183]
	v_pk_fma_f32 v[184:185], v[40:41], v[176:177], v[184:185]
	v_pk_fma_f32 v[186:187], v[42:43], v[178:179], v[186:187]
	v_pk_fma_f32 v[212:213], v[44:45], v[172:173], v[212:213]
	v_pk_fma_f32 v[214:215], v[46:47], v[174:175], v[214:215]
	v_pk_fma_f32 v[216:217], v[48:49], v[176:177], v[216:217]
	v_pk_fma_f32 v[218:219], v[50:51], v[178:179], v[218:219]
	v_pk_fma_f32 v[204:205], v[52:53], v[172:173], v[204:205]
	v_pk_fma_f32 v[206:207], v[54:55], v[174:175], v[206:207]
	v_pk_fma_f32 v[208:209], v[56:57], v[176:177], v[208:209]
	v_pk_fma_f32 v[210:211], v[58:59], v[178:179], v[210:211]
	v_pk_fma_f32 v[196:197], v[60:61], v[172:173], v[196:197]
	v_pk_fma_f32 v[198:199], v[62:63], v[174:175], v[198:199]
	v_pk_fma_f32 v[200:201], v[64:65], v[176:177], v[200:201]
	v_pk_fma_f32 v[202:203], v[66:67], v[178:179], v[202:203]
	v_mul_f32_e32 v220, 0xbfb8aa3b, v196
	v_mul_f32_e32 v221, 0xbfb8aa3b, v197
	v_mul_f32_e32 v222, 0xbfb8aa3b, v198
	v_mul_f32_e32 v223, 0xbfb8aa3b, v199
	v_mul_f32_e32 v224, 0xbfb8aa3b, v200
	v_mul_f32_e32 v225, 0xbfb8aa3b, v201
	v_mul_f32_e32 v226, 0xbfb8aa3b, v202
	v_mul_f32_e32 v227, 0xbfb8aa3b, v203
	v_exp_f32_e32 v220, v220
	v_exp_f32_e32 v221, v221
	v_exp_f32_e32 v222, v222
	v_exp_f32_e32 v223, v223
	v_exp_f32_e32 v224, v224
	v_exp_f32_e32 v225, v225
	v_exp_f32_e32 v226, v226
	v_exp_f32_e32 v227, v227
	v_add_f32_e32 v220, 1.0, v220
	v_add_f32_e32 v221, 1.0, v221
	v_add_f32_e32 v222, 1.0, v222
	v_add_f32_e32 v223, 1.0, v223
	v_add_f32_e32 v224, 1.0, v224
	v_add_f32_e32 v225, 1.0, v225
	v_add_f32_e32 v226, 1.0, v226
	v_add_f32_e32 v227, 1.0, v227
	v_rcp_f32_e32 v220, v220
	v_rcp_f32_e32 v221, v221
	v_rcp_f32_e32 v222, v222
	v_rcp_f32_e32 v223, v223
	v_rcp_f32_e32 v224, v224
	v_rcp_f32_e32 v225, v225
	v_rcp_f32_e32 v226, v226
	v_rcp_f32_e32 v227, v227
	v_mul_f32_e32 v220, v196, v220
	v_mul_f32_e32 v221, v197, v221
	v_mul_f32_e32 v222, v198, v222
	v_mul_f32_e32 v223, v199, v223
	v_mul_f32_e32 v224, v200, v224
	v_mul_f32_e32 v225, v201, v225
	v_mul_f32_e32 v226, v202, v226
	v_mul_f32_e32 v227, v203, v227
	v_cvt_pk_bf16_f32 v196, v220, v221
	v_cvt_pk_bf16_f32 v197, v222, v223
	v_cvt_pk_bf16_f32 v198, v224, v225
	v_cvt_pk_bf16_f32 v199, v226, v227
	global_store_dwordx4 v26, v[196:199], s[54:55] sc1
	s_add_u32 s54, s54, 0x1000
	s_addc_u32 s55, s55, 0
	s_waitcnt vmcnt(15)
	v_lshlrev_b32_e32 v172, 16, v124
	v_and_b32_e32 v173, 0xffff0000, v124
	v_lshlrev_b32_e32 v174, 16, v125
	v_and_b32_e32 v175, 0xffff0000, v125
	v_lshlrev_b32_e32 v176, 16, v126
	v_and_b32_e32 v177, 0xffff0000, v126
	v_lshlrev_b32_e32 v178, 16, v127
	v_and_b32_e32 v179, 0xffff0000, v127
	v_pk_fma_f32 v[196:197], v[28:29], v[172:173], v[68:69]
	v_pk_fma_f32 v[198:199], v[30:31], v[174:175], v[70:71]
	v_pk_fma_f32 v[200:201], v[32:33], v[176:177], v[72:73]
	v_pk_fma_f32 v[202:203], v[34:35], v[178:179], v[74:75]
	v_pk_fma_f32 v[188:189], v[36:37], v[172:173], v[188:189]
	v_pk_fma_f32 v[190:191], v[38:39], v[174:175], v[190:191]
	v_pk_fma_f32 v[192:193], v[40:41], v[176:177], v[192:193]
	v_pk_fma_f32 v[194:195], v[42:43], v[178:179], v[194:195]
	v_pk_fma_f32 v[180:181], v[44:45], v[172:173], v[180:181]
	v_pk_fma_f32 v[182:183], v[46:47], v[174:175], v[182:183]
	v_pk_fma_f32 v[184:185], v[48:49], v[176:177], v[184:185]
	v_pk_fma_f32 v[186:187], v[50:51], v[178:179], v[186:187]
	v_pk_fma_f32 v[212:213], v[52:53], v[172:173], v[212:213]
	v_pk_fma_f32 v[214:215], v[54:55], v[174:175], v[214:215]
	v_pk_fma_f32 v[216:217], v[56:57], v[176:177], v[216:217]
	v_pk_fma_f32 v[218:219], v[58:59], v[178:179], v[218:219]
	v_pk_fma_f32 v[204:205], v[60:61], v[172:173], v[204:205]
	v_pk_fma_f32 v[206:207], v[62:63], v[174:175], v[206:207]
	v_pk_fma_f32 v[208:209], v[64:65], v[176:177], v[208:209]
	v_pk_fma_f32 v[210:211], v[66:67], v[178:179], v[210:211]
	v_mul_f32_e32 v220, 0xbfb8aa3b, v204
	v_mul_f32_e32 v221, 0xbfb8aa3b, v205
	v_mul_f32_e32 v222, 0xbfb8aa3b, v206
	v_mul_f32_e32 v223, 0xbfb8aa3b, v207
	v_mul_f32_e32 v224, 0xbfb8aa3b, v208
	v_mul_f32_e32 v225, 0xbfb8aa3b, v209
	v_mul_f32_e32 v226, 0xbfb8aa3b, v210
	v_mul_f32_e32 v227, 0xbfb8aa3b, v211
	v_exp_f32_e32 v220, v220
	v_exp_f32_e32 v221, v221
	v_exp_f32_e32 v222, v222
	v_exp_f32_e32 v223, v223
	v_exp_f32_e32 v224, v224
	v_exp_f32_e32 v225, v225
	v_exp_f32_e32 v226, v226
	v_exp_f32_e32 v227, v227
	v_add_f32_e32 v220, 1.0, v220
	v_add_f32_e32 v221, 1.0, v221
	v_add_f32_e32 v222, 1.0, v222
	v_add_f32_e32 v223, 1.0, v223
	v_add_f32_e32 v224, 1.0, v224
	v_add_f32_e32 v225, 1.0, v225
	v_add_f32_e32 v226, 1.0, v226
	v_add_f32_e32 v227, 1.0, v227
	v_rcp_f32_e32 v220, v220
	v_rcp_f32_e32 v221, v221
	v_rcp_f32_e32 v222, v222
	v_rcp_f32_e32 v223, v223
	v_rcp_f32_e32 v224, v224
	v_rcp_f32_e32 v225, v225
	v_rcp_f32_e32 v226, v226
	v_rcp_f32_e32 v227, v227
	v_mul_f32_e32 v220, v204, v220
	v_mul_f32_e32 v221, v205, v221
	v_mul_f32_e32 v222, v206, v222
	v_mul_f32_e32 v223, v207, v223
	v_mul_f32_e32 v224, v208, v224
	v_mul_f32_e32 v225, v209, v225
	v_mul_f32_e32 v226, v210, v226
	v_mul_f32_e32 v227, v211, v227
	v_cvt_pk_bf16_f32 v204, v220, v221
	v_cvt_pk_bf16_f32 v205, v222, v223
	v_cvt_pk_bf16_f32 v206, v224, v225
	v_cvt_pk_bf16_f32 v207, v226, v227
	global_store_dwordx4 v26, v[204:207], s[54:55] sc1
	s_add_u32 s54, s54, 0x1000
	s_addc_u32 s55, s55, 0
	s_waitcnt vmcnt(15)
	v_lshlrev_b32_e32 v172, 16, v132
	v_and_b32_e32 v173, 0xffff0000, v132
	v_lshlrev_b32_e32 v174, 16, v133
	v_and_b32_e32 v175, 0xffff0000, v133
	v_lshlrev_b32_e32 v176, 16, v134
	v_and_b32_e32 v177, 0xffff0000, v134
	v_lshlrev_b32_e32 v178, 16, v135
	v_and_b32_e32 v179, 0xffff0000, v135
	v_pk_fma_f32 v[204:205], v[28:29], v[172:173], v[68:69]
	v_pk_fma_f32 v[206:207], v[30:31], v[174:175], v[70:71]
	v_pk_fma_f32 v[208:209], v[32:33], v[176:177], v[72:73]
	v_pk_fma_f32 v[210:211], v[34:35], v[178:179], v[74:75]
	v_pk_fma_f32 v[196:197], v[36:37], v[172:173], v[196:197]
	v_pk_fma_f32 v[198:199], v[38:39], v[174:175], v[198:199]
	v_pk_fma_f32 v[200:201], v[40:41], v[176:177], v[200:201]
	v_pk_fma_f32 v[202:203], v[42:43], v[178:179], v[202:203]
	v_pk_fma_f32 v[188:189], v[44:45], v[172:173], v[188:189]
	v_pk_fma_f32 v[190:191], v[46:47], v[174:175], v[190:191]
	v_pk_fma_f32 v[192:193], v[48:49], v[176:177], v[192:193]
	v_pk_fma_f32 v[194:195], v[50:51], v[178:179], v[194:195]
	v_pk_fma_f32 v[180:181], v[52:53], v[172:173], v[180:181]
	v_pk_fma_f32 v[182:183], v[54:55], v[174:175], v[182:183]
	v_pk_fma_f32 v[184:185], v[56:57], v[176:177], v[184:185]
	v_pk_fma_f32 v[186:187], v[58:59], v[178:179], v[186:187]
	v_pk_fma_f32 v[212:213], v[60:61], v[172:173], v[212:213]
	v_pk_fma_f32 v[214:215], v[62:63], v[174:175], v[214:215]
	v_pk_fma_f32 v[216:217], v[64:65], v[176:177], v[216:217]
	v_pk_fma_f32 v[218:219], v[66:67], v[178:179], v[218:219]
	v_mul_f32_e32 v220, 0xbfb8aa3b, v212
	v_mul_f32_e32 v221, 0xbfb8aa3b, v213
	v_mul_f32_e32 v222, 0xbfb8aa3b, v214
	v_mul_f32_e32 v223, 0xbfb8aa3b, v215
	v_mul_f32_e32 v224, 0xbfb8aa3b, v216
	v_mul_f32_e32 v225, 0xbfb8aa3b, v217
	v_mul_f32_e32 v226, 0xbfb8aa3b, v218
	v_mul_f32_e32 v227, 0xbfb8aa3b, v219
	v_exp_f32_e32 v220, v220
	v_exp_f32_e32 v221, v221
	v_exp_f32_e32 v222, v222
	v_exp_f32_e32 v223, v223
	v_exp_f32_e32 v224, v224
	v_exp_f32_e32 v225, v225
	v_exp_f32_e32 v226, v226
	v_exp_f32_e32 v227, v227
	v_add_f32_e32 v220, 1.0, v220
	v_add_f32_e32 v221, 1.0, v221
	v_add_f32_e32 v222, 1.0, v222
	v_add_f32_e32 v223, 1.0, v223
	v_add_f32_e32 v224, 1.0, v224
	v_add_f32_e32 v225, 1.0, v225
	v_add_f32_e32 v226, 1.0, v226
	v_add_f32_e32 v227, 1.0, v227
	v_rcp_f32_e32 v220, v220
	v_rcp_f32_e32 v221, v221
	v_rcp_f32_e32 v222, v222
	v_rcp_f32_e32 v223, v223
	v_rcp_f32_e32 v224, v224
	v_rcp_f32_e32 v225, v225
	v_rcp_f32_e32 v226, v226
	v_rcp_f32_e32 v227, v227
	v_mul_f32_e32 v220, v212, v220
	v_mul_f32_e32 v221, v213, v221
	v_mul_f32_e32 v222, v214, v222
	v_mul_f32_e32 v223, v215, v223
	v_mul_f32_e32 v224, v216, v224
	v_mul_f32_e32 v225, v217, v225
	v_mul_f32_e32 v226, v218, v226
	v_mul_f32_e32 v227, v219, v227
	v_cvt_pk_bf16_f32 v212, v220, v221
	v_cvt_pk_bf16_f32 v213, v222, v223
	v_cvt_pk_bf16_f32 v214, v224, v225
	v_cvt_pk_bf16_f32 v215, v226, v227
	global_store_dwordx4 v26, v[212:215], s[54:55] sc1
	s_add_u32 s54, s54, 0x1000
	s_addc_u32 s55, s55, 0
	s_waitcnt vmcnt(15)
	v_lshlrev_b32_e32 v172, 16, v136
	v_and_b32_e32 v173, 0xffff0000, v136
	v_lshlrev_b32_e32 v174, 16, v137
	v_and_b32_e32 v175, 0xffff0000, v137
	v_lshlrev_b32_e32 v176, 16, v138
	v_and_b32_e32 v177, 0xffff0000, v138
	v_lshlrev_b32_e32 v178, 16, v139
	v_and_b32_e32 v179, 0xffff0000, v139
	v_pk_fma_f32 v[212:213], v[28:29], v[172:173], v[68:69]
	v_pk_fma_f32 v[214:215], v[30:31], v[174:175], v[70:71]
	v_pk_fma_f32 v[216:217], v[32:33], v[176:177], v[72:73]
	v_pk_fma_f32 v[218:219], v[34:35], v[178:179], v[74:75]
	v_pk_fma_f32 v[204:205], v[36:37], v[172:173], v[204:205]
	v_pk_fma_f32 v[206:207], v[38:39], v[174:175], v[206:207]
	v_pk_fma_f32 v[208:209], v[40:41], v[176:177], v[208:209]
	v_pk_fma_f32 v[210:211], v[42:43], v[178:179], v[210:211]
	v_pk_fma_f32 v[196:197], v[44:45], v[172:173], v[196:197]
	v_pk_fma_f32 v[198:199], v[46:47], v[174:175], v[198:199]
	v_pk_fma_f32 v[200:201], v[48:49], v[176:177], v[200:201]
	v_pk_fma_f32 v[202:203], v[50:51], v[178:179], v[202:203]
	v_pk_fma_f32 v[188:189], v[52:53], v[172:173], v[188:189]
	v_pk_fma_f32 v[190:191], v[54:55], v[174:175], v[190:191]
	v_pk_fma_f32 v[192:193], v[56:57], v[176:177], v[192:193]
	v_pk_fma_f32 v[194:195], v[58:59], v[178:179], v[194:195]
	v_pk_fma_f32 v[180:181], v[60:61], v[172:173], v[180:181]
	v_pk_fma_f32 v[182:183], v[62:63], v[174:175], v[182:183]
	v_pk_fma_f32 v[184:185], v[64:65], v[176:177], v[184:185]
	v_pk_fma_f32 v[186:187], v[66:67], v[178:179], v[186:187]
	v_mul_f32_e32 v220, 0xbfb8aa3b, v180
	v_mul_f32_e32 v221, 0xbfb8aa3b, v181
	v_mul_f32_e32 v222, 0xbfb8aa3b, v182
	v_mul_f32_e32 v223, 0xbfb8aa3b, v183
	v_mul_f32_e32 v224, 0xbfb8aa3b, v184
	v_mul_f32_e32 v225, 0xbfb8aa3b, v185
	v_mul_f32_e32 v226, 0xbfb8aa3b, v186
	v_mul_f32_e32 v227, 0xbfb8aa3b, v187
	v_exp_f32_e32 v220, v220
	v_exp_f32_e32 v221, v221
	v_exp_f32_e32 v222, v222
	v_exp_f32_e32 v223, v223
	v_exp_f32_e32 v224, v224
	v_exp_f32_e32 v225, v225
	v_exp_f32_e32 v226, v226
	v_exp_f32_e32 v227, v227
	v_add_f32_e32 v220, 1.0, v220
	v_add_f32_e32 v221, 1.0, v221
	v_add_f32_e32 v222, 1.0, v222
	v_add_f32_e32 v223, 1.0, v223
	v_add_f32_e32 v224, 1.0, v224
	v_add_f32_e32 v225, 1.0, v225
	v_add_f32_e32 v226, 1.0, v226
	v_add_f32_e32 v227, 1.0, v227
	v_rcp_f32_e32 v220, v220
	v_rcp_f32_e32 v221, v221
	v_rcp_f32_e32 v222, v222
	v_rcp_f32_e32 v223, v223
	v_rcp_f32_e32 v224, v224
	v_rcp_f32_e32 v225, v225
	v_rcp_f32_e32 v226, v226
	v_rcp_f32_e32 v227, v227
	v_mul_f32_e32 v220, v180, v220
	v_mul_f32_e32 v221, v181, v221
	v_mul_f32_e32 v222, v182, v222
	v_mul_f32_e32 v223, v183, v223
	v_mul_f32_e32 v224, v184, v224
	v_mul_f32_e32 v225, v185, v225
	v_mul_f32_e32 v226, v186, v226
	v_mul_f32_e32 v227, v187, v227
	v_cvt_pk_bf16_f32 v180, v220, v221
	v_cvt_pk_bf16_f32 v181, v222, v223
	v_cvt_pk_bf16_f32 v182, v224, v225
	v_cvt_pk_bf16_f32 v183, v226, v227
	global_store_dwordx4 v26, v[180:183], s[54:55] sc1
	s_add_u32 s54, s54, 0x1000
	s_addc_u32 s55, s55, 0
	s_waitcnt vmcnt(15)
	v_lshlrev_b32_e32 v172, 16, v140
	v_and_b32_e32 v173, 0xffff0000, v140
	v_lshlrev_b32_e32 v174, 16, v141
	v_and_b32_e32 v175, 0xffff0000, v141
	v_lshlrev_b32_e32 v176, 16, v142
	v_and_b32_e32 v177, 0xffff0000, v142
	v_lshlrev_b32_e32 v178, 16, v143
	v_and_b32_e32 v179, 0xffff0000, v143
	v_pk_fma_f32 v[180:181], v[28:29], v[172:173], v[68:69]
	v_pk_fma_f32 v[182:183], v[30:31], v[174:175], v[70:71]
	v_pk_fma_f32 v[184:185], v[32:33], v[176:177], v[72:73]
	v_pk_fma_f32 v[186:187], v[34:35], v[178:179], v[74:75]
	v_pk_fma_f32 v[212:213], v[36:37], v[172:173], v[212:213]
	v_pk_fma_f32 v[214:215], v[38:39], v[174:175], v[214:215]
	v_pk_fma_f32 v[216:217], v[40:41], v[176:177], v[216:217]
	v_pk_fma_f32 v[218:219], v[42:43], v[178:179], v[218:219]
	v_pk_fma_f32 v[204:205], v[44:45], v[172:173], v[204:205]
	v_pk_fma_f32 v[206:207], v[46:47], v[174:175], v[206:207]
	v_pk_fma_f32 v[208:209], v[48:49], v[176:177], v[208:209]
	v_pk_fma_f32 v[210:211], v[50:51], v[178:179], v[210:211]
	v_pk_fma_f32 v[196:197], v[52:53], v[172:173], v[196:197]
	v_pk_fma_f32 v[198:199], v[54:55], v[174:175], v[198:199]
	v_pk_fma_f32 v[200:201], v[56:57], v[176:177], v[200:201]
	v_pk_fma_f32 v[202:203], v[58:59], v[178:179], v[202:203]
	v_pk_fma_f32 v[188:189], v[60:61], v[172:173], v[188:189]
	v_pk_fma_f32 v[190:191], v[62:63], v[174:175], v[190:191]
	v_pk_fma_f32 v[192:193], v[64:65], v[176:177], v[192:193]
	v_pk_fma_f32 v[194:195], v[66:67], v[178:179], v[194:195]
	v_mul_f32_e32 v220, 0xbfb8aa3b, v188
	v_mul_f32_e32 v221, 0xbfb8aa3b, v189
	v_mul_f32_e32 v222, 0xbfb8aa3b, v190
	v_mul_f32_e32 v223, 0xbfb8aa3b, v191
	v_mul_f32_e32 v224, 0xbfb8aa3b, v192
	v_mul_f32_e32 v225, 0xbfb8aa3b, v193
	v_mul_f32_e32 v226, 0xbfb8aa3b, v194
	v_mul_f32_e32 v227, 0xbfb8aa3b, v195
	v_exp_f32_e32 v220, v220
	v_exp_f32_e32 v221, v221
	v_exp_f32_e32 v222, v222
	v_exp_f32_e32 v223, v223
	v_exp_f32_e32 v224, v224
	v_exp_f32_e32 v225, v225
	v_exp_f32_e32 v226, v226
	v_exp_f32_e32 v227, v227
	v_add_f32_e32 v220, 1.0, v220
	v_add_f32_e32 v221, 1.0, v221
	v_add_f32_e32 v222, 1.0, v222
	v_add_f32_e32 v223, 1.0, v223
	v_add_f32_e32 v224, 1.0, v224
	v_add_f32_e32 v225, 1.0, v225
	v_add_f32_e32 v226, 1.0, v226
	v_add_f32_e32 v227, 1.0, v227
	v_rcp_f32_e32 v220, v220
	v_rcp_f32_e32 v221, v221
	v_rcp_f32_e32 v222, v222
	v_rcp_f32_e32 v223, v223
	v_rcp_f32_e32 v224, v224
	v_rcp_f32_e32 v225, v225
	v_rcp_f32_e32 v226, v226
	v_rcp_f32_e32 v227, v227
	v_mul_f32_e32 v220, v188, v220
	v_mul_f32_e32 v221, v189, v221
	v_mul_f32_e32 v222, v190, v222
	v_mul_f32_e32 v223, v191, v223
	v_mul_f32_e32 v224, v192, v224
	v_mul_f32_e32 v225, v193, v225
	v_mul_f32_e32 v226, v194, v226
	v_mul_f32_e32 v227, v195, v227
	v_cvt_pk_bf16_f32 v188, v220, v221
	v_cvt_pk_bf16_f32 v189, v222, v223
	v_cvt_pk_bf16_f32 v190, v224, v225
	v_cvt_pk_bf16_f32 v191, v226, v227
	global_store_dwordx4 v26, v[188:191], s[54:55] sc1
	s_add_u32 s54, s54, 0x1000
	s_addc_u32 s55, s55, 0
	s_waitcnt vmcnt(15)
	v_lshlrev_b32_e32 v172, 16, v144
	v_and_b32_e32 v173, 0xffff0000, v144
	v_lshlrev_b32_e32 v174, 16, v145
	v_and_b32_e32 v175, 0xffff0000, v145
	v_lshlrev_b32_e32 v176, 16, v146
	v_and_b32_e32 v177, 0xffff0000, v146
	v_lshlrev_b32_e32 v178, 16, v147
	v_and_b32_e32 v179, 0xffff0000, v147
	v_pk_fma_f32 v[180:181], v[36:37], v[172:173], v[180:181]
	v_pk_fma_f32 v[182:183], v[38:39], v[174:175], v[182:183]
	v_pk_fma_f32 v[184:185], v[40:41], v[176:177], v[184:185]
	v_pk_fma_f32 v[186:187], v[42:43], v[178:179], v[186:187]
	v_pk_fma_f32 v[212:213], v[44:45], v[172:173], v[212:213]
	v_pk_fma_f32 v[214:215], v[46:47], v[174:175], v[214:215]
	v_pk_fma_f32 v[216:217], v[48:49], v[176:177], v[216:217]
	v_pk_fma_f32 v[218:219], v[50:51], v[178:179], v[218:219]
	v_pk_fma_f32 v[204:205], v[52:53], v[172:173], v[204:205]
	v_pk_fma_f32 v[206:207], v[54:55], v[174:175], v[206:207]
	v_pk_fma_f32 v[208:209], v[56:57], v[176:177], v[208:209]
	v_pk_fma_f32 v[210:211], v[58:59], v[178:179], v[210:211]
	v_pk_fma_f32 v[196:197], v[60:61], v[172:173], v[196:197]
	v_pk_fma_f32 v[198:199], v[62:63], v[174:175], v[198:199]
	v_pk_fma_f32 v[200:201], v[64:65], v[176:177], v[200:201]
	v_pk_fma_f32 v[202:203], v[66:67], v[178:179], v[202:203]
	v_mul_f32_e32 v220, 0xbfb8aa3b, v196
	v_mul_f32_e32 v221, 0xbfb8aa3b, v197
	v_mul_f32_e32 v222, 0xbfb8aa3b, v198
	v_mul_f32_e32 v223, 0xbfb8aa3b, v199
	v_mul_f32_e32 v224, 0xbfb8aa3b, v200
	v_mul_f32_e32 v225, 0xbfb8aa3b, v201
	v_mul_f32_e32 v226, 0xbfb8aa3b, v202
	v_mul_f32_e32 v227, 0xbfb8aa3b, v203
	v_exp_f32_e32 v220, v220
	v_exp_f32_e32 v221, v221
	v_exp_f32_e32 v222, v222
	v_exp_f32_e32 v223, v223
	v_exp_f32_e32 v224, v224
	v_exp_f32_e32 v225, v225
	v_exp_f32_e32 v226, v226
	v_exp_f32_e32 v227, v227
	v_add_f32_e32 v220, 1.0, v220
	v_add_f32_e32 v221, 1.0, v221
	v_add_f32_e32 v222, 1.0, v222
	v_add_f32_e32 v223, 1.0, v223
	v_add_f32_e32 v224, 1.0, v224
	v_add_f32_e32 v225, 1.0, v225
	v_add_f32_e32 v226, 1.0, v226
	v_add_f32_e32 v227, 1.0, v227
	v_rcp_f32_e32 v220, v220
	v_rcp_f32_e32 v221, v221
	v_rcp_f32_e32 v222, v222
	v_rcp_f32_e32 v223, v223
	v_rcp_f32_e32 v224, v224
	v_rcp_f32_e32 v225, v225
	v_rcp_f32_e32 v226, v226
	v_rcp_f32_e32 v227, v227
	v_mul_f32_e32 v220, v196, v220
	v_mul_f32_e32 v221, v197, v221
	v_mul_f32_e32 v222, v198, v222
	v_mul_f32_e32 v223, v199, v223
	v_mul_f32_e32 v224, v200, v224
	v_mul_f32_e32 v225, v201, v225
	v_mul_f32_e32 v226, v202, v226
	v_mul_f32_e32 v227, v203, v227
	v_cvt_pk_bf16_f32 v196, v220, v221
	v_cvt_pk_bf16_f32 v197, v222, v223
	v_cvt_pk_bf16_f32 v198, v224, v225
	v_cvt_pk_bf16_f32 v199, v226, v227
	global_store_dwordx4 v26, v[196:199], s[54:55] sc1
	s_add_u32 s54, s54, 0x1000
	s_addc_u32 s55, s55, 0
	s_waitcnt vmcnt(15)
	v_lshlrev_b32_e32 v172, 16, v148
	v_and_b32_e32 v173, 0xffff0000, v148
	v_lshlrev_b32_e32 v174, 16, v149
	v_and_b32_e32 v175, 0xffff0000, v149
	v_lshlrev_b32_e32 v176, 16, v150
	v_and_b32_e32 v177, 0xffff0000, v150
	v_lshlrev_b32_e32 v178, 16, v151
	v_and_b32_e32 v179, 0xffff0000, v151
	v_pk_fma_f32 v[180:181], v[44:45], v[172:173], v[180:181]
	v_pk_fma_f32 v[182:183], v[46:47], v[174:175], v[182:183]
	v_pk_fma_f32 v[184:185], v[48:49], v[176:177], v[184:185]
	v_pk_fma_f32 v[186:187], v[50:51], v[178:179], v[186:187]
	v_pk_fma_f32 v[212:213], v[52:53], v[172:173], v[212:213]
	v_pk_fma_f32 v[214:215], v[54:55], v[174:175], v[214:215]
	v_pk_fma_f32 v[216:217], v[56:57], v[176:177], v[216:217]
	v_pk_fma_f32 v[218:219], v[58:59], v[178:179], v[218:219]
	v_pk_fma_f32 v[204:205], v[60:61], v[172:173], v[204:205]
	v_pk_fma_f32 v[206:207], v[62:63], v[174:175], v[206:207]
	v_pk_fma_f32 v[208:209], v[64:65], v[176:177], v[208:209]
	v_pk_fma_f32 v[210:211], v[66:67], v[178:179], v[210:211]
	v_mul_f32_e32 v220, 0xbfb8aa3b, v204
	v_mul_f32_e32 v221, 0xbfb8aa3b, v205
	v_mul_f32_e32 v222, 0xbfb8aa3b, v206
	v_mul_f32_e32 v223, 0xbfb8aa3b, v207
	v_mul_f32_e32 v224, 0xbfb8aa3b, v208
	v_mul_f32_e32 v225, 0xbfb8aa3b, v209
	v_mul_f32_e32 v226, 0xbfb8aa3b, v210
	v_mul_f32_e32 v227, 0xbfb8aa3b, v211
	v_exp_f32_e32 v220, v220
	v_exp_f32_e32 v221, v221
	v_exp_f32_e32 v222, v222
	v_exp_f32_e32 v223, v223
	v_exp_f32_e32 v224, v224
	v_exp_f32_e32 v225, v225
	v_exp_f32_e32 v226, v226
	v_exp_f32_e32 v227, v227
	v_add_f32_e32 v220, 1.0, v220
	v_add_f32_e32 v221, 1.0, v221
	v_add_f32_e32 v222, 1.0, v222
	v_add_f32_e32 v223, 1.0, v223
	v_add_f32_e32 v224, 1.0, v224
	v_add_f32_e32 v225, 1.0, v225
	v_add_f32_e32 v226, 1.0, v226
	v_add_f32_e32 v227, 1.0, v227
	v_rcp_f32_e32 v220, v220
	v_rcp_f32_e32 v221, v221
	v_rcp_f32_e32 v222, v222
	v_rcp_f32_e32 v223, v223
	v_rcp_f32_e32 v224, v224
	v_rcp_f32_e32 v225, v225
	v_rcp_f32_e32 v226, v226
	v_rcp_f32_e32 v227, v227
	v_mul_f32_e32 v220, v204, v220
	v_mul_f32_e32 v221, v205, v221
	v_mul_f32_e32 v222, v206, v222
	v_mul_f32_e32 v223, v207, v223
	v_mul_f32_e32 v224, v208, v224
	v_mul_f32_e32 v225, v209, v225
	v_mul_f32_e32 v226, v210, v226
	v_mul_f32_e32 v227, v211, v227
	v_cvt_pk_bf16_f32 v204, v220, v221
	v_cvt_pk_bf16_f32 v205, v222, v223
	v_cvt_pk_bf16_f32 v206, v224, v225
	v_cvt_pk_bf16_f32 v207, v226, v227
	global_store_dwordx4 v26, v[204:207], s[54:55] sc1
	s_add_u32 s54, s54, 0x1000
	s_addc_u32 s55, s55, 0
	s_waitcnt vmcnt(15)
	v_and_b32_e32 v152, s63, v152
	v_and_b32_e32 v153, s63, v153
	v_and_b32_e32 v154, s63, v154
	v_and_b32_e32 v155, s63, v155
	v_lshlrev_b32_e32 v172, 16, v152
	v_and_b32_e32 v173, 0xffff0000, v152
	v_lshlrev_b32_e32 v174, 16, v153
	v_and_b32_e32 v175, 0xffff0000, v153
	v_lshlrev_b32_e32 v176, 16, v154
	v_and_b32_e32 v177, 0xffff0000, v154
	v_lshlrev_b32_e32 v178, 16, v155
	v_and_b32_e32 v179, 0xffff0000, v155
	v_pk_fma_f32 v[180:181], v[52:53], v[172:173], v[180:181]
	v_pk_fma_f32 v[182:183], v[54:55], v[174:175], v[182:183]
	v_pk_fma_f32 v[184:185], v[56:57], v[176:177], v[184:185]
	v_pk_fma_f32 v[186:187], v[58:59], v[178:179], v[186:187]
	v_pk_fma_f32 v[212:213], v[60:61], v[172:173], v[212:213]
	v_pk_fma_f32 v[214:215], v[62:63], v[174:175], v[214:215]
	v_pk_fma_f32 v[216:217], v[64:65], v[176:177], v[216:217]
	v_pk_fma_f32 v[218:219], v[66:67], v[178:179], v[218:219]
	v_mul_f32_e32 v220, 0xbfb8aa3b, v212
	v_mul_f32_e32 v221, 0xbfb8aa3b, v213
	v_mul_f32_e32 v222, 0xbfb8aa3b, v214
	v_mul_f32_e32 v223, 0xbfb8aa3b, v215
	v_mul_f32_e32 v224, 0xbfb8aa3b, v216
	v_mul_f32_e32 v225, 0xbfb8aa3b, v217
	v_mul_f32_e32 v226, 0xbfb8aa3b, v218
	v_mul_f32_e32 v227, 0xbfb8aa3b, v219
	v_exp_f32_e32 v220, v220
	v_exp_f32_e32 v221, v221
	v_exp_f32_e32 v222, v222
	v_exp_f32_e32 v223, v223
	v_exp_f32_e32 v224, v224
	v_exp_f32_e32 v225, v225
	v_exp_f32_e32 v226, v226
	v_exp_f32_e32 v227, v227
	v_add_f32_e32 v220, 1.0, v220
	v_add_f32_e32 v221, 1.0, v221
	v_add_f32_e32 v222, 1.0, v222
	v_add_f32_e32 v223, 1.0, v223
	v_add_f32_e32 v224, 1.0, v224
	v_add_f32_e32 v225, 1.0, v225
	v_add_f32_e32 v226, 1.0, v226
	v_add_f32_e32 v227, 1.0, v227
	v_rcp_f32_e32 v220, v220
	v_rcp_f32_e32 v221, v221
	v_rcp_f32_e32 v222, v222
	v_rcp_f32_e32 v223, v223
	v_rcp_f32_e32 v224, v224
	v_rcp_f32_e32 v225, v225
	v_rcp_f32_e32 v226, v226
	v_rcp_f32_e32 v227, v227
	v_mul_f32_e32 v220, v212, v220
	v_mul_f32_e32 v221, v213, v221
	v_mul_f32_e32 v222, v214, v222
	v_mul_f32_e32 v223, v215, v223
	v_mul_f32_e32 v224, v216, v224
	v_mul_f32_e32 v225, v217, v225
	v_mul_f32_e32 v226, v218, v226
	v_mul_f32_e32 v227, v219, v227
	v_cvt_pk_bf16_f32 v212, v220, v221
	v_cvt_pk_bf16_f32 v213, v222, v223
	v_cvt_pk_bf16_f32 v214, v224, v225
	v_cvt_pk_bf16_f32 v215, v226, v227
	global_store_dwordx4 v26, v[212:215], s[54:55] sc1
	s_add_u32 s54, s54, 0x1000
	s_addc_u32 s55, s55, 0
	s_waitcnt vmcnt(15)
	v_and_b32_e32 v156, s63, v156
	v_and_b32_e32 v157, s63, v157
	v_and_b32_e32 v158, s63, v158
	v_and_b32_e32 v159, s63, v159
	v_lshlrev_b32_e32 v172, 16, v156
	v_and_b32_e32 v173, 0xffff0000, v156
	v_lshlrev_b32_e32 v174, 16, v157
	v_and_b32_e32 v175, 0xffff0000, v157
	v_lshlrev_b32_e32 v176, 16, v158
	v_and_b32_e32 v177, 0xffff0000, v158
	v_lshlrev_b32_e32 v178, 16, v159
	v_and_b32_e32 v179, 0xffff0000, v159
	v_pk_fma_f32 v[180:181], v[60:61], v[172:173], v[180:181]
	v_pk_fma_f32 v[182:183], v[62:63], v[174:175], v[182:183]
	v_pk_fma_f32 v[184:185], v[64:65], v[176:177], v[184:185]
	v_pk_fma_f32 v[186:187], v[66:67], v[178:179], v[186:187]
	v_mul_f32_e32 v220, 0xbfb8aa3b, v180
	v_mul_f32_e32 v221, 0xbfb8aa3b, v181
	v_mul_f32_e32 v222, 0xbfb8aa3b, v182
	v_mul_f32_e32 v223, 0xbfb8aa3b, v183
	v_mul_f32_e32 v224, 0xbfb8aa3b, v184
	v_mul_f32_e32 v225, 0xbfb8aa3b, v185
	v_mul_f32_e32 v226, 0xbfb8aa3b, v186
	v_mul_f32_e32 v227, 0xbfb8aa3b, v187
	v_exp_f32_e32 v220, v220
	v_exp_f32_e32 v221, v221
	v_exp_f32_e32 v222, v222
	v_exp_f32_e32 v223, v223
	v_exp_f32_e32 v224, v224
	v_exp_f32_e32 v225, v225
	v_exp_f32_e32 v226, v226
	v_exp_f32_e32 v227, v227
	v_add_f32_e32 v220, 1.0, v220
	v_add_f32_e32 v221, 1.0, v221
	v_add_f32_e32 v222, 1.0, v222
	v_add_f32_e32 v223, 1.0, v223
	v_add_f32_e32 v224, 1.0, v224
	v_add_f32_e32 v225, 1.0, v225
	v_add_f32_e32 v226, 1.0, v226
	v_add_f32_e32 v227, 1.0, v227
	v_rcp_f32_e32 v220, v220
	v_rcp_f32_e32 v221, v221
	v_rcp_f32_e32 v222, v222
	v_rcp_f32_e32 v223, v223
	v_rcp_f32_e32 v224, v224
	v_rcp_f32_e32 v225, v225
	v_rcp_f32_e32 v226, v226
	v_rcp_f32_e32 v227, v227
	v_mul_f32_e32 v220, v180, v220
	v_mul_f32_e32 v221, v181, v221
	v_mul_f32_e32 v222, v182, v222
	v_mul_f32_e32 v223, v183, v223
	v_mul_f32_e32 v224, v184, v224
	v_mul_f32_e32 v225, v185, v225
	v_mul_f32_e32 v226, v186, v226
	v_mul_f32_e32 v227, v187, v227
	v_cvt_pk_bf16_f32 v180, v220, v221
	v_cvt_pk_bf16_f32 v181, v222, v223
	v_cvt_pk_bf16_f32 v182, v224, v225
	v_cvt_pk_bf16_f32 v183, v226, v227
	global_store_dwordx4 v26, v[180:183], s[54:55] sc1
	s_add_u32 s54, s54, 0x1000
	s_addc_u32 s55, s55, 0
	s_add_u32 s3, s3, s64
	s_branch .Lcv3_rb

.LBB0_833:
	s_cmp_gt_i32 s60, 6
	s_cselect_b64 s[2:3], -1, 0
	s_cmp_lt_i32 s61, 6
	s_cselect_b64 s[4:5], -1, 0
	s_or_b64 s[2:3], s[2:3], s[4:5]
	s_and_b64 vcc, exec, s[2:3]
	s_cbranch_vccnz .LBB0_893
	s_load_dwordx2 s[4:5], s[0:1], 0xe0
	s_load_dword s16, s[0:1], 0xf0
	v_and_b32_e32 v240, 63, v162
	v_lshrrev_b32_e32 v247, 6, v162
	v_lshrrev_b32_e32 v242, 3, v240
	v_lshl_add_u32 v242, v247, 5, v242
	v_and_b32_e32 v243, 7, v240
	v_lshrrev_b32_e32 v244, 4, v240
	v_xor_b32_e32 v243, v243, v244
	v_lshlrev_b32_e32 v243, 4, v243
	v_mov_b32_e32 v241, 0x1000
	v_mad_u32_u24 v248, v242, v241, v243
	v_xor_b32_e32 v249, 64, v248
	v_add_u32_e32 v249, 0x8000, v249
	v_add_u32_e32 v250, 0x10000, v248
	v_xor_b32_e32 v251, 64, v248
	v_add_u32_e32 v251, 0x18000, v251
	v_and_b32_e32 v241, 15, v240
	v_lshrrev_b32_e32 v242, 1, v241
	v_xor_b32_e32 v242, v242, v244
	v_lshlrev_b32_e32 v242, 4, v242
	v_lshl_or_b32 v242, v241, 7, v242
	v_lshrrev_b32_e32 v243, 1, v247
	v_lshl_or_b32 v252, v243, 13, v242
	v_xor_b32_e32 v253, 64, v252
	v_and_b32_e32 v243, 1, v247
	v_lshl_or_b32 v254, v243, 13, v242
	v_xor_b32_e32 v255, 64, v254
	v_and_b32_e32 v240, 63, v162
	v_and_b32_e32 v241, 15, v240
	v_lshrrev_b32_e32 v242, 4, v240
	v_lshrrev_b32_e32 v243, 1, v247
	v_and_b32_e32 v244, 1, v247
	v_lshl_or_b32 v245, v244, 6, v241
	v_lshlrev_b32_e32 v243, 4, v243
	v_add_u32_e32 v243, v243, v242
	v_lshl_add_u32 v246, v243, 12, v245
	v_lshlrev_b32_e32 v246, 2, v246
	v_lshlrev_b32_e32 v245, 2, v245
	s_waitcnt lgkmcnt(0)
	s_add_u32 s26, s4, 0x1257a100
	s_addc_u32 s27, s5, 0
	s_add_u32 s28, s4, 0x1880000
	s_addc_u32 s29, s5, 0
	s_mov_b32 s15, s58
.Lr6_tile:
	s_cmp_lt_u32 s15, 0x200
	s_cbranch_scc0 .Lr6_end
	s_and_b32 s2, s15, 63
	s_lshr_b32 s3, s15, 6
	s_mul_i32 s14, s2, 0x80000
	s_add_u32 s8, s26, s14
	s_addc_u32 s9, s27, 0
	s_mul_i32 s14, s3, 0x80000
	s_add_u32 s10, s28, s14
	s_addc_u32 s11, s29, 0
	s_lshl_b32 s14, s2, 19
	s_lshl_b32 s6, s3, 9
	s_add_u32 s14, s14, s6
	s_add_u32 s20, s4, 0x6b7a100
	s_addc_u32 s21, s5, 0
	s_add_u32 s20, s20, s14
	s_addc_u32 s21, s21, 0
	s_sub_u32 s7, s2, 32
	s_lshr_b32 s7, s7, 3
	s_add_u32 s7, s7, 1
	s_cmp_lt_u32 s2, 32
	s_cselect_b32 s7, 0, s7
	s_mul_i32 s7, s7, 0x6000
	s_add_u32 s7, s7, s6
	s_add_u32 s22, s4, 0x6b04000
	s_addc_u32 s23, s5, 0
	s_add_u32 s22, s22, s7
	s_addc_u32 s23, s23, 0
	v_readfirstlane_b32 s12, v247
	global_load_dword v201, v245, s[22:23] offset:0
	global_load_dword v202, v245, s[22:23] offset:64
	global_load_dword v203, v245, s[22:23] offset:128
	global_load_dword v204, v245, s[22:23] offset:192
	s_mov_b64 s[18:19], s[20:21]
	global_load_dword v129, v246, s[18:19] offset:0
	global_load_dword v130, v246, s[18:19] offset:64
	global_load_dword v131, v246, s[18:19] offset:128
	global_load_dword v132, v246, s[18:19] offset:192
	s_add_u32 s18, s18, 0x1000
	s_addc_u32 s19, s19, 0
	global_load_dword v133, v246, s[18:19] offset:0
	global_load_dword v134, v246, s[18:19] offset:64
	global_load_dword v135, v246, s[18:19] offset:128
	global_load_dword v136, v246, s[18:19] offset:192
	s_add_u32 s18, s18, 0x1000
	s_addc_u32 s19, s19, 0
	global_load_dword v137, v246, s[18:19] offset:0
	global_load_dword v138, v246, s[18:19] offset:64
	global_load_dword v139, v246, s[18:19] offset:128
	global_load_dword v140, v246, s[18:19] offset:192
	s_add_u32 s18, s18, 0x1000
	s_addc_u32 s19, s19, 0
	global_load_dword v141, v246, s[18:19] offset:0
	global_load_dword v142, v246, s[18:19] offset:64
	global_load_dword v143, v246, s[18:19] offset:128
	global_load_dword v144, v246, s[18:19] offset:192
	s_add_u32 s18, s18, 0xd000
	s_addc_u32 s19, s19, 0
	global_load_dword v145, v246, s[18:19] offset:0
	global_load_dword v146, v246, s[18:19] offset:64
	global_load_dword v147, v246, s[18:19] offset:128
	global_load_dword v148, v246, s[18:19] offset:192
	s_add_u32 s18, s18, 0x1000
	s_addc_u32 s19, s19, 0
	global_load_dword v149, v246, s[18:19] offset:0
	global_load_dword v150, v246, s[18:19] offset:64
	global_load_dword v151, v246, s[18:19] offset:128
	global_load_dword v152, v246, s[18:19] offset:192
	s_add_u32 s18, s18, 0x1000
	s_addc_u32 s19, s19, 0
	global_load_dword v153, v246, s[18:19] offset:0
	global_load_dword v154, v246, s[18:19] offset:64
	global_load_dword v155, v246, s[18:19] offset:128
	global_load_dword v156, v246, s[18:19] offset:192
	s_add_u32 s18, s18, 0x1000
	s_addc_u32 s19, s19, 0
	global_load_dword v157, v246, s[18:19] offset:0
	global_load_dword v158, v246, s[18:19] offset:64
	global_load_dword v159, v246, s[18:19] offset:128
	global_load_dword v160, v246, s[18:19] offset:192
	s_add_u32 s18, s18, 0xd000
	s_addc_u32 s19, s19, 0
	global_load_dword v161, v246, s[18:19] offset:0
	global_load_dword v170, v246, s[18:19] offset:64
	global_load_dword v171, v246, s[18:19] offset:128
	global_load_dword v172, v246, s[18:19] offset:192
	s_add_u32 s18, s18, 0x1000
	s_addc_u32 s19, s19, 0
	global_load_dword v173, v246, s[18:19] offset:0
	global_load_dword v174, v246, s[18:19] offset:64
	global_load_dword v175, v246, s[18:19] offset:128
	global_load_dword v176, v246, s[18:19] offset:192
	s_add_u32 s18, s18, 0x1000
	s_addc_u32 s19, s19, 0
	global_load_dword v177, v246, s[18:19] offset:0
	global_load_dword v178, v246, s[18:19] offset:64
	global_load_dword v179, v246, s[18:19] offset:128
	global_load_dword v180, v246, s[18:19] offset:192
	s_add_u32 s18, s18, 0x1000
	s_addc_u32 s19, s19, 0
	global_load_dword v181, v246, s[18:19] offset:0
	global_load_dword v182, v246, s[18:19] offset:64
	global_load_dword v183, v246, s[18:19] offset:128
	global_load_dword v184, v246, s[18:19] offset:192
	s_add_u32 s18, s18, 0xd000
	s_addc_u32 s19, s19, 0
	global_load_dword v185, v246, s[18:19] offset:0
	global_load_dword v186, v246, s[18:19] offset:64
	global_load_dword v187, v246, s[18:19] offset:128
	global_load_dword v188, v246, s[18:19] offset:192
	s_add_u32 s18, s18, 0x1000
	s_addc_u32 s19, s19, 0
	global_load_dword v189, v246, s[18:19] offset:0
	global_load_dword v190, v246, s[18:19] offset:64
	global_load_dword v191, v246, s[18:19] offset:128
	global_load_dword v192, v246, s[18:19] offset:192
	s_add_u32 s18, s18, 0x1000
	s_addc_u32 s19, s19, 0
	global_load_dword v193, v246, s[18:19] offset:0
	global_load_dword v194, v246, s[18:19] offset:64
	global_load_dword v195, v246, s[18:19] offset:128
	global_load_dword v196, v246, s[18:19] offset:192
	s_add_u32 s18, s18, 0x1000
	s_addc_u32 s19, s19, 0
	global_load_dword v197, v246, s[18:19] offset:0
	global_load_dword v198, v246, s[18:19] offset:64
	global_load_dword v199, v246, s[18:19] offset:128
	global_load_dword v200, v246, s[18:19] offset:192
	s_lshl_b32 s12, s12, 12
	s_add_u32 m0, s12, 0x0
	v_mov_b32_e32 v0, 0
	global_load_lds_dwordx4 v248, s[8:9]
	v_mov_b32_e32 v1, 0
	s_add_u32 m0, s12, 0x400
	v_mov_b32_e32 v2, 0
	global_load_lds_dwordx4 v249, s[8:9]
	v_mov_b32_e32 v3, 0
	s_add_u32 m0, s12, 0x800
	v_mov_b32_e32 v4, 0
	global_load_lds_dwordx4 v250, s[8:9]
	v_mov_b32_e32 v5, 0
	s_add_u32 m0, s12, 0xc00
	v_mov_b32_e32 v6, 0
	global_load_lds_dwordx4 v251, s[8:9]
	v_mov_b32_e32 v7, 0
	s_add_u32 m0, s12, 0x8000
	v_mov_b32_e32 v8, 0
	global_load_lds_dwordx4 v248, s[10:11]
	v_mov_b32_e32 v9, 0
	s_add_u32 m0, s12, 0x8400
	v_mov_b32_e32 v10, 0
	global_load_lds_dwordx4 v249, s[10:11]
	v_mov_b32_e32 v11, 0
	s_add_u32 m0, s12, 0x8800
	v_mov_b32_e32 v12, 0
	global_load_lds_dwordx4 v250, s[10:11]
	v_mov_b32_e32 v13, 0
	s_add_u32 m0, s12, 0x8c00
	v_mov_b32_e32 v14, 0
	global_load_lds_dwordx4 v251, s[10:11]
	v_mov_b32_e32 v15, 0
	s_add_u32 s8, s8, 0x80
	s_addc_u32 s9, s9, 0
	s_add_u32 s10, s10, 0x80
	s_addc_u32 s11, s11, 0
	s_add_u32 m0, s12, 0x4000
	v_mov_b32_e32 v16, 0
	global_load_lds_dwordx4 v248, s[8:9]
	v_mov_b32_e32 v17, 0
	s_add_u32 m0, s12, 0x4400
	v_mov_b32_e32 v18, 0
	global_load_lds_dwordx4 v249, s[8:9]
	v_mov_b32_e32 v19, 0
	s_add_u32 m0, s12, 0x4800
	v_mov_b32_e32 v20, 0
	global_load_lds_dwordx4 v250, s[8:9]
	v_mov_b32_e32 v21, 0
	s_add_u32 m0, s12, 0x4c00
	v_mov_b32_e32 v22, 0
	global_load_lds_dwordx4 v251, s[8:9]
	v_mov_b32_e32 v23, 0
	s_add_u32 m0, s12, 0xc000
	v_mov_b32_e32 v24, 0
	global_load_lds_dwordx4 v248, s[10:11]
	v_mov_b32_e32 v25, 0
	s_add_u32 m0, s12, 0xc400
	v_mov_b32_e32 v26, 0
	global_load_lds_dwordx4 v249, s[10:11]
	v_mov_b32_e32 v27, 0
	s_add_u32 m0, s12, 0xc800
	v_mov_b32_e32 v28, 0
	global_load_lds_dwordx4 v250, s[10:11]
	v_mov_b32_e32 v29, 0
	s_add_u32 m0, s12, 0xcc00
	v_mov_b32_e32 v30, 0
	global_load_lds_dwordx4 v251, s[10:11]
	v_mov_b32_e32 v31, 0
	s_add_u32 s8, s8, 0x80
	s_addc_u32 s9, s9, 0
	s_add_u32 s10, s10, 0x80
	s_addc_u32 s11, s11, 0
	v_mov_b32_e32 v32, 0
	v_mov_b32_e32 v33, 0
	v_mov_b32_e32 v34, 0
	v_mov_b32_e32 v35, 0
	v_mov_b32_e32 v36, 0
	v_mov_b32_e32 v37, 0
	v_mov_b32_e32 v38, 0
	v_mov_b32_e32 v39, 0
	v_mov_b32_e32 v40, 0
	v_mov_b32_e32 v41, 0
	v_mov_b32_e32 v42, 0
	v_mov_b32_e32 v43, 0
	v_mov_b32_e32 v44, 0
	v_mov_b32_e32 v45, 0
	v_mov_b32_e32 v46, 0
	v_mov_b32_e32 v47, 0
	v_mov_b32_e32 v48, 0
	v_mov_b32_e32 v49, 0
	v_mov_b32_e32 v50, 0
	v_mov_b32_e32 v51, 0
	v_mov_b32_e32 v52, 0
	v_mov_b32_e32 v53, 0
	v_mov_b32_e32 v54, 0
	v_mov_b32_e32 v55, 0
	v_mov_b32_e32 v56, 0
	v_mov_b32_e32 v57, 0
	v_mov_b32_e32 v58, 0
	v_mov_b32_e32 v59, 0
	v_mov_b32_e32 v60, 0
	v_mov_b32_e32 v61, 0
	v_mov_b32_e32 v62, 0
	v_mov_b32_e32 v63, 0
	s_waitcnt vmcnt(8)
	s_barrier
	ds_read_b128 v[64:67], v252 offset:0
	ds_read_b128 v[96:99], v254 offset:32768
	ds_read_b128 v[100:103], v254 offset:34816
	ds_read_b128 v[104:107], v254 offset:36864
	ds_read_b128 v[108:111], v254 offset:38912
	ds_read_b128 v[68:71], v252 offset:2048
	ds_read_b128 v[72:75], v252 offset:4096
	ds_read_b128 v[76:79], v252 offset:6144
	ds_read_b128 v[80:83], v253 offset:0
	ds_read_b128 v[112:115], v255 offset:32768
	ds_read_b128 v[116:119], v255 offset:34816
	ds_read_b128 v[120:123], v255 offset:36864
	ds_read_b128 v[124:127], v255 offset:38912
	s_waitcnt lgkmcnt(11)
	v_mfma_f32_16x16x32_bf16 v[0:3], v[64:67], v[96:99], v[0:3]
	s_waitcnt lgkmcnt(10)
	v_mfma_f32_16x16x32_bf16 v[4:7], v[64:67], v[100:103], v[4:7]
	s_waitcnt lgkmcnt(9)
	v_mfma_f32_16x16x32_bf16 v[8:11], v[64:67], v[104:107], v[8:11]
	s_waitcnt lgkmcnt(8)
	v_mfma_f32_16x16x32_bf16 v[12:15], v[64:67], v[108:111], v[12:15]
	ds_read_b128 v[84:87], v253 offset:2048
	ds_read_b128 v[88:91], v253 offset:4096
	ds_read_b128 v[92:95], v253 offset:6144
	s_waitcnt lgkmcnt(10)
	v_mfma_f32_16x16x32_bf16 v[16:19], v[68:71], v[96:99], v[16:19]
	v_mfma_f32_16x16x32_bf16 v[20:23], v[68:71], v[100:103], v[20:23]
	v_mfma_f32_16x16x32_bf16 v[24:27], v[68:71], v[104:107], v[24:27]
	v_mfma_f32_16x16x32_bf16 v[28:31], v[68:71], v[108:111], v[28:31]
	s_waitcnt lgkmcnt(0)
	s_barrier
	s_add_u32 m0, s12, 0x0
	v_mfma_f32_16x16x32_bf16 v[32:35], v[72:75], v[96:99], v[32:35]
	global_load_lds_dwordx4 v248, s[8:9]
	s_add_u32 m0, s12, 0x400
	v_mfma_f32_16x16x32_bf16 v[36:39], v[72:75], v[100:103], v[36:39]
	global_load_lds_dwordx4 v249, s[8:9]
	s_add_u32 m0, s12, 0x800
	v_mfma_f32_16x16x32_bf16 v[40:43], v[72:75], v[104:107], v[40:43]
	global_load_lds_dwordx4 v250, s[8:9]
	s_add_u32 m0, s12, 0xc00
	v_mfma_f32_16x16x32_bf16 v[44:47], v[72:75], v[108:111], v[44:47]
	global_load_lds_dwordx4 v251, s[8:9]
	s_add_u32 m0, s12, 0x8000
	v_mfma_f32_16x16x32_bf16 v[48:51], v[76:79], v[96:99], v[48:51]
	global_load_lds_dwordx4 v248, s[10:11]
	s_add_u32 m0, s12, 0x8400
	v_mfma_f32_16x16x32_bf16 v[52:55], v[76:79], v[100:103], v[52:55]
	global_load_lds_dwordx4 v249, s[10:11]
	s_add_u32 m0, s12, 0x8800
	v_mfma_f32_16x16x32_bf16 v[56:59], v[76:79], v[104:107], v[56:59]
	global_load_lds_dwordx4 v250, s[10:11]
	s_add_u32 m0, s12, 0x8c00
	v_mfma_f32_16x16x32_bf16 v[60:63], v[76:79], v[108:111], v[60:63]
	global_load_lds_dwordx4 v251, s[10:11]
	s_add_u32 s8, s8, 0x80
	s_addc_u32 s9, s9, 0
	s_add_u32 s10, s10, 0x80
	s_addc_u32 s11, s11, 0
	s_waitcnt vmcnt(8)
	s_barrier
	ds_read_b128 v[64:67], v252 offset:16384
	ds_read_b128 v[96:99], v254 offset:49152
	ds_read_b128 v[100:103], v254 offset:51200
	ds_read_b128 v[104:107], v254 offset:53248
	ds_read_b128 v[108:111], v254 offset:55296
	ds_read_b128 v[68:71], v252 offset:18432
	ds_read_b128 v[72:75], v252 offset:20480
	ds_read_b128 v[76:79], v252 offset:22528
	v_mfma_f32_16x16x32_bf16 v[0:3], v[80:83], v[112:115], v[0:3]
	v_mfma_f32_16x16x32_bf16 v[4:7], v[80:83], v[116:119], v[4:7]
	v_mfma_f32_16x16x32_bf16 v[8:11], v[80:83], v[120:123], v[8:11]
	v_mfma_f32_16x16x32_bf16 v[12:15], v[80:83], v[124:127], v[12:15]
	v_mfma_f32_16x16x32_bf16 v[16:19], v[84:87], v[112:115], v[16:19]
	v_mfma_f32_16x16x32_bf16 v[20:23], v[84:87], v[116:119], v[20:23]
	v_mfma_f32_16x16x32_bf16 v[24:27], v[84:87], v[120:123], v[24:27]
	v_mfma_f32_16x16x32_bf16 v[28:31], v[84:87], v[124:127], v[28:31]
	v_mfma_f32_16x16x32_bf16 v[32:35], v[88:91], v[112:115], v[32:35]
	v_mfma_f32_16x16x32_bf16 v[36:39], v[88:91], v[116:119], v[36:39]
	v_mfma_f32_16x16x32_bf16 v[40:43], v[88:91], v[120:123], v[40:43]
	v_mfma_f32_16x16x32_bf16 v[44:47], v[88:91], v[124:127], v[44:47]
	v_mfma_f32_16x16x32_bf16 v[48:51], v[92:95], v[112:115], v[48:51]
	v_mfma_f32_16x16x32_bf16 v[52:55], v[92:95], v[116:119], v[52:55]
	v_mfma_f32_16x16x32_bf16 v[56:59], v[92:95], v[120:123], v[56:59]
	v_mfma_f32_16x16x32_bf16 v[60:63], v[92:95], v[124:127], v[60:63]
	ds_read_b128 v[80:83], v253 offset:16384
	ds_read_b128 v[112:115], v255 offset:49152
	ds_read_b128 v[116:119], v255 offset:51200
	ds_read_b128 v[120:123], v255 offset:53248
	ds_read_b128 v[124:127], v255 offset:55296
	ds_read_b128 v[84:87], v253 offset:18432
	ds_read_b128 v[88:91], v253 offset:20480
	ds_read_b128 v[92:95], v253 offset:22528
	s_waitcnt lgkmcnt(14)
	v_mfma_f32_16x16x32_bf16 v[0:3], v[64:67], v[96:99], v[0:3]
	s_waitcnt lgkmcnt(13)
	v_mfma_f32_16x16x32_bf16 v[4:7], v[64:67], v[100:103], v[4:7]
	s_waitcnt lgkmcnt(12)
	v_mfma_f32_16x16x32_bf16 v[8:11], v[64:67], v[104:107], v[8:11]
	s_waitcnt lgkmcnt(11)
	v_mfma_f32_16x16x32_bf16 v[12:15], v[64:67], v[108:111], v[12:15]
	s_waitcnt lgkmcnt(10)
	v_mfma_f32_16x16x32_bf16 v[16:19], v[68:71], v[96:99], v[16:19]
	v_mfma_f32_16x16x32_bf16 v[20:23], v[68:71], v[100:103], v[20:23]
	v_mfma_f32_16x16x32_bf16 v[24:27], v[68:71], v[104:107], v[24:27]
	v_mfma_f32_16x16x32_bf16 v[28:31], v[68:71], v[108:111], v[28:31]
	s_waitcnt lgkmcnt(0)
	s_barrier
	s_add_u32 m0, s12, 0x4000
	v_mfma_f32_16x16x32_bf16 v[32:35], v[72:75], v[96:99], v[32:35]
	global_load_lds_dwordx4 v248, s[8:9]
	s_add_u32 m0, s12, 0x4400
	v_mfma_f32_16x16x32_bf16 v[36:39], v[72:75], v[100:103], v[36:39]
	global_load_lds_dwordx4 v249, s[8:9]
	s_add_u32 m0, s12, 0x4800
	v_mfma_f32_16x16x32_bf16 v[40:43], v[72:75], v[104:107], v[40:43]
	global_load_lds_dwordx4 v250, s[8:9]
	s_add_u32 m0, s12, 0x4c00
	v_mfma_f32_16x16x32_bf16 v[44:47], v[72:75], v[108:111], v[44:47]
	global_load_lds_dwordx4 v251, s[8:9]
	s_add_u32 m0, s12, 0xc000
	v_mfma_f32_16x16x32_bf16 v[48:51], v[76:79], v[96:99], v[48:51]
	global_load_lds_dwordx4 v248, s[10:11]
	s_add_u32 m0, s12, 0xc400
	v_mfma_f32_16x16x32_bf16 v[52:55], v[76:79], v[100:103], v[52:55]
	global_load_lds_dwordx4 v249, s[10:11]
	s_add_u32 m0, s12, 0xc800
	v_mfma_f32_16x16x32_bf16 v[56:59], v[76:79], v[104:107], v[56:59]
	global_load_lds_dwordx4 v250, s[10:11]
	s_add_u32 m0, s12, 0xcc00
	v_mfma_f32_16x16x32_bf16 v[60:63], v[76:79], v[108:111], v[60:63]
	global_load_lds_dwordx4 v251, s[10:11]
	s_add_u32 s8, s8, 0x80
	s_addc_u32 s9, s9, 0
	s_add_u32 s10, s10, 0x80
	s_addc_u32 s11, s11, 0
	s_mov_b32 s13, 14
.Lr6_loop:
	s_waitcnt vmcnt(8)
	s_barrier
	ds_read_b128 v[64:67], v252 offset:0
	ds_read_b128 v[96:99], v254 offset:32768
	ds_read_b128 v[100:103], v254 offset:34816
	ds_read_b128 v[104:107], v254 offset:36864
	ds_read_b128 v[108:111], v254 offset:38912
	ds_read_b128 v[68:71], v252 offset:2048
	ds_read_b128 v[72:75], v252 offset:4096
	ds_read_b128 v[76:79], v252 offset:6144
	v_mfma_f32_16x16x32_bf16 v[0:3], v[80:83], v[112:115], v[0:3]
	v_mfma_f32_16x16x32_bf16 v[4:7], v[80:83], v[116:119], v[4:7]
	v_mfma_f32_16x16x32_bf16 v[8:11], v[80:83], v[120:123], v[8:11]
	v_mfma_f32_16x16x32_bf16 v[12:15], v[80:83], v[124:127], v[12:15]
	v_mfma_f32_16x16x32_bf16 v[16:19], v[84:87], v[112:115], v[16:19]
	v_mfma_f32_16x16x32_bf16 v[20:23], v[84:87], v[116:119], v[20:23]
	v_mfma_f32_16x16x32_bf16 v[24:27], v[84:87], v[120:123], v[24:27]
	v_mfma_f32_16x16x32_bf16 v[28:31], v[84:87], v[124:127], v[28:31]
	v_mfma_f32_16x16x32_bf16 v[32:35], v[88:91], v[112:115], v[32:35]
	v_mfma_f32_16x16x32_bf16 v[36:39], v[88:91], v[116:119], v[36:39]
	v_mfma_f32_16x16x32_bf16 v[40:43], v[88:91], v[120:123], v[40:43]
	v_mfma_f32_16x16x32_bf16 v[44:47], v[88:91], v[124:127], v[44:47]
	v_mfma_f32_16x16x32_bf16 v[48:51], v[92:95], v[112:115], v[48:51]
	v_mfma_f32_16x16x32_bf16 v[52:55], v[92:95], v[116:119], v[52:55]
	v_mfma_f32_16x16x32_bf16 v[56:59], v[92:95], v[120:123], v[56:59]
	v_mfma_f32_16x16x32_bf16 v[60:63], v[92:95], v[124:127], v[60:63]
	ds_read_b128 v[80:83], v253 offset:0
	ds_read_b128 v[112:115], v255 offset:32768
	ds_read_b128 v[116:119], v255 offset:34816
	ds_read_b128 v[120:123], v255 offset:36864
	ds_read_b128 v[124:127], v255 offset:38912
	ds_read_b128 v[84:87], v253 offset:2048
	ds_read_b128 v[88:91], v253 offset:4096
	ds_read_b128 v[92:95], v253 offset:6144
	s_waitcnt lgkmcnt(14)
	v_mfma_f32_16x16x32_bf16 v[0:3], v[64:67], v[96:99], v[0:3]
	s_waitcnt lgkmcnt(13)
	v_mfma_f32_16x16x32_bf16 v[4:7], v[64:67], v[100:103], v[4:7]
	s_waitcnt lgkmcnt(12)
	v_mfma_f32_16x16x32_bf16 v[8:11], v[64:67], v[104:107], v[8:11]
	s_waitcnt lgkmcnt(11)
	v_mfma_f32_16x16x32_bf16 v[12:15], v[64:67], v[108:111], v[12:15]
	s_waitcnt lgkmcnt(10)
	v_mfma_f32_16x16x32_bf16 v[16:19], v[68:71], v[96:99], v[16:19]
	v_mfma_f32_16x16x32_bf16 v[20:23], v[68:71], v[100:103], v[20:23]
	v_mfma_f32_16x16x32_bf16 v[24:27], v[68:71], v[104:107], v[24:27]
	v_mfma_f32_16x16x32_bf16 v[28:31], v[68:71], v[108:111], v[28:31]
	s_waitcnt lgkmcnt(0)
	s_barrier
	s_add_u32 m0, s12, 0x0
	v_mfma_f32_16x16x32_bf16 v[32:35], v[72:75], v[96:99], v[32:35]
	global_load_lds_dwordx4 v248, s[8:9]
	s_add_u32 m0, s12, 0x400
	v_mfma_f32_16x16x32_bf16 v[36:39], v[72:75], v[100:103], v[36:39]
	global_load_lds_dwordx4 v249, s[8:9]
	s_add_u32 m0, s12, 0x800
	v_mfma_f32_16x16x32_bf16 v[40:43], v[72:75], v[104:107], v[40:43]
	global_load_lds_dwordx4 v250, s[8:9]
	s_add_u32 m0, s12, 0xc00
	v_mfma_f32_16x16x32_bf16 v[44:47], v[72:75], v[108:111], v[44:47]
	global_load_lds_dwordx4 v251, s[8:9]
	s_add_u32 m0, s12, 0x8000
	v_mfma_f32_16x16x32_bf16 v[48:51], v[76:79], v[96:99], v[48:51]
	global_load_lds_dwordx4 v248, s[10:11]
	s_add_u32 m0, s12, 0x8400
	v_mfma_f32_16x16x32_bf16 v[52:55], v[76:79], v[100:103], v[52:55]
	global_load_lds_dwordx4 v249, s[10:11]
	s_add_u32 m0, s12, 0x8800
	v_mfma_f32_16x16x32_bf16 v[56:59], v[76:79], v[104:107], v[56:59]
	global_load_lds_dwordx4 v250, s[10:11]
	s_add_u32 m0, s12, 0x8c00
	v_mfma_f32_16x16x32_bf16 v[60:63], v[76:79], v[108:111], v[60:63]
	global_load_lds_dwordx4 v251, s[10:11]
	s_add_u32 s8, s8, 0x80
	s_addc_u32 s9, s9, 0
	s_add_u32 s10, s10, 0x80
	s_addc_u32 s11, s11, 0
	s_waitcnt vmcnt(8)
	s_barrier
	ds_read_b128 v[64:67], v252 offset:16384
	ds_read_b128 v[96:99], v254 offset:49152
	ds_read_b128 v[100:103], v254 offset:51200
	ds_read_b128 v[104:107], v254 offset:53248
	ds_read_b128 v[108:111], v254 offset:55296
	ds_read_b128 v[68:71], v252 offset:18432
	ds_read_b128 v[72:75], v252 offset:20480
	ds_read_b128 v[76:79], v252 offset:22528
	v_mfma_f32_16x16x32_bf16 v[0:3], v[80:83], v[112:115], v[0:3]
	v_mfma_f32_16x16x32_bf16 v[4:7], v[80:83], v[116:119], v[4:7]
	v_mfma_f32_16x16x32_bf16 v[8:11], v[80:83], v[120:123], v[8:11]
	v_mfma_f32_16x16x32_bf16 v[12:15], v[80:83], v[124:127], v[12:15]
	v_mfma_f32_16x16x32_bf16 v[16:19], v[84:87], v[112:115], v[16:19]
	v_mfma_f32_16x16x32_bf16 v[20:23], v[84:87], v[116:119], v[20:23]
	v_mfma_f32_16x16x32_bf16 v[24:27], v[84:87], v[120:123], v[24:27]
	v_mfma_f32_16x16x32_bf16 v[28:31], v[84:87], v[124:127], v[28:31]
	v_mfma_f32_16x16x32_bf16 v[32:35], v[88:91], v[112:115], v[32:35]
	v_mfma_f32_16x16x32_bf16 v[36:39], v[88:91], v[116:119], v[36:39]
	v_mfma_f32_16x16x32_bf16 v[40:43], v[88:91], v[120:123], v[40:43]
	v_mfma_f32_16x16x32_bf16 v[44:47], v[88:91], v[124:127], v[44:47]
	v_mfma_f32_16x16x32_bf16 v[48:51], v[92:95], v[112:115], v[48:51]
	v_mfma_f32_16x16x32_bf16 v[52:55], v[92:95], v[116:119], v[52:55]
	v_mfma_f32_16x16x32_bf16 v[56:59], v[92:95], v[120:123], v[56:59]
	v_mfma_f32_16x16x32_bf16 v[60:63], v[92:95], v[124:127], v[60:63]
	ds_read_b128 v[80:83], v253 offset:16384
	ds_read_b128 v[112:115], v255 offset:49152
	ds_read_b128 v[116:119], v255 offset:51200
	ds_read_b128 v[120:123], v255 offset:53248
	ds_read_b128 v[124:127], v255 offset:55296
	ds_read_b128 v[84:87], v253 offset:18432
	ds_read_b128 v[88:91], v253 offset:20480
	ds_read_b128 v[92:95], v253 offset:22528
	s_waitcnt lgkmcnt(14)
	v_mfma_f32_16x16x32_bf16 v[0:3], v[64:67], v[96:99], v[0:3]
	s_waitcnt lgkmcnt(13)
	v_mfma_f32_16x16x32_bf16 v[4:7], v[64:67], v[100:103], v[4:7]
	s_waitcnt lgkmcnt(12)
	v_mfma_f32_16x16x32_bf16 v[8:11], v[64:67], v[104:107], v[8:11]
	s_waitcnt lgkmcnt(11)
	v_mfma_f32_16x16x32_bf16 v[12:15], v[64:67], v[108:111], v[12:15]
	s_waitcnt lgkmcnt(10)
	v_mfma_f32_16x16x32_bf16 v[16:19], v[68:71], v[96:99], v[16:19]
	v_mfma_f32_16x16x32_bf16 v[20:23], v[68:71], v[100:103], v[20:23]
	v_mfma_f32_16x16x32_bf16 v[24:27], v[68:71], v[104:107], v[24:27]
	v_mfma_f32_16x16x32_bf16 v[28:31], v[68:71], v[108:111], v[28:31]
	s_waitcnt lgkmcnt(0)
	s_barrier
	s_add_u32 m0, s12, 0x4000
	v_mfma_f32_16x16x32_bf16 v[32:35], v[72:75], v[96:99], v[32:35]
	global_load_lds_dwordx4 v248, s[8:9]
	s_add_u32 m0, s12, 0x4400
	v_mfma_f32_16x16x32_bf16 v[36:39], v[72:75], v[100:103], v[36:39]
	global_load_lds_dwordx4 v249, s[8:9]
	s_add_u32 m0, s12, 0x4800
	v_mfma_f32_16x16x32_bf16 v[40:43], v[72:75], v[104:107], v[40:43]
	global_load_lds_dwordx4 v250, s[8:9]
	s_add_u32 m0, s12, 0x4c00
	v_mfma_f32_16x16x32_bf16 v[44:47], v[72:75], v[108:111], v[44:47]
	global_load_lds_dwordx4 v251, s[8:9]
	s_add_u32 m0, s12, 0xc000
	v_mfma_f32_16x16x32_bf16 v[48:51], v[76:79], v[96:99], v[48:51]
	global_load_lds_dwordx4 v248, s[10:11]
	s_add_u32 m0, s12, 0xc400
	v_mfma_f32_16x16x32_bf16 v[52:55], v[76:79], v[100:103], v[52:55]
	global_load_lds_dwordx4 v249, s[10:11]
	s_add_u32 m0, s12, 0xc800
	v_mfma_f32_16x16x32_bf16 v[56:59], v[76:79], v[104:107], v[56:59]
	global_load_lds_dwordx4 v250, s[10:11]
	s_add_u32 m0, s12, 0xcc00
	v_mfma_f32_16x16x32_bf16 v[60:63], v[76:79], v[108:111], v[60:63]
	global_load_lds_dwordx4 v251, s[10:11]
	s_add_u32 s8, s8, 0x80
	s_addc_u32 s9, s9, 0
	s_add_u32 s10, s10, 0x80
	s_addc_u32 s11, s11, 0
	s_sub_u32 s13, s13, 1
	s_cmp_lg_u32 s13, 0
	s_cbranch_scc1 .Lr6_loop
	s_waitcnt vmcnt(8)
	s_barrier
	ds_read_b128 v[64:67], v252 offset:0
	ds_read_b128 v[96:99], v254 offset:32768
	ds_read_b128 v[100:103], v254 offset:34816
	ds_read_b128 v[104:107], v254 offset:36864
	ds_read_b128 v[108:111], v254 offset:38912
	ds_read_b128 v[68:71], v252 offset:2048
	ds_read_b128 v[72:75], v252 offset:4096
	ds_read_b128 v[76:79], v252 offset:6144
	v_mfma_f32_16x16x32_bf16 v[0:3], v[80:83], v[112:115], v[0:3]
	v_mfma_f32_16x16x32_bf16 v[4:7], v[80:83], v[116:119], v[4:7]
	v_mfma_f32_16x16x32_bf16 v[8:11], v[80:83], v[120:123], v[8:11]
	v_mfma_f32_16x16x32_bf16 v[12:15], v[80:83], v[124:127], v[12:15]
	v_mfma_f32_16x16x32_bf16 v[16:19], v[84:87], v[112:115], v[16:19]
	v_mfma_f32_16x16x32_bf16 v[20:23], v[84:87], v[116:119], v[20:23]
	v_mfma_f32_16x16x32_bf16 v[24:27], v[84:87], v[120:123], v[24:27]
	v_mfma_f32_16x16x32_bf16 v[28:31], v[84:87], v[124:127], v[28:31]
	v_mfma_f32_16x16x32_bf16 v[32:35], v[88:91], v[112:115], v[32:35]
	v_mfma_f32_16x16x32_bf16 v[36:39], v[88:91], v[116:119], v[36:39]
	v_mfma_f32_16x16x32_bf16 v[40:43], v[88:91], v[120:123], v[40:43]
	v_mfma_f32_16x16x32_bf16 v[44:47], v[88:91], v[124:127], v[44:47]
	v_mfma_f32_16x16x32_bf16 v[48:51], v[92:95], v[112:115], v[48:51]
	v_mfma_f32_16x16x32_bf16 v[52:55], v[92:95], v[116:119], v[52:55]
	v_mfma_f32_16x16x32_bf16 v[56:59], v[92:95], v[120:123], v[56:59]
	v_mfma_f32_16x16x32_bf16 v[60:63], v[92:95], v[124:127], v[60:63]
	ds_read_b128 v[80:83], v253 offset:0
	ds_read_b128 v[112:115], v255 offset:32768
	ds_read_b128 v[116:119], v255 offset:34816
	ds_read_b128 v[120:123], v255 offset:36864
	ds_read_b128 v[124:127], v255 offset:38912
	ds_read_b128 v[84:87], v253 offset:2048
	ds_read_b128 v[88:91], v253 offset:4096
	ds_read_b128 v[92:95], v253 offset:6144
	s_waitcnt lgkmcnt(14)
	v_mfma_f32_16x16x32_bf16 v[0:3], v[64:67], v[96:99], v[0:3]
	s_waitcnt lgkmcnt(13)
	v_mfma_f32_16x16x32_bf16 v[4:7], v[64:67], v[100:103], v[4:7]
	s_waitcnt lgkmcnt(12)
	v_mfma_f32_16x16x32_bf16 v[8:11], v[64:67], v[104:107], v[8:11]
	s_waitcnt lgkmcnt(11)
	v_mfma_f32_16x16x32_bf16 v[12:15], v[64:67], v[108:111], v[12:15]
	s_waitcnt lgkmcnt(10)
	v_mfma_f32_16x16x32_bf16 v[16:19], v[68:71], v[96:99], v[16:19]
	v_mfma_f32_16x16x32_bf16 v[20:23], v[68:71], v[100:103], v[20:23]
	v_mfma_f32_16x16x32_bf16 v[24:27], v[68:71], v[104:107], v[24:27]
	v_mfma_f32_16x16x32_bf16 v[28:31], v[68:71], v[108:111], v[28:31]
	s_waitcnt lgkmcnt(0)
	s_barrier
	v_mfma_f32_16x16x32_bf16 v[32:35], v[72:75], v[96:99], v[32:35]
	v_mfma_f32_16x16x32_bf16 v[36:39], v[72:75], v[100:103], v[36:39]
	v_mfma_f32_16x16x32_bf16 v[40:43], v[72:75], v[104:107], v[40:43]
	v_mfma_f32_16x16x32_bf16 v[44:47], v[72:75], v[108:111], v[44:47]
	v_mfma_f32_16x16x32_bf16 v[48:51], v[76:79], v[96:99], v[48:51]
	v_mfma_f32_16x16x32_bf16 v[52:55], v[76:79], v[100:103], v[52:55]
	v_mfma_f32_16x16x32_bf16 v[56:59], v[76:79], v[104:107], v[56:59]
	v_mfma_f32_16x16x32_bf16 v[60:63], v[76:79], v[108:111], v[60:63]
	s_waitcnt vmcnt(0)
	s_barrier
	ds_read_b128 v[64:67], v252 offset:16384
	ds_read_b128 v[96:99], v254 offset:49152
	ds_read_b128 v[100:103], v254 offset:51200
	ds_read_b128 v[104:107], v254 offset:53248
	ds_read_b128 v[108:111], v254 offset:55296
	ds_read_b128 v[68:71], v252 offset:18432
	ds_read_b128 v[72:75], v252 offset:20480
	ds_read_b128 v[76:79], v252 offset:22528
	v_mfma_f32_16x16x32_bf16 v[0:3], v[80:83], v[112:115], v[0:3]
	v_mfma_f32_16x16x32_bf16 v[4:7], v[80:83], v[116:119], v[4:7]
	v_mfma_f32_16x16x32_bf16 v[8:11], v[80:83], v[120:123], v[8:11]
	v_mfma_f32_16x16x32_bf16 v[12:15], v[80:83], v[124:127], v[12:15]
	v_mfma_f32_16x16x32_bf16 v[16:19], v[84:87], v[112:115], v[16:19]
	v_mfma_f32_16x16x32_bf16 v[20:23], v[84:87], v[116:119], v[20:23]
	v_mfma_f32_16x16x32_bf16 v[24:27], v[84:87], v[120:123], v[24:27]
	v_mfma_f32_16x16x32_bf16 v[28:31], v[84:87], v[124:127], v[28:31]
	v_mfma_f32_16x16x32_bf16 v[32:35], v[88:91], v[112:115], v[32:35]
	v_mfma_f32_16x16x32_bf16 v[36:39], v[88:91], v[116:119], v[36:39]
	v_mfma_f32_16x16x32_bf16 v[40:43], v[88:91], v[120:123], v[40:43]
	v_mfma_f32_16x16x32_bf16 v[44:47], v[88:91], v[124:127], v[44:47]
	v_mfma_f32_16x16x32_bf16 v[48:51], v[92:95], v[112:115], v[48:51]
	v_mfma_f32_16x16x32_bf16 v[52:55], v[92:95], v[116:119], v[52:55]
	v_mfma_f32_16x16x32_bf16 v[56:59], v[92:95], v[120:123], v[56:59]
	v_mfma_f32_16x16x32_bf16 v[60:63], v[92:95], v[124:127], v[60:63]
	ds_read_b128 v[80:83], v253 offset:16384
	ds_read_b128 v[112:115], v255 offset:49152
	ds_read_b128 v[116:119], v255 offset:51200
	ds_read_b128 v[120:123], v255 offset:53248
	ds_read_b128 v[124:127], v255 offset:55296
	ds_read_b128 v[84:87], v253 offset:18432
	ds_read_b128 v[88:91], v253 offset:20480
	ds_read_b128 v[92:95], v253 offset:22528
	s_waitcnt lgkmcnt(14)
	v_mfma_f32_16x16x32_bf16 v[0:3], v[64:67], v[96:99], v[0:3]
	s_waitcnt lgkmcnt(13)
	v_mfma_f32_16x16x32_bf16 v[4:7], v[64:67], v[100:103], v[4:7]
	s_waitcnt lgkmcnt(12)
	v_mfma_f32_16x16x32_bf16 v[8:11], v[64:67], v[104:107], v[8:11]
	s_waitcnt lgkmcnt(11)
	v_mfma_f32_16x16x32_bf16 v[12:15], v[64:67], v[108:111], v[12:15]
	s_waitcnt lgkmcnt(10)
	v_mfma_f32_16x16x32_bf16 v[16:19], v[68:71], v[96:99], v[16:19]
	v_mfma_f32_16x16x32_bf16 v[20:23], v[68:71], v[100:103], v[20:23]
	v_mfma_f32_16x16x32_bf16 v[24:27], v[68:71], v[104:107], v[24:27]
	v_mfma_f32_16x16x32_bf16 v[28:31], v[68:71], v[108:111], v[28:31]
	s_waitcnt lgkmcnt(0)
	s_barrier
	v_mfma_f32_16x16x32_bf16 v[32:35], v[72:75], v[96:99], v[32:35]
	v_mfma_f32_16x16x32_bf16 v[36:39], v[72:75], v[100:103], v[36:39]
	v_mfma_f32_16x16x32_bf16 v[40:43], v[72:75], v[104:107], v[40:43]
	v_mfma_f32_16x16x32_bf16 v[44:47], v[72:75], v[108:111], v[44:47]
	v_mfma_f32_16x16x32_bf16 v[48:51], v[76:79], v[96:99], v[48:51]
	v_mfma_f32_16x16x32_bf16 v[52:55], v[76:79], v[100:103], v[52:55]
	v_mfma_f32_16x16x32_bf16 v[56:59], v[76:79], v[104:107], v[56:59]
	v_mfma_f32_16x16x32_bf16 v[60:63], v[76:79], v[108:111], v[60:63]
	v_mfma_f32_16x16x32_bf16 v[0:3], v[80:83], v[112:115], v[0:3]
	v_mfma_f32_16x16x32_bf16 v[4:7], v[80:83], v[116:119], v[4:7]
	v_mfma_f32_16x16x32_bf16 v[8:11], v[80:83], v[120:123], v[8:11]
	v_mfma_f32_16x16x32_bf16 v[12:15], v[80:83], v[124:127], v[12:15]
	v_mfma_f32_16x16x32_bf16 v[16:19], v[84:87], v[112:115], v[16:19]
	v_mfma_f32_16x16x32_bf16 v[20:23], v[84:87], v[116:119], v[20:23]
	v_mfma_f32_16x16x32_bf16 v[24:27], v[84:87], v[120:123], v[24:27]
	v_mfma_f32_16x16x32_bf16 v[28:31], v[84:87], v[124:127], v[28:31]
	v_mfma_f32_16x16x32_bf16 v[32:35], v[88:91], v[112:115], v[32:35]
	v_mfma_f32_16x16x32_bf16 v[36:39], v[88:91], v[116:119], v[36:39]
	v_mfma_f32_16x16x32_bf16 v[40:43], v[88:91], v[120:123], v[40:43]
	v_mfma_f32_16x16x32_bf16 v[44:47], v[88:91], v[124:127], v[44:47]
	v_mfma_f32_16x16x32_bf16 v[48:51], v[92:95], v[112:115], v[48:51]
	v_mfma_f32_16x16x32_bf16 v[52:55], v[92:95], v[116:119], v[52:55]
	v_mfma_f32_16x16x32_bf16 v[56:59], v[92:95], v[120:123], v[56:59]
	v_mfma_f32_16x16x32_bf16 v[60:63], v[92:95], v[124:127], v[60:63]
	s_nop 7
	s_nop 1
	s_mov_b64 s[18:19], s[20:21]
	v_fma_f32 v129, v201, v0, v129
	v_fma_f32 v130, v202, v4, v130
	v_fma_f32 v131, v203, v8, v131
	v_fma_f32 v132, v204, v12, v132
	global_store_dword v246, v129, s[18:19] offset:0
	global_store_dword v246, v130, s[18:19] offset:64
	global_store_dword v246, v131, s[18:19] offset:128
	global_store_dword v246, v132, s[18:19] offset:192
	s_add_u32 s18, s18, 0x1000
	s_addc_u32 s19, s19, 0
	v_fma_f32 v133, v201, v1, v133
	v_fma_f32 v134, v202, v5, v134
	v_fma_f32 v135, v203, v9, v135
	v_fma_f32 v136, v204, v13, v136
	global_store_dword v246, v133, s[18:19] offset:0
	global_store_dword v246, v134, s[18:19] offset:64
	global_store_dword v246, v135, s[18:19] offset:128
	global_store_dword v246, v136, s[18:19] offset:192
	s_add_u32 s18, s18, 0x1000
	s_addc_u32 s19, s19, 0
	v_fma_f32 v137, v201, v2, v137
	v_fma_f32 v138, v202, v6, v138
	v_fma_f32 v139, v203, v10, v139
	v_fma_f32 v140, v204, v14, v140
	global_store_dword v246, v137, s[18:19] offset:0
	global_store_dword v246, v138, s[18:19] offset:64
	global_store_dword v246, v139, s[18:19] offset:128
	global_store_dword v246, v140, s[18:19] offset:192
	s_add_u32 s18, s18, 0x1000
	s_addc_u32 s19, s19, 0
	v_fma_f32 v141, v201, v3, v141
	v_fma_f32 v142, v202, v7, v142
	v_fma_f32 v143, v203, v11, v143
	v_fma_f32 v144, v204, v15, v144
	global_store_dword v246, v141, s[18:19] offset:0
	global_store_dword v246, v142, s[18:19] offset:64
	global_store_dword v246, v143, s[18:19] offset:128
	global_store_dword v246, v144, s[18:19] offset:192
	s_add_u32 s18, s18, 0xd000
	s_addc_u32 s19, s19, 0
	v_fma_f32 v145, v201, v16, v145
	v_fma_f32 v146, v202, v20, v146
	v_fma_f32 v147, v203, v24, v147
	v_fma_f32 v148, v204, v28, v148
	global_store_dword v246, v145, s[18:19] offset:0
	global_store_dword v246, v146, s[18:19] offset:64
	global_store_dword v246, v147, s[18:19] offset:128
	global_store_dword v246, v148, s[18:19] offset:192
	s_add_u32 s18, s18, 0x1000
	s_addc_u32 s19, s19, 0
	v_fma_f32 v149, v201, v17, v149
	v_fma_f32 v150, v202, v21, v150
	v_fma_f32 v151, v203, v25, v151
	v_fma_f32 v152, v204, v29, v152
	global_store_dword v246, v149, s[18:19] offset:0
	global_store_dword v246, v150, s[18:19] offset:64
	global_store_dword v246, v151, s[18:19] offset:128
	global_store_dword v246, v152, s[18:19] offset:192
	s_add_u32 s18, s18, 0x1000
	s_addc_u32 s19, s19, 0
	v_fma_f32 v153, v201, v18, v153
	v_fma_f32 v154, v202, v22, v154
	v_fma_f32 v155, v203, v26, v155
	v_fma_f32 v156, v204, v30, v156
	global_store_dword v246, v153, s[18:19] offset:0
	global_store_dword v246, v154, s[18:19] offset:64
	global_store_dword v246, v155, s[18:19] offset:128
	global_store_dword v246, v156, s[18:19] offset:192
	s_add_u32 s18, s18, 0x1000
	s_addc_u32 s19, s19, 0
	v_fma_f32 v157, v201, v19, v157
	v_fma_f32 v158, v202, v23, v158
	v_fma_f32 v159, v203, v27, v159
	v_fma_f32 v160, v204, v31, v160
	global_store_dword v246, v157, s[18:19] offset:0
	global_store_dword v246, v158, s[18:19] offset:64
	global_store_dword v246, v159, s[18:19] offset:128
	global_store_dword v246, v160, s[18:19] offset:192
	s_add_u32 s18, s18, 0xd000
	s_addc_u32 s19, s19, 0
	v_fma_f32 v161, v201, v32, v161
	v_fma_f32 v170, v202, v36, v170
	v_fma_f32 v171, v203, v40, v171
	v_fma_f32 v172, v204, v44, v172
	global_store_dword v246, v161, s[18:19] offset:0
	global_store_dword v246, v170, s[18:19] offset:64
	global_store_dword v246, v171, s[18:19] offset:128
	global_store_dword v246, v172, s[18:19] offset:192
	s_add_u32 s18, s18, 0x1000
	s_addc_u32 s19, s19, 0
	v_fma_f32 v173, v201, v33, v173
	v_fma_f32 v174, v202, v37, v174
	v_fma_f32 v175, v203, v41, v175
	v_fma_f32 v176, v204, v45, v176
	global_store_dword v246, v173, s[18:19] offset:0
	global_store_dword v246, v174, s[18:19] offset:64
	global_store_dword v246, v175, s[18:19] offset:128
	global_store_dword v246, v176, s[18:19] offset:192
	s_add_u32 s18, s18, 0x1000
	s_addc_u32 s19, s19, 0
	v_fma_f32 v177, v201, v34, v177
	v_fma_f32 v178, v202, v38, v178
	v_fma_f32 v179, v203, v42, v179
	v_fma_f32 v180, v204, v46, v180
	global_store_dword v246, v177, s[18:19] offset:0
	global_store_dword v246, v178, s[18:19] offset:64
	global_store_dword v246, v179, s[18:19] offset:128
	global_store_dword v246, v180, s[18:19] offset:192
	s_add_u32 s18, s18, 0x1000
	s_addc_u32 s19, s19, 0
	v_fma_f32 v181, v201, v35, v181
	v_fma_f32 v182, v202, v39, v182
	v_fma_f32 v183, v203, v43, v183
	v_fma_f32 v184, v204, v47, v184
	global_store_dword v246, v181, s[18:19] offset:0
	global_store_dword v246, v182, s[18:19] offset:64
	global_store_dword v246, v183, s[18:19] offset:128
	global_store_dword v246, v184, s[18:19] offset:192
	s_add_u32 s18, s18, 0xd000
	s_addc_u32 s19, s19, 0
	v_fma_f32 v185, v201, v48, v185
	v_fma_f32 v186, v202, v52, v186
	v_fma_f32 v187, v203, v56, v187
	v_fma_f32 v188, v204, v60, v188
	global_store_dword v246, v185, s[18:19] offset:0
	global_store_dword v246, v186, s[18:19] offset:64
	global_store_dword v246, v187, s[18:19] offset:128
	global_store_dword v246, v188, s[18:19] offset:192
	s_add_u32 s18, s18, 0x1000
	s_addc_u32 s19, s19, 0
	v_fma_f32 v189, v201, v49, v189
	v_fma_f32 v190, v202, v53, v190
	v_fma_f32 v191, v203, v57, v191
	v_fma_f32 v192, v204, v61, v192
	global_store_dword v246, v189, s[18:19] offset:0
	global_store_dword v246, v190, s[18:19] offset:64
	global_store_dword v246, v191, s[18:19] offset:128
	global_store_dword v246, v192, s[18:19] offset:192
	s_add_u32 s18, s18, 0x1000
	s_addc_u32 s19, s19, 0
	v_fma_f32 v193, v201, v50, v193
	v_fma_f32 v194, v202, v54, v194
	v_fma_f32 v195, v203, v58, v195
	v_fma_f32 v196, v204, v62, v196
	global_store_dword v246, v193, s[18:19] offset:0
	global_store_dword v246, v194, s[18:19] offset:64
	global_store_dword v246, v195, s[18:19] offset:128
	global_store_dword v246, v196, s[18:19] offset:192
	s_add_u32 s18, s18, 0x1000
	s_addc_u32 s19, s19, 0
	v_fma_f32 v197, v201, v51, v197
	v_fma_f32 v198, v202, v55, v198
	v_fma_f32 v199, v203, v59, v199
	v_fma_f32 v200, v204, v63, v200
	global_store_dword v246, v197, s[18:19] offset:0
	global_store_dword v246, v198, s[18:19] offset:64
	global_store_dword v246, v199, s[18:19] offset:128
	global_store_dword v246, v200, s[18:19] offset:192
	s_add_u32 s15, s15, s16
	s_branch .Lr6_tile
.Lr6_end:
.LBB0_839:
	s_cmp_lt_i32 s61, 7
	s_cbranch_scc1 .LBB0_893
	s_waitcnt vmcnt(0)
	s_waitcnt vmcnt(63) expcnt(7) lgkmcnt(15)
	s_barrier
	s_and_saveexec_b64 s[4:5], s[52:53]
	s_cbranch_execz .LBB0_892
	v_mov_b32_e32 v0, 0x12000
	s_waitcnt vmcnt(0) expcnt(0) lgkmcnt(0)
	ds_read_b32 v2, v0
	v_mov_b32_e32 v0, 0x12004
	ds_read_b32 v0, v0
	s_waitcnt lgkmcnt(1)
	v_cmp_ne_u32_e32 vcc, 0, v2
	s_cbranch_vccnz .LBB0_856
	s_load_dwordx2 s[2:3], s[0:1], 0xf0
	s_load_dword s9, s[0:1], 0xf8
	s_add_u32 s6, s56, 0x1457a300
	s_addc_u32 s7, s57, 0
	s_add_u32 s8, s56, 0x1457a500
	s_waitcnt lgkmcnt(0)
	s_mul_i32 s2, s3, s2
	s_mul_i32 s2, s2, s9
	s_addc_u32 s9, s57, 0
	s_add_u32 s10, s56, 0x1457a600
	s_addc_u32 s11, s57, 0
	s_add_u32 s12, s56, 0x1457a700
	s_addc_u32 s13, s57, 0
	s_add_u32 s14, s56, 0x1457a800
	s_addc_u32 s15, s57, 0
	s_add_u32 s16, s56, 0x1457a900
	s_addc_u32 s17, s57, 0
	s_add_u32 s18, s56, 0x1457aa00
	s_addc_u32 s19, s57, 0
	s_add_u32 s20, s56, 0x1457ab00
	s_addc_u32 s21, s57, 0
	s_add_u32 s22, s56, 0x1457ac00
	s_addc_u32 s23, s57, 0
	s_add_u32 s24, s56, 0x1457ad00
	s_addc_u32 s25, s57, 0
	s_add_u32 s26, s56, 0x1457ae00
	s_addc_u32 s27, s57, 0
	s_add_u32 s28, s56, 0x1457af00
	s_addc_u32 s29, s57, 0
	s_add_u32 s30, s56, 0x1457b000
	s_addc_u32 s31, s57, 0
	s_add_u32 s34, s56, 0x1457b100
	s_addc_u32 s35, s57, 0
	s_add_u32 s36, s56, 0x1457b200
	s_addc_u32 s37, s57, 0
	s_add_u32 s38, s56, 0x1457b300
	s_addc_u32 s39, s57, 0
	s_add_u32 s40, s56, 0x1457b400
	s_addc_u32 s41, s57, 0
	s_mov_b32 s3, 1
	v_mov_b32_e32 v16, 0
	s_branch .LBB0_844

.LBB0_1015:
	s_cmp_gt_i32 s60, 9
	s_cselect_b64 s[2:3], -1, 0
	s_cmp_lt_i32 s61, 9
	s_cselect_b64 s[4:5], -1, 0
	s_or_b64 s[2:3], s[2:3], s[4:5]
	s_and_b64 vcc, exec, s[2:3]
	s_cbranch_vccnz .LBB0_1075
	s_load_dwordx2 s[4:5], s[0:1], 0xe0
	s_load_dword s16, s[0:1], 0xf0
	v_and_b32_e32 v240, 63, v162
	v_lshrrev_b32_e32 v247, 6, v162
	v_lshrrev_b32_e32 v242, 3, v240
	v_lshl_add_u32 v242, v247, 5, v242
	v_and_b32_e32 v243, 7, v240
	v_lshrrev_b32_e32 v244, 4, v240
	v_xor_b32_e32 v243, v243, v244
	v_lshlrev_b32_e32 v243, 4, v243
	v_mov_b32_e32 v241, 0x1600
	v_mad_u32_u24 v248, v242, v241, v243
	v_xor_b32_e32 v249, 64, v248
	v_add_u32_e32 v249, 0xb000, v249
	v_add_u32_e32 v250, 0x16000, v248
	v_xor_b32_e32 v251, 64, v248
	v_add_u32_e32 v251, 0x21000, v251
	v_and_b32_e32 v241, 15, v240
	v_lshrrev_b32_e32 v242, 1, v241
	v_xor_b32_e32 v242, v242, v244
	v_lshlrev_b32_e32 v242, 4, v242
	v_lshl_or_b32 v242, v241, 7, v242
	v_lshrrev_b32_e32 v243, 1, v247
	v_lshl_or_b32 v252, v243, 13, v242
	v_xor_b32_e32 v253, 64, v252
	v_and_b32_e32 v243, 1, v247
	v_lshl_or_b32 v254, v243, 13, v242
	v_xor_b32_e32 v255, 64, v254
	v_and_b32_e32 v240, 63, v162
	v_and_b32_e32 v241, 15, v240
	v_lshrrev_b32_e32 v242, 4, v240
	v_lshrrev_b32_e32 v243, 1, v247
	v_and_b32_e32 v244, 1, v247
	v_lshl_or_b32 v245, v244, 6, v241
	v_lshlrev_b32_e32 v243, 4, v243
	v_add_u32_e32 v243, v243, v242
	v_lshl_add_u32 v246, v243, 12, v245
	v_lshlrev_b32_e32 v246, 2, v246
	v_lshlrev_b32_e32 v245, 2, v245
	s_waitcnt lgkmcnt(0)
	s_add_u32 s26, s4, 0x9b7a100
	s_addc_u32 s27, s5, 0
	s_add_u32 s28, s4, 0x5080000
	s_addc_u32 s29, s5, 0
	s_mov_b32 s15, s58
.Lr9_tile:
	s_cmp_lt_u32 s15, 0x200
	s_cbranch_scc0 .Lr9_end
	s_and_b32 s2, s15, 63
	s_lshr_b32 s3, s15, 6
	s_mul_i32 s14, s2, 0xb0000
	s_add_u32 s8, s26, s14
	s_addc_u32 s9, s27, 0
	s_mul_i32 s14, s3, 0xb0000
	s_add_u32 s10, s28, s14
	s_addc_u32 s11, s29, 0
	s_lshl_b32 s14, s2, 19
	s_lshl_b32 s6, s3, 9
	s_add_u32 s14, s14, s6
	s_add_u32 s20, s4, 0x6b7a100
	s_addc_u32 s21, s5, 0
	s_add_u32 s20, s20, s14
	s_addc_u32 s21, s21, 0
	s_sub_u32 s7, s2, 32
	s_lshr_b32 s7, s7, 3
	s_add_u32 s7, s7, 1
	s_cmp_lt_u32 s2, 32
	s_cselect_b32 s7, 0, s7
	s_mul_i32 s7, s7, 0x6000
	s_add_u32 s7, s7, s6
	s_add_u32 s22, s4, 0x6b07000
	s_addc_u32 s23, s5, 0
	s_add_u32 s22, s22, s7
	s_addc_u32 s23, s23, 0
	v_readfirstlane_b32 s12, v247
	global_load_dword v201, v245, s[22:23] offset:0
	global_load_dword v202, v245, s[22:23] offset:64
	global_load_dword v203, v245, s[22:23] offset:128
	global_load_dword v204, v245, s[22:23] offset:192
	s_mov_b64 s[18:19], s[20:21]
	global_load_dword v129, v246, s[18:19] offset:0
	global_load_dword v130, v246, s[18:19] offset:64
	global_load_dword v131, v246, s[18:19] offset:128
	global_load_dword v132, v246, s[18:19] offset:192
	s_add_u32 s18, s18, 0x1000
	s_addc_u32 s19, s19, 0
	global_load_dword v133, v246, s[18:19] offset:0
	global_load_dword v134, v246, s[18:19] offset:64
	global_load_dword v135, v246, s[18:19] offset:128
	global_load_dword v136, v246, s[18:19] offset:192
	s_add_u32 s18, s18, 0x1000
	s_addc_u32 s19, s19, 0
	global_load_dword v137, v246, s[18:19] offset:0
	global_load_dword v138, v246, s[18:19] offset:64
	global_load_dword v139, v246, s[18:19] offset:128
	global_load_dword v140, v246, s[18:19] offset:192
	s_add_u32 s18, s18, 0x1000
	s_addc_u32 s19, s19, 0
	global_load_dword v141, v246, s[18:19] offset:0
	global_load_dword v142, v246, s[18:19] offset:64
	global_load_dword v143, v246, s[18:19] offset:128
	global_load_dword v144, v246, s[18:19] offset:192
	s_add_u32 s18, s18, 0xd000
	s_addc_u32 s19, s19, 0
	global_load_dword v145, v246, s[18:19] offset:0
	global_load_dword v146, v246, s[18:19] offset:64
	global_load_dword v147, v246, s[18:19] offset:128
	global_load_dword v148, v246, s[18:19] offset:192
	s_add_u32 s18, s18, 0x1000
	s_addc_u32 s19, s19, 0
	global_load_dword v149, v246, s[18:19] offset:0
	global_load_dword v150, v246, s[18:19] offset:64
	global_load_dword v151, v246, s[18:19] offset:128
	global_load_dword v152, v246, s[18:19] offset:192
	s_add_u32 s18, s18, 0x1000
	s_addc_u32 s19, s19, 0
	global_load_dword v153, v246, s[18:19] offset:0
	global_load_dword v154, v246, s[18:19] offset:64
	global_load_dword v155, v246, s[18:19] offset:128
	global_load_dword v156, v246, s[18:19] offset:192
	s_add_u32 s18, s18, 0x1000
	s_addc_u32 s19, s19, 0
	global_load_dword v157, v246, s[18:19] offset:0
	global_load_dword v158, v246, s[18:19] offset:64
	global_load_dword v159, v246, s[18:19] offset:128
	global_load_dword v160, v246, s[18:19] offset:192
	s_add_u32 s18, s18, 0xd000
	s_addc_u32 s19, s19, 0
	global_load_dword v161, v246, s[18:19] offset:0
	global_load_dword v170, v246, s[18:19] offset:64
	global_load_dword v171, v246, s[18:19] offset:128
	global_load_dword v172, v246, s[18:19] offset:192
	s_add_u32 s18, s18, 0x1000
	s_addc_u32 s19, s19, 0
	global_load_dword v173, v246, s[18:19] offset:0
	global_load_dword v174, v246, s[18:19] offset:64
	global_load_dword v175, v246, s[18:19] offset:128
	global_load_dword v176, v246, s[18:19] offset:192
	s_add_u32 s18, s18, 0x1000
	s_addc_u32 s19, s19, 0
	global_load_dword v177, v246, s[18:19] offset:0
	global_load_dword v178, v246, s[18:19] offset:64
	global_load_dword v179, v246, s[18:19] offset:128
	global_load_dword v180, v246, s[18:19] offset:192
	s_add_u32 s18, s18, 0x1000
	s_addc_u32 s19, s19, 0
	global_load_dword v181, v246, s[18:19] offset:0
	global_load_dword v182, v246, s[18:19] offset:64
	global_load_dword v183, v246, s[18:19] offset:128
	global_load_dword v184, v246, s[18:19] offset:192
	s_add_u32 s18, s18, 0xd000
	s_addc_u32 s19, s19, 0
	global_load_dword v185, v246, s[18:19] offset:0
	global_load_dword v186, v246, s[18:19] offset:64
	global_load_dword v187, v246, s[18:19] offset:128
	global_load_dword v188, v246, s[18:19] offset:192
	s_add_u32 s18, s18, 0x1000
	s_addc_u32 s19, s19, 0
	global_load_dword v189, v246, s[18:19] offset:0
	global_load_dword v190, v246, s[18:19] offset:64
	global_load_dword v191, v246, s[18:19] offset:128
	global_load_dword v192, v246, s[18:19] offset:192
	s_add_u32 s18, s18, 0x1000
	s_addc_u32 s19, s19, 0
	global_load_dword v193, v246, s[18:19] offset:0
	global_load_dword v194, v246, s[18:19] offset:64
	global_load_dword v195, v246, s[18:19] offset:128
	global_load_dword v196, v246, s[18:19] offset:192
	s_add_u32 s18, s18, 0x1000
	s_addc_u32 s19, s19, 0
	global_load_dword v197, v246, s[18:19] offset:0
	global_load_dword v198, v246, s[18:19] offset:64
	global_load_dword v199, v246, s[18:19] offset:128
	global_load_dword v200, v246, s[18:19] offset:192
	s_lshl_b32 s12, s12, 12
	s_add_u32 m0, s12, 0x0
	v_mov_b32_e32 v0, 0
	global_load_lds_dwordx4 v248, s[8:9]
	v_mov_b32_e32 v1, 0
	s_add_u32 m0, s12, 0x400
	v_mov_b32_e32 v2, 0
	global_load_lds_dwordx4 v249, s[8:9]
	v_mov_b32_e32 v3, 0
	s_add_u32 m0, s12, 0x800
	v_mov_b32_e32 v4, 0
	global_load_lds_dwordx4 v250, s[8:9]
	v_mov_b32_e32 v5, 0
	s_add_u32 m0, s12, 0xc00
	v_mov_b32_e32 v6, 0
	global_load_lds_dwordx4 v251, s[8:9]
	v_mov_b32_e32 v7, 0
	s_add_u32 m0, s12, 0x8000
	v_mov_b32_e32 v8, 0
	global_load_lds_dwordx4 v248, s[10:11]
	v_mov_b32_e32 v9, 0
	s_add_u32 m0, s12, 0x8400
	v_mov_b32_e32 v10, 0
	global_load_lds_dwordx4 v249, s[10:11]
	v_mov_b32_e32 v11, 0
	s_add_u32 m0, s12, 0x8800
	v_mov_b32_e32 v12, 0
	global_load_lds_dwordx4 v250, s[10:11]
	v_mov_b32_e32 v13, 0
	s_add_u32 m0, s12, 0x8c00
	v_mov_b32_e32 v14, 0
	global_load_lds_dwordx4 v251, s[10:11]
	v_mov_b32_e32 v15, 0
	s_add_u32 s8, s8, 0x80
	s_addc_u32 s9, s9, 0
	s_add_u32 s10, s10, 0x80
	s_addc_u32 s11, s11, 0
	s_add_u32 m0, s12, 0x4000
	v_mov_b32_e32 v16, 0
	global_load_lds_dwordx4 v248, s[8:9]
	v_mov_b32_e32 v17, 0
	s_add_u32 m0, s12, 0x4400
	v_mov_b32_e32 v18, 0
	global_load_lds_dwordx4 v249, s[8:9]
	v_mov_b32_e32 v19, 0
	s_add_u32 m0, s12, 0x4800
	v_mov_b32_e32 v20, 0
	global_load_lds_dwordx4 v250, s[8:9]
	v_mov_b32_e32 v21, 0
	s_add_u32 m0, s12, 0x4c00
	v_mov_b32_e32 v22, 0
	global_load_lds_dwordx4 v251, s[8:9]
	v_mov_b32_e32 v23, 0
	s_add_u32 m0, s12, 0xc000
	v_mov_b32_e32 v24, 0
	global_load_lds_dwordx4 v248, s[10:11]
	v_mov_b32_e32 v25, 0
	s_add_u32 m0, s12, 0xc400
	v_mov_b32_e32 v26, 0
	global_load_lds_dwordx4 v249, s[10:11]
	v_mov_b32_e32 v27, 0
	s_add_u32 m0, s12, 0xc800
	v_mov_b32_e32 v28, 0
	global_load_lds_dwordx4 v250, s[10:11]
	v_mov_b32_e32 v29, 0
	s_add_u32 m0, s12, 0xcc00
	v_mov_b32_e32 v30, 0
	global_load_lds_dwordx4 v251, s[10:11]
	v_mov_b32_e32 v31, 0
	s_add_u32 s8, s8, 0x80
	s_addc_u32 s9, s9, 0
	s_add_u32 s10, s10, 0x80
	s_addc_u32 s11, s11, 0
	v_mov_b32_e32 v32, 0
	v_mov_b32_e32 v33, 0
	v_mov_b32_e32 v34, 0
	v_mov_b32_e32 v35, 0
	v_mov_b32_e32 v36, 0
	v_mov_b32_e32 v37, 0
	v_mov_b32_e32 v38, 0
	v_mov_b32_e32 v39, 0
	v_mov_b32_e32 v40, 0
	v_mov_b32_e32 v41, 0
	v_mov_b32_e32 v42, 0
	v_mov_b32_e32 v43, 0
	v_mov_b32_e32 v44, 0
	v_mov_b32_e32 v45, 0
	v_mov_b32_e32 v46, 0
	v_mov_b32_e32 v47, 0
	v_mov_b32_e32 v48, 0
	v_mov_b32_e32 v49, 0
	v_mov_b32_e32 v50, 0
	v_mov_b32_e32 v51, 0
	v_mov_b32_e32 v52, 0
	v_mov_b32_e32 v53, 0
	v_mov_b32_e32 v54, 0
	v_mov_b32_e32 v55, 0
	v_mov_b32_e32 v56, 0
	v_mov_b32_e32 v57, 0
	v_mov_b32_e32 v58, 0
	v_mov_b32_e32 v59, 0
	v_mov_b32_e32 v60, 0
	v_mov_b32_e32 v61, 0
	v_mov_b32_e32 v62, 0
	v_mov_b32_e32 v63, 0
	s_waitcnt vmcnt(8)
	s_barrier
	ds_read_b128 v[64:67], v252 offset:0
	ds_read_b128 v[96:99], v254 offset:32768
	ds_read_b128 v[100:103], v254 offset:34816
	ds_read_b128 v[104:107], v254 offset:36864
	ds_read_b128 v[108:111], v254 offset:38912
	ds_read_b128 v[68:71], v252 offset:2048
	ds_read_b128 v[72:75], v252 offset:4096
	ds_read_b128 v[76:79], v252 offset:6144
	ds_read_b128 v[80:83], v253 offset:0
	ds_read_b128 v[112:115], v255 offset:32768
	ds_read_b128 v[116:119], v255 offset:34816
	ds_read_b128 v[120:123], v255 offset:36864
	ds_read_b128 v[124:127], v255 offset:38912
	s_waitcnt lgkmcnt(11)
	v_mfma_f32_16x16x32_bf16 v[0:3], v[64:67], v[96:99], v[0:3]
	s_waitcnt lgkmcnt(10)
	v_mfma_f32_16x16x32_bf16 v[4:7], v[64:67], v[100:103], v[4:7]
	s_waitcnt lgkmcnt(9)
	v_mfma_f32_16x16x32_bf16 v[8:11], v[64:67], v[104:107], v[8:11]
	s_waitcnt lgkmcnt(8)
	v_mfma_f32_16x16x32_bf16 v[12:15], v[64:67], v[108:111], v[12:15]
	ds_read_b128 v[84:87], v253 offset:2048
	ds_read_b128 v[88:91], v253 offset:4096
	ds_read_b128 v[92:95], v253 offset:6144
	s_waitcnt lgkmcnt(10)
	v_mfma_f32_16x16x32_bf16 v[16:19], v[68:71], v[96:99], v[16:19]
	v_mfma_f32_16x16x32_bf16 v[20:23], v[68:71], v[100:103], v[20:23]
	v_mfma_f32_16x16x32_bf16 v[24:27], v[68:71], v[104:107], v[24:27]
	v_mfma_f32_16x16x32_bf16 v[28:31], v[68:71], v[108:111], v[28:31]
	s_waitcnt lgkmcnt(0)
	s_barrier
	s_add_u32 m0, s12, 0x0
	v_mfma_f32_16x16x32_bf16 v[32:35], v[72:75], v[96:99], v[32:35]
	global_load_lds_dwordx4 v248, s[8:9]
	s_add_u32 m0, s12, 0x400
	v_mfma_f32_16x16x32_bf16 v[36:39], v[72:75], v[100:103], v[36:39]
	global_load_lds_dwordx4 v249, s[8:9]
	s_add_u32 m0, s12, 0x800
	v_mfma_f32_16x16x32_bf16 v[40:43], v[72:75], v[104:107], v[40:43]
	global_load_lds_dwordx4 v250, s[8:9]
	s_add_u32 m0, s12, 0xc00
	v_mfma_f32_16x16x32_bf16 v[44:47], v[72:75], v[108:111], v[44:47]
	global_load_lds_dwordx4 v251, s[8:9]
	s_add_u32 m0, s12, 0x8000
	v_mfma_f32_16x16x32_bf16 v[48:51], v[76:79], v[96:99], v[48:51]
	global_load_lds_dwordx4 v248, s[10:11]
	s_add_u32 m0, s12, 0x8400
	v_mfma_f32_16x16x32_bf16 v[52:55], v[76:79], v[100:103], v[52:55]
	global_load_lds_dwordx4 v249, s[10:11]
	s_add_u32 m0, s12, 0x8800
	v_mfma_f32_16x16x32_bf16 v[56:59], v[76:79], v[104:107], v[56:59]
	global_load_lds_dwordx4 v250, s[10:11]
	s_add_u32 m0, s12, 0x8c00
	v_mfma_f32_16x16x32_bf16 v[60:63], v[76:79], v[108:111], v[60:63]
	global_load_lds_dwordx4 v251, s[10:11]
	s_add_u32 s8, s8, 0x80
	s_addc_u32 s9, s9, 0
	s_add_u32 s10, s10, 0x80
	s_addc_u32 s11, s11, 0
	s_waitcnt vmcnt(8)
	s_barrier
	ds_read_b128 v[64:67], v252 offset:16384
	ds_read_b128 v[96:99], v254 offset:49152
	ds_read_b128 v[100:103], v254 offset:51200
	ds_read_b128 v[104:107], v254 offset:53248
	ds_read_b128 v[108:111], v254 offset:55296
	ds_read_b128 v[68:71], v252 offset:18432
	ds_read_b128 v[72:75], v252 offset:20480
	ds_read_b128 v[76:79], v252 offset:22528
	v_mfma_f32_16x16x32_bf16 v[0:3], v[80:83], v[112:115], v[0:3]
	v_mfma_f32_16x16x32_bf16 v[4:7], v[80:83], v[116:119], v[4:7]
	v_mfma_f32_16x16x32_bf16 v[8:11], v[80:83], v[120:123], v[8:11]
	v_mfma_f32_16x16x32_bf16 v[12:15], v[80:83], v[124:127], v[12:15]
	v_mfma_f32_16x16x32_bf16 v[16:19], v[84:87], v[112:115], v[16:19]
	v_mfma_f32_16x16x32_bf16 v[20:23], v[84:87], v[116:119], v[20:23]
	v_mfma_f32_16x16x32_bf16 v[24:27], v[84:87], v[120:123], v[24:27]
	v_mfma_f32_16x16x32_bf16 v[28:31], v[84:87], v[124:127], v[28:31]
	v_mfma_f32_16x16x32_bf16 v[32:35], v[88:91], v[112:115], v[32:35]
	v_mfma_f32_16x16x32_bf16 v[36:39], v[88:91], v[116:119], v[36:39]
	v_mfma_f32_16x16x32_bf16 v[40:43], v[88:91], v[120:123], v[40:43]
	v_mfma_f32_16x16x32_bf16 v[44:47], v[88:91], v[124:127], v[44:47]
	v_mfma_f32_16x16x32_bf16 v[48:51], v[92:95], v[112:115], v[48:51]
	v_mfma_f32_16x16x32_bf16 v[52:55], v[92:95], v[116:119], v[52:55]
	v_mfma_f32_16x16x32_bf16 v[56:59], v[92:95], v[120:123], v[56:59]
	v_mfma_f32_16x16x32_bf16 v[60:63], v[92:95], v[124:127], v[60:63]
	ds_read_b128 v[80:83], v253 offset:16384
	ds_read_b128 v[112:115], v255 offset:49152
	ds_read_b128 v[116:119], v255 offset:51200
	ds_read_b128 v[120:123], v255 offset:53248
	ds_read_b128 v[124:127], v255 offset:55296
	ds_read_b128 v[84:87], v253 offset:18432
	ds_read_b128 v[88:91], v253 offset:20480
	ds_read_b128 v[92:95], v253 offset:22528
	s_waitcnt lgkmcnt(14)
	v_mfma_f32_16x16x32_bf16 v[0:3], v[64:67], v[96:99], v[0:3]
	s_waitcnt lgkmcnt(13)
	v_mfma_f32_16x16x32_bf16 v[4:7], v[64:67], v[100:103], v[4:7]
	s_waitcnt lgkmcnt(12)
	v_mfma_f32_16x16x32_bf16 v[8:11], v[64:67], v[104:107], v[8:11]
	s_waitcnt lgkmcnt(11)
	v_mfma_f32_16x16x32_bf16 v[12:15], v[64:67], v[108:111], v[12:15]
	s_waitcnt lgkmcnt(10)
	v_mfma_f32_16x16x32_bf16 v[16:19], v[68:71], v[96:99], v[16:19]
	v_mfma_f32_16x16x32_bf16 v[20:23], v[68:71], v[100:103], v[20:23]
	v_mfma_f32_16x16x32_bf16 v[24:27], v[68:71], v[104:107], v[24:27]
	v_mfma_f32_16x16x32_bf16 v[28:31], v[68:71], v[108:111], v[28:31]
	s_waitcnt lgkmcnt(0)
	s_barrier
	s_add_u32 m0, s12, 0x4000
	v_mfma_f32_16x16x32_bf16 v[32:35], v[72:75], v[96:99], v[32:35]
	global_load_lds_dwordx4 v248, s[8:9]
	s_add_u32 m0, s12, 0x4400
	v_mfma_f32_16x16x32_bf16 v[36:39], v[72:75], v[100:103], v[36:39]
	global_load_lds_dwordx4 v249, s[8:9]
	s_add_u32 m0, s12, 0x4800
	v_mfma_f32_16x16x32_bf16 v[40:43], v[72:75], v[104:107], v[40:43]
	global_load_lds_dwordx4 v250, s[8:9]
	s_add_u32 m0, s12, 0x4c00
	v_mfma_f32_16x16x32_bf16 v[44:47], v[72:75], v[108:111], v[44:47]
	global_load_lds_dwordx4 v251, s[8:9]
	s_add_u32 m0, s12, 0xc000
	v_mfma_f32_16x16x32_bf16 v[48:51], v[76:79], v[96:99], v[48:51]
	global_load_lds_dwordx4 v248, s[10:11]
	s_add_u32 m0, s12, 0xc400
	v_mfma_f32_16x16x32_bf16 v[52:55], v[76:79], v[100:103], v[52:55]
	global_load_lds_dwordx4 v249, s[10:11]
	s_add_u32 m0, s12, 0xc800
	v_mfma_f32_16x16x32_bf16 v[56:59], v[76:79], v[104:107], v[56:59]
	global_load_lds_dwordx4 v250, s[10:11]
	s_add_u32 m0, s12, 0xcc00
	v_mfma_f32_16x16x32_bf16 v[60:63], v[76:79], v[108:111], v[60:63]
	global_load_lds_dwordx4 v251, s[10:11]
	s_add_u32 s8, s8, 0x80
	s_addc_u32 s9, s9, 0
	s_add_u32 s10, s10, 0x80
	s_addc_u32 s11, s11, 0
	s_mov_b32 s13, 20

.Lr9_end:
.LBB0_1021:
	s_cmp_lt_i32 s61, 10
	s_cbranch_scc1 .LBB0_1075
	s_waitcnt vmcnt(0)
	s_waitcnt vmcnt(63) expcnt(7) lgkmcnt(15)
	s_barrier
	s_and_saveexec_b64 s[4:5], s[52:53]
	s_cbranch_execz .LBB0_1074
	v_mov_b32_e32 v0, 0x12000
	s_waitcnt vmcnt(0) expcnt(0) lgkmcnt(0)
	ds_read_b32 v2, v0
	v_mov_b32_e32 v0, 0x12004
	ds_read_b32 v0, v0
	s_waitcnt lgkmcnt(1)
	v_cmp_ne_u32_e32 vcc, 0, v2
	s_cbranch_vccnz .LBB0_1038
	s_load_dwordx2 s[2:3], s[0:1], 0xf0
	s_load_dword s9, s[0:1], 0xf8
	s_add_u32 s6, s56, 0x1457a300
	s_addc_u32 s7, s57, 0
	s_add_u32 s8, s56, 0x1457a500
	s_waitcnt lgkmcnt(0)
	s_mul_i32 s2, s3, s2
	s_mul_i32 s2, s2, s9
	s_addc_u32 s9, s57, 0
	s_add_u32 s10, s56, 0x1457a600
	s_addc_u32 s11, s57, 0
	s_add_u32 s12, s56, 0x1457a700
	s_addc_u32 s13, s57, 0
	s_add_u32 s14, s56, 0x1457a800
	s_addc_u32 s15, s57, 0
	s_add_u32 s16, s56, 0x1457a900
	s_addc_u32 s17, s57, 0
	s_add_u32 s18, s56, 0x1457aa00
	s_addc_u32 s19, s57, 0
	s_add_u32 s20, s56, 0x1457ab00
	s_addc_u32 s21, s57, 0
	s_add_u32 s22, s56, 0x1457ac00
	s_addc_u32 s23, s57, 0
	s_add_u32 s24, s56, 0x1457ad00
	s_addc_u32 s25, s57, 0
	s_add_u32 s26, s56, 0x1457ae00
	s_addc_u32 s27, s57, 0
	s_add_u32 s28, s56, 0x1457af00
	s_addc_u32 s29, s57, 0
	s_add_u32 s30, s56, 0x1457b000
	s_addc_u32 s31, s57, 0
	s_add_u32 s34, s56, 0x1457b100
	s_addc_u32 s35, s57, 0
	s_add_u32 s36, s56, 0x1457b200
	s_addc_u32 s37, s57, 0
	s_add_u32 s38, s56, 0x1457b300
	s_addc_u32 s39, s57, 0
	s_add_u32 s40, s56, 0x1457b400
	s_addc_u32 s41, s57, 0
	s_mov_b32 s3, 1
	v_mov_b32_e32 v16, 0
	s_branch .LBB0_1026

.LBB0_1260:
	s_cmp_gt_i32 s60, 13
	s_cselect_b64 s[2:3], -1, 0
	s_cmp_lt_i32 s61, 13
	s_cselect_b64 s[4:5], -1, 0
	s_or_b64 s[2:3], s[2:3], s[4:5]
	s_and_b64 vcc, exec, s[2:3]
	s_cbranch_vccnz .LBB0_1328
	s_load_dwordx2 s[4:5], s[0:1], 0xe0
	s_load_dword s16, s[0:1], 0xf0
	s_load_dwordx2 s[24:25], s[0:1], 0xb8
	v_and_b32_e32 v240, 63, v162
	v_lshrrev_b32_e32 v247, 6, v162
	v_lshrrev_b32_e32 v242, 3, v240
	v_lshl_add_u32 v242, v247, 5, v242
	v_and_b32_e32 v243, 7, v240
	v_lshrrev_b32_e32 v244, 4, v240
	v_xor_b32_e32 v243, v243, v244
	v_lshlrev_b32_e32 v243, 4, v243
	v_mov_b32_e32 v241, 0x800
	v_mad_u32_u24 v248, v242, v241, v243
	v_xor_b32_e32 v249, 64, v248
	v_add_u32_e32 v249, 0x4000, v249
	v_add_u32_e32 v250, 0x8000, v248
	v_xor_b32_e32 v251, 64, v248
	v_add_u32_e32 v251, 0xc000, v251
	v_and_b32_e32 v241, 15, v240
	v_lshrrev_b32_e32 v242, 1, v241
	v_xor_b32_e32 v242, v242, v244
	v_lshlrev_b32_e32 v242, 4, v242
	v_lshl_or_b32 v242, v241, 7, v242
	v_lshrrev_b32_e32 v243, 1, v247
	v_lshl_or_b32 v252, v243, 13, v242
	v_xor_b32_e32 v253, 64, v252
	v_and_b32_e32 v243, 1, v247
	v_lshl_or_b32 v254, v243, 13, v242
	v_xor_b32_e32 v255, 64, v254
	v_and_b32_e32 v240, 63, v162
	v_and_b32_e32 v241, 15, v240
	v_lshrrev_b32_e32 v242, 4, v240
	v_lshrrev_b32_e32 v243, 1, v247
	v_and_b32_e32 v244, 1, v247
	v_lshl_or_b32 v245, v244, 6, v241
	v_lshlrev_b32_e32 v243, 4, v243
	v_add_u32_e32 v243, v243, v242
	v_lshl_add_u32 v246, v243, 12, v245
	v_lshlrev_b32_e32 v246, 2, v246
	v_lshlrev_b32_e32 v245, 2, v245
	s_waitcnt lgkmcnt(0)
	s_add_u32 s26, s4, 0x9b7a100
	s_addc_u32 s27, s5, 0
	s_add_u32 s28, s4, 0x2080000
	s_addc_u32 s29, s5, 0
	s_mov_b32 s15, s58
.Lr13_tile:
	s_cmp_lt_u32 s15, 0x200
	s_cbranch_scc0 .Lr13_end
	s_and_b32 s2, s15, 63
	s_lshr_b32 s3, s15, 6
	s_mul_i32 s14, s2, 0x40000
	s_add_u32 s8, s26, s14
	s_addc_u32 s9, s27, 0
	s_mul_i32 s14, s3, 0x40000
	s_add_u32 s10, s28, s14
	s_addc_u32 s11, s29, 0
	s_lshl_b32 s14, s2, 19
	s_lshl_b32 s6, s3, 9
	s_add_u32 s14, s14, s6
	s_add_u32 s20, s4, 0x6b7a100
	s_addc_u32 s21, s5, 0
	s_add_u32 s20, s20, s14
	s_addc_u32 s21, s21, 0
	s_sub_u32 s7, s2, 32
	s_lshr_b32 s7, s7, 3
	s_add_u32 s7, s7, 1
	s_cmp_lt_u32 s2, 32
	s_cselect_b32 s7, 0, s7
	s_mul_i32 s7, s7, 0x6000
	s_add_u32 s7, s7, s6
	s_add_u32 s22, s4, 0x6b22000
	s_addc_u32 s23, s5, 0
	s_add_u32 s22, s22, s7
	s_addc_u32 s23, s23, 0
	s_add_u32 s30, s24, 0x0
	s_addc_u32 s31, s25, 0
	s_add_u32 s30, s30, s6
	s_addc_u32 s31, s31, 0
	v_readfirstlane_b32 s12, v247
	global_load_dword v201, v245, s[22:23] offset:0
	global_load_dword v202, v245, s[22:23] offset:64
	global_load_dword v203, v245, s[22:23] offset:128
	global_load_dword v204, v245, s[22:23] offset:192
	global_load_dword v205, v245, s[30:31] offset:0
	global_load_dword v206, v245, s[30:31] offset:64
	global_load_dword v207, v245, s[30:31] offset:128
	global_load_dword v208, v245, s[30:31] offset:192
	s_mov_b64 s[18:19], s[20:21]
	global_load_dword v129, v246, s[18:19] offset:0
	global_load_dword v130, v246, s[18:19] offset:64
	global_load_dword v131, v246, s[18:19] offset:128
	global_load_dword v132, v246, s[18:19] offset:192
	s_add_u32 s18, s18, 0x1000
	s_addc_u32 s19, s19, 0
	global_load_dword v133, v246, s[18:19] offset:0
	global_load_dword v134, v246, s[18:19] offset:64
	global_load_dword v135, v246, s[18:19] offset:128
	global_load_dword v136, v246, s[18:19] offset:192
	s_add_u32 s18, s18, 0x1000
	s_addc_u32 s19, s19, 0
	global_load_dword v137, v246, s[18:19] offset:0
	global_load_dword v138, v246, s[18:19] offset:64
	global_load_dword v139, v246, s[18:19] offset:128
	global_load_dword v140, v246, s[18:19] offset:192
	s_add_u32 s18, s18, 0x1000
	s_addc_u32 s19, s19, 0
	global_load_dword v141, v246, s[18:19] offset:0
	global_load_dword v142, v246, s[18:19] offset:64
	global_load_dword v143, v246, s[18:19] offset:128
	global_load_dword v144, v246, s[18:19] offset:192
	s_add_u32 s18, s18, 0xd000
	s_addc_u32 s19, s19, 0
	global_load_dword v145, v246, s[18:19] offset:0
	global_load_dword v146, v246, s[18:19] offset:64
	global_load_dword v147, v246, s[18:19] offset:128
	global_load_dword v148, v246, s[18:19] offset:192
	s_add_u32 s18, s18, 0x1000
	s_addc_u32 s19, s19, 0
	global_load_dword v149, v246, s[18:19] offset:0
	global_load_dword v150, v246, s[18:19] offset:64
	global_load_dword v151, v246, s[18:19] offset:128
	global_load_dword v152, v246, s[18:19] offset:192
	s_add_u32 s18, s18, 0x1000
	s_addc_u32 s19, s19, 0
	global_load_dword v153, v246, s[18:19] offset:0
	global_load_dword v154, v246, s[18:19] offset:64
	global_load_dword v155, v246, s[18:19] offset:128
	global_load_dword v156, v246, s[18:19] offset:192
	s_add_u32 s18, s18, 0x1000
	s_addc_u32 s19, s19, 0
	global_load_dword v157, v246, s[18:19] offset:0
	global_load_dword v158, v246, s[18:19] offset:64
	global_load_dword v159, v246, s[18:19] offset:128
	global_load_dword v160, v246, s[18:19] offset:192
	s_add_u32 s18, s18, 0xd000
	s_addc_u32 s19, s19, 0
	global_load_dword v161, v246, s[18:19] offset:0
	global_load_dword v170, v246, s[18:19] offset:64
	global_load_dword v171, v246, s[18:19] offset:128
	global_load_dword v172, v246, s[18:19] offset:192
	s_add_u32 s18, s18, 0x1000
	s_addc_u32 s19, s19, 0
	global_load_dword v173, v246, s[18:19] offset:0
	global_load_dword v174, v246, s[18:19] offset:64
	global_load_dword v175, v246, s[18:19] offset:128
	global_load_dword v176, v246, s[18:19] offset:192
	s_add_u32 s18, s18, 0x1000
	s_addc_u32 s19, s19, 0
	global_load_dword v177, v246, s[18:19] offset:0
	global_load_dword v178, v246, s[18:19] offset:64
	global_load_dword v179, v246, s[18:19] offset:128
	global_load_dword v180, v246, s[18:19] offset:192
	s_add_u32 s18, s18, 0x1000
	s_addc_u32 s19, s19, 0
	global_load_dword v181, v246, s[18:19] offset:0
	global_load_dword v182, v246, s[18:19] offset:64
	global_load_dword v183, v246, s[18:19] offset:128
	global_load_dword v184, v246, s[18:19] offset:192
	s_add_u32 s18, s18, 0xd000
	s_addc_u32 s19, s19, 0
	global_load_dword v185, v246, s[18:19] offset:0
	global_load_dword v186, v246, s[18:19] offset:64
	global_load_dword v187, v246, s[18:19] offset:128
	global_load_dword v188, v246, s[18:19] offset:192
	s_add_u32 s18, s18, 0x1000
	s_addc_u32 s19, s19, 0
	global_load_dword v189, v246, s[18:19] offset:0
	global_load_dword v190, v246, s[18:19] offset:64
	global_load_dword v191, v246, s[18:19] offset:128
	global_load_dword v192, v246, s[18:19] offset:192
	s_add_u32 s18, s18, 0x1000
	s_addc_u32 s19, s19, 0
	global_load_dword v193, v246, s[18:19] offset:0
	global_load_dword v194, v246, s[18:19] offset:64
	global_load_dword v195, v246, s[18:19] offset:128
	global_load_dword v196, v246, s[18:19] offset:192
	s_add_u32 s18, s18, 0x1000
	s_addc_u32 s19, s19, 0
	global_load_dword v197, v246, s[18:19] offset:0
	global_load_dword v198, v246, s[18:19] offset:64
	global_load_dword v199, v246, s[18:19] offset:128
	global_load_dword v200, v246, s[18:19] offset:192
	s_lshl_b32 s12, s12, 12
	s_add_u32 m0, s12, 0x0
	v_mov_b32_e32 v0, 0
	global_load_lds_dwordx4 v248, s[8:9]
	v_mov_b32_e32 v1, 0
	s_add_u32 m0, s12, 0x400
	v_mov_b32_e32 v2, 0
	global_load_lds_dwordx4 v249, s[8:9]
	v_mov_b32_e32 v3, 0
	s_add_u32 m0, s12, 0x800
	v_mov_b32_e32 v4, 0
	global_load_lds_dwordx4 v250, s[8:9]
	v_mov_b32_e32 v5, 0
	s_add_u32 m0, s12, 0xc00
	v_mov_b32_e32 v6, 0
	global_load_lds_dwordx4 v251, s[8:9]
	v_mov_b32_e32 v7, 0
	s_add_u32 m0, s12, 0x8000
	v_mov_b32_e32 v8, 0
	global_load_lds_dwordx4 v248, s[10:11]
	v_mov_b32_e32 v9, 0
	s_add_u32 m0, s12, 0x8400
	v_mov_b32_e32 v10, 0
	global_load_lds_dwordx4 v249, s[10:11]
	v_mov_b32_e32 v11, 0
	s_add_u32 m0, s12, 0x8800
	v_mov_b32_e32 v12, 0
	global_load_lds_dwordx4 v250, s[10:11]
	v_mov_b32_e32 v13, 0
	s_add_u32 m0, s12, 0x8c00
	v_mov_b32_e32 v14, 0
	global_load_lds_dwordx4 v251, s[10:11]
	v_mov_b32_e32 v15, 0
	s_add_u32 s8, s8, 0x80
	s_addc_u32 s9, s9, 0
	s_add_u32 s10, s10, 0x80
	s_addc_u32 s11, s11, 0
	s_add_u32 m0, s12, 0x4000
	v_mov_b32_e32 v16, 0
	global_load_lds_dwordx4 v248, s[8:9]
	v_mov_b32_e32 v17, 0
	s_add_u32 m0, s12, 0x4400
	v_mov_b32_e32 v18, 0
	global_load_lds_dwordx4 v249, s[8:9]
	v_mov_b32_e32 v19, 0
	s_add_u32 m0, s12, 0x4800
	v_mov_b32_e32 v20, 0
	global_load_lds_dwordx4 v250, s[8:9]
	v_mov_b32_e32 v21, 0
	s_add_u32 m0, s12, 0x4c00
	v_mov_b32_e32 v22, 0
	global_load_lds_dwordx4 v251, s[8:9]
	v_mov_b32_e32 v23, 0
	s_add_u32 m0, s12, 0xc000
	v_mov_b32_e32 v24, 0
	global_load_lds_dwordx4 v248, s[10:11]
	v_mov_b32_e32 v25, 0
	s_add_u32 m0, s12, 0xc400
	v_mov_b32_e32 v26, 0
	global_load_lds_dwordx4 v249, s[10:11]
	v_mov_b32_e32 v27, 0
	s_add_u32 m0, s12, 0xc800
	v_mov_b32_e32 v28, 0
	global_load_lds_dwordx4 v250, s[10:11]
	v_mov_b32_e32 v29, 0
	s_add_u32 m0, s12, 0xcc00
	v_mov_b32_e32 v30, 0
	global_load_lds_dwordx4 v251, s[10:11]
	v_mov_b32_e32 v31, 0
	s_add_u32 s8, s8, 0x80
	s_addc_u32 s9, s9, 0
	s_add_u32 s10, s10, 0x80
	s_addc_u32 s11, s11, 0
	v_mov_b32_e32 v32, 0
	v_mov_b32_e32 v33, 0
	v_mov_b32_e32 v34, 0
	v_mov_b32_e32 v35, 0
	v_mov_b32_e32 v36, 0
	v_mov_b32_e32 v37, 0
	v_mov_b32_e32 v38, 0
	v_mov_b32_e32 v39, 0
	v_mov_b32_e32 v40, 0
	v_mov_b32_e32 v41, 0
	v_mov_b32_e32 v42, 0
	v_mov_b32_e32 v43, 0
	v_mov_b32_e32 v44, 0
	v_mov_b32_e32 v45, 0
	v_mov_b32_e32 v46, 0
	v_mov_b32_e32 v47, 0
	v_mov_b32_e32 v48, 0
	v_mov_b32_e32 v49, 0
	v_mov_b32_e32 v50, 0
	v_mov_b32_e32 v51, 0
	v_mov_b32_e32 v52, 0
	v_mov_b32_e32 v53, 0
	v_mov_b32_e32 v54, 0
	v_mov_b32_e32 v55, 0
	v_mov_b32_e32 v56, 0
	v_mov_b32_e32 v57, 0
	v_mov_b32_e32 v58, 0
	v_mov_b32_e32 v59, 0
	v_mov_b32_e32 v60, 0
	v_mov_b32_e32 v61, 0
	v_mov_b32_e32 v62, 0
	v_mov_b32_e32 v63, 0
	s_waitcnt vmcnt(8)
	s_barrier
	ds_read_b128 v[64:67], v252 offset:0
	ds_read_b128 v[96:99], v254 offset:32768
	ds_read_b128 v[100:103], v254 offset:34816
	ds_read_b128 v[104:107], v254 offset:36864
	ds_read_b128 v[108:111], v254 offset:38912
	ds_read_b128 v[68:71], v252 offset:2048
	ds_read_b128 v[72:75], v252 offset:4096
	ds_read_b128 v[76:79], v252 offset:6144
	ds_read_b128 v[80:83], v253 offset:0
	ds_read_b128 v[112:115], v255 offset:32768
	ds_read_b128 v[116:119], v255 offset:34816
	ds_read_b128 v[120:123], v255 offset:36864
	ds_read_b128 v[124:127], v255 offset:38912
	s_waitcnt lgkmcnt(11)
	v_mfma_f32_16x16x32_bf16 v[0:3], v[64:67], v[96:99], v[0:3]
	s_waitcnt lgkmcnt(10)
	v_mfma_f32_16x16x32_bf16 v[4:7], v[64:67], v[100:103], v[4:7]
	s_waitcnt lgkmcnt(9)
	v_mfma_f32_16x16x32_bf16 v[8:11], v[64:67], v[104:107], v[8:11]
	s_waitcnt lgkmcnt(8)
	v_mfma_f32_16x16x32_bf16 v[12:15], v[64:67], v[108:111], v[12:15]
	ds_read_b128 v[84:87], v253 offset:2048
	ds_read_b128 v[88:91], v253 offset:4096
	ds_read_b128 v[92:95], v253 offset:6144
	s_waitcnt lgkmcnt(10)
	v_mfma_f32_16x16x32_bf16 v[16:19], v[68:71], v[96:99], v[16:19]
	v_mfma_f32_16x16x32_bf16 v[20:23], v[68:71], v[100:103], v[20:23]
	v_mfma_f32_16x16x32_bf16 v[24:27], v[68:71], v[104:107], v[24:27]
	v_mfma_f32_16x16x32_bf16 v[28:31], v[68:71], v[108:111], v[28:31]
	s_waitcnt lgkmcnt(0)
	s_barrier
	s_add_u32 m0, s12, 0x0
	v_mfma_f32_16x16x32_bf16 v[32:35], v[72:75], v[96:99], v[32:35]
	global_load_lds_dwordx4 v248, s[8:9]
	s_add_u32 m0, s12, 0x400
	v_mfma_f32_16x16x32_bf16 v[36:39], v[72:75], v[100:103], v[36:39]
	global_load_lds_dwordx4 v249, s[8:9]
	s_add_u32 m0, s12, 0x800
	v_mfma_f32_16x16x32_bf16 v[40:43], v[72:75], v[104:107], v[40:43]
	global_load_lds_dwordx4 v250, s[8:9]
	s_add_u32 m0, s12, 0xc00
	v_mfma_f32_16x16x32_bf16 v[44:47], v[72:75], v[108:111], v[44:47]
	global_load_lds_dwordx4 v251, s[8:9]
	s_add_u32 m0, s12, 0x8000
	v_mfma_f32_16x16x32_bf16 v[48:51], v[76:79], v[96:99], v[48:51]
	global_load_lds_dwordx4 v248, s[10:11]
	s_add_u32 m0, s12, 0x8400
	v_mfma_f32_16x16x32_bf16 v[52:55], v[76:79], v[100:103], v[52:55]
	global_load_lds_dwordx4 v249, s[10:11]
	s_add_u32 m0, s12, 0x8800
	v_mfma_f32_16x16x32_bf16 v[56:59], v[76:79], v[104:107], v[56:59]
	global_load_lds_dwordx4 v250, s[10:11]
	s_add_u32 m0, s12, 0x8c00
	v_mfma_f32_16x16x32_bf16 v[60:63], v[76:79], v[108:111], v[60:63]
	global_load_lds_dwordx4 v251, s[10:11]
	s_add_u32 s8, s8, 0x80
	s_addc_u32 s9, s9, 0
	s_add_u32 s10, s10, 0x80
	s_addc_u32 s11, s11, 0
	s_waitcnt vmcnt(8)
	s_barrier
	ds_read_b128 v[64:67], v252 offset:16384
	ds_read_b128 v[96:99], v254 offset:49152
	ds_read_b128 v[100:103], v254 offset:51200
	ds_read_b128 v[104:107], v254 offset:53248
	ds_read_b128 v[108:111], v254 offset:55296
	ds_read_b128 v[68:71], v252 offset:18432
	ds_read_b128 v[72:75], v252 offset:20480
	ds_read_b128 v[76:79], v252 offset:22528
	v_mfma_f32_16x16x32_bf16 v[0:3], v[80:83], v[112:115], v[0:3]
	v_mfma_f32_16x16x32_bf16 v[4:7], v[80:83], v[116:119], v[4:7]
	v_mfma_f32_16x16x32_bf16 v[8:11], v[80:83], v[120:123], v[8:11]
	v_mfma_f32_16x16x32_bf16 v[12:15], v[80:83], v[124:127], v[12:15]
	v_mfma_f32_16x16x32_bf16 v[16:19], v[84:87], v[112:115], v[16:19]
	v_mfma_f32_16x16x32_bf16 v[20:23], v[84:87], v[116:119], v[20:23]
	v_mfma_f32_16x16x32_bf16 v[24:27], v[84:87], v[120:123], v[24:27]
	v_mfma_f32_16x16x32_bf16 v[28:31], v[84:87], v[124:127], v[28:31]
	v_mfma_f32_16x16x32_bf16 v[32:35], v[88:91], v[112:115], v[32:35]
	v_mfma_f32_16x16x32_bf16 v[36:39], v[88:91], v[116:119], v[36:39]
	v_mfma_f32_16x16x32_bf16 v[40:43], v[88:91], v[120:123], v[40:43]
	v_mfma_f32_16x16x32_bf16 v[44:47], v[88:91], v[124:127], v[44:47]
	v_mfma_f32_16x16x32_bf16 v[48:51], v[92:95], v[112:115], v[48:51]
	v_mfma_f32_16x16x32_bf16 v[52:55], v[92:95], v[116:119], v[52:55]
	v_mfma_f32_16x16x32_bf16 v[56:59], v[92:95], v[120:123], v[56:59]
	v_mfma_f32_16x16x32_bf16 v[60:63], v[92:95], v[124:127], v[60:63]
	ds_read_b128 v[80:83], v253 offset:16384
	ds_read_b128 v[112:115], v255 offset:49152
	ds_read_b128 v[116:119], v255 offset:51200
	ds_read_b128 v[120:123], v255 offset:53248
	ds_read_b128 v[124:127], v255 offset:55296
	ds_read_b128 v[84:87], v253 offset:18432
	ds_read_b128 v[88:91], v253 offset:20480
	ds_read_b128 v[92:95], v253 offset:22528
	s_waitcnt lgkmcnt(14)
	v_mfma_f32_16x16x32_bf16 v[0:3], v[64:67], v[96:99], v[0:3]
	s_waitcnt lgkmcnt(13)
	v_mfma_f32_16x16x32_bf16 v[4:7], v[64:67], v[100:103], v[4:7]
	s_waitcnt lgkmcnt(12)
	v_mfma_f32_16x16x32_bf16 v[8:11], v[64:67], v[104:107], v[8:11]
	s_waitcnt lgkmcnt(11)
	v_mfma_f32_16x16x32_bf16 v[12:15], v[64:67], v[108:111], v[12:15]
	s_waitcnt lgkmcnt(10)
	v_mfma_f32_16x16x32_bf16 v[16:19], v[68:71], v[96:99], v[16:19]
	v_mfma_f32_16x16x32_bf16 v[20:23], v[68:71], v[100:103], v[20:23]
	v_mfma_f32_16x16x32_bf16 v[24:27], v[68:71], v[104:107], v[24:27]
	v_mfma_f32_16x16x32_bf16 v[28:31], v[68:71], v[108:111], v[28:31]
	s_waitcnt lgkmcnt(0)
	s_barrier
	s_add_u32 m0, s12, 0x4000
	v_mfma_f32_16x16x32_bf16 v[32:35], v[72:75], v[96:99], v[32:35]
	global_load_lds_dwordx4 v248, s[8:9]
	s_add_u32 m0, s12, 0x4400
	v_mfma_f32_16x16x32_bf16 v[36:39], v[72:75], v[100:103], v[36:39]
	global_load_lds_dwordx4 v249, s[8:9]
	s_add_u32 m0, s12, 0x4800
	v_mfma_f32_16x16x32_bf16 v[40:43], v[72:75], v[104:107], v[40:43]
	global_load_lds_dwordx4 v250, s[8:9]
	s_add_u32 m0, s12, 0x4c00
	v_mfma_f32_16x16x32_bf16 v[44:47], v[72:75], v[108:111], v[44:47]
	global_load_lds_dwordx4 v251, s[8:9]
	s_add_u32 m0, s12, 0xc000
	v_mfma_f32_16x16x32_bf16 v[48:51], v[76:79], v[96:99], v[48:51]
	global_load_lds_dwordx4 v248, s[10:11]
	s_add_u32 m0, s12, 0xc400
	v_mfma_f32_16x16x32_bf16 v[52:55], v[76:79], v[100:103], v[52:55]
	global_load_lds_dwordx4 v249, s[10:11]
	s_add_u32 m0, s12, 0xc800
	v_mfma_f32_16x16x32_bf16 v[56:59], v[76:79], v[104:107], v[56:59]
	global_load_lds_dwordx4 v250, s[10:11]
	s_add_u32 m0, s12, 0xcc00
	v_mfma_f32_16x16x32_bf16 v[60:63], v[76:79], v[108:111], v[60:63]
	global_load_lds_dwordx4 v251, s[10:11]
	s_add_u32 s8, s8, 0x80
	s_addc_u32 s9, s9, 0
	s_add_u32 s10, s10, 0x80
	s_addc_u32 s11, s11, 0
	s_mov_b32 s13, 6
.Lr13_loop:
	s_waitcnt vmcnt(8)
	s_barrier
	ds_read_b128 v[64:67], v252 offset:0
	ds_read_b128 v[96:99], v254 offset:32768
	ds_read_b128 v[100:103], v254 offset:34816
	ds_read_b128 v[104:107], v254 offset:36864
	ds_read_b128 v[108:111], v254 offset:38912
	ds_read_b128 v[68:71], v252 offset:2048
	ds_read_b128 v[72:75], v252 offset:4096
	ds_read_b128 v[76:79], v252 offset:6144
	v_mfma_f32_16x16x32_bf16 v[0:3], v[80:83], v[112:115], v[0:3]
	v_mfma_f32_16x16x32_bf16 v[4:7], v[80:83], v[116:119], v[4:7]
	v_mfma_f32_16x16x32_bf16 v[8:11], v[80:83], v[120:123], v[8:11]
	v_mfma_f32_16x16x32_bf16 v[12:15], v[80:83], v[124:127], v[12:15]
	v_mfma_f32_16x16x32_bf16 v[16:19], v[84:87], v[112:115], v[16:19]
	v_mfma_f32_16x16x32_bf16 v[20:23], v[84:87], v[116:119], v[20:23]
	v_mfma_f32_16x16x32_bf16 v[24:27], v[84:87], v[120:123], v[24:27]
	v_mfma_f32_16x16x32_bf16 v[28:31], v[84:87], v[124:127], v[28:31]
	v_mfma_f32_16x16x32_bf16 v[32:35], v[88:91], v[112:115], v[32:35]
	v_mfma_f32_16x16x32_bf16 v[36:39], v[88:91], v[116:119], v[36:39]
	v_mfma_f32_16x16x32_bf16 v[40:43], v[88:91], v[120:123], v[40:43]
	v_mfma_f32_16x16x32_bf16 v[44:47], v[88:91], v[124:127], v[44:47]
	v_mfma_f32_16x16x32_bf16 v[48:51], v[92:95], v[112:115], v[48:51]
	v_mfma_f32_16x16x32_bf16 v[52:55], v[92:95], v[116:119], v[52:55]
	v_mfma_f32_16x16x32_bf16 v[56:59], v[92:95], v[120:123], v[56:59]
	v_mfma_f32_16x16x32_bf16 v[60:63], v[92:95], v[124:127], v[60:63]
	ds_read_b128 v[80:83], v253 offset:0
	ds_read_b128 v[112:115], v255 offset:32768
	ds_read_b128 v[116:119], v255 offset:34816
	ds_read_b128 v[120:123], v255 offset:36864
	ds_read_b128 v[124:127], v255 offset:38912
	ds_read_b128 v[84:87], v253 offset:2048
	ds_read_b128 v[88:91], v253 offset:4096
	ds_read_b128 v[92:95], v253 offset:6144
	s_waitcnt lgkmcnt(14)
	v_mfma_f32_16x16x32_bf16 v[0:3], v[64:67], v[96:99], v[0:3]
	s_waitcnt lgkmcnt(13)
	v_mfma_f32_16x16x32_bf16 v[4:7], v[64:67], v[100:103], v[4:7]
	s_waitcnt lgkmcnt(12)
	v_mfma_f32_16x16x32_bf16 v[8:11], v[64:67], v[104:107], v[8:11]
	s_waitcnt lgkmcnt(11)
	v_mfma_f32_16x16x32_bf16 v[12:15], v[64:67], v[108:111], v[12:15]
	s_waitcnt lgkmcnt(10)
	v_mfma_f32_16x16x32_bf16 v[16:19], v[68:71], v[96:99], v[16:19]
	v_mfma_f32_16x16x32_bf16 v[20:23], v[68:71], v[100:103], v[20:23]
	v_mfma_f32_16x16x32_bf16 v[24:27], v[68:71], v[104:107], v[24:27]
	v_mfma_f32_16x16x32_bf16 v[28:31], v[68:71], v[108:111], v[28:31]
	s_waitcnt lgkmcnt(0)
	s_barrier
	s_add_u32 m0, s12, 0x0
	v_mfma_f32_16x16x32_bf16 v[32:35], v[72:75], v[96:99], v[32:35]
	global_load_lds_dwordx4 v248, s[8:9]
	s_add_u32 m0, s12, 0x400
	v_mfma_f32_16x16x32_bf16 v[36:39], v[72:75], v[100:103], v[36:39]
	global_load_lds_dwordx4 v249, s[8:9]
	s_add_u32 m0, s12, 0x800
	v_mfma_f32_16x16x32_bf16 v[40:43], v[72:75], v[104:107], v[40:43]
	global_load_lds_dwordx4 v250, s[8:9]
	s_add_u32 m0, s12, 0xc00
	v_mfma_f32_16x16x32_bf16 v[44:47], v[72:75], v[108:111], v[44:47]
	global_load_lds_dwordx4 v251, s[8:9]
	s_add_u32 m0, s12, 0x8000
	v_mfma_f32_16x16x32_bf16 v[48:51], v[76:79], v[96:99], v[48:51]
	global_load_lds_dwordx4 v248, s[10:11]
	s_add_u32 m0, s12, 0x8400
	v_mfma_f32_16x16x32_bf16 v[52:55], v[76:79], v[100:103], v[52:55]
	global_load_lds_dwordx4 v249, s[10:11]
	s_add_u32 m0, s12, 0x8800
	v_mfma_f32_16x16x32_bf16 v[56:59], v[76:79], v[104:107], v[56:59]
	global_load_lds_dwordx4 v250, s[10:11]
	s_add_u32 m0, s12, 0x8c00
	v_mfma_f32_16x16x32_bf16 v[60:63], v[76:79], v[108:111], v[60:63]
	global_load_lds_dwordx4 v251, s[10:11]
	s_add_u32 s8, s8, 0x80
	s_addc_u32 s9, s9, 0
	s_add_u32 s10, s10, 0x80
	s_addc_u32 s11, s11, 0
	s_waitcnt vmcnt(8)
	s_barrier
	ds_read_b128 v[64:67], v252 offset:16384
	ds_read_b128 v[96:99], v254 offset:49152
	ds_read_b128 v[100:103], v254 offset:51200
	ds_read_b128 v[104:107], v254 offset:53248
	ds_read_b128 v[108:111], v254 offset:55296
	ds_read_b128 v[68:71], v252 offset:18432
	ds_read_b128 v[72:75], v252 offset:20480
	ds_read_b128 v[76:79], v252 offset:22528
	v_mfma_f32_16x16x32_bf16 v[0:3], v[80:83], v[112:115], v[0:3]
	v_mfma_f32_16x16x32_bf16 v[4:7], v[80:83], v[116:119], v[4:7]
	v_mfma_f32_16x16x32_bf16 v[8:11], v[80:83], v[120:123], v[8:11]
	v_mfma_f32_16x16x32_bf16 v[12:15], v[80:83], v[124:127], v[12:15]
	v_mfma_f32_16x16x32_bf16 v[16:19], v[84:87], v[112:115], v[16:19]
	v_mfma_f32_16x16x32_bf16 v[20:23], v[84:87], v[116:119], v[20:23]
	v_mfma_f32_16x16x32_bf16 v[24:27], v[84:87], v[120:123], v[24:27]
	v_mfma_f32_16x16x32_bf16 v[28:31], v[84:87], v[124:127], v[28:31]
	v_mfma_f32_16x16x32_bf16 v[32:35], v[88:91], v[112:115], v[32:35]
	v_mfma_f32_16x16x32_bf16 v[36:39], v[88:91], v[116:119], v[36:39]
	v_mfma_f32_16x16x32_bf16 v[40:43], v[88:91], v[120:123], v[40:43]
	v_mfma_f32_16x16x32_bf16 v[44:47], v[88:91], v[124:127], v[44:47]
	v_mfma_f32_16x16x32_bf16 v[48:51], v[92:95], v[112:115], v[48:51]
	v_mfma_f32_16x16x32_bf16 v[52:55], v[92:95], v[116:119], v[52:55]
	v_mfma_f32_16x16x32_bf16 v[56:59], v[92:95], v[120:123], v[56:59]
	v_mfma_f32_16x16x32_bf16 v[60:63], v[92:95], v[124:127], v[60:63]
	ds_read_b128 v[80:83], v253 offset:16384
	ds_read_b128 v[112:115], v255 offset:49152
	ds_read_b128 v[116:119], v255 offset:51200
	ds_read_b128 v[120:123], v255 offset:53248
	ds_read_b128 v[124:127], v255 offset:55296
	ds_read_b128 v[84:87], v253 offset:18432
	ds_read_b128 v[88:91], v253 offset:20480
	ds_read_b128 v[92:95], v253 offset:22528
	s_waitcnt lgkmcnt(14)
	v_mfma_f32_16x16x32_bf16 v[0:3], v[64:67], v[96:99], v[0:3]
	s_waitcnt lgkmcnt(13)
	v_mfma_f32_16x16x32_bf16 v[4:7], v[64:67], v[100:103], v[4:7]
	s_waitcnt lgkmcnt(12)
	v_mfma_f32_16x16x32_bf16 v[8:11], v[64:67], v[104:107], v[8:11]
	s_waitcnt lgkmcnt(11)
	v_mfma_f32_16x16x32_bf16 v[12:15], v[64:67], v[108:111], v[12:15]
	s_waitcnt lgkmcnt(10)
	v_mfma_f32_16x16x32_bf16 v[16:19], v[68:71], v[96:99], v[16:19]
	v_mfma_f32_16x16x32_bf16 v[20:23], v[68:71], v[100:103], v[20:23]
	v_mfma_f32_16x16x32_bf16 v[24:27], v[68:71], v[104:107], v[24:27]
	v_mfma_f32_16x16x32_bf16 v[28:31], v[68:71], v[108:111], v[28:31]
	s_waitcnt lgkmcnt(0)
	s_barrier
	s_add_u32 m0, s12, 0x4000
	v_mfma_f32_16x16x32_bf16 v[32:35], v[72:75], v[96:99], v[32:35]
	global_load_lds_dwordx4 v248, s[8:9]
	s_add_u32 m0, s12, 0x4400
	v_mfma_f32_16x16x32_bf16 v[36:39], v[72:75], v[100:103], v[36:39]
	global_load_lds_dwordx4 v249, s[8:9]
	s_add_u32 m0, s12, 0x4800
	v_mfma_f32_16x16x32_bf16 v[40:43], v[72:75], v[104:107], v[40:43]
	global_load_lds_dwordx4 v250, s[8:9]
	s_add_u32 m0, s12, 0x4c00
	v_mfma_f32_16x16x32_bf16 v[44:47], v[72:75], v[108:111], v[44:47]
	global_load_lds_dwordx4 v251, s[8:9]
	s_add_u32 m0, s12, 0xc000
	v_mfma_f32_16x16x32_bf16 v[48:51], v[76:79], v[96:99], v[48:51]
	global_load_lds_dwordx4 v248, s[10:11]
	s_add_u32 m0, s12, 0xc400
	v_mfma_f32_16x16x32_bf16 v[52:55], v[76:79], v[100:103], v[52:55]
	global_load_lds_dwordx4 v249, s[10:11]
	s_add_u32 m0, s12, 0xc800
	v_mfma_f32_16x16x32_bf16 v[56:59], v[76:79], v[104:107], v[56:59]
	global_load_lds_dwordx4 v250, s[10:11]
	s_add_u32 m0, s12, 0xcc00
	v_mfma_f32_16x16x32_bf16 v[60:63], v[76:79], v[108:111], v[60:63]
	global_load_lds_dwordx4 v251, s[10:11]
	s_add_u32 s8, s8, 0x80
	s_addc_u32 s9, s9, 0
	s_add_u32 s10, s10, 0x80
	s_addc_u32 s11, s11, 0
	s_sub_u32 s13, s13, 1
	s_cmp_lg_u32 s13, 0
	s_cbranch_scc1 .Lr13_loop
	s_waitcnt vmcnt(8)
	s_barrier
	ds_read_b128 v[64:67], v252 offset:0
	ds_read_b128 v[96:99], v254 offset:32768
	ds_read_b128 v[100:103], v254 offset:34816
	ds_read_b128 v[104:107], v254 offset:36864
	ds_read_b128 v[108:111], v254 offset:38912
	ds_read_b128 v[68:71], v252 offset:2048
	ds_read_b128 v[72:75], v252 offset:4096
	ds_read_b128 v[76:79], v252 offset:6144
	v_mfma_f32_16x16x32_bf16 v[0:3], v[80:83], v[112:115], v[0:3]
	v_mfma_f32_16x16x32_bf16 v[4:7], v[80:83], v[116:119], v[4:7]
	v_mfma_f32_16x16x32_bf16 v[8:11], v[80:83], v[120:123], v[8:11]
	v_mfma_f32_16x16x32_bf16 v[12:15], v[80:83], v[124:127], v[12:15]
	v_mfma_f32_16x16x32_bf16 v[16:19], v[84:87], v[112:115], v[16:19]
	v_mfma_f32_16x16x32_bf16 v[20:23], v[84:87], v[116:119], v[20:23]
	v_mfma_f32_16x16x32_bf16 v[24:27], v[84:87], v[120:123], v[24:27]
	v_mfma_f32_16x16x32_bf16 v[28:31], v[84:87], v[124:127], v[28:31]
	v_mfma_f32_16x16x32_bf16 v[32:35], v[88:91], v[112:115], v[32:35]
	v_mfma_f32_16x16x32_bf16 v[36:39], v[88:91], v[116:119], v[36:39]
	v_mfma_f32_16x16x32_bf16 v[40:43], v[88:91], v[120:123], v[40:43]
	v_mfma_f32_16x16x32_bf16 v[44:47], v[88:91], v[124:127], v[44:47]
	v_mfma_f32_16x16x32_bf16 v[48:51], v[92:95], v[112:115], v[48:51]
	v_mfma_f32_16x16x32_bf16 v[52:55], v[92:95], v[116:119], v[52:55]
	v_mfma_f32_16x16x32_bf16 v[56:59], v[92:95], v[120:123], v[56:59]
	v_mfma_f32_16x16x32_bf16 v[60:63], v[92:95], v[124:127], v[60:63]
	ds_read_b128 v[80:83], v253 offset:0
	ds_read_b128 v[112:115], v255 offset:32768
	ds_read_b128 v[116:119], v255 offset:34816
	ds_read_b128 v[120:123], v255 offset:36864
	ds_read_b128 v[124:127], v255 offset:38912
	ds_read_b128 v[84:87], v253 offset:2048
	ds_read_b128 v[88:91], v253 offset:4096
	ds_read_b128 v[92:95], v253 offset:6144
	s_waitcnt lgkmcnt(14)
	v_mfma_f32_16x16x32_bf16 v[0:3], v[64:67], v[96:99], v[0:3]
	s_waitcnt lgkmcnt(13)
	v_mfma_f32_16x16x32_bf16 v[4:7], v[64:67], v[100:103], v[4:7]
	s_waitcnt lgkmcnt(12)
	v_mfma_f32_16x16x32_bf16 v[8:11], v[64:67], v[104:107], v[8:11]
	s_waitcnt lgkmcnt(11)
	v_mfma_f32_16x16x32_bf16 v[12:15], v[64:67], v[108:111], v[12:15]
	s_waitcnt lgkmcnt(10)
	v_mfma_f32_16x16x32_bf16 v[16:19], v[68:71], v[96:99], v[16:19]
	v_mfma_f32_16x16x32_bf16 v[20:23], v[68:71], v[100:103], v[20:23]
	v_mfma_f32_16x16x32_bf16 v[24:27], v[68:71], v[104:107], v[24:27]
	v_mfma_f32_16x16x32_bf16 v[28:31], v[68:71], v[108:111], v[28:31]
	s_waitcnt lgkmcnt(0)
	s_barrier
	v_mfma_f32_16x16x32_bf16 v[32:35], v[72:75], v[96:99], v[32:35]
	v_mfma_f32_16x16x32_bf16 v[36:39], v[72:75], v[100:103], v[36:39]
	v_mfma_f32_16x16x32_bf16 v[40:43], v[72:75], v[104:107], v[40:43]
	v_mfma_f32_16x16x32_bf16 v[44:47], v[72:75], v[108:111], v[44:47]
	v_mfma_f32_16x16x32_bf16 v[48:51], v[76:79], v[96:99], v[48:51]
	v_mfma_f32_16x16x32_bf16 v[52:55], v[76:79], v[100:103], v[52:55]
	v_mfma_f32_16x16x32_bf16 v[56:59], v[76:79], v[104:107], v[56:59]
	v_mfma_f32_16x16x32_bf16 v[60:63], v[76:79], v[108:111], v[60:63]
	s_waitcnt vmcnt(0)
	s_barrier
	ds_read_b128 v[64:67], v252 offset:16384
	ds_read_b128 v[96:99], v254 offset:49152
	ds_read_b128 v[100:103], v254 offset:51200
	ds_read_b128 v[104:107], v254 offset:53248
	ds_read_b128 v[108:111], v254 offset:55296
	ds_read_b128 v[68:71], v252 offset:18432
	ds_read_b128 v[72:75], v252 offset:20480
	ds_read_b128 v[76:79], v252 offset:22528
	v_mfma_f32_16x16x32_bf16 v[0:3], v[80:83], v[112:115], v[0:3]
	v_mfma_f32_16x16x32_bf16 v[4:7], v[80:83], v[116:119], v[4:7]
	v_mfma_f32_16x16x32_bf16 v[8:11], v[80:83], v[120:123], v[8:11]
	v_mfma_f32_16x16x32_bf16 v[12:15], v[80:83], v[124:127], v[12:15]
	v_mfma_f32_16x16x32_bf16 v[16:19], v[84:87], v[112:115], v[16:19]
	v_mfma_f32_16x16x32_bf16 v[20:23], v[84:87], v[116:119], v[20:23]
	v_mfma_f32_16x16x32_bf16 v[24:27], v[84:87], v[120:123], v[24:27]
	v_mfma_f32_16x16x32_bf16 v[28:31], v[84:87], v[124:127], v[28:31]
	v_mfma_f32_16x16x32_bf16 v[32:35], v[88:91], v[112:115], v[32:35]
	v_mfma_f32_16x16x32_bf16 v[36:39], v[88:91], v[116:119], v[36:39]
	v_mfma_f32_16x16x32_bf16 v[40:43], v[88:91], v[120:123], v[40:43]
	v_mfma_f32_16x16x32_bf16 v[44:47], v[88:91], v[124:127], v[44:47]
	v_mfma_f32_16x16x32_bf16 v[48:51], v[92:95], v[112:115], v[48:51]
	v_mfma_f32_16x16x32_bf16 v[52:55], v[92:95], v[116:119], v[52:55]
	v_mfma_f32_16x16x32_bf16 v[56:59], v[92:95], v[120:123], v[56:59]
	v_mfma_f32_16x16x32_bf16 v[60:63], v[92:95], v[124:127], v[60:63]
	ds_read_b128 v[80:83], v253 offset:16384
	ds_read_b128 v[112:115], v255 offset:49152
	ds_read_b128 v[116:119], v255 offset:51200
	ds_read_b128 v[120:123], v255 offset:53248
	ds_read_b128 v[124:127], v255 offset:55296
	ds_read_b128 v[84:87], v253 offset:18432
	ds_read_b128 v[88:91], v253 offset:20480
	ds_read_b128 v[92:95], v253 offset:22528
	s_waitcnt lgkmcnt(14)
	v_mfma_f32_16x16x32_bf16 v[0:3], v[64:67], v[96:99], v[0:3]
	s_waitcnt lgkmcnt(13)
	v_mfma_f32_16x16x32_bf16 v[4:7], v[64:67], v[100:103], v[4:7]
	s_waitcnt lgkmcnt(12)
	v_mfma_f32_16x16x32_bf16 v[8:11], v[64:67], v[104:107], v[8:11]
	s_waitcnt lgkmcnt(11)
	v_mfma_f32_16x16x32_bf16 v[12:15], v[64:67], v[108:111], v[12:15]
	s_waitcnt lgkmcnt(10)
	v_mfma_f32_16x16x32_bf16 v[16:19], v[68:71], v[96:99], v[16:19]
	v_mfma_f32_16x16x32_bf16 v[20:23], v[68:71], v[100:103], v[20:23]
	v_mfma_f32_16x16x32_bf16 v[24:27], v[68:71], v[104:107], v[24:27]
	v_mfma_f32_16x16x32_bf16 v[28:31], v[68:71], v[108:111], v[28:31]
	s_waitcnt lgkmcnt(0)
	s_barrier
	v_mfma_f32_16x16x32_bf16 v[32:35], v[72:75], v[96:99], v[32:35]
	v_mfma_f32_16x16x32_bf16 v[36:39], v[72:75], v[100:103], v[36:39]
	v_mfma_f32_16x16x32_bf16 v[40:43], v[72:75], v[104:107], v[40:43]
	v_mfma_f32_16x16x32_bf16 v[44:47], v[72:75], v[108:111], v[44:47]
	v_mfma_f32_16x16x32_bf16 v[48:51], v[76:79], v[96:99], v[48:51]
	v_mfma_f32_16x16x32_bf16 v[52:55], v[76:79], v[100:103], v[52:55]
	v_mfma_f32_16x16x32_bf16 v[56:59], v[76:79], v[104:107], v[56:59]
	v_mfma_f32_16x16x32_bf16 v[60:63], v[76:79], v[108:111], v[60:63]
	v_mfma_f32_16x16x32_bf16 v[0:3], v[80:83], v[112:115], v[0:3]
	v_mfma_f32_16x16x32_bf16 v[4:7], v[80:83], v[116:119], v[4:7]
	v_mfma_f32_16x16x32_bf16 v[8:11], v[80:83], v[120:123], v[8:11]
	v_mfma_f32_16x16x32_bf16 v[12:15], v[80:83], v[124:127], v[12:15]
	v_mfma_f32_16x16x32_bf16 v[16:19], v[84:87], v[112:115], v[16:19]
	v_mfma_f32_16x16x32_bf16 v[20:23], v[84:87], v[116:119], v[20:23]
	v_mfma_f32_16x16x32_bf16 v[24:27], v[84:87], v[120:123], v[24:27]
	v_mfma_f32_16x16x32_bf16 v[28:31], v[84:87], v[124:127], v[28:31]
	v_mfma_f32_16x16x32_bf16 v[32:35], v[88:91], v[112:115], v[32:35]
	v_mfma_f32_16x16x32_bf16 v[36:39], v[88:91], v[116:119], v[36:39]
	v_mfma_f32_16x16x32_bf16 v[40:43], v[88:91], v[120:123], v[40:43]
	v_mfma_f32_16x16x32_bf16 v[44:47], v[88:91], v[124:127], v[44:47]
	v_mfma_f32_16x16x32_bf16 v[48:51], v[92:95], v[112:115], v[48:51]
	v_mfma_f32_16x16x32_bf16 v[52:55], v[92:95], v[116:119], v[52:55]
	v_mfma_f32_16x16x32_bf16 v[56:59], v[92:95], v[120:123], v[56:59]
	v_mfma_f32_16x16x32_bf16 v[60:63], v[92:95], v[124:127], v[60:63]
	s_nop 7
	s_nop 1
	s_mov_b64 s[18:19], s[20:21]
	v_add_f32_e32 v0, v0, v205
	v_add_f32_e32 v4, v4, v206
	v_add_f32_e32 v8, v8, v207
	v_add_f32_e32 v12, v12, v208
	v_fma_f32 v129, v201, v0, v129
	v_fma_f32 v130, v202, v4, v130
	v_fma_f32 v131, v203, v8, v131
	v_fma_f32 v132, v204, v12, v132
	global_store_dword v246, v129, s[18:19] offset:0
	global_store_dword v246, v130, s[18:19] offset:64
	global_store_dword v246, v131, s[18:19] offset:128
	global_store_dword v246, v132, s[18:19] offset:192
	s_add_u32 s18, s18, 0x1000
	s_addc_u32 s19, s19, 0
	v_add_f32_e32 v1, v1, v205
	v_add_f32_e32 v5, v5, v206
	v_add_f32_e32 v9, v9, v207
	v_add_f32_e32 v13, v13, v208
	v_fma_f32 v133, v201, v1, v133
	v_fma_f32 v134, v202, v5, v134
	v_fma_f32 v135, v203, v9, v135
	v_fma_f32 v136, v204, v13, v136
	global_store_dword v246, v133, s[18:19] offset:0
	global_store_dword v246, v134, s[18:19] offset:64
	global_store_dword v246, v135, s[18:19] offset:128
	global_store_dword v246, v136, s[18:19] offset:192
	s_add_u32 s18, s18, 0x1000
	s_addc_u32 s19, s19, 0
	v_add_f32_e32 v2, v2, v205
	v_add_f32_e32 v6, v6, v206
	v_add_f32_e32 v10, v10, v207
	v_add_f32_e32 v14, v14, v208
	v_fma_f32 v137, v201, v2, v137
	v_fma_f32 v138, v202, v6, v138
	v_fma_f32 v139, v203, v10, v139
	v_fma_f32 v140, v204, v14, v140
	global_store_dword v246, v137, s[18:19] offset:0
	global_store_dword v246, v138, s[18:19] offset:64
	global_store_dword v246, v139, s[18:19] offset:128
	global_store_dword v246, v140, s[18:19] offset:192
	s_add_u32 s18, s18, 0x1000
	s_addc_u32 s19, s19, 0
	v_add_f32_e32 v3, v3, v205
	v_add_f32_e32 v7, v7, v206
	v_add_f32_e32 v11, v11, v207
	v_add_f32_e32 v15, v15, v208
	v_fma_f32 v141, v201, v3, v141
	v_fma_f32 v142, v202, v7, v142
	v_fma_f32 v143, v203, v11, v143
	v_fma_f32 v144, v204, v15, v144
	global_store_dword v246, v141, s[18:19] offset:0
	global_store_dword v246, v142, s[18:19] offset:64
	global_store_dword v246, v143, s[18:19] offset:128
	global_store_dword v246, v144, s[18:19] offset:192
	s_add_u32 s18, s18, 0xd000
	s_addc_u32 s19, s19, 0
	v_add_f32_e32 v16, v16, v205
	v_add_f32_e32 v20, v20, v206
	v_add_f32_e32 v24, v24, v207
	v_add_f32_e32 v28, v28, v208
	v_fma_f32 v145, v201, v16, v145
	v_fma_f32 v146, v202, v20, v146
	v_fma_f32 v147, v203, v24, v147
	v_fma_f32 v148, v204, v28, v148
	global_store_dword v246, v145, s[18:19] offset:0
	global_store_dword v246, v146, s[18:19] offset:64
	global_store_dword v246, v147, s[18:19] offset:128
	global_store_dword v246, v148, s[18:19] offset:192
	s_add_u32 s18, s18, 0x1000
	s_addc_u32 s19, s19, 0
	v_add_f32_e32 v17, v17, v205
	v_add_f32_e32 v21, v21, v206
	v_add_f32_e32 v25, v25, v207
	v_add_f32_e32 v29, v29, v208
	v_fma_f32 v149, v201, v17, v149
	v_fma_f32 v150, v202, v21, v150
	v_fma_f32 v151, v203, v25, v151
	v_fma_f32 v152, v204, v29, v152
	global_store_dword v246, v149, s[18:19] offset:0
	global_store_dword v246, v150, s[18:19] offset:64
	global_store_dword v246, v151, s[18:19] offset:128
	global_store_dword v246, v152, s[18:19] offset:192
	s_add_u32 s18, s18, 0x1000
	s_addc_u32 s19, s19, 0
	v_add_f32_e32 v18, v18, v205
	v_add_f32_e32 v22, v22, v206
	v_add_f32_e32 v26, v26, v207
	v_add_f32_e32 v30, v30, v208
	v_fma_f32 v153, v201, v18, v153
	v_fma_f32 v154, v202, v22, v154
	v_fma_f32 v155, v203, v26, v155
	v_fma_f32 v156, v204, v30, v156
	global_store_dword v246, v153, s[18:19] offset:0
	global_store_dword v246, v154, s[18:19] offset:64
	global_store_dword v246, v155, s[18:19] offset:128
	global_store_dword v246, v156, s[18:19] offset:192
	s_add_u32 s18, s18, 0x1000
	s_addc_u32 s19, s19, 0
	v_add_f32_e32 v19, v19, v205
	v_add_f32_e32 v23, v23, v206
	v_add_f32_e32 v27, v27, v207
	v_add_f32_e32 v31, v31, v208
	v_fma_f32 v157, v201, v19, v157
	v_fma_f32 v158, v202, v23, v158
	v_fma_f32 v159, v203, v27, v159
	v_fma_f32 v160, v204, v31, v160
	global_store_dword v246, v157, s[18:19] offset:0
	global_store_dword v246, v158, s[18:19] offset:64
	global_store_dword v246, v159, s[18:19] offset:128
	global_store_dword v246, v160, s[18:19] offset:192
	s_add_u32 s18, s18, 0xd000
	s_addc_u32 s19, s19, 0
	v_add_f32_e32 v32, v32, v205
	v_add_f32_e32 v36, v36, v206
	v_add_f32_e32 v40, v40, v207
	v_add_f32_e32 v44, v44, v208
	v_fma_f32 v161, v201, v32, v161
	v_fma_f32 v170, v202, v36, v170
	v_fma_f32 v171, v203, v40, v171
	v_fma_f32 v172, v204, v44, v172
	global_store_dword v246, v161, s[18:19] offset:0
	global_store_dword v246, v170, s[18:19] offset:64
	global_store_dword v246, v171, s[18:19] offset:128
	global_store_dword v246, v172, s[18:19] offset:192
	s_add_u32 s18, s18, 0x1000
	s_addc_u32 s19, s19, 0
	v_add_f32_e32 v33, v33, v205
	v_add_f32_e32 v37, v37, v206
	v_add_f32_e32 v41, v41, v207
	v_add_f32_e32 v45, v45, v208
	v_fma_f32 v173, v201, v33, v173
	v_fma_f32 v174, v202, v37, v174
	v_fma_f32 v175, v203, v41, v175
	v_fma_f32 v176, v204, v45, v176
	global_store_dword v246, v173, s[18:19] offset:0
	global_store_dword v246, v174, s[18:19] offset:64
	global_store_dword v246, v175, s[18:19] offset:128
	global_store_dword v246, v176, s[18:19] offset:192
	s_add_u32 s18, s18, 0x1000
	s_addc_u32 s19, s19, 0
	v_add_f32_e32 v34, v34, v205
	v_add_f32_e32 v38, v38, v206
	v_add_f32_e32 v42, v42, v207
	v_add_f32_e32 v46, v46, v208
	v_fma_f32 v177, v201, v34, v177
	v_fma_f32 v178, v202, v38, v178
	v_fma_f32 v179, v203, v42, v179
	v_fma_f32 v180, v204, v46, v180
	global_store_dword v246, v177, s[18:19] offset:0
	global_store_dword v246, v178, s[18:19] offset:64
	global_store_dword v246, v179, s[18:19] offset:128
	global_store_dword v246, v180, s[18:19] offset:192
	s_add_u32 s18, s18, 0x1000
	s_addc_u32 s19, s19, 0
	v_add_f32_e32 v35, v35, v205
	v_add_f32_e32 v39, v39, v206
	v_add_f32_e32 v43, v43, v207
	v_add_f32_e32 v47, v47, v208
	v_fma_f32 v181, v201, v35, v181
	v_fma_f32 v182, v202, v39, v182
	v_fma_f32 v183, v203, v43, v183
	v_fma_f32 v184, v204, v47, v184
	global_store_dword v246, v181, s[18:19] offset:0
	global_store_dword v246, v182, s[18:19] offset:64
	global_store_dword v246, v183, s[18:19] offset:128
	global_store_dword v246, v184, s[18:19] offset:192
	s_add_u32 s18, s18, 0xd000
	s_addc_u32 s19, s19, 0
	v_add_f32_e32 v48, v48, v205
	v_add_f32_e32 v52, v52, v206
	v_add_f32_e32 v56, v56, v207
	v_add_f32_e32 v60, v60, v208
	v_fma_f32 v185, v201, v48, v185
	v_fma_f32 v186, v202, v52, v186
	v_fma_f32 v187, v203, v56, v187
	v_fma_f32 v188, v204, v60, v188
	global_store_dword v246, v185, s[18:19] offset:0
	global_store_dword v246, v186, s[18:19] offset:64
	global_store_dword v246, v187, s[18:19] offset:128
	global_store_dword v246, v188, s[18:19] offset:192
	s_add_u32 s18, s18, 0x1000
	s_addc_u32 s19, s19, 0
	v_add_f32_e32 v49, v49, v205
	v_add_f32_e32 v53, v53, v206
	v_add_f32_e32 v57, v57, v207
	v_add_f32_e32 v61, v61, v208
	v_fma_f32 v189, v201, v49, v189
	v_fma_f32 v190, v202, v53, v190
	v_fma_f32 v191, v203, v57, v191
	v_fma_f32 v192, v204, v61, v192
	global_store_dword v246, v189, s[18:19] offset:0
	global_store_dword v246, v190, s[18:19] offset:64
	global_store_dword v246, v191, s[18:19] offset:128
	global_store_dword v246, v192, s[18:19] offset:192
	s_add_u32 s18, s18, 0x1000
	s_addc_u32 s19, s19, 0
	v_add_f32_e32 v50, v50, v205
	v_add_f32_e32 v54, v54, v206
	v_add_f32_e32 v58, v58, v207
	v_add_f32_e32 v62, v62, v208
	v_fma_f32 v193, v201, v50, v193
	v_fma_f32 v194, v202, v54, v194
	v_fma_f32 v195, v203, v58, v195
	v_fma_f32 v196, v204, v62, v196
	global_store_dword v246, v193, s[18:19] offset:0
	global_store_dword v246, v194, s[18:19] offset:64
	global_store_dword v246, v195, s[18:19] offset:128
	global_store_dword v246, v196, s[18:19] offset:192
	s_add_u32 s18, s18, 0x1000
	s_addc_u32 s19, s19, 0
	v_add_f32_e32 v51, v51, v205
	v_add_f32_e32 v55, v55, v206
	v_add_f32_e32 v59, v59, v207
	v_add_f32_e32 v63, v63, v208
	v_fma_f32 v197, v201, v51, v197
	v_fma_f32 v198, v202, v55, v198
	v_fma_f32 v199, v203, v59, v199
	v_fma_f32 v200, v204, v63, v200
	global_store_dword v246, v197, s[18:19] offset:0
	global_store_dword v246, v198, s[18:19] offset:64
	global_store_dword v246, v199, s[18:19] offset:128
	global_store_dword v246, v200, s[18:19] offset:192
	s_add_u32 s15, s15, s16
	s_branch .Lr13_tile
.Lr13_end:
.LBB0_1274:
	s_cmp_lt_i32 s61, 14
	s_cbranch_scc1 .LBB0_1328
	s_waitcnt vmcnt(0)
	s_waitcnt vmcnt(63) expcnt(7) lgkmcnt(15)
	s_barrier
	s_and_saveexec_b64 s[4:5], s[52:53]
	s_cbranch_execz .LBB0_1327
	v_mov_b32_e32 v0, 0x12000
	s_waitcnt vmcnt(0) expcnt(0) lgkmcnt(0)
	ds_read_b32 v2, v0
	v_mov_b32_e32 v0, 0x12004
	ds_read_b32 v0, v0
	s_waitcnt lgkmcnt(1)
	v_cmp_ne_u32_e32 vcc, 0, v2
	s_cbranch_vccnz .LBB0_1291
	s_load_dwordx2 s[2:3], s[0:1], 0xf0
	s_load_dword s9, s[0:1], 0xf8
	s_add_u32 s6, s56, 0x1457a300
	s_addc_u32 s7, s57, 0
	s_add_u32 s8, s56, 0x1457a500
	s_waitcnt lgkmcnt(0)
	s_mul_i32 s2, s3, s2
	s_mul_i32 s2, s2, s9
	s_addc_u32 s9, s57, 0
	s_add_u32 s10, s56, 0x1457a600
	s_addc_u32 s11, s57, 0
	s_add_u32 s12, s56, 0x1457a700
	s_addc_u32 s13, s57, 0
	s_add_u32 s14, s56, 0x1457a800
	s_addc_u32 s15, s57, 0
	s_add_u32 s16, s56, 0x1457a900
	s_addc_u32 s17, s57, 0
	s_add_u32 s18, s56, 0x1457aa00
	s_addc_u32 s19, s57, 0
	s_add_u32 s20, s56, 0x1457ab00
	s_addc_u32 s21, s57, 0
	s_add_u32 s22, s56, 0x1457ac00
	s_addc_u32 s23, s57, 0
	s_add_u32 s24, s56, 0x1457ad00
	s_addc_u32 s25, s57, 0
	s_add_u32 s26, s56, 0x1457ae00
	s_addc_u32 s27, s57, 0
	s_add_u32 s28, s56, 0x1457af00
	s_addc_u32 s29, s57, 0
	s_add_u32 s30, s56, 0x1457b000
	s_addc_u32 s31, s57, 0
	s_add_u32 s34, s56, 0x1457b100
	s_addc_u32 s35, s57, 0
	s_add_u32 s36, s56, 0x1457b200
	s_addc_u32 s37, s57, 0
	s_add_u32 s38, s56, 0x1457b300
	s_addc_u32 s39, s57, 0
	s_add_u32 s40, s56, 0x1457b400
	s_addc_u32 s41, s57, 0
	s_mov_b32 s3, 1
	v_mov_b32_e32 v16, 0
	s_branch .LBB0_1279

.LBB0_1450:
	s_cmp_gt_i32 s60, 16
	s_cselect_b64 s[2:3], -1, 0
	s_cmp_lt_i32 s61, 16
	s_cselect_b64 s[4:5], -1, 0
	s_or_b64 s[2:3], s[2:3], s[4:5]
	s_and_b64 vcc, exec, s[2:3]
	s_cbranch_vccnz .LBB0_1510
	s_load_dwordx2 s[4:5], s[0:1], 0xe0
	s_load_dword s16, s[0:1], 0xf0
	v_and_b32_e32 v240, 63, v162
	v_lshrrev_b32_e32 v247, 6, v162
	v_lshrrev_b32_e32 v242, 3, v240
	v_lshl_add_u32 v242, v247, 5, v242
	v_and_b32_e32 v243, 7, v240
	v_lshrrev_b32_e32 v244, 4, v240
	v_xor_b32_e32 v243, v243, v244
	v_lshlrev_b32_e32 v243, 4, v243
	v_mov_b32_e32 v241, 0x1600
	v_mad_u32_u24 v248, v242, v241, v243
	v_xor_b32_e32 v249, 64, v248
	v_add_u32_e32 v249, 0xb000, v249
	v_add_u32_e32 v250, 0x16000, v248
	v_xor_b32_e32 v251, 64, v248
	v_add_u32_e32 v251, 0x21000, v251
	v_and_b32_e32 v241, 15, v240
	v_lshrrev_b32_e32 v242, 1, v241
	v_xor_b32_e32 v242, v242, v244
	v_lshlrev_b32_e32 v242, 4, v242
	v_lshl_or_b32 v242, v241, 7, v242
	v_lshrrev_b32_e32 v243, 1, v247
	v_lshl_or_b32 v252, v243, 13, v242
	v_xor_b32_e32 v253, 64, v252
	v_and_b32_e32 v243, 1, v247
	v_lshl_or_b32 v254, v243, 13, v242
	v_xor_b32_e32 v255, 64, v254
	v_and_b32_e32 v240, 63, v162
	v_and_b32_e32 v241, 15, v240
	v_lshrrev_b32_e32 v242, 4, v240
	v_lshrrev_b32_e32 v243, 1, v247
	v_and_b32_e32 v244, 1, v247
	v_lshl_or_b32 v245, v244, 6, v241
	v_lshlrev_b32_e32 v243, 4, v243
	v_add_u32_e32 v243, v243, v242
	v_lshl_add_u32 v246, v243, 12, v245
	v_lshlrev_b32_e32 v246, 2, v246
	v_lshlrev_b32_e32 v245, 2, v245
	s_waitcnt lgkmcnt(0)
	s_add_u32 s26, s4, 0x9b7a100
	s_addc_u32 s27, s5, 0
	s_add_u32 s28, s4, 0x5600000
	s_addc_u32 s29, s5, 0
	s_mov_b32 s15, s58
.Lr16_tile:
	s_cmp_lt_u32 s15, 0x200
	s_cbranch_scc0 .Lr16_end
	s_and_b32 s2, s15, 63
	s_lshr_b32 s3, s15, 6
	s_mul_i32 s14, s2, 0xb0000
	s_add_u32 s8, s26, s14
	s_addc_u32 s9, s27, 0
	s_mul_i32 s14, s3, 0xb0000
	s_add_u32 s10, s28, s14
	s_addc_u32 s11, s29, 0
	s_lshl_b32 s14, s2, 19
	s_lshl_b32 s6, s3, 9
	s_add_u32 s14, s14, s6
	s_add_u32 s20, s4, 0x6b7a100
	s_addc_u32 s21, s5, 0
	s_add_u32 s20, s20, s14
	s_addc_u32 s21, s21, 0
	s_sub_u32 s7, s2, 32
	s_lshr_b32 s7, s7, 3
	s_add_u32 s7, s7, 1
	s_cmp_lt_u32 s2, 32
	s_cselect_b32 s7, 0, s7
	s_mul_i32 s7, s7, 0x6000
	s_add_u32 s7, s7, s6
	s_add_u32 s22, s4, 0x6b25000
	s_addc_u32 s23, s5, 0
	s_add_u32 s22, s22, s7
	s_addc_u32 s23, s23, 0
	v_readfirstlane_b32 s12, v247
	global_load_dword v201, v245, s[22:23] offset:0
	global_load_dword v202, v245, s[22:23] offset:64
	global_load_dword v203, v245, s[22:23] offset:128
	global_load_dword v204, v245, s[22:23] offset:192
	s_mov_b64 s[18:19], s[20:21]
	global_load_dword v129, v246, s[18:19] offset:0
	global_load_dword v130, v246, s[18:19] offset:64
	global_load_dword v131, v246, s[18:19] offset:128
	global_load_dword v132, v246, s[18:19] offset:192
	s_add_u32 s18, s18, 0x1000
	s_addc_u32 s19, s19, 0
	global_load_dword v133, v246, s[18:19] offset:0
	global_load_dword v134, v246, s[18:19] offset:64
	global_load_dword v135, v246, s[18:19] offset:128
	global_load_dword v136, v246, s[18:19] offset:192
	s_add_u32 s18, s18, 0x1000
	s_addc_u32 s19, s19, 0
	global_load_dword v137, v246, s[18:19] offset:0
	global_load_dword v138, v246, s[18:19] offset:64
	global_load_dword v139, v246, s[18:19] offset:128
	global_load_dword v140, v246, s[18:19] offset:192
	s_add_u32 s18, s18, 0x1000
	s_addc_u32 s19, s19, 0
	global_load_dword v141, v246, s[18:19] offset:0
	global_load_dword v142, v246, s[18:19] offset:64
	global_load_dword v143, v246, s[18:19] offset:128
	global_load_dword v144, v246, s[18:19] offset:192
	s_add_u32 s18, s18, 0xd000
	s_addc_u32 s19, s19, 0
	global_load_dword v145, v246, s[18:19] offset:0
	global_load_dword v146, v246, s[18:19] offset:64
	global_load_dword v147, v246, s[18:19] offset:128
	global_load_dword v148, v246, s[18:19] offset:192
	s_add_u32 s18, s18, 0x1000
	s_addc_u32 s19, s19, 0
	global_load_dword v149, v246, s[18:19] offset:0
	global_load_dword v150, v246, s[18:19] offset:64
	global_load_dword v151, v246, s[18:19] offset:128
	global_load_dword v152, v246, s[18:19] offset:192
	s_add_u32 s18, s18, 0x1000
	s_addc_u32 s19, s19, 0
	global_load_dword v153, v246, s[18:19] offset:0
	global_load_dword v154, v246, s[18:19] offset:64
	global_load_dword v155, v246, s[18:19] offset:128
	global_load_dword v156, v246, s[18:19] offset:192
	s_add_u32 s18, s18, 0x1000
	s_addc_u32 s19, s19, 0
	global_load_dword v157, v246, s[18:19] offset:0
	global_load_dword v158, v246, s[18:19] offset:64
	global_load_dword v159, v246, s[18:19] offset:128
	global_load_dword v160, v246, s[18:19] offset:192
	s_add_u32 s18, s18, 0xd000
	s_addc_u32 s19, s19, 0
	global_load_dword v161, v246, s[18:19] offset:0
	global_load_dword v170, v246, s[18:19] offset:64
	global_load_dword v171, v246, s[18:19] offset:128
	global_load_dword v172, v246, s[18:19] offset:192
	s_add_u32 s18, s18, 0x1000
	s_addc_u32 s19, s19, 0
	global_load_dword v173, v246, s[18:19] offset:0
	global_load_dword v174, v246, s[18:19] offset:64
	global_load_dword v175, v246, s[18:19] offset:128
	global_load_dword v176, v246, s[18:19] offset:192
	s_add_u32 s18, s18, 0x1000
	s_addc_u32 s19, s19, 0
	global_load_dword v177, v246, s[18:19] offset:0
	global_load_dword v178, v246, s[18:19] offset:64
	global_load_dword v179, v246, s[18:19] offset:128
	global_load_dword v180, v246, s[18:19] offset:192
	s_add_u32 s18, s18, 0x1000
	s_addc_u32 s19, s19, 0
	global_load_dword v181, v246, s[18:19] offset:0
	global_load_dword v182, v246, s[18:19] offset:64
	global_load_dword v183, v246, s[18:19] offset:128
	global_load_dword v184, v246, s[18:19] offset:192
	s_add_u32 s18, s18, 0xd000
	s_addc_u32 s19, s19, 0
	global_load_dword v185, v246, s[18:19] offset:0
	global_load_dword v186, v246, s[18:19] offset:64
	global_load_dword v187, v246, s[18:19] offset:128
	global_load_dword v188, v246, s[18:19] offset:192
	s_add_u32 s18, s18, 0x1000
	s_addc_u32 s19, s19, 0
	global_load_dword v189, v246, s[18:19] offset:0
	global_load_dword v190, v246, s[18:19] offset:64
	global_load_dword v191, v246, s[18:19] offset:128
	global_load_dword v192, v246, s[18:19] offset:192
	s_add_u32 s18, s18, 0x1000
	s_addc_u32 s19, s19, 0
	global_load_dword v193, v246, s[18:19] offset:0
	global_load_dword v194, v246, s[18:19] offset:64
	global_load_dword v195, v246, s[18:19] offset:128
	global_load_dword v196, v246, s[18:19] offset:192
	s_add_u32 s18, s18, 0x1000
	s_addc_u32 s19, s19, 0
	global_load_dword v197, v246, s[18:19] offset:0
	global_load_dword v198, v246, s[18:19] offset:64
	global_load_dword v199, v246, s[18:19] offset:128
	global_load_dword v200, v246, s[18:19] offset:192
	s_lshl_b32 s12, s12, 12
	s_add_u32 m0, s12, 0x0
	v_mov_b32_e32 v0, 0
	global_load_lds_dwordx4 v248, s[8:9]
	v_mov_b32_e32 v1, 0
	s_add_u32 m0, s12, 0x400
	v_mov_b32_e32 v2, 0
	global_load_lds_dwordx4 v249, s[8:9]
	v_mov_b32_e32 v3, 0
	s_add_u32 m0, s12, 0x800
	v_mov_b32_e32 v4, 0
	global_load_lds_dwordx4 v250, s[8:9]
	v_mov_b32_e32 v5, 0
	s_add_u32 m0, s12, 0xc00
	v_mov_b32_e32 v6, 0
	global_load_lds_dwordx4 v251, s[8:9]
	v_mov_b32_e32 v7, 0
	s_add_u32 m0, s12, 0x8000
	v_mov_b32_e32 v8, 0
	global_load_lds_dwordx4 v248, s[10:11]
	v_mov_b32_e32 v9, 0
	s_add_u32 m0, s12, 0x8400
	v_mov_b32_e32 v10, 0
	global_load_lds_dwordx4 v249, s[10:11]
	v_mov_b32_e32 v11, 0
	s_add_u32 m0, s12, 0x8800
	v_mov_b32_e32 v12, 0
	global_load_lds_dwordx4 v250, s[10:11]
	v_mov_b32_e32 v13, 0
	s_add_u32 m0, s12, 0x8c00
	v_mov_b32_e32 v14, 0
	global_load_lds_dwordx4 v251, s[10:11]
	v_mov_b32_e32 v15, 0
	s_add_u32 s8, s8, 0x80
	s_addc_u32 s9, s9, 0
	s_add_u32 s10, s10, 0x80
	s_addc_u32 s11, s11, 0
	s_add_u32 m0, s12, 0x4000
	v_mov_b32_e32 v16, 0
	global_load_lds_dwordx4 v248, s[8:9]
	v_mov_b32_e32 v17, 0
	s_add_u32 m0, s12, 0x4400
	v_mov_b32_e32 v18, 0
	global_load_lds_dwordx4 v249, s[8:9]
	v_mov_b32_e32 v19, 0
	s_add_u32 m0, s12, 0x4800
	v_mov_b32_e32 v20, 0
	global_load_lds_dwordx4 v250, s[8:9]
	v_mov_b32_e32 v21, 0
	s_add_u32 m0, s12, 0x4c00
	v_mov_b32_e32 v22, 0
	global_load_lds_dwordx4 v251, s[8:9]
	v_mov_b32_e32 v23, 0
	s_add_u32 m0, s12, 0xc000
	v_mov_b32_e32 v24, 0
	global_load_lds_dwordx4 v248, s[10:11]
	v_mov_b32_e32 v25, 0
	s_add_u32 m0, s12, 0xc400
	v_mov_b32_e32 v26, 0
	global_load_lds_dwordx4 v249, s[10:11]
	v_mov_b32_e32 v27, 0
	s_add_u32 m0, s12, 0xc800
	v_mov_b32_e32 v28, 0
	global_load_lds_dwordx4 v250, s[10:11]
	v_mov_b32_e32 v29, 0
	s_add_u32 m0, s12, 0xcc00
	v_mov_b32_e32 v30, 0
	global_load_lds_dwordx4 v251, s[10:11]
	v_mov_b32_e32 v31, 0
	s_add_u32 s8, s8, 0x80
	s_addc_u32 s9, s9, 0
	s_add_u32 s10, s10, 0x80
	s_addc_u32 s11, s11, 0
	v_mov_b32_e32 v32, 0
	v_mov_b32_e32 v33, 0
	v_mov_b32_e32 v34, 0
	v_mov_b32_e32 v35, 0
	v_mov_b32_e32 v36, 0
	v_mov_b32_e32 v37, 0
	v_mov_b32_e32 v38, 0
	v_mov_b32_e32 v39, 0
	v_mov_b32_e32 v40, 0
	v_mov_b32_e32 v41, 0
	v_mov_b32_e32 v42, 0
	v_mov_b32_e32 v43, 0
	v_mov_b32_e32 v44, 0
	v_mov_b32_e32 v45, 0
	v_mov_b32_e32 v46, 0
	v_mov_b32_e32 v47, 0
	v_mov_b32_e32 v48, 0
	v_mov_b32_e32 v49, 0
	v_mov_b32_e32 v50, 0
	v_mov_b32_e32 v51, 0
	v_mov_b32_e32 v52, 0
	v_mov_b32_e32 v53, 0
	v_mov_b32_e32 v54, 0
	v_mov_b32_e32 v55, 0
	v_mov_b32_e32 v56, 0
	v_mov_b32_e32 v57, 0
	v_mov_b32_e32 v58, 0
	v_mov_b32_e32 v59, 0
	v_mov_b32_e32 v60, 0
	v_mov_b32_e32 v61, 0
	v_mov_b32_e32 v62, 0
	v_mov_b32_e32 v63, 0
	s_waitcnt vmcnt(8)
	s_barrier
	ds_read_b128 v[64:67], v252 offset:0
	ds_read_b128 v[96:99], v254 offset:32768
	ds_read_b128 v[100:103], v254 offset:34816
	ds_read_b128 v[104:107], v254 offset:36864
	ds_read_b128 v[108:111], v254 offset:38912
	ds_read_b128 v[68:71], v252 offset:2048
	ds_read_b128 v[72:75], v252 offset:4096
	ds_read_b128 v[76:79], v252 offset:6144
	ds_read_b128 v[80:83], v253 offset:0
	ds_read_b128 v[112:115], v255 offset:32768
	ds_read_b128 v[116:119], v255 offset:34816
	ds_read_b128 v[120:123], v255 offset:36864
	ds_read_b128 v[124:127], v255 offset:38912
	s_waitcnt lgkmcnt(11)
	v_mfma_f32_16x16x32_bf16 v[0:3], v[64:67], v[96:99], v[0:3]
	s_waitcnt lgkmcnt(10)
	v_mfma_f32_16x16x32_bf16 v[4:7], v[64:67], v[100:103], v[4:7]
	s_waitcnt lgkmcnt(9)
	v_mfma_f32_16x16x32_bf16 v[8:11], v[64:67], v[104:107], v[8:11]
	s_waitcnt lgkmcnt(8)
	v_mfma_f32_16x16x32_bf16 v[12:15], v[64:67], v[108:111], v[12:15]
	ds_read_b128 v[84:87], v253 offset:2048
	ds_read_b128 v[88:91], v253 offset:4096
	ds_read_b128 v[92:95], v253 offset:6144
	s_waitcnt lgkmcnt(10)
	v_mfma_f32_16x16x32_bf16 v[16:19], v[68:71], v[96:99], v[16:19]
	v_mfma_f32_16x16x32_bf16 v[20:23], v[68:71], v[100:103], v[20:23]
	v_mfma_f32_16x16x32_bf16 v[24:27], v[68:71], v[104:107], v[24:27]
	v_mfma_f32_16x16x32_bf16 v[28:31], v[68:71], v[108:111], v[28:31]
	s_waitcnt lgkmcnt(0)
	s_barrier
	s_add_u32 m0, s12, 0x0
	v_mfma_f32_16x16x32_bf16 v[32:35], v[72:75], v[96:99], v[32:35]
	global_load_lds_dwordx4 v248, s[8:9]
	s_add_u32 m0, s12, 0x400
	v_mfma_f32_16x16x32_bf16 v[36:39], v[72:75], v[100:103], v[36:39]
	global_load_lds_dwordx4 v249, s[8:9]
	s_add_u32 m0, s12, 0x800
	v_mfma_f32_16x16x32_bf16 v[40:43], v[72:75], v[104:107], v[40:43]
	global_load_lds_dwordx4 v250, s[8:9]
	s_add_u32 m0, s12, 0xc00
	v_mfma_f32_16x16x32_bf16 v[44:47], v[72:75], v[108:111], v[44:47]
	global_load_lds_dwordx4 v251, s[8:9]
	s_add_u32 m0, s12, 0x8000
	v_mfma_f32_16x16x32_bf16 v[48:51], v[76:79], v[96:99], v[48:51]
	global_load_lds_dwordx4 v248, s[10:11]
	s_add_u32 m0, s12, 0x8400
	v_mfma_f32_16x16x32_bf16 v[52:55], v[76:79], v[100:103], v[52:55]
	global_load_lds_dwordx4 v249, s[10:11]
	s_add_u32 m0, s12, 0x8800
	v_mfma_f32_16x16x32_bf16 v[56:59], v[76:79], v[104:107], v[56:59]
	global_load_lds_dwordx4 v250, s[10:11]
	s_add_u32 m0, s12, 0x8c00
	v_mfma_f32_16x16x32_bf16 v[60:63], v[76:79], v[108:111], v[60:63]
	global_load_lds_dwordx4 v251, s[10:11]
	s_add_u32 s8, s8, 0x80
	s_addc_u32 s9, s9, 0
	s_add_u32 s10, s10, 0x80
	s_addc_u32 s11, s11, 0
	s_waitcnt vmcnt(8)
	s_barrier
	ds_read_b128 v[64:67], v252 offset:16384
	ds_read_b128 v[96:99], v254 offset:49152
	ds_read_b128 v[100:103], v254 offset:51200
	ds_read_b128 v[104:107], v254 offset:53248
	ds_read_b128 v[108:111], v254 offset:55296
	ds_read_b128 v[68:71], v252 offset:18432
	ds_read_b128 v[72:75], v252 offset:20480
	ds_read_b128 v[76:79], v252 offset:22528
	v_mfma_f32_16x16x32_bf16 v[0:3], v[80:83], v[112:115], v[0:3]
	v_mfma_f32_16x16x32_bf16 v[4:7], v[80:83], v[116:119], v[4:7]
	v_mfma_f32_16x16x32_bf16 v[8:11], v[80:83], v[120:123], v[8:11]
	v_mfma_f32_16x16x32_bf16 v[12:15], v[80:83], v[124:127], v[12:15]
	v_mfma_f32_16x16x32_bf16 v[16:19], v[84:87], v[112:115], v[16:19]
	v_mfma_f32_16x16x32_bf16 v[20:23], v[84:87], v[116:119], v[20:23]
	v_mfma_f32_16x16x32_bf16 v[24:27], v[84:87], v[120:123], v[24:27]
	v_mfma_f32_16x16x32_bf16 v[28:31], v[84:87], v[124:127], v[28:31]
	v_mfma_f32_16x16x32_bf16 v[32:35], v[88:91], v[112:115], v[32:35]
	v_mfma_f32_16x16x32_bf16 v[36:39], v[88:91], v[116:119], v[36:39]
	v_mfma_f32_16x16x32_bf16 v[40:43], v[88:91], v[120:123], v[40:43]
	v_mfma_f32_16x16x32_bf16 v[44:47], v[88:91], v[124:127], v[44:47]
	v_mfma_f32_16x16x32_bf16 v[48:51], v[92:95], v[112:115], v[48:51]
	v_mfma_f32_16x16x32_bf16 v[52:55], v[92:95], v[116:119], v[52:55]
	v_mfma_f32_16x16x32_bf16 v[56:59], v[92:95], v[120:123], v[56:59]
	v_mfma_f32_16x16x32_bf16 v[60:63], v[92:95], v[124:127], v[60:63]
	ds_read_b128 v[80:83], v253 offset:16384
	ds_read_b128 v[112:115], v255 offset:49152
	ds_read_b128 v[116:119], v255 offset:51200
	ds_read_b128 v[120:123], v255 offset:53248
	ds_read_b128 v[124:127], v255 offset:55296
	ds_read_b128 v[84:87], v253 offset:18432
	ds_read_b128 v[88:91], v253 offset:20480
	ds_read_b128 v[92:95], v253 offset:22528
	s_waitcnt lgkmcnt(14)
	v_mfma_f32_16x16x32_bf16 v[0:3], v[64:67], v[96:99], v[0:3]
	s_waitcnt lgkmcnt(13)
	v_mfma_f32_16x16x32_bf16 v[4:7], v[64:67], v[100:103], v[4:7]
	s_waitcnt lgkmcnt(12)
	v_mfma_f32_16x16x32_bf16 v[8:11], v[64:67], v[104:107], v[8:11]
	s_waitcnt lgkmcnt(11)
	v_mfma_f32_16x16x32_bf16 v[12:15], v[64:67], v[108:111], v[12:15]
	s_waitcnt lgkmcnt(10)
	v_mfma_f32_16x16x32_bf16 v[16:19], v[68:71], v[96:99], v[16:19]
	v_mfma_f32_16x16x32_bf16 v[20:23], v[68:71], v[100:103], v[20:23]
	v_mfma_f32_16x16x32_bf16 v[24:27], v[68:71], v[104:107], v[24:27]
	v_mfma_f32_16x16x32_bf16 v[28:31], v[68:71], v[108:111], v[28:31]
	s_waitcnt lgkmcnt(0)
	s_barrier
	s_add_u32 m0, s12, 0x4000
	v_mfma_f32_16x16x32_bf16 v[32:35], v[72:75], v[96:99], v[32:35]
	global_load_lds_dwordx4 v248, s[8:9]
	s_add_u32 m0, s12, 0x4400
	v_mfma_f32_16x16x32_bf16 v[36:39], v[72:75], v[100:103], v[36:39]
	global_load_lds_dwordx4 v249, s[8:9]
	s_add_u32 m0, s12, 0x4800
	v_mfma_f32_16x16x32_bf16 v[40:43], v[72:75], v[104:107], v[40:43]
	global_load_lds_dwordx4 v250, s[8:9]
	s_add_u32 m0, s12, 0x4c00
	v_mfma_f32_16x16x32_bf16 v[44:47], v[72:75], v[108:111], v[44:47]
	global_load_lds_dwordx4 v251, s[8:9]
	s_add_u32 m0, s12, 0xc000
	v_mfma_f32_16x16x32_bf16 v[48:51], v[76:79], v[96:99], v[48:51]
	global_load_lds_dwordx4 v248, s[10:11]
	s_add_u32 m0, s12, 0xc400
	v_mfma_f32_16x16x32_bf16 v[52:55], v[76:79], v[100:103], v[52:55]
	global_load_lds_dwordx4 v249, s[10:11]
	s_add_u32 m0, s12, 0xc800
	v_mfma_f32_16x16x32_bf16 v[56:59], v[76:79], v[104:107], v[56:59]
	global_load_lds_dwordx4 v250, s[10:11]
	s_add_u32 m0, s12, 0xcc00
	v_mfma_f32_16x16x32_bf16 v[60:63], v[76:79], v[108:111], v[60:63]
	global_load_lds_dwordx4 v251, s[10:11]
	s_add_u32 s8, s8, 0x80
	s_addc_u32 s9, s9, 0
	s_add_u32 s10, s10, 0x80
	s_addc_u32 s11, s11, 0
	s_mov_b32 s13, 20

.Lr16_end:
.LBB0_1456:
	s_cmp_lt_i32 s61, 17
	s_cbranch_scc1 .LBB0_1510
	s_waitcnt vmcnt(0)
	s_waitcnt vmcnt(63) expcnt(7) lgkmcnt(15)
	s_barrier
	s_and_saveexec_b64 s[4:5], s[52:53]
	s_cbranch_execz .LBB0_1509
	v_mov_b32_e32 v0, 0x12000
	s_waitcnt vmcnt(0) expcnt(0) lgkmcnt(0)
	ds_read_b32 v2, v0
	v_mov_b32_e32 v0, 0x12004
	ds_read_b32 v0, v0
	s_waitcnt lgkmcnt(1)
	v_cmp_ne_u32_e32 vcc, 0, v2
	s_cbranch_vccnz .LBB0_1473
	s_load_dwordx2 s[2:3], s[0:1], 0xf0
	s_load_dword s9, s[0:1], 0xf8
	s_add_u32 s6, s56, 0x1457a300
	s_addc_u32 s7, s57, 0
	s_add_u32 s8, s56, 0x1457a500
	s_waitcnt lgkmcnt(0)
	s_mul_i32 s2, s3, s2
	s_mul_i32 s2, s2, s9
	s_addc_u32 s9, s57, 0
	s_add_u32 s10, s56, 0x1457a600
	s_addc_u32 s11, s57, 0
	s_add_u32 s12, s56, 0x1457a700
	s_addc_u32 s13, s57, 0
	s_add_u32 s14, s56, 0x1457a800
	s_addc_u32 s15, s57, 0
	s_add_u32 s16, s56, 0x1457a900
	s_addc_u32 s17, s57, 0
	s_add_u32 s18, s56, 0x1457aa00
	s_addc_u32 s19, s57, 0
	s_add_u32 s20, s56, 0x1457ab00
	s_addc_u32 s21, s57, 0
	s_add_u32 s22, s56, 0x1457ac00
	s_addc_u32 s23, s57, 0
	s_add_u32 s24, s56, 0x1457ad00
	s_addc_u32 s25, s57, 0
	s_add_u32 s26, s56, 0x1457ae00
	s_addc_u32 s27, s57, 0
	s_add_u32 s28, s56, 0x1457af00
	s_addc_u32 s29, s57, 0
	s_add_u32 s30, s56, 0x1457b000
	s_addc_u32 s31, s57, 0
	s_add_u32 s34, s56, 0x1457b100
	s_addc_u32 s35, s57, 0
	s_add_u32 s36, s56, 0x1457b200
	s_addc_u32 s37, s57, 0
	s_add_u32 s38, s56, 0x1457b300
	s_addc_u32 s39, s57, 0
	s_add_u32 s40, s56, 0x1457b400
	s_addc_u32 s41, s57, 0
	s_mov_b32 s3, 1
	v_mov_b32_e32 v16, 0
	s_branch .LBB0_1461

.Lcv19_rb:
	s_cmp_lt_u32 s3, 0x200
	s_cbranch_scc0 .Lcv19_end
	s_lshl_b32 s32, s3, 4
	s_cmp_lt_u32 s32, 0x1000
	s_mov_b32 s59, 0x3ff
	s_cselect_b32 s59, 0xff, s59
	s_and_b32 s65, s32, s59
	s_cmp_lg_u32 s65, 0
	s_cselect_b32 s62, -1, 0
	s_add_u32 s65, s65, 15
	s_cmp_lg_u32 s65, s59
	s_cselect_b32 s63, -1, 0
	s_lshl_b32 s65, s32, 12
	s_add_u32 s4, s10, 0xab7a100
	s_addc_u32 s5, s11, 0
	s_add_u32 s4, s4, s65
	s_addc_u32 s5, s5, 0
	s_sub_u32 s4, s4, 0x2000
	s_subb_u32 s5, s5, 0
	s_add_u32 s54, s10, 0x1037a100
	s_addc_u32 s55, s11, 0
	s_add_u32 s54, s54, s65
	s_addc_u32 s55, s55, 0
	global_load_dwordx4 v[76:79], v25, s[4:5]
	s_add_u32 s4, s4, 0x1000
	s_addc_u32 s5, s5, 0
	global_load_dwordx4 v[80:83], v25, s[4:5]
	s_add_u32 s4, s4, 0x1000
	s_addc_u32 s5, s5, 0
	global_load_dwordx4 v[84:87], v25, s[4:5]
	s_add_u32 s4, s4, 0x1000
	s_addc_u32 s5, s5, 0
	global_load_dwordx4 v[88:91], v25, s[4:5]
	s_add_u32 s4, s4, 0x1000
	s_addc_u32 s5, s5, 0
	global_load_dwordx4 v[92:95], v25, s[4:5]
	s_add_u32 s4, s4, 0x1000
	s_addc_u32 s5, s5, 0
	global_load_dwordx4 v[96:99], v25, s[4:5]
	s_add_u32 s4, s4, 0x1000
	s_addc_u32 s5, s5, 0
	global_load_dwordx4 v[100:103], v25, s[4:5]
	s_add_u32 s4, s4, 0x1000
	s_addc_u32 s5, s5, 0
	global_load_dwordx4 v[104:107], v25, s[4:5]
	s_add_u32 s4, s4, 0x1000
	s_addc_u32 s5, s5, 0
	global_load_dwordx4 v[108:111], v25, s[4:5]
	s_add_u32 s4, s4, 0x1000
	s_addc_u32 s5, s5, 0
	global_load_dwordx4 v[112:115], v25, s[4:5]
	s_add_u32 s4, s4, 0x1000
	s_addc_u32 s5, s5, 0
	global_load_dwordx4 v[116:119], v25, s[4:5]
	s_add_u32 s4, s4, 0x1000
	s_addc_u32 s5, s5, 0
	global_load_dwordx4 v[120:123], v25, s[4:5]
	s_add_u32 s4, s4, 0x1000
	s_addc_u32 s5, s5, 0
	global_load_dwordx4 v[124:127], v25, s[4:5]
	s_add_u32 s4, s4, 0x1000
	s_addc_u32 s5, s5, 0
	global_load_dwordx4 v[132:135], v25, s[4:5]
	s_add_u32 s4, s4, 0x1000
	s_addc_u32 s5, s5, 0
	global_load_dwordx4 v[136:139], v25, s[4:5]
	s_add_u32 s4, s4, 0x1000
	s_addc_u32 s5, s5, 0
	global_load_dwordx4 v[140:143], v25, s[4:5]
	s_add_u32 s4, s4, 0x1000
	s_addc_u32 s5, s5, 0
	global_load_dwordx4 v[144:147], v25, s[4:5]
	s_add_u32 s4, s4, 0x1000
	s_addc_u32 s5, s5, 0
	global_load_dwordx4 v[148:151], v25, s[4:5]
	s_add_u32 s4, s4, 0x1000
	s_addc_u32 s5, s5, 0
	global_load_dwordx4 v[152:155], v25, s[4:5]
	s_add_u32 s4, s4, 0x1000
	s_addc_u32 s5, s5, 0
	global_load_dwordx4 v[156:159], v25, s[4:5]
	s_waitcnt vmcnt(19)
	v_and_b32_e32 v76, s62, v76
	v_and_b32_e32 v77, s62, v77
	v_and_b32_e32 v78, s62, v78
	v_and_b32_e32 v79, s62, v79
	v_lshlrev_b32_e32 v172, 16, v76
	v_and_b32_e32 v173, 0xffff0000, v76
	v_lshlrev_b32_e32 v174, 16, v77
	v_and_b32_e32 v175, 0xffff0000, v77
	v_lshlrev_b32_e32 v176, 16, v78
	v_and_b32_e32 v177, 0xffff0000, v78
	v_lshlrev_b32_e32 v178, 16, v79
	v_and_b32_e32 v179, 0xffff0000, v79
	v_pk_fma_f32 v[180:181], v[28:29], v[172:173], v[68:69]
	v_pk_fma_f32 v[182:183], v[30:31], v[174:175], v[70:71]
	v_pk_fma_f32 v[184:185], v[32:33], v[176:177], v[72:73]
	v_pk_fma_f32 v[186:187], v[34:35], v[178:179], v[74:75]
	s_waitcnt vmcnt(18)
	v_and_b32_e32 v80, s62, v80
	v_and_b32_e32 v81, s62, v81
	v_and_b32_e32 v82, s62, v82
	v_and_b32_e32 v83, s62, v83
	v_lshlrev_b32_e32 v172, 16, v80
	v_and_b32_e32 v173, 0xffff0000, v80
	v_lshlrev_b32_e32 v174, 16, v81
	v_and_b32_e32 v175, 0xffff0000, v81
	v_lshlrev_b32_e32 v176, 16, v82
	v_and_b32_e32 v177, 0xffff0000, v82
	v_lshlrev_b32_e32 v178, 16, v83
	v_and_b32_e32 v179, 0xffff0000, v83
	v_pk_fma_f32 v[188:189], v[28:29], v[172:173], v[68:69]
	v_pk_fma_f32 v[190:191], v[30:31], v[174:175], v[70:71]
	v_pk_fma_f32 v[192:193], v[32:33], v[176:177], v[72:73]
	v_pk_fma_f32 v[194:195], v[34:35], v[178:179], v[74:75]
	v_pk_fma_f32 v[180:181], v[36:37], v[172:173], v[180:181]
	v_pk_fma_f32 v[182:183], v[38:39], v[174:175], v[182:183]
	v_pk_fma_f32 v[184:185], v[40:41], v[176:177], v[184:185]
	v_pk_fma_f32 v[186:187], v[42:43], v[178:179], v[186:187]
	s_waitcnt vmcnt(17)
	v_lshlrev_b32_e32 v172, 16, v84
	v_and_b32_e32 v173, 0xffff0000, v84
	v_lshlrev_b32_e32 v174, 16, v85
	v_and_b32_e32 v175, 0xffff0000, v85
	v_lshlrev_b32_e32 v176, 16, v86
	v_and_b32_e32 v177, 0xffff0000, v86
	v_lshlrev_b32_e32 v178, 16, v87
	v_and_b32_e32 v179, 0xffff0000, v87
	v_pk_fma_f32 v[196:197], v[28:29], v[172:173], v[68:69]
	v_pk_fma_f32 v[198:199], v[30:31], v[174:175], v[70:71]
	v_pk_fma_f32 v[200:201], v[32:33], v[176:177], v[72:73]
	v_pk_fma_f32 v[202:203], v[34:35], v[178:179], v[74:75]
	v_pk_fma_f32 v[188:189], v[36:37], v[172:173], v[188:189]
	v_pk_fma_f32 v[190:191], v[38:39], v[174:175], v[190:191]
	v_pk_fma_f32 v[192:193], v[40:41], v[176:177], v[192:193]
	v_pk_fma_f32 v[194:195], v[42:43], v[178:179], v[194:195]
	v_pk_fma_f32 v[180:181], v[44:45], v[172:173], v[180:181]
	v_pk_fma_f32 v[182:183], v[46:47], v[174:175], v[182:183]
	v_pk_fma_f32 v[184:185], v[48:49], v[176:177], v[184:185]
	v_pk_fma_f32 v[186:187], v[50:51], v[178:179], v[186:187]
	s_waitcnt vmcnt(16)
	v_lshlrev_b32_e32 v172, 16, v88
	v_and_b32_e32 v173, 0xffff0000, v88
	v_lshlrev_b32_e32 v174, 16, v89
	v_and_b32_e32 v175, 0xffff0000, v89
	v_lshlrev_b32_e32 v176, 16, v90
	v_and_b32_e32 v177, 0xffff0000, v90
	v_lshlrev_b32_e32 v178, 16, v91
	v_and_b32_e32 v179, 0xffff0000, v91
	v_pk_fma_f32 v[204:205], v[28:29], v[172:173], v[68:69]
	v_pk_fma_f32 v[206:207], v[30:31], v[174:175], v[70:71]
	v_pk_fma_f32 v[208:209], v[32:33], v[176:177], v[72:73]
	v_pk_fma_f32 v[210:211], v[34:35], v[178:179], v[74:75]
	v_pk_fma_f32 v[196:197], v[36:37], v[172:173], v[196:197]
	v_pk_fma_f32 v[198:199], v[38:39], v[174:175], v[198:199]
	v_pk_fma_f32 v[200:201], v[40:41], v[176:177], v[200:201]
	v_pk_fma_f32 v[202:203], v[42:43], v[178:179], v[202:203]
	v_pk_fma_f32 v[188:189], v[44:45], v[172:173], v[188:189]
	v_pk_fma_f32 v[190:191], v[46:47], v[174:175], v[190:191]
	v_pk_fma_f32 v[192:193], v[48:49], v[176:177], v[192:193]
	v_pk_fma_f32 v[194:195], v[50:51], v[178:179], v[194:195]
	v_pk_fma_f32 v[180:181], v[52:53], v[172:173], v[180:181]
	v_pk_fma_f32 v[182:183], v[54:55], v[174:175], v[182:183]
	v_pk_fma_f32 v[184:185], v[56:57], v[176:177], v[184:185]
	v_pk_fma_f32 v[186:187], v[58:59], v[178:179], v[186:187]
	s_waitcnt vmcnt(15)
	v_lshlrev_b32_e32 v172, 16, v92
	v_and_b32_e32 v173, 0xffff0000, v92
	v_lshlrev_b32_e32 v174, 16, v93
	v_and_b32_e32 v175, 0xffff0000, v93
	v_lshlrev_b32_e32 v176, 16, v94
	v_and_b32_e32 v177, 0xffff0000, v94
	v_lshlrev_b32_e32 v178, 16, v95
	v_and_b32_e32 v179, 0xffff0000, v95
	v_pk_fma_f32 v[212:213], v[28:29], v[172:173], v[68:69]
	v_pk_fma_f32 v[214:215], v[30:31], v[174:175], v[70:71]
	v_pk_fma_f32 v[216:217], v[32:33], v[176:177], v[72:73]
	v_pk_fma_f32 v[218:219], v[34:35], v[178:179], v[74:75]
	v_pk_fma_f32 v[204:205], v[36:37], v[172:173], v[204:205]
	v_pk_fma_f32 v[206:207], v[38:39], v[174:175], v[206:207]
	v_pk_fma_f32 v[208:209], v[40:41], v[176:177], v[208:209]
	v_pk_fma_f32 v[210:211], v[42:43], v[178:179], v[210:211]
	v_pk_fma_f32 v[196:197], v[44:45], v[172:173], v[196:197]
	v_pk_fma_f32 v[198:199], v[46:47], v[174:175], v[198:199]
	v_pk_fma_f32 v[200:201], v[48:49], v[176:177], v[200:201]
	v_pk_fma_f32 v[202:203], v[50:51], v[178:179], v[202:203]
	v_pk_fma_f32 v[188:189], v[52:53], v[172:173], v[188:189]
	v_pk_fma_f32 v[190:191], v[54:55], v[174:175], v[190:191]
	v_pk_fma_f32 v[192:193], v[56:57], v[176:177], v[192:193]
	v_pk_fma_f32 v[194:195], v[58:59], v[178:179], v[194:195]
	v_pk_fma_f32 v[180:181], v[60:61], v[172:173], v[180:181]
	v_pk_fma_f32 v[182:183], v[62:63], v[174:175], v[182:183]
	v_pk_fma_f32 v[184:185], v[64:65], v[176:177], v[184:185]
	v_pk_fma_f32 v[186:187], v[66:67], v[178:179], v[186:187]
	v_mul_f32_e32 v220, 0xbfb8aa3b, v180
	v_mul_f32_e32 v221, 0xbfb8aa3b, v181
	v_mul_f32_e32 v222, 0xbfb8aa3b, v182
	v_mul_f32_e32 v223, 0xbfb8aa3b, v183
	v_mul_f32_e32 v224, 0xbfb8aa3b, v184
	v_mul_f32_e32 v225, 0xbfb8aa3b, v185
	v_mul_f32_e32 v226, 0xbfb8aa3b, v186
	v_mul_f32_e32 v227, 0xbfb8aa3b, v187
	v_exp_f32_e32 v220, v220
	v_exp_f32_e32 v221, v221
	v_exp_f32_e32 v222, v222
	v_exp_f32_e32 v223, v223
	v_exp_f32_e32 v224, v224
	v_exp_f32_e32 v225, v225
	v_exp_f32_e32 v226, v226
	v_exp_f32_e32 v227, v227
	v_add_f32_e32 v220, 1.0, v220
	v_add_f32_e32 v221, 1.0, v221
	v_add_f32_e32 v222, 1.0, v222
	v_add_f32_e32 v223, 1.0, v223
	v_add_f32_e32 v224, 1.0, v224
	v_add_f32_e32 v225, 1.0, v225
	v_add_f32_e32 v226, 1.0, v226
	v_add_f32_e32 v227, 1.0, v227
	v_rcp_f32_e32 v220, v220
	v_rcp_f32_e32 v221, v221
	v_rcp_f32_e32 v222, v222
	v_rcp_f32_e32 v223, v223
	v_rcp_f32_e32 v224, v224
	v_rcp_f32_e32 v225, v225
	v_rcp_f32_e32 v226, v226
	v_rcp_f32_e32 v227, v227
	v_mul_f32_e32 v220, v180, v220
	v_mul_f32_e32 v221, v181, v221
	v_mul_f32_e32 v222, v182, v222
	v_mul_f32_e32 v223, v183, v223
	v_mul_f32_e32 v224, v184, v224
	v_mul_f32_e32 v225, v185, v225
	v_mul_f32_e32 v226, v186, v226
	v_mul_f32_e32 v227, v187, v227
	v_cvt_pk_bf16_f32 v180, v220, v221
	v_cvt_pk_bf16_f32 v181, v222, v223
	v_cvt_pk_bf16_f32 v182, v224, v225
	v_cvt_pk_bf16_f32 v183, v226, v227
	global_store_dwordx4 v25, v[180:183], s[54:55] sc1
	s_add_u32 s54, s54, 0x1000
	s_addc_u32 s55, s55, 0
	s_waitcnt vmcnt(15)
	v_lshlrev_b32_e32 v172, 16, v96
	v_and_b32_e32 v173, 0xffff0000, v96
	v_lshlrev_b32_e32 v174, 16, v97
	v_and_b32_e32 v175, 0xffff0000, v97
	v_lshlrev_b32_e32 v176, 16, v98
	v_and_b32_e32 v177, 0xffff0000, v98
	v_lshlrev_b32_e32 v178, 16, v99
	v_and_b32_e32 v179, 0xffff0000, v99
	v_pk_fma_f32 v[180:181], v[28:29], v[172:173], v[68:69]
	v_pk_fma_f32 v[182:183], v[30:31], v[174:175], v[70:71]
	v_pk_fma_f32 v[184:185], v[32:33], v[176:177], v[72:73]
	v_pk_fma_f32 v[186:187], v[34:35], v[178:179], v[74:75]
	v_pk_fma_f32 v[212:213], v[36:37], v[172:173], v[212:213]
	v_pk_fma_f32 v[214:215], v[38:39], v[174:175], v[214:215]
	v_pk_fma_f32 v[216:217], v[40:41], v[176:177], v[216:217]
	v_pk_fma_f32 v[218:219], v[42:43], v[178:179], v[218:219]
	v_pk_fma_f32 v[204:205], v[44:45], v[172:173], v[204:205]
	v_pk_fma_f32 v[206:207], v[46:47], v[174:175], v[206:207]
	v_pk_fma_f32 v[208:209], v[48:49], v[176:177], v[208:209]
	v_pk_fma_f32 v[210:211], v[50:51], v[178:179], v[210:211]
	v_pk_fma_f32 v[196:197], v[52:53], v[172:173], v[196:197]
	v_pk_fma_f32 v[198:199], v[54:55], v[174:175], v[198:199]
	v_pk_fma_f32 v[200:201], v[56:57], v[176:177], v[200:201]
	v_pk_fma_f32 v[202:203], v[58:59], v[178:179], v[202:203]
	v_pk_fma_f32 v[188:189], v[60:61], v[172:173], v[188:189]
	v_pk_fma_f32 v[190:191], v[62:63], v[174:175], v[190:191]
	v_pk_fma_f32 v[192:193], v[64:65], v[176:177], v[192:193]
	v_pk_fma_f32 v[194:195], v[66:67], v[178:179], v[194:195]
	v_mul_f32_e32 v220, 0xbfb8aa3b, v188
	v_mul_f32_e32 v221, 0xbfb8aa3b, v189
	v_mul_f32_e32 v222, 0xbfb8aa3b, v190
	v_mul_f32_e32 v223, 0xbfb8aa3b, v191
	v_mul_f32_e32 v224, 0xbfb8aa3b, v192
	v_mul_f32_e32 v225, 0xbfb8aa3b, v193
	v_mul_f32_e32 v226, 0xbfb8aa3b, v194
	v_mul_f32_e32 v227, 0xbfb8aa3b, v195
	v_exp_f32_e32 v220, v220
	v_exp_f32_e32 v221, v221
	v_exp_f32_e32 v222, v222
	v_exp_f32_e32 v223, v223
	v_exp_f32_e32 v224, v224
	v_exp_f32_e32 v225, v225
	v_exp_f32_e32 v226, v226
	v_exp_f32_e32 v227, v227
	v_add_f32_e32 v220, 1.0, v220
	v_add_f32_e32 v221, 1.0, v221
	v_add_f32_e32 v222, 1.0, v222
	v_add_f32_e32 v223, 1.0, v223
	v_add_f32_e32 v224, 1.0, v224
	v_add_f32_e32 v225, 1.0, v225
	v_add_f32_e32 v226, 1.0, v226
	v_add_f32_e32 v227, 1.0, v227
	v_rcp_f32_e32 v220, v220
	v_rcp_f32_e32 v221, v221
	v_rcp_f32_e32 v222, v222
	v_rcp_f32_e32 v223, v223
	v_rcp_f32_e32 v224, v224
	v_rcp_f32_e32 v225, v225
	v_rcp_f32_e32 v226, v226
	v_rcp_f32_e32 v227, v227
	v_mul_f32_e32 v220, v188, v220
	v_mul_f32_e32 v221, v189, v221
	v_mul_f32_e32 v222, v190, v222
	v_mul_f32_e32 v223, v191, v223
	v_mul_f32_e32 v224, v192, v224
	v_mul_f32_e32 v225, v193, v225
	v_mul_f32_e32 v226, v194, v226
	v_mul_f32_e32 v227, v195, v227
	v_cvt_pk_bf16_f32 v188, v220, v221
	v_cvt_pk_bf16_f32 v189, v222, v223
	v_cvt_pk_bf16_f32 v190, v224, v225
	v_cvt_pk_bf16_f32 v191, v226, v227
	global_store_dwordx4 v25, v[188:191], s[54:55] sc1
	s_add_u32 s54, s54, 0x1000
	s_addc_u32 s55, s55, 0
	s_waitcnt vmcnt(15)
	v_lshlrev_b32_e32 v172, 16, v100
	v_and_b32_e32 v173, 0xffff0000, v100
	v_lshlrev_b32_e32 v174, 16, v101
	v_and_b32_e32 v175, 0xffff0000, v101
	v_lshlrev_b32_e32 v176, 16, v102
	v_and_b32_e32 v177, 0xffff0000, v102
	v_lshlrev_b32_e32 v178, 16, v103
	v_and_b32_e32 v179, 0xffff0000, v103
	v_pk_fma_f32 v[188:189], v[28:29], v[172:173], v[68:69]
	v_pk_fma_f32 v[190:191], v[30:31], v[174:175], v[70:71]
	v_pk_fma_f32 v[192:193], v[32:33], v[176:177], v[72:73]
	v_pk_fma_f32 v[194:195], v[34:35], v[178:179], v[74:75]
	v_pk_fma_f32 v[180:181], v[36:37], v[172:173], v[180:181]
	v_pk_fma_f32 v[182:183], v[38:39], v[174:175], v[182:183]
	v_pk_fma_f32 v[184:185], v[40:41], v[176:177], v[184:185]
	v_pk_fma_f32 v[186:187], v[42:43], v[178:179], v[186:187]
	v_pk_fma_f32 v[212:213], v[44:45], v[172:173], v[212:213]
	v_pk_fma_f32 v[214:215], v[46:47], v[174:175], v[214:215]
	v_pk_fma_f32 v[216:217], v[48:49], v[176:177], v[216:217]
	v_pk_fma_f32 v[218:219], v[50:51], v[178:179], v[218:219]
	v_pk_fma_f32 v[204:205], v[52:53], v[172:173], v[204:205]
	v_pk_fma_f32 v[206:207], v[54:55], v[174:175], v[206:207]
	v_pk_fma_f32 v[208:209], v[56:57], v[176:177], v[208:209]
	v_pk_fma_f32 v[210:211], v[58:59], v[178:179], v[210:211]
	v_pk_fma_f32 v[196:197], v[60:61], v[172:173], v[196:197]
	v_pk_fma_f32 v[198:199], v[62:63], v[174:175], v[198:199]
	v_pk_fma_f32 v[200:201], v[64:65], v[176:177], v[200:201]
	v_pk_fma_f32 v[202:203], v[66:67], v[178:179], v[202:203]
	v_mul_f32_e32 v220, 0xbfb8aa3b, v196
	v_mul_f32_e32 v221, 0xbfb8aa3b, v197
	v_mul_f32_e32 v222, 0xbfb8aa3b, v198
	v_mul_f32_e32 v223, 0xbfb8aa3b, v199
	v_mul_f32_e32 v224, 0xbfb8aa3b, v200
	v_mul_f32_e32 v225, 0xbfb8aa3b, v201
	v_mul_f32_e32 v226, 0xbfb8aa3b, v202
	v_mul_f32_e32 v227, 0xbfb8aa3b, v203
	v_exp_f32_e32 v220, v220
	v_exp_f32_e32 v221, v221
	v_exp_f32_e32 v222, v222
	v_exp_f32_e32 v223, v223
	v_exp_f32_e32 v224, v224
	v_exp_f32_e32 v225, v225
	v_exp_f32_e32 v226, v226
	v_exp_f32_e32 v227, v227
	v_add_f32_e32 v220, 1.0, v220
	v_add_f32_e32 v221, 1.0, v221
	v_add_f32_e32 v222, 1.0, v222
	v_add_f32_e32 v223, 1.0, v223
	v_add_f32_e32 v224, 1.0, v224
	v_add_f32_e32 v225, 1.0, v225
	v_add_f32_e32 v226, 1.0, v226
	v_add_f32_e32 v227, 1.0, v227
	v_rcp_f32_e32 v220, v220
	v_rcp_f32_e32 v221, v221
	v_rcp_f32_e32 v222, v222
	v_rcp_f32_e32 v223, v223
	v_rcp_f32_e32 v224, v224
	v_rcp_f32_e32 v225, v225
	v_rcp_f32_e32 v226, v226
	v_rcp_f32_e32 v227, v227
	v_mul_f32_e32 v220, v196, v220
	v_mul_f32_e32 v221, v197, v221
	v_mul_f32_e32 v222, v198, v222
	v_mul_f32_e32 v223, v199, v223
	v_mul_f32_e32 v224, v200, v224
	v_mul_f32_e32 v225, v201, v225
	v_mul_f32_e32 v226, v202, v226
	v_mul_f32_e32 v227, v203, v227
	v_cvt_pk_bf16_f32 v196, v220, v221
	v_cvt_pk_bf16_f32 v197, v222, v223
	v_cvt_pk_bf16_f32 v198, v224, v225
	v_cvt_pk_bf16_f32 v199, v226, v227
	global_store_dwordx4 v25, v[196:199], s[54:55] sc1
	s_add_u32 s54, s54, 0x1000
	s_addc_u32 s55, s55, 0
	s_waitcnt vmcnt(15)
	v_lshlrev_b32_e32 v172, 16, v104
	v_and_b32_e32 v173, 0xffff0000, v104
	v_lshlrev_b32_e32 v174, 16, v105
	v_and_b32_e32 v175, 0xffff0000, v105
	v_lshlrev_b32_e32 v176, 16, v106
	v_and_b32_e32 v177, 0xffff0000, v106
	v_lshlrev_b32_e32 v178, 16, v107
	v_and_b32_e32 v179, 0xffff0000, v107
	v_pk_fma_f32 v[196:197], v[28:29], v[172:173], v[68:69]
	v_pk_fma_f32 v[198:199], v[30:31], v[174:175], v[70:71]
	v_pk_fma_f32 v[200:201], v[32:33], v[176:177], v[72:73]
	v_pk_fma_f32 v[202:203], v[34:35], v[178:179], v[74:75]
	v_pk_fma_f32 v[188:189], v[36:37], v[172:173], v[188:189]
	v_pk_fma_f32 v[190:191], v[38:39], v[174:175], v[190:191]
	v_pk_fma_f32 v[192:193], v[40:41], v[176:177], v[192:193]
	v_pk_fma_f32 v[194:195], v[42:43], v[178:179], v[194:195]
	v_pk_fma_f32 v[180:181], v[44:45], v[172:173], v[180:181]
	v_pk_fma_f32 v[182:183], v[46:47], v[174:175], v[182:183]
	v_pk_fma_f32 v[184:185], v[48:49], v[176:177], v[184:185]
	v_pk_fma_f32 v[186:187], v[50:51], v[178:179], v[186:187]
	v_pk_fma_f32 v[212:213], v[52:53], v[172:173], v[212:213]
	v_pk_fma_f32 v[214:215], v[54:55], v[174:175], v[214:215]
	v_pk_fma_f32 v[216:217], v[56:57], v[176:177], v[216:217]
	v_pk_fma_f32 v[218:219], v[58:59], v[178:179], v[218:219]
	v_pk_fma_f32 v[204:205], v[60:61], v[172:173], v[204:205]
	v_pk_fma_f32 v[206:207], v[62:63], v[174:175], v[206:207]
	v_pk_fma_f32 v[208:209], v[64:65], v[176:177], v[208:209]
	v_pk_fma_f32 v[210:211], v[66:67], v[178:179], v[210:211]
	v_mul_f32_e32 v220, 0xbfb8aa3b, v204
	v_mul_f32_e32 v221, 0xbfb8aa3b, v205
	v_mul_f32_e32 v222, 0xbfb8aa3b, v206
	v_mul_f32_e32 v223, 0xbfb8aa3b, v207
	v_mul_f32_e32 v224, 0xbfb8aa3b, v208
	v_mul_f32_e32 v225, 0xbfb8aa3b, v209
	v_mul_f32_e32 v226, 0xbfb8aa3b, v210
	v_mul_f32_e32 v227, 0xbfb8aa3b, v211
	v_exp_f32_e32 v220, v220
	v_exp_f32_e32 v221, v221
	v_exp_f32_e32 v222, v222
	v_exp_f32_e32 v223, v223
	v_exp_f32_e32 v224, v224
	v_exp_f32_e32 v225, v225
	v_exp_f32_e32 v226, v226
	v_exp_f32_e32 v227, v227
	v_add_f32_e32 v220, 1.0, v220
	v_add_f32_e32 v221, 1.0, v221
	v_add_f32_e32 v222, 1.0, v222
	v_add_f32_e32 v223, 1.0, v223
	v_add_f32_e32 v224, 1.0, v224
	v_add_f32_e32 v225, 1.0, v225
	v_add_f32_e32 v226, 1.0, v226
	v_add_f32_e32 v227, 1.0, v227
	v_rcp_f32_e32 v220, v220
	v_rcp_f32_e32 v221, v221
	v_rcp_f32_e32 v222, v222
	v_rcp_f32_e32 v223, v223
	v_rcp_f32_e32 v224, v224
	v_rcp_f32_e32 v225, v225
	v_rcp_f32_e32 v226, v226
	v_rcp_f32_e32 v227, v227
	v_mul_f32_e32 v220, v204, v220
	v_mul_f32_e32 v221, v205, v221
	v_mul_f32_e32 v222, v206, v222
	v_mul_f32_e32 v223, v207, v223
	v_mul_f32_e32 v224, v208, v224
	v_mul_f32_e32 v225, v209, v225
	v_mul_f32_e32 v226, v210, v226
	v_mul_f32_e32 v227, v211, v227
	v_cvt_pk_bf16_f32 v204, v220, v221
	v_cvt_pk_bf16_f32 v205, v222, v223
	v_cvt_pk_bf16_f32 v206, v224, v225
	v_cvt_pk_bf16_f32 v207, v226, v227
	global_store_dwordx4 v25, v[204:207], s[54:55] sc1
	s_add_u32 s54, s54, 0x1000
	s_addc_u32 s55, s55, 0
	s_waitcnt vmcnt(15)
	v_lshlrev_b32_e32 v172, 16, v108
	v_and_b32_e32 v173, 0xffff0000, v108
	v_lshlrev_b32_e32 v174, 16, v109
	v_and_b32_e32 v175, 0xffff0000, v109
	v_lshlrev_b32_e32 v176, 16, v110
	v_and_b32_e32 v177, 0xffff0000, v110
	v_lshlrev_b32_e32 v178, 16, v111
	v_and_b32_e32 v179, 0xffff0000, v111
	v_pk_fma_f32 v[204:205], v[28:29], v[172:173], v[68:69]
	v_pk_fma_f32 v[206:207], v[30:31], v[174:175], v[70:71]
	v_pk_fma_f32 v[208:209], v[32:33], v[176:177], v[72:73]
	v_pk_fma_f32 v[210:211], v[34:35], v[178:179], v[74:75]
	v_pk_fma_f32 v[196:197], v[36:37], v[172:173], v[196:197]
	v_pk_fma_f32 v[198:199], v[38:39], v[174:175], v[198:199]
	v_pk_fma_f32 v[200:201], v[40:41], v[176:177], v[200:201]
	v_pk_fma_f32 v[202:203], v[42:43], v[178:179], v[202:203]
	v_pk_fma_f32 v[188:189], v[44:45], v[172:173], v[188:189]
	v_pk_fma_f32 v[190:191], v[46:47], v[174:175], v[190:191]
	v_pk_fma_f32 v[192:193], v[48:49], v[176:177], v[192:193]
	v_pk_fma_f32 v[194:195], v[50:51], v[178:179], v[194:195]
	v_pk_fma_f32 v[180:181], v[52:53], v[172:173], v[180:181]
	v_pk_fma_f32 v[182:183], v[54:55], v[174:175], v[182:183]
	v_pk_fma_f32 v[184:185], v[56:57], v[176:177], v[184:185]
	v_pk_fma_f32 v[186:187], v[58:59], v[178:179], v[186:187]
	v_pk_fma_f32 v[212:213], v[60:61], v[172:173], v[212:213]
	v_pk_fma_f32 v[214:215], v[62:63], v[174:175], v[214:215]
	v_pk_fma_f32 v[216:217], v[64:65], v[176:177], v[216:217]
	v_pk_fma_f32 v[218:219], v[66:67], v[178:179], v[218:219]
	v_mul_f32_e32 v220, 0xbfb8aa3b, v212
	v_mul_f32_e32 v221, 0xbfb8aa3b, v213
	v_mul_f32_e32 v222, 0xbfb8aa3b, v214
	v_mul_f32_e32 v223, 0xbfb8aa3b, v215
	v_mul_f32_e32 v224, 0xbfb8aa3b, v216
	v_mul_f32_e32 v225, 0xbfb8aa3b, v217
	v_mul_f32_e32 v226, 0xbfb8aa3b, v218
	v_mul_f32_e32 v227, 0xbfb8aa3b, v219
	v_exp_f32_e32 v220, v220
	v_exp_f32_e32 v221, v221
	v_exp_f32_e32 v222, v222
	v_exp_f32_e32 v223, v223
	v_exp_f32_e32 v224, v224
	v_exp_f32_e32 v225, v225
	v_exp_f32_e32 v226, v226
	v_exp_f32_e32 v227, v227
	v_add_f32_e32 v220, 1.0, v220
	v_add_f32_e32 v221, 1.0, v221
	v_add_f32_e32 v222, 1.0, v222
	v_add_f32_e32 v223, 1.0, v223
	v_add_f32_e32 v224, 1.0, v224
	v_add_f32_e32 v225, 1.0, v225
	v_add_f32_e32 v226, 1.0, v226
	v_add_f32_e32 v227, 1.0, v227
	v_rcp_f32_e32 v220, v220
	v_rcp_f32_e32 v221, v221
	v_rcp_f32_e32 v222, v222
	v_rcp_f32_e32 v223, v223
	v_rcp_f32_e32 v224, v224
	v_rcp_f32_e32 v225, v225
	v_rcp_f32_e32 v226, v226
	v_rcp_f32_e32 v227, v227
	v_mul_f32_e32 v220, v212, v220
	v_mul_f32_e32 v221, v213, v221
	v_mul_f32_e32 v222, v214, v222
	v_mul_f32_e32 v223, v215, v223
	v_mul_f32_e32 v224, v216, v224
	v_mul_f32_e32 v225, v217, v225
	v_mul_f32_e32 v226, v218, v226
	v_mul_f32_e32 v227, v219, v227
	v_cvt_pk_bf16_f32 v212, v220, v221
	v_cvt_pk_bf16_f32 v213, v222, v223
	v_cvt_pk_bf16_f32 v214, v224, v225
	v_cvt_pk_bf16_f32 v215, v226, v227
	global_store_dwordx4 v25, v[212:215], s[54:55] sc1
	s_add_u32 s54, s54, 0x1000
	s_addc_u32 s55, s55, 0
	s_waitcnt vmcnt(15)
	v_lshlrev_b32_e32 v172, 16, v112
	v_and_b32_e32 v173, 0xffff0000, v112
	v_lshlrev_b32_e32 v174, 16, v113
	v_and_b32_e32 v175, 0xffff0000, v113
	v_lshlrev_b32_e32 v176, 16, v114
	v_and_b32_e32 v177, 0xffff0000, v114
	v_lshlrev_b32_e32 v178, 16, v115
	v_and_b32_e32 v179, 0xffff0000, v115
	v_pk_fma_f32 v[212:213], v[28:29], v[172:173], v[68:69]
	v_pk_fma_f32 v[214:215], v[30:31], v[174:175], v[70:71]
	v_pk_fma_f32 v[216:217], v[32:33], v[176:177], v[72:73]
	v_pk_fma_f32 v[218:219], v[34:35], v[178:179], v[74:75]
	v_pk_fma_f32 v[204:205], v[36:37], v[172:173], v[204:205]
	v_pk_fma_f32 v[206:207], v[38:39], v[174:175], v[206:207]
	v_pk_fma_f32 v[208:209], v[40:41], v[176:177], v[208:209]
	v_pk_fma_f32 v[210:211], v[42:43], v[178:179], v[210:211]
	v_pk_fma_f32 v[196:197], v[44:45], v[172:173], v[196:197]
	v_pk_fma_f32 v[198:199], v[46:47], v[174:175], v[198:199]
	v_pk_fma_f32 v[200:201], v[48:49], v[176:177], v[200:201]
	v_pk_fma_f32 v[202:203], v[50:51], v[178:179], v[202:203]
	v_pk_fma_f32 v[188:189], v[52:53], v[172:173], v[188:189]
	v_pk_fma_f32 v[190:191], v[54:55], v[174:175], v[190:191]
	v_pk_fma_f32 v[192:193], v[56:57], v[176:177], v[192:193]
	v_pk_fma_f32 v[194:195], v[58:59], v[178:179], v[194:195]
	v_pk_fma_f32 v[180:181], v[60:61], v[172:173], v[180:181]
	v_pk_fma_f32 v[182:183], v[62:63], v[174:175], v[182:183]
	v_pk_fma_f32 v[184:185], v[64:65], v[176:177], v[184:185]
	v_pk_fma_f32 v[186:187], v[66:67], v[178:179], v[186:187]
	v_mul_f32_e32 v220, 0xbfb8aa3b, v180
	v_mul_f32_e32 v221, 0xbfb8aa3b, v181
	v_mul_f32_e32 v222, 0xbfb8aa3b, v182
	v_mul_f32_e32 v223, 0xbfb8aa3b, v183
	v_mul_f32_e32 v224, 0xbfb8aa3b, v184
	v_mul_f32_e32 v225, 0xbfb8aa3b, v185
	v_mul_f32_e32 v226, 0xbfb8aa3b, v186
	v_mul_f32_e32 v227, 0xbfb8aa3b, v187
	v_exp_f32_e32 v220, v220
	v_exp_f32_e32 v221, v221
	v_exp_f32_e32 v222, v222
	v_exp_f32_e32 v223, v223
	v_exp_f32_e32 v224, v224
	v_exp_f32_e32 v225, v225
	v_exp_f32_e32 v226, v226
	v_exp_f32_e32 v227, v227
	v_add_f32_e32 v220, 1.0, v220
	v_add_f32_e32 v221, 1.0, v221
	v_add_f32_e32 v222, 1.0, v222
	v_add_f32_e32 v223, 1.0, v223
	v_add_f32_e32 v224, 1.0, v224
	v_add_f32_e32 v225, 1.0, v225
	v_add_f32_e32 v226, 1.0, v226
	v_add_f32_e32 v227, 1.0, v227
	v_rcp_f32_e32 v220, v220
	v_rcp_f32_e32 v221, v221
	v_rcp_f32_e32 v222, v222
	v_rcp_f32_e32 v223, v223
	v_rcp_f32_e32 v224, v224
	v_rcp_f32_e32 v225, v225
	v_rcp_f32_e32 v226, v226
	v_rcp_f32_e32 v227, v227
	v_mul_f32_e32 v220, v180, v220
	v_mul_f32_e32 v221, v181, v221
	v_mul_f32_e32 v222, v182, v222
	v_mul_f32_e32 v223, v183, v223
	v_mul_f32_e32 v224, v184, v224
	v_mul_f32_e32 v225, v185, v225
	v_mul_f32_e32 v226, v186, v226
	v_mul_f32_e32 v227, v187, v227
	v_cvt_pk_bf16_f32 v180, v220, v221
	v_cvt_pk_bf16_f32 v181, v222, v223
	v_cvt_pk_bf16_f32 v182, v224, v225
	v_cvt_pk_bf16_f32 v183, v226, v227
	global_store_dwordx4 v25, v[180:183], s[54:55] sc1
	s_add_u32 s54, s54, 0x1000
	s_addc_u32 s55, s55, 0
	s_waitcnt vmcnt(15)
	v_lshlrev_b32_e32 v172, 16, v116
	v_and_b32_e32 v173, 0xffff0000, v116
	v_lshlrev_b32_e32 v174, 16, v117
	v_and_b32_e32 v175, 0xffff0000, v117
	v_lshlrev_b32_e32 v176, 16, v118
	v_and_b32_e32 v177, 0xffff0000, v118
	v_lshlrev_b32_e32 v178, 16, v119
	v_and_b32_e32 v179, 0xffff0000, v119
	v_pk_fma_f32 v[180:181], v[28:29], v[172:173], v[68:69]
	v_pk_fma_f32 v[182:183], v[30:31], v[174:175], v[70:71]
	v_pk_fma_f32 v[184:185], v[32:33], v[176:177], v[72:73]
	v_pk_fma_f32 v[186:187], v[34:35], v[178:179], v[74:75]
	v_pk_fma_f32 v[212:213], v[36:37], v[172:173], v[212:213]
	v_pk_fma_f32 v[214:215], v[38:39], v[174:175], v[214:215]
	v_pk_fma_f32 v[216:217], v[40:41], v[176:177], v[216:217]
	v_pk_fma_f32 v[218:219], v[42:43], v[178:179], v[218:219]
	v_pk_fma_f32 v[204:205], v[44:45], v[172:173], v[204:205]
	v_pk_fma_f32 v[206:207], v[46:47], v[174:175], v[206:207]
	v_pk_fma_f32 v[208:209], v[48:49], v[176:177], v[208:209]
	v_pk_fma_f32 v[210:211], v[50:51], v[178:179], v[210:211]
	v_pk_fma_f32 v[196:197], v[52:53], v[172:173], v[196:197]
	v_pk_fma_f32 v[198:199], v[54:55], v[174:175], v[198:199]
	v_pk_fma_f32 v[200:201], v[56:57], v[176:177], v[200:201]
	v_pk_fma_f32 v[202:203], v[58:59], v[178:179], v[202:203]
	v_pk_fma_f32 v[188:189], v[60:61], v[172:173], v[188:189]
	v_pk_fma_f32 v[190:191], v[62:63], v[174:175], v[190:191]
	v_pk_fma_f32 v[192:193], v[64:65], v[176:177], v[192:193]
	v_pk_fma_f32 v[194:195], v[66:67], v[178:179], v[194:195]
	v_mul_f32_e32 v220, 0xbfb8aa3b, v188
	v_mul_f32_e32 v221, 0xbfb8aa3b, v189
	v_mul_f32_e32 v222, 0xbfb8aa3b, v190
	v_mul_f32_e32 v223, 0xbfb8aa3b, v191
	v_mul_f32_e32 v224, 0xbfb8aa3b, v192
	v_mul_f32_e32 v225, 0xbfb8aa3b, v193
	v_mul_f32_e32 v226, 0xbfb8aa3b, v194
	v_mul_f32_e32 v227, 0xbfb8aa3b, v195
	v_exp_f32_e32 v220, v220
	v_exp_f32_e32 v221, v221
	v_exp_f32_e32 v222, v222
	v_exp_f32_e32 v223, v223
	v_exp_f32_e32 v224, v224
	v_exp_f32_e32 v225, v225
	v_exp_f32_e32 v226, v226
	v_exp_f32_e32 v227, v227
	v_add_f32_e32 v220, 1.0, v220
	v_add_f32_e32 v221, 1.0, v221
	v_add_f32_e32 v222, 1.0, v222
	v_add_f32_e32 v223, 1.0, v223
	v_add_f32_e32 v224, 1.0, v224
	v_add_f32_e32 v225, 1.0, v225
	v_add_f32_e32 v226, 1.0, v226
	v_add_f32_e32 v227, 1.0, v227
	v_rcp_f32_e32 v220, v220
	v_rcp_f32_e32 v221, v221
	v_rcp_f32_e32 v222, v222
	v_rcp_f32_e32 v223, v223
	v_rcp_f32_e32 v224, v224
	v_rcp_f32_e32 v225, v225
	v_rcp_f32_e32 v226, v226
	v_rcp_f32_e32 v227, v227
	v_mul_f32_e32 v220, v188, v220
	v_mul_f32_e32 v221, v189, v221
	v_mul_f32_e32 v222, v190, v222
	v_mul_f32_e32 v223, v191, v223
	v_mul_f32_e32 v224, v192, v224
	v_mul_f32_e32 v225, v193, v225
	v_mul_f32_e32 v226, v194, v226
	v_mul_f32_e32 v227, v195, v227
	v_cvt_pk_bf16_f32 v188, v220, v221
	v_cvt_pk_bf16_f32 v189, v222, v223
	v_cvt_pk_bf16_f32 v190, v224, v225
	v_cvt_pk_bf16_f32 v191, v226, v227
	global_store_dwordx4 v25, v[188:191], s[54:55] sc1
	s_add_u32 s54, s54, 0x1000
	s_addc_u32 s55, s55, 0
	s_waitcnt vmcnt(15)
	v_lshlrev_b32_e32 v172, 16, v120
	v_and_b32_e32 v173, 0xffff0000, v120
	v_lshlrev_b32_e32 v174, 16, v121
	v_and_b32_e32 v175, 0xffff0000, v121
	v_lshlrev_b32_e32 v176, 16, v122
	v_and_b32_e32 v177, 0xffff0000, v122
	v_lshlrev_b32_e32 v178, 16, v123
	v_and_b32_e32 v179, 0xffff0000, v123
	v_pk_fma_f32 v[188:189], v[28:29], v[172:173], v[68:69]
	v_pk_fma_f32 v[190:191], v[30:31], v[174:175], v[70:71]
	v_pk_fma_f32 v[192:193], v[32:33], v[176:177], v[72:73]
	v_pk_fma_f32 v[194:195], v[34:35], v[178:179], v[74:75]
	v_pk_fma_f32 v[180:181], v[36:37], v[172:173], v[180:181]
	v_pk_fma_f32 v[182:183], v[38:39], v[174:175], v[182:183]
	v_pk_fma_f32 v[184:185], v[40:41], v[176:177], v[184:185]
	v_pk_fma_f32 v[186:187], v[42:43], v[178:179], v[186:187]
	v_pk_fma_f32 v[212:213], v[44:45], v[172:173], v[212:213]
	v_pk_fma_f32 v[214:215], v[46:47], v[174:175], v[214:215]
	v_pk_fma_f32 v[216:217], v[48:49], v[176:177], v[216:217]
	v_pk_fma_f32 v[218:219], v[50:51], v[178:179], v[218:219]
	v_pk_fma_f32 v[204:205], v[52:53], v[172:173], v[204:205]
	v_pk_fma_f32 v[206:207], v[54:55], v[174:175], v[206:207]
	v_pk_fma_f32 v[208:209], v[56:57], v[176:177], v[208:209]
	v_pk_fma_f32 v[210:211], v[58:59], v[178:179], v[210:211]
	v_pk_fma_f32 v[196:197], v[60:61], v[172:173], v[196:197]
	v_pk_fma_f32 v[198:199], v[62:63], v[174:175], v[198:199]
	v_pk_fma_f32 v[200:201], v[64:65], v[176:177], v[200:201]
	v_pk_fma_f32 v[202:203], v[66:67], v[178:179], v[202:203]
	v_mul_f32_e32 v220, 0xbfb8aa3b, v196
	v_mul_f32_e32 v221, 0xbfb8aa3b, v197
	v_mul_f32_e32 v222, 0xbfb8aa3b, v198
	v_mul_f32_e32 v223, 0xbfb8aa3b, v199
	v_mul_f32_e32 v224, 0xbfb8aa3b, v200
	v_mul_f32_e32 v225, 0xbfb8aa3b, v201
	v_mul_f32_e32 v226, 0xbfb8aa3b, v202
	v_mul_f32_e32 v227, 0xbfb8aa3b, v203
	v_exp_f32_e32 v220, v220
	v_exp_f32_e32 v221, v221
	v_exp_f32_e32 v222, v222
	v_exp_f32_e32 v223, v223
	v_exp_f32_e32 v224, v224
	v_exp_f32_e32 v225, v225
	v_exp_f32_e32 v226, v226
	v_exp_f32_e32 v227, v227
	v_add_f32_e32 v220, 1.0, v220
	v_add_f32_e32 v221, 1.0, v221
	v_add_f32_e32 v222, 1.0, v222
	v_add_f32_e32 v223, 1.0, v223
	v_add_f32_e32 v224, 1.0, v224
	v_add_f32_e32 v225, 1.0, v225
	v_add_f32_e32 v226, 1.0, v226
	v_add_f32_e32 v227, 1.0, v227
	v_rcp_f32_e32 v220, v220
	v_rcp_f32_e32 v221, v221
	v_rcp_f32_e32 v222, v222
	v_rcp_f32_e32 v223, v223
	v_rcp_f32_e32 v224, v224
	v_rcp_f32_e32 v225, v225
	v_rcp_f32_e32 v226, v226
	v_rcp_f32_e32 v227, v227
	v_mul_f32_e32 v220, v196, v220
	v_mul_f32_e32 v221, v197, v221
	v_mul_f32_e32 v222, v198, v222
	v_mul_f32_e32 v223, v199, v223
	v_mul_f32_e32 v224, v200, v224
	v_mul_f32_e32 v225, v201, v225
	v_mul_f32_e32 v226, v202, v226
	v_mul_f32_e32 v227, v203, v227
	v_cvt_pk_bf16_f32 v196, v220, v221
	v_cvt_pk_bf16_f32 v197, v222, v223
	v_cvt_pk_bf16_f32 v198, v224, v225
	v_cvt_pk_bf16_f32 v199, v226, v227
	global_store_dwordx4 v25, v[196:199], s[54:55] sc1
	s_add_u32 s54, s54, 0x1000
	s_addc_u32 s55, s55, 0
	s_waitcnt vmcnt(15)
	v_lshlrev_b32_e32 v172, 16, v124
	v_and_b32_e32 v173, 0xffff0000, v124
	v_lshlrev_b32_e32 v174, 16, v125
	v_and_b32_e32 v175, 0xffff0000, v125
	v_lshlrev_b32_e32 v176, 16, v126
	v_and_b32_e32 v177, 0xffff0000, v126
	v_lshlrev_b32_e32 v178, 16, v127
	v_and_b32_e32 v179, 0xffff0000, v127
	v_pk_fma_f32 v[196:197], v[28:29], v[172:173], v[68:69]
	v_pk_fma_f32 v[198:199], v[30:31], v[174:175], v[70:71]
	v_pk_fma_f32 v[200:201], v[32:33], v[176:177], v[72:73]
	v_pk_fma_f32 v[202:203], v[34:35], v[178:179], v[74:75]
	v_pk_fma_f32 v[188:189], v[36:37], v[172:173], v[188:189]
	v_pk_fma_f32 v[190:191], v[38:39], v[174:175], v[190:191]
	v_pk_fma_f32 v[192:193], v[40:41], v[176:177], v[192:193]
	v_pk_fma_f32 v[194:195], v[42:43], v[178:179], v[194:195]
	v_pk_fma_f32 v[180:181], v[44:45], v[172:173], v[180:181]
	v_pk_fma_f32 v[182:183], v[46:47], v[174:175], v[182:183]
	v_pk_fma_f32 v[184:185], v[48:49], v[176:177], v[184:185]
	v_pk_fma_f32 v[186:187], v[50:51], v[178:179], v[186:187]
	v_pk_fma_f32 v[212:213], v[52:53], v[172:173], v[212:213]
	v_pk_fma_f32 v[214:215], v[54:55], v[174:175], v[214:215]
	v_pk_fma_f32 v[216:217], v[56:57], v[176:177], v[216:217]
	v_pk_fma_f32 v[218:219], v[58:59], v[178:179], v[218:219]
	v_pk_fma_f32 v[204:205], v[60:61], v[172:173], v[204:205]
	v_pk_fma_f32 v[206:207], v[62:63], v[174:175], v[206:207]
	v_pk_fma_f32 v[208:209], v[64:65], v[176:177], v[208:209]
	v_pk_fma_f32 v[210:211], v[66:67], v[178:179], v[210:211]
	v_mul_f32_e32 v220, 0xbfb8aa3b, v204
	v_mul_f32_e32 v221, 0xbfb8aa3b, v205
	v_mul_f32_e32 v222, 0xbfb8aa3b, v206
	v_mul_f32_e32 v223, 0xbfb8aa3b, v207
	v_mul_f32_e32 v224, 0xbfb8aa3b, v208
	v_mul_f32_e32 v225, 0xbfb8aa3b, v209
	v_mul_f32_e32 v226, 0xbfb8aa3b, v210
	v_mul_f32_e32 v227, 0xbfb8aa3b, v211
	v_exp_f32_e32 v220, v220
	v_exp_f32_e32 v221, v221
	v_exp_f32_e32 v222, v222
	v_exp_f32_e32 v223, v223
	v_exp_f32_e32 v224, v224
	v_exp_f32_e32 v225, v225
	v_exp_f32_e32 v226, v226
	v_exp_f32_e32 v227, v227
	v_add_f32_e32 v220, 1.0, v220
	v_add_f32_e32 v221, 1.0, v221
	v_add_f32_e32 v222, 1.0, v222
	v_add_f32_e32 v223, 1.0, v223
	v_add_f32_e32 v224, 1.0, v224
	v_add_f32_e32 v225, 1.0, v225
	v_add_f32_e32 v226, 1.0, v226
	v_add_f32_e32 v227, 1.0, v227
	v_rcp_f32_e32 v220, v220
	v_rcp_f32_e32 v221, v221
	v_rcp_f32_e32 v222, v222
	v_rcp_f32_e32 v223, v223
	v_rcp_f32_e32 v224, v224
	v_rcp_f32_e32 v225, v225
	v_rcp_f32_e32 v226, v226
	v_rcp_f32_e32 v227, v227
	v_mul_f32_e32 v220, v204, v220
	v_mul_f32_e32 v221, v205, v221
	v_mul_f32_e32 v222, v206, v222
	v_mul_f32_e32 v223, v207, v223
	v_mul_f32_e32 v224, v208, v224
	v_mul_f32_e32 v225, v209, v225
	v_mul_f32_e32 v226, v210, v226
	v_mul_f32_e32 v227, v211, v227
	v_cvt_pk_bf16_f32 v204, v220, v221
	v_cvt_pk_bf16_f32 v205, v222, v223
	v_cvt_pk_bf16_f32 v206, v224, v225
	v_cvt_pk_bf16_f32 v207, v226, v227
	global_store_dwordx4 v25, v[204:207], s[54:55] sc1
	s_add_u32 s54, s54, 0x1000
	s_addc_u32 s55, s55, 0
	s_waitcnt vmcnt(15)
	v_lshlrev_b32_e32 v172, 16, v132
	v_and_b32_e32 v173, 0xffff0000, v132
	v_lshlrev_b32_e32 v174, 16, v133
	v_and_b32_e32 v175, 0xffff0000, v133
	v_lshlrev_b32_e32 v176, 16, v134
	v_and_b32_e32 v177, 0xffff0000, v134
	v_lshlrev_b32_e32 v178, 16, v135
	v_and_b32_e32 v179, 0xffff0000, v135
	v_pk_fma_f32 v[204:205], v[28:29], v[172:173], v[68:69]
	v_pk_fma_f32 v[206:207], v[30:31], v[174:175], v[70:71]
	v_pk_fma_f32 v[208:209], v[32:33], v[176:177], v[72:73]
	v_pk_fma_f32 v[210:211], v[34:35], v[178:179], v[74:75]
	v_pk_fma_f32 v[196:197], v[36:37], v[172:173], v[196:197]
	v_pk_fma_f32 v[198:199], v[38:39], v[174:175], v[198:199]
	v_pk_fma_f32 v[200:201], v[40:41], v[176:177], v[200:201]
	v_pk_fma_f32 v[202:203], v[42:43], v[178:179], v[202:203]
	v_pk_fma_f32 v[188:189], v[44:45], v[172:173], v[188:189]
	v_pk_fma_f32 v[190:191], v[46:47], v[174:175], v[190:191]
	v_pk_fma_f32 v[192:193], v[48:49], v[176:177], v[192:193]
	v_pk_fma_f32 v[194:195], v[50:51], v[178:179], v[194:195]
	v_pk_fma_f32 v[180:181], v[52:53], v[172:173], v[180:181]
	v_pk_fma_f32 v[182:183], v[54:55], v[174:175], v[182:183]
	v_pk_fma_f32 v[184:185], v[56:57], v[176:177], v[184:185]
	v_pk_fma_f32 v[186:187], v[58:59], v[178:179], v[186:187]
	v_pk_fma_f32 v[212:213], v[60:61], v[172:173], v[212:213]
	v_pk_fma_f32 v[214:215], v[62:63], v[174:175], v[214:215]
	v_pk_fma_f32 v[216:217], v[64:65], v[176:177], v[216:217]
	v_pk_fma_f32 v[218:219], v[66:67], v[178:179], v[218:219]
	v_mul_f32_e32 v220, 0xbfb8aa3b, v212
	v_mul_f32_e32 v221, 0xbfb8aa3b, v213
	v_mul_f32_e32 v222, 0xbfb8aa3b, v214
	v_mul_f32_e32 v223, 0xbfb8aa3b, v215
	v_mul_f32_e32 v224, 0xbfb8aa3b, v216
	v_mul_f32_e32 v225, 0xbfb8aa3b, v217
	v_mul_f32_e32 v226, 0xbfb8aa3b, v218
	v_mul_f32_e32 v227, 0xbfb8aa3b, v219
	v_exp_f32_e32 v220, v220
	v_exp_f32_e32 v221, v221
	v_exp_f32_e32 v222, v222
	v_exp_f32_e32 v223, v223
	v_exp_f32_e32 v224, v224
	v_exp_f32_e32 v225, v225
	v_exp_f32_e32 v226, v226
	v_exp_f32_e32 v227, v227
	v_add_f32_e32 v220, 1.0, v220
	v_add_f32_e32 v221, 1.0, v221
	v_add_f32_e32 v222, 1.0, v222
	v_add_f32_e32 v223, 1.0, v223
	v_add_f32_e32 v224, 1.0, v224
	v_add_f32_e32 v225, 1.0, v225
	v_add_f32_e32 v226, 1.0, v226
	v_add_f32_e32 v227, 1.0, v227
	v_rcp_f32_e32 v220, v220
	v_rcp_f32_e32 v221, v221
	v_rcp_f32_e32 v222, v222
	v_rcp_f32_e32 v223, v223
	v_rcp_f32_e32 v224, v224
	v_rcp_f32_e32 v225, v225
	v_rcp_f32_e32 v226, v226
	v_rcp_f32_e32 v227, v227
	v_mul_f32_e32 v220, v212, v220
	v_mul_f32_e32 v221, v213, v221
	v_mul_f32_e32 v222, v214, v222
	v_mul_f32_e32 v223, v215, v223
	v_mul_f32_e32 v224, v216, v224
	v_mul_f32_e32 v225, v217, v225
	v_mul_f32_e32 v226, v218, v226
	v_mul_f32_e32 v227, v219, v227
	v_cvt_pk_bf16_f32 v212, v220, v221
	v_cvt_pk_bf16_f32 v213, v222, v223
	v_cvt_pk_bf16_f32 v214, v224, v225
	v_cvt_pk_bf16_f32 v215, v226, v227
	global_store_dwordx4 v25, v[212:215], s[54:55] sc1
	s_add_u32 s54, s54, 0x1000
	s_addc_u32 s55, s55, 0
	s_waitcnt vmcnt(15)
	v_lshlrev_b32_e32 v172, 16, v136
	v_and_b32_e32 v173, 0xffff0000, v136
	v_lshlrev_b32_e32 v174, 16, v137
	v_and_b32_e32 v175, 0xffff0000, v137
	v_lshlrev_b32_e32 v176, 16, v138
	v_and_b32_e32 v177, 0xffff0000, v138
	v_lshlrev_b32_e32 v178, 16, v139
	v_and_b32_e32 v179, 0xffff0000, v139
	v_pk_fma_f32 v[212:213], v[28:29], v[172:173], v[68:69]
	v_pk_fma_f32 v[214:215], v[30:31], v[174:175], v[70:71]
	v_pk_fma_f32 v[216:217], v[32:33], v[176:177], v[72:73]
	v_pk_fma_f32 v[218:219], v[34:35], v[178:179], v[74:75]
	v_pk_fma_f32 v[204:205], v[36:37], v[172:173], v[204:205]
	v_pk_fma_f32 v[206:207], v[38:39], v[174:175], v[206:207]
	v_pk_fma_f32 v[208:209], v[40:41], v[176:177], v[208:209]
	v_pk_fma_f32 v[210:211], v[42:43], v[178:179], v[210:211]
	v_pk_fma_f32 v[196:197], v[44:45], v[172:173], v[196:197]
	v_pk_fma_f32 v[198:199], v[46:47], v[174:175], v[198:199]
	v_pk_fma_f32 v[200:201], v[48:49], v[176:177], v[200:201]
	v_pk_fma_f32 v[202:203], v[50:51], v[178:179], v[202:203]
	v_pk_fma_f32 v[188:189], v[52:53], v[172:173], v[188:189]
	v_pk_fma_f32 v[190:191], v[54:55], v[174:175], v[190:191]
	v_pk_fma_f32 v[192:193], v[56:57], v[176:177], v[192:193]
	v_pk_fma_f32 v[194:195], v[58:59], v[178:179], v[194:195]
	v_pk_fma_f32 v[180:181], v[60:61], v[172:173], v[180:181]
	v_pk_fma_f32 v[182:183], v[62:63], v[174:175], v[182:183]
	v_pk_fma_f32 v[184:185], v[64:65], v[176:177], v[184:185]
	v_pk_fma_f32 v[186:187], v[66:67], v[178:179], v[186:187]
	v_mul_f32_e32 v220, 0xbfb8aa3b, v180
	v_mul_f32_e32 v221, 0xbfb8aa3b, v181
	v_mul_f32_e32 v222, 0xbfb8aa3b, v182
	v_mul_f32_e32 v223, 0xbfb8aa3b, v183
	v_mul_f32_e32 v224, 0xbfb8aa3b, v184
	v_mul_f32_e32 v225, 0xbfb8aa3b, v185
	v_mul_f32_e32 v226, 0xbfb8aa3b, v186
	v_mul_f32_e32 v227, 0xbfb8aa3b, v187
	v_exp_f32_e32 v220, v220
	v_exp_f32_e32 v221, v221
	v_exp_f32_e32 v222, v222
	v_exp_f32_e32 v223, v223
	v_exp_f32_e32 v224, v224
	v_exp_f32_e32 v225, v225
	v_exp_f32_e32 v226, v226
	v_exp_f32_e32 v227, v227
	v_add_f32_e32 v220, 1.0, v220
	v_add_f32_e32 v221, 1.0, v221
	v_add_f32_e32 v222, 1.0, v222
	v_add_f32_e32 v223, 1.0, v223
	v_add_f32_e32 v224, 1.0, v224
	v_add_f32_e32 v225, 1.0, v225
	v_add_f32_e32 v226, 1.0, v226
	v_add_f32_e32 v227, 1.0, v227
	v_rcp_f32_e32 v220, v220
	v_rcp_f32_e32 v221, v221
	v_rcp_f32_e32 v222, v222
	v_rcp_f32_e32 v223, v223
	v_rcp_f32_e32 v224, v224
	v_rcp_f32_e32 v225, v225
	v_rcp_f32_e32 v226, v226
	v_rcp_f32_e32 v227, v227
	v_mul_f32_e32 v220, v180, v220
	v_mul_f32_e32 v221, v181, v221
	v_mul_f32_e32 v222, v182, v222
	v_mul_f32_e32 v223, v183, v223
	v_mul_f32_e32 v224, v184, v224
	v_mul_f32_e32 v225, v185, v225
	v_mul_f32_e32 v226, v186, v226
	v_mul_f32_e32 v227, v187, v227
	v_cvt_pk_bf16_f32 v180, v220, v221
	v_cvt_pk_bf16_f32 v181, v222, v223
	v_cvt_pk_bf16_f32 v182, v224, v225
	v_cvt_pk_bf16_f32 v183, v226, v227
	global_store_dwordx4 v25, v[180:183], s[54:55] sc1
	s_add_u32 s54, s54, 0x1000
	s_addc_u32 s55, s55, 0
	s_waitcnt vmcnt(15)
	v_lshlrev_b32_e32 v172, 16, v140
	v_and_b32_e32 v173, 0xffff0000, v140
	v_lshlrev_b32_e32 v174, 16, v141
	v_and_b32_e32 v175, 0xffff0000, v141
	v_lshlrev_b32_e32 v176, 16, v142
	v_and_b32_e32 v177, 0xffff0000, v142
	v_lshlrev_b32_e32 v178, 16, v143
	v_and_b32_e32 v179, 0xffff0000, v143
	v_pk_fma_f32 v[180:181], v[28:29], v[172:173], v[68:69]
	v_pk_fma_f32 v[182:183], v[30:31], v[174:175], v[70:71]
	v_pk_fma_f32 v[184:185], v[32:33], v[176:177], v[72:73]
	v_pk_fma_f32 v[186:187], v[34:35], v[178:179], v[74:75]
	v_pk_fma_f32 v[212:213], v[36:37], v[172:173], v[212:213]
	v_pk_fma_f32 v[214:215], v[38:39], v[174:175], v[214:215]
	v_pk_fma_f32 v[216:217], v[40:41], v[176:177], v[216:217]
	v_pk_fma_f32 v[218:219], v[42:43], v[178:179], v[218:219]
	v_pk_fma_f32 v[204:205], v[44:45], v[172:173], v[204:205]
	v_pk_fma_f32 v[206:207], v[46:47], v[174:175], v[206:207]
	v_pk_fma_f32 v[208:209], v[48:49], v[176:177], v[208:209]
	v_pk_fma_f32 v[210:211], v[50:51], v[178:179], v[210:211]
	v_pk_fma_f32 v[196:197], v[52:53], v[172:173], v[196:197]
	v_pk_fma_f32 v[198:199], v[54:55], v[174:175], v[198:199]
	v_pk_fma_f32 v[200:201], v[56:57], v[176:177], v[200:201]
	v_pk_fma_f32 v[202:203], v[58:59], v[178:179], v[202:203]
	v_pk_fma_f32 v[188:189], v[60:61], v[172:173], v[188:189]
	v_pk_fma_f32 v[190:191], v[62:63], v[174:175], v[190:191]
	v_pk_fma_f32 v[192:193], v[64:65], v[176:177], v[192:193]
	v_pk_fma_f32 v[194:195], v[66:67], v[178:179], v[194:195]
	v_mul_f32_e32 v220, 0xbfb8aa3b, v188
	v_mul_f32_e32 v221, 0xbfb8aa3b, v189
	v_mul_f32_e32 v222, 0xbfb8aa3b, v190
	v_mul_f32_e32 v223, 0xbfb8aa3b, v191
	v_mul_f32_e32 v224, 0xbfb8aa3b, v192
	v_mul_f32_e32 v225, 0xbfb8aa3b, v193
	v_mul_f32_e32 v226, 0xbfb8aa3b, v194
	v_mul_f32_e32 v227, 0xbfb8aa3b, v195
	v_exp_f32_e32 v220, v220
	v_exp_f32_e32 v221, v221
	v_exp_f32_e32 v222, v222
	v_exp_f32_e32 v223, v223
	v_exp_f32_e32 v224, v224
	v_exp_f32_e32 v225, v225
	v_exp_f32_e32 v226, v226
	v_exp_f32_e32 v227, v227
	v_add_f32_e32 v220, 1.0, v220
	v_add_f32_e32 v221, 1.0, v221
	v_add_f32_e32 v222, 1.0, v222
	v_add_f32_e32 v223, 1.0, v223
	v_add_f32_e32 v224, 1.0, v224
	v_add_f32_e32 v225, 1.0, v225
	v_add_f32_e32 v226, 1.0, v226
	v_add_f32_e32 v227, 1.0, v227
	v_rcp_f32_e32 v220, v220
	v_rcp_f32_e32 v221, v221
	v_rcp_f32_e32 v222, v222
	v_rcp_f32_e32 v223, v223
	v_rcp_f32_e32 v224, v224
	v_rcp_f32_e32 v225, v225
	v_rcp_f32_e32 v226, v226
	v_rcp_f32_e32 v227, v227
	v_mul_f32_e32 v220, v188, v220
	v_mul_f32_e32 v221, v189, v221
	v_mul_f32_e32 v222, v190, v222
	v_mul_f32_e32 v223, v191, v223
	v_mul_f32_e32 v224, v192, v224
	v_mul_f32_e32 v225, v193, v225
	v_mul_f32_e32 v226, v194, v226
	v_mul_f32_e32 v227, v195, v227
	v_cvt_pk_bf16_f32 v188, v220, v221
	v_cvt_pk_bf16_f32 v189, v222, v223
	v_cvt_pk_bf16_f32 v190, v224, v225
	v_cvt_pk_bf16_f32 v191, v226, v227
	global_store_dwordx4 v25, v[188:191], s[54:55] sc1
	s_add_u32 s54, s54, 0x1000
	s_addc_u32 s55, s55, 0
	s_waitcnt vmcnt(15)
	v_lshlrev_b32_e32 v172, 16, v144
	v_and_b32_e32 v173, 0xffff0000, v144
	v_lshlrev_b32_e32 v174, 16, v145
	v_and_b32_e32 v175, 0xffff0000, v145
	v_lshlrev_b32_e32 v176, 16, v146
	v_and_b32_e32 v177, 0xffff0000, v146
	v_lshlrev_b32_e32 v178, 16, v147
	v_and_b32_e32 v179, 0xffff0000, v147
	v_pk_fma_f32 v[180:181], v[36:37], v[172:173], v[180:181]
	v_pk_fma_f32 v[182:183], v[38:39], v[174:175], v[182:183]
	v_pk_fma_f32 v[184:185], v[40:41], v[176:177], v[184:185]
	v_pk_fma_f32 v[186:187], v[42:43], v[178:179], v[186:187]
	v_pk_fma_f32 v[212:213], v[44:45], v[172:173], v[212:213]
	v_pk_fma_f32 v[214:215], v[46:47], v[174:175], v[214:215]
	v_pk_fma_f32 v[216:217], v[48:49], v[176:177], v[216:217]
	v_pk_fma_f32 v[218:219], v[50:51], v[178:179], v[218:219]
	v_pk_fma_f32 v[204:205], v[52:53], v[172:173], v[204:205]
	v_pk_fma_f32 v[206:207], v[54:55], v[174:175], v[206:207]
	v_pk_fma_f32 v[208:209], v[56:57], v[176:177], v[208:209]
	v_pk_fma_f32 v[210:211], v[58:59], v[178:179], v[210:211]
	v_pk_fma_f32 v[196:197], v[60:61], v[172:173], v[196:197]
	v_pk_fma_f32 v[198:199], v[62:63], v[174:175], v[198:199]
	v_pk_fma_f32 v[200:201], v[64:65], v[176:177], v[200:201]
	v_pk_fma_f32 v[202:203], v[66:67], v[178:179], v[202:203]
	v_mul_f32_e32 v220, 0xbfb8aa3b, v196
	v_mul_f32_e32 v221, 0xbfb8aa3b, v197
	v_mul_f32_e32 v222, 0xbfb8aa3b, v198
	v_mul_f32_e32 v223, 0xbfb8aa3b, v199
	v_mul_f32_e32 v224, 0xbfb8aa3b, v200
	v_mul_f32_e32 v225, 0xbfb8aa3b, v201
	v_mul_f32_e32 v226, 0xbfb8aa3b, v202
	v_mul_f32_e32 v227, 0xbfb8aa3b, v203
	v_exp_f32_e32 v220, v220
	v_exp_f32_e32 v221, v221
	v_exp_f32_e32 v222, v222
	v_exp_f32_e32 v223, v223
	v_exp_f32_e32 v224, v224
	v_exp_f32_e32 v225, v225
	v_exp_f32_e32 v226, v226
	v_exp_f32_e32 v227, v227
	v_add_f32_e32 v220, 1.0, v220
	v_add_f32_e32 v221, 1.0, v221
	v_add_f32_e32 v222, 1.0, v222
	v_add_f32_e32 v223, 1.0, v223
	v_add_f32_e32 v224, 1.0, v224
	v_add_f32_e32 v225, 1.0, v225
	v_add_f32_e32 v226, 1.0, v226
	v_add_f32_e32 v227, 1.0, v227
	v_rcp_f32_e32 v220, v220
	v_rcp_f32_e32 v221, v221
	v_rcp_f32_e32 v222, v222
	v_rcp_f32_e32 v223, v223
	v_rcp_f32_e32 v224, v224
	v_rcp_f32_e32 v225, v225
	v_rcp_f32_e32 v226, v226
	v_rcp_f32_e32 v227, v227
	v_mul_f32_e32 v220, v196, v220
	v_mul_f32_e32 v221, v197, v221
	v_mul_f32_e32 v222, v198, v222
	v_mul_f32_e32 v223, v199, v223
	v_mul_f32_e32 v224, v200, v224
	v_mul_f32_e32 v225, v201, v225
	v_mul_f32_e32 v226, v202, v226
	v_mul_f32_e32 v227, v203, v227
	v_cvt_pk_bf16_f32 v196, v220, v221
	v_cvt_pk_bf16_f32 v197, v222, v223
	v_cvt_pk_bf16_f32 v198, v224, v225
	v_cvt_pk_bf16_f32 v199, v226, v227
	global_store_dwordx4 v25, v[196:199], s[54:55] sc1
	s_add_u32 s54, s54, 0x1000
	s_addc_u32 s55, s55, 0
	s_waitcnt vmcnt(15)
	v_lshlrev_b32_e32 v172, 16, v148
	v_and_b32_e32 v173, 0xffff0000, v148
	v_lshlrev_b32_e32 v174, 16, v149
	v_and_b32_e32 v175, 0xffff0000, v149
	v_lshlrev_b32_e32 v176, 16, v150
	v_and_b32_e32 v177, 0xffff0000, v150
	v_lshlrev_b32_e32 v178, 16, v151
	v_and_b32_e32 v179, 0xffff0000, v151
	v_pk_fma_f32 v[180:181], v[44:45], v[172:173], v[180:181]
	v_pk_fma_f32 v[182:183], v[46:47], v[174:175], v[182:183]
	v_pk_fma_f32 v[184:185], v[48:49], v[176:177], v[184:185]
	v_pk_fma_f32 v[186:187], v[50:51], v[178:179], v[186:187]
	v_pk_fma_f32 v[212:213], v[52:53], v[172:173], v[212:213]
	v_pk_fma_f32 v[214:215], v[54:55], v[174:175], v[214:215]
	v_pk_fma_f32 v[216:217], v[56:57], v[176:177], v[216:217]
	v_pk_fma_f32 v[218:219], v[58:59], v[178:179], v[218:219]
	v_pk_fma_f32 v[204:205], v[60:61], v[172:173], v[204:205]
	v_pk_fma_f32 v[206:207], v[62:63], v[174:175], v[206:207]
	v_pk_fma_f32 v[208:209], v[64:65], v[176:177], v[208:209]
	v_pk_fma_f32 v[210:211], v[66:67], v[178:179], v[210:211]
	v_mul_f32_e32 v220, 0xbfb8aa3b, v204
	v_mul_f32_e32 v221, 0xbfb8aa3b, v205
	v_mul_f32_e32 v222, 0xbfb8aa3b, v206
	v_mul_f32_e32 v223, 0xbfb8aa3b, v207
	v_mul_f32_e32 v224, 0xbfb8aa3b, v208
	v_mul_f32_e32 v225, 0xbfb8aa3b, v209
	v_mul_f32_e32 v226, 0xbfb8aa3b, v210
	v_mul_f32_e32 v227, 0xbfb8aa3b, v211
	v_exp_f32_e32 v220, v220
	v_exp_f32_e32 v221, v221
	v_exp_f32_e32 v222, v222
	v_exp_f32_e32 v223, v223
	v_exp_f32_e32 v224, v224
	v_exp_f32_e32 v225, v225
	v_exp_f32_e32 v226, v226
	v_exp_f32_e32 v227, v227
	v_add_f32_e32 v220, 1.0, v220
	v_add_f32_e32 v221, 1.0, v221
	v_add_f32_e32 v222, 1.0, v222
	v_add_f32_e32 v223, 1.0, v223
	v_add_f32_e32 v224, 1.0, v224
	v_add_f32_e32 v225, 1.0, v225
	v_add_f32_e32 v226, 1.0, v226
	v_add_f32_e32 v227, 1.0, v227
	v_rcp_f32_e32 v220, v220
	v_rcp_f32_e32 v221, v221
	v_rcp_f32_e32 v222, v222
	v_rcp_f32_e32 v223, v223
	v_rcp_f32_e32 v224, v224
	v_rcp_f32_e32 v225, v225
	v_rcp_f32_e32 v226, v226
	v_rcp_f32_e32 v227, v227
	v_mul_f32_e32 v220, v204, v220
	v_mul_f32_e32 v221, v205, v221
	v_mul_f32_e32 v222, v206, v222
	v_mul_f32_e32 v223, v207, v223
	v_mul_f32_e32 v224, v208, v224
	v_mul_f32_e32 v225, v209, v225
	v_mul_f32_e32 v226, v210, v226
	v_mul_f32_e32 v227, v211, v227
	v_cvt_pk_bf16_f32 v204, v220, v221
	v_cvt_pk_bf16_f32 v205, v222, v223
	v_cvt_pk_bf16_f32 v206, v224, v225
	v_cvt_pk_bf16_f32 v207, v226, v227
	global_store_dwordx4 v25, v[204:207], s[54:55] sc1
	s_add_u32 s54, s54, 0x1000
	s_addc_u32 s55, s55, 0
	s_waitcnt vmcnt(15)
	v_and_b32_e32 v152, s63, v152
	v_and_b32_e32 v153, s63, v153
	v_and_b32_e32 v154, s63, v154
	v_and_b32_e32 v155, s63, v155
	v_lshlrev_b32_e32 v172, 16, v152
	v_and_b32_e32 v173, 0xffff0000, v152
	v_lshlrev_b32_e32 v174, 16, v153
	v_and_b32_e32 v175, 0xffff0000, v153
	v_lshlrev_b32_e32 v176, 16, v154
	v_and_b32_e32 v177, 0xffff0000, v154
	v_lshlrev_b32_e32 v178, 16, v155
	v_and_b32_e32 v179, 0xffff0000, v155
	v_pk_fma_f32 v[180:181], v[52:53], v[172:173], v[180:181]
	v_pk_fma_f32 v[182:183], v[54:55], v[174:175], v[182:183]
	v_pk_fma_f32 v[184:185], v[56:57], v[176:177], v[184:185]
	v_pk_fma_f32 v[186:187], v[58:59], v[178:179], v[186:187]
	v_pk_fma_f32 v[212:213], v[60:61], v[172:173], v[212:213]
	v_pk_fma_f32 v[214:215], v[62:63], v[174:175], v[214:215]
	v_pk_fma_f32 v[216:217], v[64:65], v[176:177], v[216:217]
	v_pk_fma_f32 v[218:219], v[66:67], v[178:179], v[218:219]
	v_mul_f32_e32 v220, 0xbfb8aa3b, v212
	v_mul_f32_e32 v221, 0xbfb8aa3b, v213
	v_mul_f32_e32 v222, 0xbfb8aa3b, v214
	v_mul_f32_e32 v223, 0xbfb8aa3b, v215
	v_mul_f32_e32 v224, 0xbfb8aa3b, v216
	v_mul_f32_e32 v225, 0xbfb8aa3b, v217
	v_mul_f32_e32 v226, 0xbfb8aa3b, v218
	v_mul_f32_e32 v227, 0xbfb8aa3b, v219
	v_exp_f32_e32 v220, v220
	v_exp_f32_e32 v221, v221
	v_exp_f32_e32 v222, v222
	v_exp_f32_e32 v223, v223
	v_exp_f32_e32 v224, v224
	v_exp_f32_e32 v225, v225
	v_exp_f32_e32 v226, v226
	v_exp_f32_e32 v227, v227
	v_add_f32_e32 v220, 1.0, v220
	v_add_f32_e32 v221, 1.0, v221
	v_add_f32_e32 v222, 1.0, v222
	v_add_f32_e32 v223, 1.0, v223
	v_add_f32_e32 v224, 1.0, v224
	v_add_f32_e32 v225, 1.0, v225
	v_add_f32_e32 v226, 1.0, v226
	v_add_f32_e32 v227, 1.0, v227
	v_rcp_f32_e32 v220, v220
	v_rcp_f32_e32 v221, v221
	v_rcp_f32_e32 v222, v222
	v_rcp_f32_e32 v223, v223
	v_rcp_f32_e32 v224, v224
	v_rcp_f32_e32 v225, v225
	v_rcp_f32_e32 v226, v226
	v_rcp_f32_e32 v227, v227
	v_mul_f32_e32 v220, v212, v220
	v_mul_f32_e32 v221, v213, v221
	v_mul_f32_e32 v222, v214, v222
	v_mul_f32_e32 v223, v215, v223
	v_mul_f32_e32 v224, v216, v224
	v_mul_f32_e32 v225, v217, v225
	v_mul_f32_e32 v226, v218, v226
	v_mul_f32_e32 v227, v219, v227
	v_cvt_pk_bf16_f32 v212, v220, v221
	v_cvt_pk_bf16_f32 v213, v222, v223
	v_cvt_pk_bf16_f32 v214, v224, v225
	v_cvt_pk_bf16_f32 v215, v226, v227
	global_store_dwordx4 v25, v[212:215], s[54:55] sc1
	s_add_u32 s54, s54, 0x1000
	s_addc_u32 s55, s55, 0
	s_waitcnt vmcnt(15)
	v_and_b32_e32 v156, s63, v156
	v_and_b32_e32 v157, s63, v157
	v_and_b32_e32 v158, s63, v158
	v_and_b32_e32 v159, s63, v159
	v_lshlrev_b32_e32 v172, 16, v156
	v_and_b32_e32 v173, 0xffff0000, v156
	v_lshlrev_b32_e32 v174, 16, v157
	v_and_b32_e32 v175, 0xffff0000, v157
	v_lshlrev_b32_e32 v176, 16, v158
	v_and_b32_e32 v177, 0xffff0000, v158
	v_lshlrev_b32_e32 v178, 16, v159
	v_and_b32_e32 v179, 0xffff0000, v159
	v_pk_fma_f32 v[180:181], v[60:61], v[172:173], v[180:181]
	v_pk_fma_f32 v[182:183], v[62:63], v[174:175], v[182:183]
	v_pk_fma_f32 v[184:185], v[64:65], v[176:177], v[184:185]
	v_pk_fma_f32 v[186:187], v[66:67], v[178:179], v[186:187]
	v_mul_f32_e32 v220, 0xbfb8aa3b, v180
	v_mul_f32_e32 v221, 0xbfb8aa3b, v181
	v_mul_f32_e32 v222, 0xbfb8aa3b, v182
	v_mul_f32_e32 v223, 0xbfb8aa3b, v183
	v_mul_f32_e32 v224, 0xbfb8aa3b, v184
	v_mul_f32_e32 v225, 0xbfb8aa3b, v185
	v_mul_f32_e32 v226, 0xbfb8aa3b, v186
	v_mul_f32_e32 v227, 0xbfb8aa3b, v187
	v_exp_f32_e32 v220, v220
	v_exp_f32_e32 v221, v221
	v_exp_f32_e32 v222, v222
	v_exp_f32_e32 v223, v223
	v_exp_f32_e32 v224, v224
	v_exp_f32_e32 v225, v225
	v_exp_f32_e32 v226, v226
	v_exp_f32_e32 v227, v227
	v_add_f32_e32 v220, 1.0, v220
	v_add_f32_e32 v221, 1.0, v221
	v_add_f32_e32 v222, 1.0, v222
	v_add_f32_e32 v223, 1.0, v223
	v_add_f32_e32 v224, 1.0, v224
	v_add_f32_e32 v225, 1.0, v225
	v_add_f32_e32 v226, 1.0, v226
	v_add_f32_e32 v227, 1.0, v227
	v_rcp_f32_e32 v220, v220
	v_rcp_f32_e32 v221, v221
	v_rcp_f32_e32 v222, v222
	v_rcp_f32_e32 v223, v223
	v_rcp_f32_e32 v224, v224
	v_rcp_f32_e32 v225, v225
	v_rcp_f32_e32 v226, v226
	v_rcp_f32_e32 v227, v227
	v_mul_f32_e32 v220, v180, v220
	v_mul_f32_e32 v221, v181, v221
	v_mul_f32_e32 v222, v182, v222
	v_mul_f32_e32 v223, v183, v223
	v_mul_f32_e32 v224, v184, v224
	v_mul_f32_e32 v225, v185, v225
	v_mul_f32_e32 v226, v186, v226
	v_mul_f32_e32 v227, v187, v227
	v_cvt_pk_bf16_f32 v180, v220, v221
	v_cvt_pk_bf16_f32 v181, v222, v223
	v_cvt_pk_bf16_f32 v182, v224, v225
	v_cvt_pk_bf16_f32 v183, v226, v227
	global_store_dwordx4 v25, v[180:183], s[54:55] sc1
	s_add_u32 s54, s54, 0x1000
	s_addc_u32 s55, s55, 0
	s_add_u32 s3, s3, s64
	s_branch .Lcv19_rb

.LBB0_2292:
	s_cmp_gt_i32 s60, 22
	s_cselect_b64 s[2:3], -1, 0
	s_cmp_lt_i32 s61, 22
	s_cselect_b64 s[4:5], -1, 0
	s_or_b64 s[2:3], s[2:3], s[4:5]
	s_and_b64 vcc, exec, s[2:3]
	s_cbranch_vccnz .LBB0_2352
	s_load_dwordx2 s[4:5], s[0:1], 0xe0
	s_load_dword s16, s[0:1], 0xf0
	v_and_b32_e32 v240, 63, v162
	v_lshrrev_b32_e32 v247, 6, v162
	v_lshrrev_b32_e32 v242, 3, v240
	v_lshl_add_u32 v242, v247, 5, v242
	v_and_b32_e32 v243, 7, v240
	v_lshrrev_b32_e32 v244, 4, v240
	v_xor_b32_e32 v243, v243, v244
	v_lshlrev_b32_e32 v243, 4, v243
	v_mov_b32_e32 v241, 0x1000
	v_mad_u32_u24 v248, v242, v241, v243
	v_xor_b32_e32 v249, 64, v248
	v_add_u32_e32 v249, 0x8000, v249
	v_add_u32_e32 v250, 0x10000, v248
	v_xor_b32_e32 v251, 64, v248
	v_add_u32_e32 v251, 0x18000, v251
	v_and_b32_e32 v241, 15, v240
	v_lshrrev_b32_e32 v242, 1, v241
	v_xor_b32_e32 v242, v242, v244
	v_lshlrev_b32_e32 v242, 4, v242
	v_lshl_or_b32 v242, v241, 7, v242
	v_lshrrev_b32_e32 v243, 1, v247
	v_lshl_or_b32 v252, v243, 13, v242
	v_xor_b32_e32 v253, 64, v252
	v_and_b32_e32 v243, 1, v247
	v_lshl_or_b32 v254, v243, 13, v242
	v_xor_b32_e32 v255, 64, v254
	v_and_b32_e32 v240, 63, v162
	v_and_b32_e32 v241, 15, v240
	v_lshrrev_b32_e32 v242, 4, v240
	v_lshrrev_b32_e32 v243, 1, v247
	v_and_b32_e32 v244, 1, v247
	v_lshl_or_b32 v245, v244, 6, v241
	v_lshlrev_b32_e32 v243, 4, v243
	v_add_u32_e32 v243, v243, v242
	v_lshl_add_u32 v246, v243, 12, v245
	v_lshlrev_b32_e32 v246, 2, v246
	v_lshlrev_b32_e32 v245, 2, v245
	s_waitcnt lgkmcnt(0)
	s_add_u32 s26, s4, 0x1257a100
	s_addc_u32 s27, s5, 0
	s_add_u32 s28, s4, 0x1c80000
	s_addc_u32 s29, s5, 0
	s_mov_b32 s15, s58
.Lr22_tile:
	s_cmp_lt_u32 s15, 0x200
	s_cbranch_scc0 .Lr22_end
	s_and_b32 s2, s15, 63
	s_lshr_b32 s3, s15, 6
	s_mul_i32 s14, s2, 0x80000
	s_add_u32 s8, s26, s14
	s_addc_u32 s9, s27, 0
	s_mul_i32 s14, s3, 0x80000
	s_add_u32 s10, s28, s14
	s_addc_u32 s11, s29, 0
	s_lshl_b32 s14, s2, 19
	s_lshl_b32 s6, s3, 9
	s_add_u32 s14, s14, s6
	s_add_u32 s20, s4, 0x6b7a100
	s_addc_u32 s21, s5, 0
	s_add_u32 s20, s20, s14
	s_addc_u32 s21, s21, 0
	s_sub_u32 s7, s2, 32
	s_lshr_b32 s7, s7, 3
	s_add_u32 s7, s7, 1
	s_cmp_lt_u32 s2, 32
	s_cselect_b32 s7, 0, s7
	s_mul_i32 s7, s7, 0x6000
	s_add_u32 s7, s7, s6
	s_add_u32 s22, s4, 0x6b40000
	s_addc_u32 s23, s5, 0
	s_add_u32 s22, s22, s7
	s_addc_u32 s23, s23, 0
	v_readfirstlane_b32 s12, v247
	global_load_dword v201, v245, s[22:23] offset:0
	global_load_dword v202, v245, s[22:23] offset:64
	global_load_dword v203, v245, s[22:23] offset:128
	global_load_dword v204, v245, s[22:23] offset:192
	s_mov_b64 s[18:19], s[20:21]
	global_load_dword v129, v246, s[18:19] offset:0
	global_load_dword v130, v246, s[18:19] offset:64
	global_load_dword v131, v246, s[18:19] offset:128
	global_load_dword v132, v246, s[18:19] offset:192
	s_add_u32 s18, s18, 0x1000
	s_addc_u32 s19, s19, 0
	global_load_dword v133, v246, s[18:19] offset:0
	global_load_dword v134, v246, s[18:19] offset:64
	global_load_dword v135, v246, s[18:19] offset:128
	global_load_dword v136, v246, s[18:19] offset:192
	s_add_u32 s18, s18, 0x1000
	s_addc_u32 s19, s19, 0
	global_load_dword v137, v246, s[18:19] offset:0
	global_load_dword v138, v246, s[18:19] offset:64
	global_load_dword v139, v246, s[18:19] offset:128
	global_load_dword v140, v246, s[18:19] offset:192
	s_add_u32 s18, s18, 0x1000
	s_addc_u32 s19, s19, 0
	global_load_dword v141, v246, s[18:19] offset:0
	global_load_dword v142, v246, s[18:19] offset:64
	global_load_dword v143, v246, s[18:19] offset:128
	global_load_dword v144, v246, s[18:19] offset:192
	s_add_u32 s18, s18, 0xd000
	s_addc_u32 s19, s19, 0
	global_load_dword v145, v246, s[18:19] offset:0
	global_load_dword v146, v246, s[18:19] offset:64
	global_load_dword v147, v246, s[18:19] offset:128
	global_load_dword v148, v246, s[18:19] offset:192
	s_add_u32 s18, s18, 0x1000
	s_addc_u32 s19, s19, 0
	global_load_dword v149, v246, s[18:19] offset:0
	global_load_dword v150, v246, s[18:19] offset:64
	global_load_dword v151, v246, s[18:19] offset:128
	global_load_dword v152, v246, s[18:19] offset:192
	s_add_u32 s18, s18, 0x1000
	s_addc_u32 s19, s19, 0
	global_load_dword v153, v246, s[18:19] offset:0
	global_load_dword v154, v246, s[18:19] offset:64
	global_load_dword v155, v246, s[18:19] offset:128
	global_load_dword v156, v246, s[18:19] offset:192
	s_add_u32 s18, s18, 0x1000
	s_addc_u32 s19, s19, 0
	global_load_dword v157, v246, s[18:19] offset:0
	global_load_dword v158, v246, s[18:19] offset:64
	global_load_dword v159, v246, s[18:19] offset:128
	global_load_dword v160, v246, s[18:19] offset:192
	s_add_u32 s18, s18, 0xd000
	s_addc_u32 s19, s19, 0
	global_load_dword v161, v246, s[18:19] offset:0
	global_load_dword v170, v246, s[18:19] offset:64
	global_load_dword v171, v246, s[18:19] offset:128
	global_load_dword v172, v246, s[18:19] offset:192
	s_add_u32 s18, s18, 0x1000
	s_addc_u32 s19, s19, 0
	global_load_dword v173, v246, s[18:19] offset:0
	global_load_dword v174, v246, s[18:19] offset:64
	global_load_dword v175, v246, s[18:19] offset:128
	global_load_dword v176, v246, s[18:19] offset:192
	s_add_u32 s18, s18, 0x1000
	s_addc_u32 s19, s19, 0
	global_load_dword v177, v246, s[18:19] offset:0
	global_load_dword v178, v246, s[18:19] offset:64
	global_load_dword v179, v246, s[18:19] offset:128
	global_load_dword v180, v246, s[18:19] offset:192
	s_add_u32 s18, s18, 0x1000
	s_addc_u32 s19, s19, 0
	global_load_dword v181, v246, s[18:19] offset:0
	global_load_dword v182, v246, s[18:19] offset:64
	global_load_dword v183, v246, s[18:19] offset:128
	global_load_dword v184, v246, s[18:19] offset:192
	s_add_u32 s18, s18, 0xd000
	s_addc_u32 s19, s19, 0
	global_load_dword v185, v246, s[18:19] offset:0
	global_load_dword v186, v246, s[18:19] offset:64
	global_load_dword v187, v246, s[18:19] offset:128
	global_load_dword v188, v246, s[18:19] offset:192
	s_add_u32 s18, s18, 0x1000
	s_addc_u32 s19, s19, 0
	global_load_dword v189, v246, s[18:19] offset:0
	global_load_dword v190, v246, s[18:19] offset:64
	global_load_dword v191, v246, s[18:19] offset:128
	global_load_dword v192, v246, s[18:19] offset:192
	s_add_u32 s18, s18, 0x1000
	s_addc_u32 s19, s19, 0
	global_load_dword v193, v246, s[18:19] offset:0
	global_load_dword v194, v246, s[18:19] offset:64
	global_load_dword v195, v246, s[18:19] offset:128
	global_load_dword v196, v246, s[18:19] offset:192
	s_add_u32 s18, s18, 0x1000
	s_addc_u32 s19, s19, 0
	global_load_dword v197, v246, s[18:19] offset:0
	global_load_dword v198, v246, s[18:19] offset:64
	global_load_dword v199, v246, s[18:19] offset:128
	global_load_dword v200, v246, s[18:19] offset:192
	s_lshl_b32 s12, s12, 12
	s_add_u32 m0, s12, 0x0
	v_mov_b32_e32 v0, 0
	global_load_lds_dwordx4 v248, s[8:9]
	v_mov_b32_e32 v1, 0
	s_add_u32 m0, s12, 0x400
	v_mov_b32_e32 v2, 0
	global_load_lds_dwordx4 v249, s[8:9]
	v_mov_b32_e32 v3, 0
	s_add_u32 m0, s12, 0x800
	v_mov_b32_e32 v4, 0
	global_load_lds_dwordx4 v250, s[8:9]
	v_mov_b32_e32 v5, 0
	s_add_u32 m0, s12, 0xc00
	v_mov_b32_e32 v6, 0
	global_load_lds_dwordx4 v251, s[8:9]
	v_mov_b32_e32 v7, 0
	s_add_u32 m0, s12, 0x8000
	v_mov_b32_e32 v8, 0
	global_load_lds_dwordx4 v248, s[10:11]
	v_mov_b32_e32 v9, 0
	s_add_u32 m0, s12, 0x8400
	v_mov_b32_e32 v10, 0
	global_load_lds_dwordx4 v249, s[10:11]
	v_mov_b32_e32 v11, 0
	s_add_u32 m0, s12, 0x8800
	v_mov_b32_e32 v12, 0
	global_load_lds_dwordx4 v250, s[10:11]
	v_mov_b32_e32 v13, 0
	s_add_u32 m0, s12, 0x8c00
	v_mov_b32_e32 v14, 0
	global_load_lds_dwordx4 v251, s[10:11]
	v_mov_b32_e32 v15, 0
	s_add_u32 s8, s8, 0x80
	s_addc_u32 s9, s9, 0
	s_add_u32 s10, s10, 0x80
	s_addc_u32 s11, s11, 0
	s_add_u32 m0, s12, 0x4000
	v_mov_b32_e32 v16, 0
	global_load_lds_dwordx4 v248, s[8:9]
	v_mov_b32_e32 v17, 0
	s_add_u32 m0, s12, 0x4400
	v_mov_b32_e32 v18, 0
	global_load_lds_dwordx4 v249, s[8:9]
	v_mov_b32_e32 v19, 0
	s_add_u32 m0, s12, 0x4800
	v_mov_b32_e32 v20, 0
	global_load_lds_dwordx4 v250, s[8:9]
	v_mov_b32_e32 v21, 0
	s_add_u32 m0, s12, 0x4c00
	v_mov_b32_e32 v22, 0
	global_load_lds_dwordx4 v251, s[8:9]
	v_mov_b32_e32 v23, 0
	s_add_u32 m0, s12, 0xc000
	v_mov_b32_e32 v24, 0
	global_load_lds_dwordx4 v248, s[10:11]
	v_mov_b32_e32 v25, 0
	s_add_u32 m0, s12, 0xc400
	v_mov_b32_e32 v26, 0
	global_load_lds_dwordx4 v249, s[10:11]
	v_mov_b32_e32 v27, 0
	s_add_u32 m0, s12, 0xc800
	v_mov_b32_e32 v28, 0
	global_load_lds_dwordx4 v250, s[10:11]
	v_mov_b32_e32 v29, 0
	s_add_u32 m0, s12, 0xcc00
	v_mov_b32_e32 v30, 0
	global_load_lds_dwordx4 v251, s[10:11]
	v_mov_b32_e32 v31, 0
	s_add_u32 s8, s8, 0x80
	s_addc_u32 s9, s9, 0
	s_add_u32 s10, s10, 0x80
	s_addc_u32 s11, s11, 0
	v_mov_b32_e32 v32, 0
	v_mov_b32_e32 v33, 0
	v_mov_b32_e32 v34, 0
	v_mov_b32_e32 v35, 0
	v_mov_b32_e32 v36, 0
	v_mov_b32_e32 v37, 0
	v_mov_b32_e32 v38, 0
	v_mov_b32_e32 v39, 0
	v_mov_b32_e32 v40, 0
	v_mov_b32_e32 v41, 0
	v_mov_b32_e32 v42, 0
	v_mov_b32_e32 v43, 0
	v_mov_b32_e32 v44, 0
	v_mov_b32_e32 v45, 0
	v_mov_b32_e32 v46, 0
	v_mov_b32_e32 v47, 0
	v_mov_b32_e32 v48, 0
	v_mov_b32_e32 v49, 0
	v_mov_b32_e32 v50, 0
	v_mov_b32_e32 v51, 0
	v_mov_b32_e32 v52, 0
	v_mov_b32_e32 v53, 0
	v_mov_b32_e32 v54, 0
	v_mov_b32_e32 v55, 0
	v_mov_b32_e32 v56, 0
	v_mov_b32_e32 v57, 0
	v_mov_b32_e32 v58, 0
	v_mov_b32_e32 v59, 0
	v_mov_b32_e32 v60, 0
	v_mov_b32_e32 v61, 0
	v_mov_b32_e32 v62, 0
	v_mov_b32_e32 v63, 0
	s_waitcnt vmcnt(8)
	s_barrier
	ds_read_b128 v[64:67], v252 offset:0
	ds_read_b128 v[96:99], v254 offset:32768
	ds_read_b128 v[100:103], v254 offset:34816
	ds_read_b128 v[104:107], v254 offset:36864
	ds_read_b128 v[108:111], v254 offset:38912
	ds_read_b128 v[68:71], v252 offset:2048
	ds_read_b128 v[72:75], v252 offset:4096
	ds_read_b128 v[76:79], v252 offset:6144
	ds_read_b128 v[80:83], v253 offset:0
	ds_read_b128 v[112:115], v255 offset:32768
	ds_read_b128 v[116:119], v255 offset:34816
	ds_read_b128 v[120:123], v255 offset:36864
	ds_read_b128 v[124:127], v255 offset:38912
	s_waitcnt lgkmcnt(11)
	v_mfma_f32_16x16x32_bf16 v[0:3], v[64:67], v[96:99], v[0:3]
	s_waitcnt lgkmcnt(10)
	v_mfma_f32_16x16x32_bf16 v[4:7], v[64:67], v[100:103], v[4:7]
	s_waitcnt lgkmcnt(9)
	v_mfma_f32_16x16x32_bf16 v[8:11], v[64:67], v[104:107], v[8:11]
	s_waitcnt lgkmcnt(8)
	v_mfma_f32_16x16x32_bf16 v[12:15], v[64:67], v[108:111], v[12:15]
	ds_read_b128 v[84:87], v253 offset:2048
	ds_read_b128 v[88:91], v253 offset:4096
	ds_read_b128 v[92:95], v253 offset:6144
	s_waitcnt lgkmcnt(10)
	v_mfma_f32_16x16x32_bf16 v[16:19], v[68:71], v[96:99], v[16:19]
	v_mfma_f32_16x16x32_bf16 v[20:23], v[68:71], v[100:103], v[20:23]
	v_mfma_f32_16x16x32_bf16 v[24:27], v[68:71], v[104:107], v[24:27]
	v_mfma_f32_16x16x32_bf16 v[28:31], v[68:71], v[108:111], v[28:31]
	s_waitcnt lgkmcnt(0)
	s_barrier
	s_add_u32 m0, s12, 0x0
	v_mfma_f32_16x16x32_bf16 v[32:35], v[72:75], v[96:99], v[32:35]
	global_load_lds_dwordx4 v248, s[8:9]
	s_add_u32 m0, s12, 0x400
	v_mfma_f32_16x16x32_bf16 v[36:39], v[72:75], v[100:103], v[36:39]
	global_load_lds_dwordx4 v249, s[8:9]
	s_add_u32 m0, s12, 0x800
	v_mfma_f32_16x16x32_bf16 v[40:43], v[72:75], v[104:107], v[40:43]
	global_load_lds_dwordx4 v250, s[8:9]
	s_add_u32 m0, s12, 0xc00
	v_mfma_f32_16x16x32_bf16 v[44:47], v[72:75], v[108:111], v[44:47]
	global_load_lds_dwordx4 v251, s[8:9]
	s_add_u32 m0, s12, 0x8000
	v_mfma_f32_16x16x32_bf16 v[48:51], v[76:79], v[96:99], v[48:51]
	global_load_lds_dwordx4 v248, s[10:11]
	s_add_u32 m0, s12, 0x8400
	v_mfma_f32_16x16x32_bf16 v[52:55], v[76:79], v[100:103], v[52:55]
	global_load_lds_dwordx4 v249, s[10:11]
	s_add_u32 m0, s12, 0x8800
	v_mfma_f32_16x16x32_bf16 v[56:59], v[76:79], v[104:107], v[56:59]
	global_load_lds_dwordx4 v250, s[10:11]
	s_add_u32 m0, s12, 0x8c00
	v_mfma_f32_16x16x32_bf16 v[60:63], v[76:79], v[108:111], v[60:63]
	global_load_lds_dwordx4 v251, s[10:11]
	s_add_u32 s8, s8, 0x80
	s_addc_u32 s9, s9, 0
	s_add_u32 s10, s10, 0x80
	s_addc_u32 s11, s11, 0
	s_waitcnt vmcnt(8)
	s_barrier
	ds_read_b128 v[64:67], v252 offset:16384
	ds_read_b128 v[96:99], v254 offset:49152
	ds_read_b128 v[100:103], v254 offset:51200
	ds_read_b128 v[104:107], v254 offset:53248
	ds_read_b128 v[108:111], v254 offset:55296
	ds_read_b128 v[68:71], v252 offset:18432
	ds_read_b128 v[72:75], v252 offset:20480
	ds_read_b128 v[76:79], v252 offset:22528
	v_mfma_f32_16x16x32_bf16 v[0:3], v[80:83], v[112:115], v[0:3]
	v_mfma_f32_16x16x32_bf16 v[4:7], v[80:83], v[116:119], v[4:7]
	v_mfma_f32_16x16x32_bf16 v[8:11], v[80:83], v[120:123], v[8:11]
	v_mfma_f32_16x16x32_bf16 v[12:15], v[80:83], v[124:127], v[12:15]
	v_mfma_f32_16x16x32_bf16 v[16:19], v[84:87], v[112:115], v[16:19]
	v_mfma_f32_16x16x32_bf16 v[20:23], v[84:87], v[116:119], v[20:23]
	v_mfma_f32_16x16x32_bf16 v[24:27], v[84:87], v[120:123], v[24:27]
	v_mfma_f32_16x16x32_bf16 v[28:31], v[84:87], v[124:127], v[28:31]
	v_mfma_f32_16x16x32_bf16 v[32:35], v[88:91], v[112:115], v[32:35]
	v_mfma_f32_16x16x32_bf16 v[36:39], v[88:91], v[116:119], v[36:39]
	v_mfma_f32_16x16x32_bf16 v[40:43], v[88:91], v[120:123], v[40:43]
	v_mfma_f32_16x16x32_bf16 v[44:47], v[88:91], v[124:127], v[44:47]
	v_mfma_f32_16x16x32_bf16 v[48:51], v[92:95], v[112:115], v[48:51]
	v_mfma_f32_16x16x32_bf16 v[52:55], v[92:95], v[116:119], v[52:55]
	v_mfma_f32_16x16x32_bf16 v[56:59], v[92:95], v[120:123], v[56:59]
	v_mfma_f32_16x16x32_bf16 v[60:63], v[92:95], v[124:127], v[60:63]
	ds_read_b128 v[80:83], v253 offset:16384
	ds_read_b128 v[112:115], v255 offset:49152
	ds_read_b128 v[116:119], v255 offset:51200
	ds_read_b128 v[120:123], v255 offset:53248
	ds_read_b128 v[124:127], v255 offset:55296
	ds_read_b128 v[84:87], v253 offset:18432
	ds_read_b128 v[88:91], v253 offset:20480
	ds_read_b128 v[92:95], v253 offset:22528
	s_waitcnt lgkmcnt(14)
	v_mfma_f32_16x16x32_bf16 v[0:3], v[64:67], v[96:99], v[0:3]
	s_waitcnt lgkmcnt(13)
	v_mfma_f32_16x16x32_bf16 v[4:7], v[64:67], v[100:103], v[4:7]
	s_waitcnt lgkmcnt(12)
	v_mfma_f32_16x16x32_bf16 v[8:11], v[64:67], v[104:107], v[8:11]
	s_waitcnt lgkmcnt(11)
	v_mfma_f32_16x16x32_bf16 v[12:15], v[64:67], v[108:111], v[12:15]
	s_waitcnt lgkmcnt(10)
	v_mfma_f32_16x16x32_bf16 v[16:19], v[68:71], v[96:99], v[16:19]
	v_mfma_f32_16x16x32_bf16 v[20:23], v[68:71], v[100:103], v[20:23]
	v_mfma_f32_16x16x32_bf16 v[24:27], v[68:71], v[104:107], v[24:27]
	v_mfma_f32_16x16x32_bf16 v[28:31], v[68:71], v[108:111], v[28:31]
	s_waitcnt lgkmcnt(0)
	s_barrier
	s_add_u32 m0, s12, 0x4000
	v_mfma_f32_16x16x32_bf16 v[32:35], v[72:75], v[96:99], v[32:35]
	global_load_lds_dwordx4 v248, s[8:9]
	s_add_u32 m0, s12, 0x4400
	v_mfma_f32_16x16x32_bf16 v[36:39], v[72:75], v[100:103], v[36:39]
	global_load_lds_dwordx4 v249, s[8:9]
	s_add_u32 m0, s12, 0x4800
	v_mfma_f32_16x16x32_bf16 v[40:43], v[72:75], v[104:107], v[40:43]
	global_load_lds_dwordx4 v250, s[8:9]
	s_add_u32 m0, s12, 0x4c00
	v_mfma_f32_16x16x32_bf16 v[44:47], v[72:75], v[108:111], v[44:47]
	global_load_lds_dwordx4 v251, s[8:9]
	s_add_u32 m0, s12, 0xc000
	v_mfma_f32_16x16x32_bf16 v[48:51], v[76:79], v[96:99], v[48:51]
	global_load_lds_dwordx4 v248, s[10:11]
	s_add_u32 m0, s12, 0xc400
	v_mfma_f32_16x16x32_bf16 v[52:55], v[76:79], v[100:103], v[52:55]
	global_load_lds_dwordx4 v249, s[10:11]
	s_add_u32 m0, s12, 0xc800
	v_mfma_f32_16x16x32_bf16 v[56:59], v[76:79], v[104:107], v[56:59]
	global_load_lds_dwordx4 v250, s[10:11]
	s_add_u32 m0, s12, 0xcc00
	v_mfma_f32_16x16x32_bf16 v[60:63], v[76:79], v[108:111], v[60:63]
	global_load_lds_dwordx4 v251, s[10:11]
	s_add_u32 s8, s8, 0x80
	s_addc_u32 s9, s9, 0
	s_add_u32 s10, s10, 0x80
	s_addc_u32 s11, s11, 0
	s_mov_b32 s13, 14

.Lr22_end:
.LBB0_2298:
	s_cmp_lt_i32 s61, 23
	s_cbranch_scc1 .LBB0_2352
	s_waitcnt vmcnt(0)
	s_waitcnt vmcnt(63) expcnt(7) lgkmcnt(15)
	s_barrier
	s_and_saveexec_b64 s[4:5], s[52:53]
	s_cbranch_execz .LBB0_2351
	v_mov_b32_e32 v0, 0x12000
	s_waitcnt vmcnt(0) expcnt(0) lgkmcnt(0)
	ds_read_b32 v2, v0
	v_mov_b32_e32 v0, 0x12004
	ds_read_b32 v0, v0
	s_waitcnt lgkmcnt(1)
	v_cmp_ne_u32_e32 vcc, 0, v2
	s_cbranch_vccnz .LBB0_2315
	s_load_dwordx2 s[2:3], s[0:1], 0xf0
	s_load_dword s9, s[0:1], 0xf8
	s_add_u32 s6, s56, 0x1457a300
	s_addc_u32 s7, s57, 0
	s_add_u32 s8, s56, 0x1457a500
	s_waitcnt lgkmcnt(0)
	s_mul_i32 s2, s3, s2
	s_mul_i32 s2, s2, s9
	s_addc_u32 s9, s57, 0
	s_add_u32 s10, s56, 0x1457a600
	s_addc_u32 s11, s57, 0
	s_add_u32 s12, s56, 0x1457a700
	s_addc_u32 s13, s57, 0
	s_add_u32 s14, s56, 0x1457a800
	s_addc_u32 s15, s57, 0
	s_add_u32 s16, s56, 0x1457a900
	s_addc_u32 s17, s57, 0
	s_add_u32 s18, s56, 0x1457aa00
	s_addc_u32 s19, s57, 0
	s_add_u32 s20, s56, 0x1457ab00
	s_addc_u32 s21, s57, 0
	s_add_u32 s22, s56, 0x1457ac00
	s_addc_u32 s23, s57, 0
	s_add_u32 s24, s56, 0x1457ad00
	s_addc_u32 s25, s57, 0
	s_add_u32 s26, s56, 0x1457ae00
	s_addc_u32 s27, s57, 0
	s_add_u32 s28, s56, 0x1457af00
	s_addc_u32 s29, s57, 0
	s_add_u32 s30, s56, 0x1457b000
	s_addc_u32 s31, s57, 0
	s_add_u32 s34, s56, 0x1457b100
	s_addc_u32 s35, s57, 0
	s_add_u32 s36, s56, 0x1457b200
	s_addc_u32 s37, s57, 0
	s_add_u32 s38, s56, 0x1457b300
	s_addc_u32 s39, s57, 0
	s_add_u32 s40, s56, 0x1457b400
	s_addc_u32 s41, s57, 0
	s_mov_b32 s3, 1
	v_mov_b32_e32 v16, 0
	s_branch .LBB0_2303

.LBB0_2474:
	s_cmp_gt_i32 s60, 25
	s_cselect_b64 s[2:3], -1, 0
	s_cmp_lt_i32 s61, 25
	s_cselect_b64 s[4:5], -1, 0
	s_or_b64 s[2:3], s[2:3], s[4:5]
	s_and_b64 vcc, exec, s[2:3]
	s_cbranch_vccnz .LBB0_2534
	s_load_dwordx2 s[4:5], s[0:1], 0xe0
	s_load_dword s16, s[0:1], 0xf0
	v_and_b32_e32 v240, 63, v162
	v_lshrrev_b32_e32 v247, 6, v162
	v_lshrrev_b32_e32 v242, 3, v240
	v_lshl_add_u32 v242, v247, 5, v242
	v_and_b32_e32 v243, 7, v240
	v_lshrrev_b32_e32 v244, 4, v240
	v_xor_b32_e32 v243, v243, v244
	v_lshlrev_b32_e32 v243, 4, v243
	v_mov_b32_e32 v241, 0x1600
	v_mad_u32_u24 v248, v242, v241, v243
	v_xor_b32_e32 v249, 64, v248
	v_add_u32_e32 v249, 0xb000, v249
	v_add_u32_e32 v250, 0x16000, v248
	v_xor_b32_e32 v251, 64, v248
	v_add_u32_e32 v251, 0x21000, v251
	v_and_b32_e32 v241, 15, v240
	v_lshrrev_b32_e32 v242, 1, v241
	v_xor_b32_e32 v242, v242, v244
	v_lshlrev_b32_e32 v242, 4, v242
	v_lshl_or_b32 v242, v241, 7, v242
	v_lshrrev_b32_e32 v243, 1, v247
	v_lshl_or_b32 v252, v243, 13, v242
	v_xor_b32_e32 v253, 64, v252
	v_and_b32_e32 v243, 1, v247
	v_lshl_or_b32 v254, v243, 13, v242
	v_xor_b32_e32 v255, 64, v254
	v_and_b32_e32 v240, 63, v162
	v_and_b32_e32 v241, 15, v240
	v_lshrrev_b32_e32 v242, 4, v240
	v_lshrrev_b32_e32 v243, 1, v247
	v_and_b32_e32 v244, 1, v247
	v_lshl_or_b32 v245, v244, 6, v241
	v_lshlrev_b32_e32 v243, 4, v243
	v_add_u32_e32 v243, v243, v242
	v_lshl_add_u32 v246, v243, 12, v245
	v_lshlrev_b32_e32 v246, 2, v246
	v_lshlrev_b32_e32 v245, 2, v245
	s_waitcnt lgkmcnt(0)
	s_add_u32 s26, s4, 0x9b7a100
	s_addc_u32 s27, s5, 0
	s_add_u32 s28, s4, 0x5b80000
	s_addc_u32 s29, s5, 0
	s_mov_b32 s15, s58
.Lr25_tile:
	s_cmp_lt_u32 s15, 0x200
	s_cbranch_scc0 .Lr25_end
	s_and_b32 s2, s15, 63
	s_lshr_b32 s3, s15, 6
	s_mul_i32 s14, s2, 0xb0000
	s_add_u32 s8, s26, s14
	s_addc_u32 s9, s27, 0
	s_mul_i32 s14, s3, 0xb0000
	s_add_u32 s10, s28, s14
	s_addc_u32 s11, s29, 0
	s_lshl_b32 s14, s2, 19
	s_lshl_b32 s6, s3, 9
	s_add_u32 s14, s14, s6
	s_add_u32 s20, s4, 0x6b7a100
	s_addc_u32 s21, s5, 0
	s_add_u32 s20, s20, s14
	s_addc_u32 s21, s21, 0
	s_sub_u32 s7, s2, 32
	s_lshr_b32 s7, s7, 3
	s_add_u32 s7, s7, 1
	s_cmp_lt_u32 s2, 32
	s_cselect_b32 s7, 0, s7
	s_mul_i32 s7, s7, 0x6000
	s_add_u32 s7, s7, s6
	s_add_u32 s22, s4, 0x6b43000
	s_addc_u32 s23, s5, 0
	s_add_u32 s22, s22, s7
	s_addc_u32 s23, s23, 0
	v_readfirstlane_b32 s12, v247
	global_load_dword v201, v245, s[22:23] offset:0
	global_load_dword v202, v245, s[22:23] offset:64
	global_load_dword v203, v245, s[22:23] offset:128
	global_load_dword v204, v245, s[22:23] offset:192
	s_mov_b64 s[18:19], s[20:21]
	global_load_dword v129, v246, s[18:19] offset:0
	global_load_dword v130, v246, s[18:19] offset:64
	global_load_dword v131, v246, s[18:19] offset:128
	global_load_dword v132, v246, s[18:19] offset:192
	s_add_u32 s18, s18, 0x1000
	s_addc_u32 s19, s19, 0
	global_load_dword v133, v246, s[18:19] offset:0
	global_load_dword v134, v246, s[18:19] offset:64
	global_load_dword v135, v246, s[18:19] offset:128
	global_load_dword v136, v246, s[18:19] offset:192
	s_add_u32 s18, s18, 0x1000
	s_addc_u32 s19, s19, 0
	global_load_dword v137, v246, s[18:19] offset:0
	global_load_dword v138, v246, s[18:19] offset:64
	global_load_dword v139, v246, s[18:19] offset:128
	global_load_dword v140, v246, s[18:19] offset:192
	s_add_u32 s18, s18, 0x1000
	s_addc_u32 s19, s19, 0
	global_load_dword v141, v246, s[18:19] offset:0
	global_load_dword v142, v246, s[18:19] offset:64
	global_load_dword v143, v246, s[18:19] offset:128
	global_load_dword v144, v246, s[18:19] offset:192
	s_add_u32 s18, s18, 0xd000
	s_addc_u32 s19, s19, 0
	global_load_dword v145, v246, s[18:19] offset:0
	global_load_dword v146, v246, s[18:19] offset:64
	global_load_dword v147, v246, s[18:19] offset:128
	global_load_dword v148, v246, s[18:19] offset:192
	s_add_u32 s18, s18, 0x1000
	s_addc_u32 s19, s19, 0
	global_load_dword v149, v246, s[18:19] offset:0
	global_load_dword v150, v246, s[18:19] offset:64
	global_load_dword v151, v246, s[18:19] offset:128
	global_load_dword v152, v246, s[18:19] offset:192
	s_add_u32 s18, s18, 0x1000
	s_addc_u32 s19, s19, 0
	global_load_dword v153, v246, s[18:19] offset:0
	global_load_dword v154, v246, s[18:19] offset:64
	global_load_dword v155, v246, s[18:19] offset:128
	global_load_dword v156, v246, s[18:19] offset:192
	s_add_u32 s18, s18, 0x1000
	s_addc_u32 s19, s19, 0
	global_load_dword v157, v246, s[18:19] offset:0
	global_load_dword v158, v246, s[18:19] offset:64
	global_load_dword v159, v246, s[18:19] offset:128
	global_load_dword v160, v246, s[18:19] offset:192
	s_add_u32 s18, s18, 0xd000
	s_addc_u32 s19, s19, 0
	global_load_dword v161, v246, s[18:19] offset:0
	global_load_dword v170, v246, s[18:19] offset:64
	global_load_dword v171, v246, s[18:19] offset:128
	global_load_dword v172, v246, s[18:19] offset:192
	s_add_u32 s18, s18, 0x1000
	s_addc_u32 s19, s19, 0
	global_load_dword v173, v246, s[18:19] offset:0
	global_load_dword v174, v246, s[18:19] offset:64
	global_load_dword v175, v246, s[18:19] offset:128
	global_load_dword v176, v246, s[18:19] offset:192
	s_add_u32 s18, s18, 0x1000
	s_addc_u32 s19, s19, 0
	global_load_dword v177, v246, s[18:19] offset:0
	global_load_dword v178, v246, s[18:19] offset:64
	global_load_dword v179, v246, s[18:19] offset:128
	global_load_dword v180, v246, s[18:19] offset:192
	s_add_u32 s18, s18, 0x1000
	s_addc_u32 s19, s19, 0
	global_load_dword v181, v246, s[18:19] offset:0
	global_load_dword v182, v246, s[18:19] offset:64
	global_load_dword v183, v246, s[18:19] offset:128
	global_load_dword v184, v246, s[18:19] offset:192
	s_add_u32 s18, s18, 0xd000
	s_addc_u32 s19, s19, 0
	global_load_dword v185, v246, s[18:19] offset:0
	global_load_dword v186, v246, s[18:19] offset:64
	global_load_dword v187, v246, s[18:19] offset:128
	global_load_dword v188, v246, s[18:19] offset:192
	s_add_u32 s18, s18, 0x1000
	s_addc_u32 s19, s19, 0
	global_load_dword v189, v246, s[18:19] offset:0
	global_load_dword v190, v246, s[18:19] offset:64
	global_load_dword v191, v246, s[18:19] offset:128
	global_load_dword v192, v246, s[18:19] offset:192
	s_add_u32 s18, s18, 0x1000
	s_addc_u32 s19, s19, 0
	global_load_dword v193, v246, s[18:19] offset:0
	global_load_dword v194, v246, s[18:19] offset:64
	global_load_dword v195, v246, s[18:19] offset:128
	global_load_dword v196, v246, s[18:19] offset:192
	s_add_u32 s18, s18, 0x1000
	s_addc_u32 s19, s19, 0
	global_load_dword v197, v246, s[18:19] offset:0
	global_load_dword v198, v246, s[18:19] offset:64
	global_load_dword v199, v246, s[18:19] offset:128
	global_load_dword v200, v246, s[18:19] offset:192
	s_lshl_b32 s12, s12, 12
	s_add_u32 m0, s12, 0x0
	v_mov_b32_e32 v0, 0
	global_load_lds_dwordx4 v248, s[8:9]
	v_mov_b32_e32 v1, 0
	s_add_u32 m0, s12, 0x400
	v_mov_b32_e32 v2, 0
	global_load_lds_dwordx4 v249, s[8:9]
	v_mov_b32_e32 v3, 0
	s_add_u32 m0, s12, 0x800
	v_mov_b32_e32 v4, 0
	global_load_lds_dwordx4 v250, s[8:9]
	v_mov_b32_e32 v5, 0
	s_add_u32 m0, s12, 0xc00
	v_mov_b32_e32 v6, 0
	global_load_lds_dwordx4 v251, s[8:9]
	v_mov_b32_e32 v7, 0
	s_add_u32 m0, s12, 0x8000
	v_mov_b32_e32 v8, 0
	global_load_lds_dwordx4 v248, s[10:11]
	v_mov_b32_e32 v9, 0
	s_add_u32 m0, s12, 0x8400
	v_mov_b32_e32 v10, 0
	global_load_lds_dwordx4 v249, s[10:11]
	v_mov_b32_e32 v11, 0
	s_add_u32 m0, s12, 0x8800
	v_mov_b32_e32 v12, 0
	global_load_lds_dwordx4 v250, s[10:11]
	v_mov_b32_e32 v13, 0
	s_add_u32 m0, s12, 0x8c00
	v_mov_b32_e32 v14, 0
	global_load_lds_dwordx4 v251, s[10:11]
	v_mov_b32_e32 v15, 0
	s_add_u32 s8, s8, 0x80
	s_addc_u32 s9, s9, 0
	s_add_u32 s10, s10, 0x80
	s_addc_u32 s11, s11, 0
	s_add_u32 m0, s12, 0x4000
	v_mov_b32_e32 v16, 0
	global_load_lds_dwordx4 v248, s[8:9]
	v_mov_b32_e32 v17, 0
	s_add_u32 m0, s12, 0x4400
	v_mov_b32_e32 v18, 0
	global_load_lds_dwordx4 v249, s[8:9]
	v_mov_b32_e32 v19, 0
	s_add_u32 m0, s12, 0x4800
	v_mov_b32_e32 v20, 0
	global_load_lds_dwordx4 v250, s[8:9]
	v_mov_b32_e32 v21, 0
	s_add_u32 m0, s12, 0x4c00
	v_mov_b32_e32 v22, 0
	global_load_lds_dwordx4 v251, s[8:9]
	v_mov_b32_e32 v23, 0
	s_add_u32 m0, s12, 0xc000
	v_mov_b32_e32 v24, 0
	global_load_lds_dwordx4 v248, s[10:11]
	v_mov_b32_e32 v25, 0
	s_add_u32 m0, s12, 0xc400
	v_mov_b32_e32 v26, 0
	global_load_lds_dwordx4 v249, s[10:11]
	v_mov_b32_e32 v27, 0
	s_add_u32 m0, s12, 0xc800
	v_mov_b32_e32 v28, 0
	global_load_lds_dwordx4 v250, s[10:11]
	v_mov_b32_e32 v29, 0
	s_add_u32 m0, s12, 0xcc00
	v_mov_b32_e32 v30, 0
	global_load_lds_dwordx4 v251, s[10:11]
	v_mov_b32_e32 v31, 0
	s_add_u32 s8, s8, 0x80
	s_addc_u32 s9, s9, 0
	s_add_u32 s10, s10, 0x80
	s_addc_u32 s11, s11, 0
	v_mov_b32_e32 v32, 0
	v_mov_b32_e32 v33, 0
	v_mov_b32_e32 v34, 0
	v_mov_b32_e32 v35, 0
	v_mov_b32_e32 v36, 0
	v_mov_b32_e32 v37, 0
	v_mov_b32_e32 v38, 0
	v_mov_b32_e32 v39, 0
	v_mov_b32_e32 v40, 0
	v_mov_b32_e32 v41, 0
	v_mov_b32_e32 v42, 0
	v_mov_b32_e32 v43, 0
	v_mov_b32_e32 v44, 0
	v_mov_b32_e32 v45, 0
	v_mov_b32_e32 v46, 0
	v_mov_b32_e32 v47, 0
	v_mov_b32_e32 v48, 0
	v_mov_b32_e32 v49, 0
	v_mov_b32_e32 v50, 0
	v_mov_b32_e32 v51, 0
	v_mov_b32_e32 v52, 0
	v_mov_b32_e32 v53, 0
	v_mov_b32_e32 v54, 0
	v_mov_b32_e32 v55, 0
	v_mov_b32_e32 v56, 0
	v_mov_b32_e32 v57, 0
	v_mov_b32_e32 v58, 0
	v_mov_b32_e32 v59, 0
	v_mov_b32_e32 v60, 0
	v_mov_b32_e32 v61, 0
	v_mov_b32_e32 v62, 0
	v_mov_b32_e32 v63, 0
	s_waitcnt vmcnt(8)
	s_barrier
	ds_read_b128 v[64:67], v252 offset:0
	ds_read_b128 v[96:99], v254 offset:32768
	ds_read_b128 v[100:103], v254 offset:34816
	ds_read_b128 v[104:107], v254 offset:36864
	ds_read_b128 v[108:111], v254 offset:38912
	ds_read_b128 v[68:71], v252 offset:2048
	ds_read_b128 v[72:75], v252 offset:4096
	ds_read_b128 v[76:79], v252 offset:6144
	ds_read_b128 v[80:83], v253 offset:0
	ds_read_b128 v[112:115], v255 offset:32768
	ds_read_b128 v[116:119], v255 offset:34816
	ds_read_b128 v[120:123], v255 offset:36864
	ds_read_b128 v[124:127], v255 offset:38912
	s_waitcnt lgkmcnt(11)
	v_mfma_f32_16x16x32_bf16 v[0:3], v[64:67], v[96:99], v[0:3]
	s_waitcnt lgkmcnt(10)
	v_mfma_f32_16x16x32_bf16 v[4:7], v[64:67], v[100:103], v[4:7]
	s_waitcnt lgkmcnt(9)
	v_mfma_f32_16x16x32_bf16 v[8:11], v[64:67], v[104:107], v[8:11]
	s_waitcnt lgkmcnt(8)
	v_mfma_f32_16x16x32_bf16 v[12:15], v[64:67], v[108:111], v[12:15]
	ds_read_b128 v[84:87], v253 offset:2048
	ds_read_b128 v[88:91], v253 offset:4096
	ds_read_b128 v[92:95], v253 offset:6144
	s_waitcnt lgkmcnt(10)
	v_mfma_f32_16x16x32_bf16 v[16:19], v[68:71], v[96:99], v[16:19]
	v_mfma_f32_16x16x32_bf16 v[20:23], v[68:71], v[100:103], v[20:23]
	v_mfma_f32_16x16x32_bf16 v[24:27], v[68:71], v[104:107], v[24:27]
	v_mfma_f32_16x16x32_bf16 v[28:31], v[68:71], v[108:111], v[28:31]
	s_waitcnt lgkmcnt(0)
	s_barrier
	s_add_u32 m0, s12, 0x0
	v_mfma_f32_16x16x32_bf16 v[32:35], v[72:75], v[96:99], v[32:35]
	global_load_lds_dwordx4 v248, s[8:9]
	s_add_u32 m0, s12, 0x400
	v_mfma_f32_16x16x32_bf16 v[36:39], v[72:75], v[100:103], v[36:39]
	global_load_lds_dwordx4 v249, s[8:9]
	s_add_u32 m0, s12, 0x800
	v_mfma_f32_16x16x32_bf16 v[40:43], v[72:75], v[104:107], v[40:43]
	global_load_lds_dwordx4 v250, s[8:9]
	s_add_u32 m0, s12, 0xc00
	v_mfma_f32_16x16x32_bf16 v[44:47], v[72:75], v[108:111], v[44:47]
	global_load_lds_dwordx4 v251, s[8:9]
	s_add_u32 m0, s12, 0x8000
	v_mfma_f32_16x16x32_bf16 v[48:51], v[76:79], v[96:99], v[48:51]
	global_load_lds_dwordx4 v248, s[10:11]
	s_add_u32 m0, s12, 0x8400
	v_mfma_f32_16x16x32_bf16 v[52:55], v[76:79], v[100:103], v[52:55]
	global_load_lds_dwordx4 v249, s[10:11]
	s_add_u32 m0, s12, 0x8800
	v_mfma_f32_16x16x32_bf16 v[56:59], v[76:79], v[104:107], v[56:59]
	global_load_lds_dwordx4 v250, s[10:11]
	s_add_u32 m0, s12, 0x8c00
	v_mfma_f32_16x16x32_bf16 v[60:63], v[76:79], v[108:111], v[60:63]
	global_load_lds_dwordx4 v251, s[10:11]
	s_add_u32 s8, s8, 0x80
	s_addc_u32 s9, s9, 0
	s_add_u32 s10, s10, 0x80
	s_addc_u32 s11, s11, 0
	s_waitcnt vmcnt(8)
	s_barrier
	ds_read_b128 v[64:67], v252 offset:16384
	ds_read_b128 v[96:99], v254 offset:49152
	ds_read_b128 v[100:103], v254 offset:51200
	ds_read_b128 v[104:107], v254 offset:53248
	ds_read_b128 v[108:111], v254 offset:55296
	ds_read_b128 v[68:71], v252 offset:18432
	ds_read_b128 v[72:75], v252 offset:20480
	ds_read_b128 v[76:79], v252 offset:22528
	v_mfma_f32_16x16x32_bf16 v[0:3], v[80:83], v[112:115], v[0:3]
	v_mfma_f32_16x16x32_bf16 v[4:7], v[80:83], v[116:119], v[4:7]
	v_mfma_f32_16x16x32_bf16 v[8:11], v[80:83], v[120:123], v[8:11]
	v_mfma_f32_16x16x32_bf16 v[12:15], v[80:83], v[124:127], v[12:15]
	v_mfma_f32_16x16x32_bf16 v[16:19], v[84:87], v[112:115], v[16:19]
	v_mfma_f32_16x16x32_bf16 v[20:23], v[84:87], v[116:119], v[20:23]
	v_mfma_f32_16x16x32_bf16 v[24:27], v[84:87], v[120:123], v[24:27]
	v_mfma_f32_16x16x32_bf16 v[28:31], v[84:87], v[124:127], v[28:31]
	v_mfma_f32_16x16x32_bf16 v[32:35], v[88:91], v[112:115], v[32:35]
	v_mfma_f32_16x16x32_bf16 v[36:39], v[88:91], v[116:119], v[36:39]
	v_mfma_f32_16x16x32_bf16 v[40:43], v[88:91], v[120:123], v[40:43]
	v_mfma_f32_16x16x32_bf16 v[44:47], v[88:91], v[124:127], v[44:47]
	v_mfma_f32_16x16x32_bf16 v[48:51], v[92:95], v[112:115], v[48:51]
	v_mfma_f32_16x16x32_bf16 v[52:55], v[92:95], v[116:119], v[52:55]
	v_mfma_f32_16x16x32_bf16 v[56:59], v[92:95], v[120:123], v[56:59]
	v_mfma_f32_16x16x32_bf16 v[60:63], v[92:95], v[124:127], v[60:63]
	ds_read_b128 v[80:83], v253 offset:16384
	ds_read_b128 v[112:115], v255 offset:49152
	ds_read_b128 v[116:119], v255 offset:51200
	ds_read_b128 v[120:123], v255 offset:53248
	ds_read_b128 v[124:127], v255 offset:55296
	ds_read_b128 v[84:87], v253 offset:18432
	ds_read_b128 v[88:91], v253 offset:20480
	ds_read_b128 v[92:95], v253 offset:22528
	s_waitcnt lgkmcnt(14)
	v_mfma_f32_16x16x32_bf16 v[0:3], v[64:67], v[96:99], v[0:3]
	s_waitcnt lgkmcnt(13)
	v_mfma_f32_16x16x32_bf16 v[4:7], v[64:67], v[100:103], v[4:7]
	s_waitcnt lgkmcnt(12)
	v_mfma_f32_16x16x32_bf16 v[8:11], v[64:67], v[104:107], v[8:11]
	s_waitcnt lgkmcnt(11)
	v_mfma_f32_16x16x32_bf16 v[12:15], v[64:67], v[108:111], v[12:15]
	s_waitcnt lgkmcnt(10)
	v_mfma_f32_16x16x32_bf16 v[16:19], v[68:71], v[96:99], v[16:19]
	v_mfma_f32_16x16x32_bf16 v[20:23], v[68:71], v[100:103], v[20:23]
	v_mfma_f32_16x16x32_bf16 v[24:27], v[68:71], v[104:107], v[24:27]
	v_mfma_f32_16x16x32_bf16 v[28:31], v[68:71], v[108:111], v[28:31]
	s_waitcnt lgkmcnt(0)
	s_barrier
	s_add_u32 m0, s12, 0x4000
	v_mfma_f32_16x16x32_bf16 v[32:35], v[72:75], v[96:99], v[32:35]
	global_load_lds_dwordx4 v248, s[8:9]
	s_add_u32 m0, s12, 0x4400
	v_mfma_f32_16x16x32_bf16 v[36:39], v[72:75], v[100:103], v[36:39]
	global_load_lds_dwordx4 v249, s[8:9]
	s_add_u32 m0, s12, 0x4800
	v_mfma_f32_16x16x32_bf16 v[40:43], v[72:75], v[104:107], v[40:43]
	global_load_lds_dwordx4 v250, s[8:9]
	s_add_u32 m0, s12, 0x4c00
	v_mfma_f32_16x16x32_bf16 v[44:47], v[72:75], v[108:111], v[44:47]
	global_load_lds_dwordx4 v251, s[8:9]
	s_add_u32 m0, s12, 0xc000
	v_mfma_f32_16x16x32_bf16 v[48:51], v[76:79], v[96:99], v[48:51]
	global_load_lds_dwordx4 v248, s[10:11]
	s_add_u32 m0, s12, 0xc400
	v_mfma_f32_16x16x32_bf16 v[52:55], v[76:79], v[100:103], v[52:55]
	global_load_lds_dwordx4 v249, s[10:11]
	s_add_u32 m0, s12, 0xc800
	v_mfma_f32_16x16x32_bf16 v[56:59], v[76:79], v[104:107], v[56:59]
	global_load_lds_dwordx4 v250, s[10:11]
	s_add_u32 m0, s12, 0xcc00
	v_mfma_f32_16x16x32_bf16 v[60:63], v[76:79], v[108:111], v[60:63]
	global_load_lds_dwordx4 v251, s[10:11]
	s_add_u32 s8, s8, 0x80
	s_addc_u32 s9, s9, 0
	s_add_u32 s10, s10, 0x80
	s_addc_u32 s11, s11, 0
	s_mov_b32 s13, 20

.Lr25_end:
.LBB0_2480:
	s_cmp_lt_i32 s61, 26
	s_cbranch_scc1 .LBB0_2534
	s_waitcnt vmcnt(0)
	s_waitcnt vmcnt(63) expcnt(7) lgkmcnt(15)
	s_barrier
	s_and_saveexec_b64 s[4:5], s[52:53]
	s_cbranch_execz .LBB0_2533
	v_mov_b32_e32 v0, 0x12000
	s_waitcnt vmcnt(0) expcnt(0) lgkmcnt(0)
	ds_read_b32 v2, v0
	v_mov_b32_e32 v0, 0x12004
	ds_read_b32 v0, v0
	s_waitcnt lgkmcnt(1)
	v_cmp_ne_u32_e32 vcc, 0, v2
	s_cbranch_vccnz .LBB0_2497
	s_load_dwordx2 s[2:3], s[0:1], 0xf0
	s_load_dword s9, s[0:1], 0xf8
	s_add_u32 s6, s56, 0x1457a300
	s_addc_u32 s7, s57, 0
	s_add_u32 s8, s56, 0x1457a500
	s_waitcnt lgkmcnt(0)
	s_mul_i32 s2, s3, s2
	s_mul_i32 s2, s2, s9
	s_addc_u32 s9, s57, 0
	s_add_u32 s10, s56, 0x1457a600
	s_addc_u32 s11, s57, 0
	s_add_u32 s12, s56, 0x1457a700
	s_addc_u32 s13, s57, 0
	s_add_u32 s14, s56, 0x1457a800
	s_addc_u32 s15, s57, 0
	s_add_u32 s16, s56, 0x1457a900
	s_addc_u32 s17, s57, 0
	s_add_u32 s18, s56, 0x1457aa00
	s_addc_u32 s19, s57, 0
	s_add_u32 s20, s56, 0x1457ab00
	s_addc_u32 s21, s57, 0
	s_add_u32 s22, s56, 0x1457ac00
	s_addc_u32 s23, s57, 0
	s_add_u32 s24, s56, 0x1457ad00
	s_addc_u32 s25, s57, 0
	s_add_u32 s26, s56, 0x1457ae00
	s_addc_u32 s27, s57, 0
	s_add_u32 s28, s56, 0x1457af00
	s_addc_u32 s29, s57, 0
	s_add_u32 s30, s56, 0x1457b000
	s_addc_u32 s31, s57, 0
	s_add_u32 s34, s56, 0x1457b100
	s_addc_u32 s35, s57, 0
	s_add_u32 s36, s56, 0x1457b200
	s_addc_u32 s37, s57, 0
	s_add_u32 s38, s56, 0x1457b300
	s_addc_u32 s39, s57, 0
	s_add_u32 s40, s56, 0x1457b400
	s_addc_u32 s41, s57, 0
	s_mov_b32 s3, 1
	v_mov_b32_e32 v16, 0
	s_branch .LBB0_2485

.LBB0_2719:
	s_cmp_gt_i32 s60, 29
	s_cselect_b64 s[2:3], -1, 0
	s_cmp_lt_i32 s61, 29
	s_cselect_b64 s[4:5], -1, 0
	s_or_b64 s[2:3], s[2:3], s[4:5]
	s_and_b64 vcc, exec, s[2:3]
	s_cbranch_vccnz .LBB0_2787
	s_load_dwordx2 s[4:5], s[0:1], 0xe0
	s_load_dword s16, s[0:1], 0xf0
	s_load_dwordx2 s[24:25], s[0:1], 0xb8
	v_and_b32_e32 v240, 63, v162
	v_lshrrev_b32_e32 v247, 6, v162
	v_lshrrev_b32_e32 v242, 3, v240
	v_lshl_add_u32 v242, v247, 5, v242
	v_and_b32_e32 v243, 7, v240
	v_lshrrev_b32_e32 v244, 4, v240
	v_xor_b32_e32 v243, v243, v244
	v_lshlrev_b32_e32 v243, 4, v243
	v_mov_b32_e32 v241, 0x800
	v_mad_u32_u24 v248, v242, v241, v243
	v_xor_b32_e32 v249, 64, v248
	v_add_u32_e32 v249, 0x4000, v249
	v_add_u32_e32 v250, 0x8000, v248
	v_xor_b32_e32 v251, 64, v248
	v_add_u32_e32 v251, 0xc000, v251
	v_and_b32_e32 v241, 15, v240
	v_lshrrev_b32_e32 v242, 1, v241
	v_xor_b32_e32 v242, v242, v244
	v_lshlrev_b32_e32 v242, 4, v242
	v_lshl_or_b32 v242, v241, 7, v242
	v_lshrrev_b32_e32 v243, 1, v247
	v_lshl_or_b32 v252, v243, 13, v242
	v_xor_b32_e32 v253, 64, v252
	v_and_b32_e32 v243, 1, v247
	v_lshl_or_b32 v254, v243, 13, v242
	v_xor_b32_e32 v255, 64, v254
	v_and_b32_e32 v240, 63, v162
	v_and_b32_e32 v241, 15, v240
	v_lshrrev_b32_e32 v242, 4, v240
	v_lshrrev_b32_e32 v243, 1, v247
	v_and_b32_e32 v244, 1, v247
	v_lshl_or_b32 v245, v244, 6, v241
	v_lshlrev_b32_e32 v243, 4, v243
	v_add_u32_e32 v243, v243, v242
	v_lshl_add_u32 v246, v243, 12, v245
	v_lshlrev_b32_e32 v246, 2, v246
	v_lshlrev_b32_e32 v245, 2, v245
	s_waitcnt lgkmcnt(0)
	s_add_u32 s26, s4, 0x9b7a100
	s_addc_u32 s27, s5, 0
	s_add_u32 s28, s4, 0x2280000
	s_addc_u32 s29, s5, 0
	s_mov_b32 s15, s58
.Lr29_tile:
	s_cmp_lt_u32 s15, 0x200
	s_cbranch_scc0 .Lr29_end
	s_and_b32 s2, s15, 63
	s_lshr_b32 s3, s15, 6
	s_mul_i32 s14, s2, 0x40000
	s_add_u32 s8, s26, s14
	s_addc_u32 s9, s27, 0
	s_mul_i32 s14, s3, 0x40000
	s_add_u32 s10, s28, s14
	s_addc_u32 s11, s29, 0
	s_lshl_b32 s14, s2, 19
	s_lshl_b32 s6, s3, 9
	s_add_u32 s14, s14, s6
	s_add_u32 s20, s4, 0x6b7a100
	s_addc_u32 s21, s5, 0
	s_add_u32 s20, s20, s14
	s_addc_u32 s21, s21, 0
	s_sub_u32 s7, s2, 32
	s_lshr_b32 s7, s7, 3
	s_add_u32 s7, s7, 1
	s_cmp_lt_u32 s2, 32
	s_cselect_b32 s7, 0, s7
	s_mul_i32 s7, s7, 0x6000
	s_add_u32 s7, s7, s6
	s_add_u32 s22, s4, 0x6b5e000
	s_addc_u32 s23, s5, 0
	s_add_u32 s22, s22, s7
	s_addc_u32 s23, s23, 0
	s_add_u32 s30, s24, 0x1000
	s_addc_u32 s31, s25, 0
	s_add_u32 s30, s30, s6
	s_addc_u32 s31, s31, 0
	v_readfirstlane_b32 s12, v247
	global_load_dword v201, v245, s[22:23] offset:0
	global_load_dword v202, v245, s[22:23] offset:64
	global_load_dword v203, v245, s[22:23] offset:128
	global_load_dword v204, v245, s[22:23] offset:192
	global_load_dword v205, v245, s[30:31] offset:0
	global_load_dword v206, v245, s[30:31] offset:64
	global_load_dword v207, v245, s[30:31] offset:128
	global_load_dword v208, v245, s[30:31] offset:192
	s_mov_b64 s[18:19], s[20:21]
	global_load_dword v129, v246, s[18:19] offset:0
	global_load_dword v130, v246, s[18:19] offset:64
	global_load_dword v131, v246, s[18:19] offset:128
	global_load_dword v132, v246, s[18:19] offset:192
	s_add_u32 s18, s18, 0x1000
	s_addc_u32 s19, s19, 0
	global_load_dword v133, v246, s[18:19] offset:0
	global_load_dword v134, v246, s[18:19] offset:64
	global_load_dword v135, v246, s[18:19] offset:128
	global_load_dword v136, v246, s[18:19] offset:192
	s_add_u32 s18, s18, 0x1000
	s_addc_u32 s19, s19, 0
	global_load_dword v137, v246, s[18:19] offset:0
	global_load_dword v138, v246, s[18:19] offset:64
	global_load_dword v139, v246, s[18:19] offset:128
	global_load_dword v140, v246, s[18:19] offset:192
	s_add_u32 s18, s18, 0x1000
	s_addc_u32 s19, s19, 0
	global_load_dword v141, v246, s[18:19] offset:0
	global_load_dword v142, v246, s[18:19] offset:64
	global_load_dword v143, v246, s[18:19] offset:128
	global_load_dword v144, v246, s[18:19] offset:192
	s_add_u32 s18, s18, 0xd000
	s_addc_u32 s19, s19, 0
	global_load_dword v145, v246, s[18:19] offset:0
	global_load_dword v146, v246, s[18:19] offset:64
	global_load_dword v147, v246, s[18:19] offset:128
	global_load_dword v148, v246, s[18:19] offset:192
	s_add_u32 s18, s18, 0x1000
	s_addc_u32 s19, s19, 0
	global_load_dword v149, v246, s[18:19] offset:0
	global_load_dword v150, v246, s[18:19] offset:64
	global_load_dword v151, v246, s[18:19] offset:128
	global_load_dword v152, v246, s[18:19] offset:192
	s_add_u32 s18, s18, 0x1000
	s_addc_u32 s19, s19, 0
	global_load_dword v153, v246, s[18:19] offset:0
	global_load_dword v154, v246, s[18:19] offset:64
	global_load_dword v155, v246, s[18:19] offset:128
	global_load_dword v156, v246, s[18:19] offset:192
	s_add_u32 s18, s18, 0x1000
	s_addc_u32 s19, s19, 0
	global_load_dword v157, v246, s[18:19] offset:0
	global_load_dword v158, v246, s[18:19] offset:64
	global_load_dword v159, v246, s[18:19] offset:128
	global_load_dword v160, v246, s[18:19] offset:192
	s_add_u32 s18, s18, 0xd000
	s_addc_u32 s19, s19, 0
	global_load_dword v161, v246, s[18:19] offset:0
	global_load_dword v170, v246, s[18:19] offset:64
	global_load_dword v171, v246, s[18:19] offset:128
	global_load_dword v172, v246, s[18:19] offset:192
	s_add_u32 s18, s18, 0x1000
	s_addc_u32 s19, s19, 0
	global_load_dword v173, v246, s[18:19] offset:0
	global_load_dword v174, v246, s[18:19] offset:64
	global_load_dword v175, v246, s[18:19] offset:128
	global_load_dword v176, v246, s[18:19] offset:192
	s_add_u32 s18, s18, 0x1000
	s_addc_u32 s19, s19, 0
	global_load_dword v177, v246, s[18:19] offset:0
	global_load_dword v178, v246, s[18:19] offset:64
	global_load_dword v179, v246, s[18:19] offset:128
	global_load_dword v180, v246, s[18:19] offset:192
	s_add_u32 s18, s18, 0x1000
	s_addc_u32 s19, s19, 0
	global_load_dword v181, v246, s[18:19] offset:0
	global_load_dword v182, v246, s[18:19] offset:64
	global_load_dword v183, v246, s[18:19] offset:128
	global_load_dword v184, v246, s[18:19] offset:192
	s_add_u32 s18, s18, 0xd000
	s_addc_u32 s19, s19, 0
	global_load_dword v185, v246, s[18:19] offset:0
	global_load_dword v186, v246, s[18:19] offset:64
	global_load_dword v187, v246, s[18:19] offset:128
	global_load_dword v188, v246, s[18:19] offset:192
	s_add_u32 s18, s18, 0x1000
	s_addc_u32 s19, s19, 0
	global_load_dword v189, v246, s[18:19] offset:0
	global_load_dword v190, v246, s[18:19] offset:64
	global_load_dword v191, v246, s[18:19] offset:128
	global_load_dword v192, v246, s[18:19] offset:192
	s_add_u32 s18, s18, 0x1000
	s_addc_u32 s19, s19, 0
	global_load_dword v193, v246, s[18:19] offset:0
	global_load_dword v194, v246, s[18:19] offset:64
	global_load_dword v195, v246, s[18:19] offset:128
	global_load_dword v196, v246, s[18:19] offset:192
	s_add_u32 s18, s18, 0x1000
	s_addc_u32 s19, s19, 0
	global_load_dword v197, v246, s[18:19] offset:0
	global_load_dword v198, v246, s[18:19] offset:64
	global_load_dword v199, v246, s[18:19] offset:128
	global_load_dword v200, v246, s[18:19] offset:192
	s_lshl_b32 s12, s12, 12
	s_add_u32 m0, s12, 0x0
	v_mov_b32_e32 v0, 0
	global_load_lds_dwordx4 v248, s[8:9]
	v_mov_b32_e32 v1, 0
	s_add_u32 m0, s12, 0x400
	v_mov_b32_e32 v2, 0
	global_load_lds_dwordx4 v249, s[8:9]
	v_mov_b32_e32 v3, 0
	s_add_u32 m0, s12, 0x800
	v_mov_b32_e32 v4, 0
	global_load_lds_dwordx4 v250, s[8:9]
	v_mov_b32_e32 v5, 0
	s_add_u32 m0, s12, 0xc00
	v_mov_b32_e32 v6, 0
	global_load_lds_dwordx4 v251, s[8:9]
	v_mov_b32_e32 v7, 0
	s_add_u32 m0, s12, 0x8000
	v_mov_b32_e32 v8, 0
	global_load_lds_dwordx4 v248, s[10:11]
	v_mov_b32_e32 v9, 0
	s_add_u32 m0, s12, 0x8400
	v_mov_b32_e32 v10, 0
	global_load_lds_dwordx4 v249, s[10:11]
	v_mov_b32_e32 v11, 0
	s_add_u32 m0, s12, 0x8800
	v_mov_b32_e32 v12, 0
	global_load_lds_dwordx4 v250, s[10:11]
	v_mov_b32_e32 v13, 0
	s_add_u32 m0, s12, 0x8c00
	v_mov_b32_e32 v14, 0
	global_load_lds_dwordx4 v251, s[10:11]
	v_mov_b32_e32 v15, 0
	s_add_u32 s8, s8, 0x80
	s_addc_u32 s9, s9, 0
	s_add_u32 s10, s10, 0x80
	s_addc_u32 s11, s11, 0
	s_add_u32 m0, s12, 0x4000
	v_mov_b32_e32 v16, 0
	global_load_lds_dwordx4 v248, s[8:9]
	v_mov_b32_e32 v17, 0
	s_add_u32 m0, s12, 0x4400
	v_mov_b32_e32 v18, 0
	global_load_lds_dwordx4 v249, s[8:9]
	v_mov_b32_e32 v19, 0
	s_add_u32 m0, s12, 0x4800
	v_mov_b32_e32 v20, 0
	global_load_lds_dwordx4 v250, s[8:9]
	v_mov_b32_e32 v21, 0
	s_add_u32 m0, s12, 0x4c00
	v_mov_b32_e32 v22, 0
	global_load_lds_dwordx4 v251, s[8:9]
	v_mov_b32_e32 v23, 0
	s_add_u32 m0, s12, 0xc000
	v_mov_b32_e32 v24, 0
	global_load_lds_dwordx4 v248, s[10:11]
	v_mov_b32_e32 v25, 0
	s_add_u32 m0, s12, 0xc400
	v_mov_b32_e32 v26, 0
	global_load_lds_dwordx4 v249, s[10:11]
	v_mov_b32_e32 v27, 0
	s_add_u32 m0, s12, 0xc800
	v_mov_b32_e32 v28, 0
	global_load_lds_dwordx4 v250, s[10:11]
	v_mov_b32_e32 v29, 0
	s_add_u32 m0, s12, 0xcc00
	v_mov_b32_e32 v30, 0
	global_load_lds_dwordx4 v251, s[10:11]
	v_mov_b32_e32 v31, 0
	s_add_u32 s8, s8, 0x80
	s_addc_u32 s9, s9, 0
	s_add_u32 s10, s10, 0x80
	s_addc_u32 s11, s11, 0
	v_mov_b32_e32 v32, 0
	v_mov_b32_e32 v33, 0
	v_mov_b32_e32 v34, 0
	v_mov_b32_e32 v35, 0
	v_mov_b32_e32 v36, 0
	v_mov_b32_e32 v37, 0
	v_mov_b32_e32 v38, 0
	v_mov_b32_e32 v39, 0
	v_mov_b32_e32 v40, 0
	v_mov_b32_e32 v41, 0
	v_mov_b32_e32 v42, 0
	v_mov_b32_e32 v43, 0
	v_mov_b32_e32 v44, 0
	v_mov_b32_e32 v45, 0
	v_mov_b32_e32 v46, 0
	v_mov_b32_e32 v47, 0
	v_mov_b32_e32 v48, 0
	v_mov_b32_e32 v49, 0
	v_mov_b32_e32 v50, 0
	v_mov_b32_e32 v51, 0
	v_mov_b32_e32 v52, 0
	v_mov_b32_e32 v53, 0
	v_mov_b32_e32 v54, 0
	v_mov_b32_e32 v55, 0
	v_mov_b32_e32 v56, 0
	v_mov_b32_e32 v57, 0
	v_mov_b32_e32 v58, 0
	v_mov_b32_e32 v59, 0
	v_mov_b32_e32 v60, 0
	v_mov_b32_e32 v61, 0
	v_mov_b32_e32 v62, 0
	v_mov_b32_e32 v63, 0
	s_waitcnt vmcnt(8)
	s_barrier
	ds_read_b128 v[64:67], v252 offset:0
	ds_read_b128 v[96:99], v254 offset:32768
	ds_read_b128 v[100:103], v254 offset:34816
	ds_read_b128 v[104:107], v254 offset:36864
	ds_read_b128 v[108:111], v254 offset:38912
	ds_read_b128 v[68:71], v252 offset:2048
	ds_read_b128 v[72:75], v252 offset:4096
	ds_read_b128 v[76:79], v252 offset:6144
	ds_read_b128 v[80:83], v253 offset:0
	ds_read_b128 v[112:115], v255 offset:32768
	ds_read_b128 v[116:119], v255 offset:34816
	ds_read_b128 v[120:123], v255 offset:36864
	ds_read_b128 v[124:127], v255 offset:38912
	s_waitcnt lgkmcnt(11)
	v_mfma_f32_16x16x32_bf16 v[0:3], v[64:67], v[96:99], v[0:3]
	s_waitcnt lgkmcnt(10)
	v_mfma_f32_16x16x32_bf16 v[4:7], v[64:67], v[100:103], v[4:7]
	s_waitcnt lgkmcnt(9)
	v_mfma_f32_16x16x32_bf16 v[8:11], v[64:67], v[104:107], v[8:11]
	s_waitcnt lgkmcnt(8)
	v_mfma_f32_16x16x32_bf16 v[12:15], v[64:67], v[108:111], v[12:15]
	ds_read_b128 v[84:87], v253 offset:2048
	ds_read_b128 v[88:91], v253 offset:4096
	ds_read_b128 v[92:95], v253 offset:6144
	s_waitcnt lgkmcnt(10)
	v_mfma_f32_16x16x32_bf16 v[16:19], v[68:71], v[96:99], v[16:19]
	v_mfma_f32_16x16x32_bf16 v[20:23], v[68:71], v[100:103], v[20:23]
	v_mfma_f32_16x16x32_bf16 v[24:27], v[68:71], v[104:107], v[24:27]
	v_mfma_f32_16x16x32_bf16 v[28:31], v[68:71], v[108:111], v[28:31]
	s_waitcnt lgkmcnt(0)
	s_barrier
	s_add_u32 m0, s12, 0x0
	v_mfma_f32_16x16x32_bf16 v[32:35], v[72:75], v[96:99], v[32:35]
	global_load_lds_dwordx4 v248, s[8:9]
	s_add_u32 m0, s12, 0x400
	v_mfma_f32_16x16x32_bf16 v[36:39], v[72:75], v[100:103], v[36:39]
	global_load_lds_dwordx4 v249, s[8:9]
	s_add_u32 m0, s12, 0x800
	v_mfma_f32_16x16x32_bf16 v[40:43], v[72:75], v[104:107], v[40:43]
	global_load_lds_dwordx4 v250, s[8:9]
	s_add_u32 m0, s12, 0xc00
	v_mfma_f32_16x16x32_bf16 v[44:47], v[72:75], v[108:111], v[44:47]
	global_load_lds_dwordx4 v251, s[8:9]
	s_add_u32 m0, s12, 0x8000
	v_mfma_f32_16x16x32_bf16 v[48:51], v[76:79], v[96:99], v[48:51]
	global_load_lds_dwordx4 v248, s[10:11]
	s_add_u32 m0, s12, 0x8400
	v_mfma_f32_16x16x32_bf16 v[52:55], v[76:79], v[100:103], v[52:55]
	global_load_lds_dwordx4 v249, s[10:11]
	s_add_u32 m0, s12, 0x8800
	v_mfma_f32_16x16x32_bf16 v[56:59], v[76:79], v[104:107], v[56:59]
	global_load_lds_dwordx4 v250, s[10:11]
	s_add_u32 m0, s12, 0x8c00
	v_mfma_f32_16x16x32_bf16 v[60:63], v[76:79], v[108:111], v[60:63]
	global_load_lds_dwordx4 v251, s[10:11]
	s_add_u32 s8, s8, 0x80
	s_addc_u32 s9, s9, 0
	s_add_u32 s10, s10, 0x80
	s_addc_u32 s11, s11, 0
	s_waitcnt vmcnt(8)
	s_barrier
	ds_read_b128 v[64:67], v252 offset:16384
	ds_read_b128 v[96:99], v254 offset:49152
	ds_read_b128 v[100:103], v254 offset:51200
	ds_read_b128 v[104:107], v254 offset:53248
	ds_read_b128 v[108:111], v254 offset:55296
	ds_read_b128 v[68:71], v252 offset:18432
	ds_read_b128 v[72:75], v252 offset:20480
	ds_read_b128 v[76:79], v252 offset:22528
	v_mfma_f32_16x16x32_bf16 v[0:3], v[80:83], v[112:115], v[0:3]
	v_mfma_f32_16x16x32_bf16 v[4:7], v[80:83], v[116:119], v[4:7]
	v_mfma_f32_16x16x32_bf16 v[8:11], v[80:83], v[120:123], v[8:11]
	v_mfma_f32_16x16x32_bf16 v[12:15], v[80:83], v[124:127], v[12:15]
	v_mfma_f32_16x16x32_bf16 v[16:19], v[84:87], v[112:115], v[16:19]
	v_mfma_f32_16x16x32_bf16 v[20:23], v[84:87], v[116:119], v[20:23]
	v_mfma_f32_16x16x32_bf16 v[24:27], v[84:87], v[120:123], v[24:27]
	v_mfma_f32_16x16x32_bf16 v[28:31], v[84:87], v[124:127], v[28:31]
	v_mfma_f32_16x16x32_bf16 v[32:35], v[88:91], v[112:115], v[32:35]
	v_mfma_f32_16x16x32_bf16 v[36:39], v[88:91], v[116:119], v[36:39]
	v_mfma_f32_16x16x32_bf16 v[40:43], v[88:91], v[120:123], v[40:43]
	v_mfma_f32_16x16x32_bf16 v[44:47], v[88:91], v[124:127], v[44:47]
	v_mfma_f32_16x16x32_bf16 v[48:51], v[92:95], v[112:115], v[48:51]
	v_mfma_f32_16x16x32_bf16 v[52:55], v[92:95], v[116:119], v[52:55]
	v_mfma_f32_16x16x32_bf16 v[56:59], v[92:95], v[120:123], v[56:59]
	v_mfma_f32_16x16x32_bf16 v[60:63], v[92:95], v[124:127], v[60:63]
	ds_read_b128 v[80:83], v253 offset:16384
	ds_read_b128 v[112:115], v255 offset:49152
	ds_read_b128 v[116:119], v255 offset:51200
	ds_read_b128 v[120:123], v255 offset:53248
	ds_read_b128 v[124:127], v255 offset:55296
	ds_read_b128 v[84:87], v253 offset:18432
	ds_read_b128 v[88:91], v253 offset:20480
	ds_read_b128 v[92:95], v253 offset:22528
	s_waitcnt lgkmcnt(14)
	v_mfma_f32_16x16x32_bf16 v[0:3], v[64:67], v[96:99], v[0:3]
	s_waitcnt lgkmcnt(13)
	v_mfma_f32_16x16x32_bf16 v[4:7], v[64:67], v[100:103], v[4:7]
	s_waitcnt lgkmcnt(12)
	v_mfma_f32_16x16x32_bf16 v[8:11], v[64:67], v[104:107], v[8:11]
	s_waitcnt lgkmcnt(11)
	v_mfma_f32_16x16x32_bf16 v[12:15], v[64:67], v[108:111], v[12:15]
	s_waitcnt lgkmcnt(10)
	v_mfma_f32_16x16x32_bf16 v[16:19], v[68:71], v[96:99], v[16:19]
	v_mfma_f32_16x16x32_bf16 v[20:23], v[68:71], v[100:103], v[20:23]
	v_mfma_f32_16x16x32_bf16 v[24:27], v[68:71], v[104:107], v[24:27]
	v_mfma_f32_16x16x32_bf16 v[28:31], v[68:71], v[108:111], v[28:31]
	s_waitcnt lgkmcnt(0)
	s_barrier
	s_add_u32 m0, s12, 0x4000
	v_mfma_f32_16x16x32_bf16 v[32:35], v[72:75], v[96:99], v[32:35]
	global_load_lds_dwordx4 v248, s[8:9]
	s_add_u32 m0, s12, 0x4400
	v_mfma_f32_16x16x32_bf16 v[36:39], v[72:75], v[100:103], v[36:39]
	global_load_lds_dwordx4 v249, s[8:9]
	s_add_u32 m0, s12, 0x4800
	v_mfma_f32_16x16x32_bf16 v[40:43], v[72:75], v[104:107], v[40:43]
	global_load_lds_dwordx4 v250, s[8:9]
	s_add_u32 m0, s12, 0x4c00
	v_mfma_f32_16x16x32_bf16 v[44:47], v[72:75], v[108:111], v[44:47]
	global_load_lds_dwordx4 v251, s[8:9]
	s_add_u32 m0, s12, 0xc000
	v_mfma_f32_16x16x32_bf16 v[48:51], v[76:79], v[96:99], v[48:51]
	global_load_lds_dwordx4 v248, s[10:11]
	s_add_u32 m0, s12, 0xc400
	v_mfma_f32_16x16x32_bf16 v[52:55], v[76:79], v[100:103], v[52:55]
	global_load_lds_dwordx4 v249, s[10:11]
	s_add_u32 m0, s12, 0xc800
	v_mfma_f32_16x16x32_bf16 v[56:59], v[76:79], v[104:107], v[56:59]
	global_load_lds_dwordx4 v250, s[10:11]
	s_add_u32 m0, s12, 0xcc00
	v_mfma_f32_16x16x32_bf16 v[60:63], v[76:79], v[108:111], v[60:63]
	global_load_lds_dwordx4 v251, s[10:11]
	s_add_u32 s8, s8, 0x80
	s_addc_u32 s9, s9, 0
	s_add_u32 s10, s10, 0x80
	s_addc_u32 s11, s11, 0
	s_mov_b32 s13, 6

.Lr29_end:
.LBB0_2733:
	s_cmp_lt_i32 s61, 30
	s_cbranch_scc1 .LBB0_2787
	s_waitcnt vmcnt(0)
	s_waitcnt vmcnt(63) expcnt(7) lgkmcnt(15)
	s_barrier
	s_and_saveexec_b64 s[4:5], s[52:53]
	s_cbranch_execz .LBB0_2786
	v_mov_b32_e32 v0, 0x12000
	s_waitcnt vmcnt(0) expcnt(0) lgkmcnt(0)
	ds_read_b32 v2, v0
	v_mov_b32_e32 v0, 0x12004
	ds_read_b32 v0, v0
	s_waitcnt lgkmcnt(1)
	v_cmp_ne_u32_e32 vcc, 0, v2
	s_cbranch_vccnz .LBB0_2750
	s_load_dwordx2 s[2:3], s[0:1], 0xf0
	s_load_dword s9, s[0:1], 0xf8
	s_add_u32 s6, s56, 0x1457a300
	s_addc_u32 s7, s57, 0
	s_add_u32 s8, s56, 0x1457a500
	s_waitcnt lgkmcnt(0)
	s_mul_i32 s2, s3, s2
	s_mul_i32 s2, s2, s9
	s_addc_u32 s9, s57, 0
	s_add_u32 s10, s56, 0x1457a600
	s_addc_u32 s11, s57, 0
	s_add_u32 s12, s56, 0x1457a700
	s_addc_u32 s13, s57, 0
	s_add_u32 s14, s56, 0x1457a800
	s_addc_u32 s15, s57, 0
	s_add_u32 s16, s56, 0x1457a900
	s_addc_u32 s17, s57, 0
	s_add_u32 s18, s56, 0x1457aa00
	s_addc_u32 s19, s57, 0
	s_add_u32 s20, s56, 0x1457ab00
	s_addc_u32 s21, s57, 0
	s_add_u32 s22, s56, 0x1457ac00
	s_addc_u32 s23, s57, 0
	s_add_u32 s24, s56, 0x1457ad00
	s_addc_u32 s25, s57, 0
	s_add_u32 s26, s56, 0x1457ae00
	s_addc_u32 s27, s57, 0
	s_add_u32 s28, s56, 0x1457af00
	s_addc_u32 s29, s57, 0
	s_add_u32 s30, s56, 0x1457b000
	s_addc_u32 s31, s57, 0
	s_add_u32 s34, s56, 0x1457b100
	s_addc_u32 s35, s57, 0
	s_add_u32 s36, s56, 0x1457b200
	s_addc_u32 s37, s57, 0
	s_add_u32 s38, s56, 0x1457b300
	s_addc_u32 s39, s57, 0
	s_add_u32 s40, s56, 0x1457b400
	s_addc_u32 s41, s57, 0
	s_mov_b32 s3, 1
	v_mov_b32_e32 v16, 0
	s_branch .LBB0_2738

.LBB0_2909:
	s_cmp_gt_i32 s60, 32
	s_cselect_b64 s[2:3], -1, 0
	s_cmp_lt_i32 s61, 32
	s_cselect_b64 s[4:5], -1, 0
	s_or_b64 s[2:3], s[2:3], s[4:5]
	s_and_b64 vcc, exec, s[2:3]
	s_cbranch_vccnz .LBB0_2969
	s_load_dwordx2 s[4:5], s[0:1], 0xe0
	s_load_dword s16, s[0:1], 0xf0
	v_and_b32_e32 v240, 63, v162
	v_lshrrev_b32_e32 v247, 6, v162
	v_lshrrev_b32_e32 v242, 3, v240
	v_lshl_add_u32 v242, v247, 5, v242
	v_and_b32_e32 v243, 7, v240
	v_lshrrev_b32_e32 v244, 4, v240
	v_xor_b32_e32 v243, v243, v244
	v_lshlrev_b32_e32 v243, 4, v243
	v_mov_b32_e32 v241, 0x1600
	v_mad_u32_u24 v248, v242, v241, v243
	v_xor_b32_e32 v249, 64, v248
	v_add_u32_e32 v249, 0xb000, v249
	v_add_u32_e32 v250, 0x16000, v248
	v_xor_b32_e32 v251, 64, v248
	v_add_u32_e32 v251, 0x21000, v251
	v_and_b32_e32 v241, 15, v240
	v_lshrrev_b32_e32 v242, 1, v241
	v_xor_b32_e32 v242, v242, v244
	v_lshlrev_b32_e32 v242, 4, v242
	v_lshl_or_b32 v242, v241, 7, v242
	v_lshrrev_b32_e32 v243, 1, v247
	v_lshl_or_b32 v252, v243, 13, v242
	v_xor_b32_e32 v253, 64, v252
	v_and_b32_e32 v243, 1, v247
	v_lshl_or_b32 v254, v243, 13, v242
	v_xor_b32_e32 v255, 64, v254
	v_and_b32_e32 v240, 63, v162
	v_and_b32_e32 v241, 15, v240
	v_lshrrev_b32_e32 v242, 4, v240
	v_lshrrev_b32_e32 v243, 1, v247
	v_and_b32_e32 v244, 1, v247
	v_lshl_or_b32 v245, v244, 6, v241
	v_lshlrev_b32_e32 v243, 4, v243
	v_add_u32_e32 v243, v243, v242
	v_lshl_add_u32 v246, v243, 12, v245
	v_lshlrev_b32_e32 v246, 2, v246
	v_lshlrev_b32_e32 v245, 2, v245
	s_waitcnt lgkmcnt(0)
	s_add_u32 s26, s4, 0x9b7a100
	s_addc_u32 s27, s5, 0
	s_add_u32 s28, s4, 0x6100000
	s_addc_u32 s29, s5, 0
	s_mov_b32 s15, s58
.Lr32_tile:
	s_cmp_lt_u32 s15, 0x200
	s_cbranch_scc0 .Lr32_end
	s_and_b32 s2, s15, 63
	s_lshr_b32 s3, s15, 6
	s_mul_i32 s14, s2, 0xb0000
	s_add_u32 s8, s26, s14
	s_addc_u32 s9, s27, 0
	s_mul_i32 s14, s3, 0xb0000
	s_add_u32 s10, s28, s14
	s_addc_u32 s11, s29, 0
	s_lshl_b32 s14, s2, 19
	s_lshl_b32 s6, s3, 9
	s_add_u32 s14, s14, s6
	s_add_u32 s20, s4, 0x6b7a100
	s_addc_u32 s21, s5, 0
	s_add_u32 s20, s20, s14
	s_addc_u32 s21, s21, 0
	s_sub_u32 s7, s2, 32
	s_lshr_b32 s7, s7, 3
	s_add_u32 s7, s7, 1
	s_cmp_lt_u32 s2, 32
	s_cselect_b32 s7, 0, s7
	s_mul_i32 s7, s7, 0x6000
	s_add_u32 s7, s7, s6
	s_add_u32 s22, s4, 0x6b61000
	s_addc_u32 s23, s5, 0
	s_add_u32 s22, s22, s7
	s_addc_u32 s23, s23, 0
	v_readfirstlane_b32 s12, v247
	global_load_dword v201, v245, s[22:23] offset:0
	global_load_dword v202, v245, s[22:23] offset:64
	global_load_dword v203, v245, s[22:23] offset:128
	global_load_dword v204, v245, s[22:23] offset:192
	s_mov_b64 s[18:19], s[20:21]
	global_load_dword v129, v246, s[18:19] offset:0
	global_load_dword v130, v246, s[18:19] offset:64
	global_load_dword v131, v246, s[18:19] offset:128
	global_load_dword v132, v246, s[18:19] offset:192
	s_add_u32 s18, s18, 0x1000
	s_addc_u32 s19, s19, 0
	global_load_dword v133, v246, s[18:19] offset:0
	global_load_dword v134, v246, s[18:19] offset:64
	global_load_dword v135, v246, s[18:19] offset:128
	global_load_dword v136, v246, s[18:19] offset:192
	s_add_u32 s18, s18, 0x1000
	s_addc_u32 s19, s19, 0
	global_load_dword v137, v246, s[18:19] offset:0
	global_load_dword v138, v246, s[18:19] offset:64
	global_load_dword v139, v246, s[18:19] offset:128
	global_load_dword v140, v246, s[18:19] offset:192
	s_add_u32 s18, s18, 0x1000
	s_addc_u32 s19, s19, 0
	global_load_dword v141, v246, s[18:19] offset:0
	global_load_dword v142, v246, s[18:19] offset:64
	global_load_dword v143, v246, s[18:19] offset:128
	global_load_dword v144, v246, s[18:19] offset:192
	s_add_u32 s18, s18, 0xd000
	s_addc_u32 s19, s19, 0
	global_load_dword v145, v246, s[18:19] offset:0
	global_load_dword v146, v246, s[18:19] offset:64
	global_load_dword v147, v246, s[18:19] offset:128
	global_load_dword v148, v246, s[18:19] offset:192
	s_add_u32 s18, s18, 0x1000
	s_addc_u32 s19, s19, 0
	global_load_dword v149, v246, s[18:19] offset:0
	global_load_dword v150, v246, s[18:19] offset:64
	global_load_dword v151, v246, s[18:19] offset:128
	global_load_dword v152, v246, s[18:19] offset:192
	s_add_u32 s18, s18, 0x1000
	s_addc_u32 s19, s19, 0
	global_load_dword v153, v246, s[18:19] offset:0
	global_load_dword v154, v246, s[18:19] offset:64
	global_load_dword v155, v246, s[18:19] offset:128
	global_load_dword v156, v246, s[18:19] offset:192
	s_add_u32 s18, s18, 0x1000
	s_addc_u32 s19, s19, 0
	global_load_dword v157, v246, s[18:19] offset:0
	global_load_dword v158, v246, s[18:19] offset:64
	global_load_dword v159, v246, s[18:19] offset:128
	global_load_dword v160, v246, s[18:19] offset:192
	s_add_u32 s18, s18, 0xd000
	s_addc_u32 s19, s19, 0
	global_load_dword v161, v246, s[18:19] offset:0
	global_load_dword v170, v246, s[18:19] offset:64
	global_load_dword v171, v246, s[18:19] offset:128
	global_load_dword v172, v246, s[18:19] offset:192
	s_add_u32 s18, s18, 0x1000
	s_addc_u32 s19, s19, 0
	global_load_dword v173, v246, s[18:19] offset:0
	global_load_dword v174, v246, s[18:19] offset:64
	global_load_dword v175, v246, s[18:19] offset:128
	global_load_dword v176, v246, s[18:19] offset:192
	s_add_u32 s18, s18, 0x1000
	s_addc_u32 s19, s19, 0
	global_load_dword v177, v246, s[18:19] offset:0
	global_load_dword v178, v246, s[18:19] offset:64
	global_load_dword v179, v246, s[18:19] offset:128
	global_load_dword v180, v246, s[18:19] offset:192
	s_add_u32 s18, s18, 0x1000
	s_addc_u32 s19, s19, 0
	global_load_dword v181, v246, s[18:19] offset:0
	global_load_dword v182, v246, s[18:19] offset:64
	global_load_dword v183, v246, s[18:19] offset:128
	global_load_dword v184, v246, s[18:19] offset:192
	s_add_u32 s18, s18, 0xd000
	s_addc_u32 s19, s19, 0
	global_load_dword v185, v246, s[18:19] offset:0
	global_load_dword v186, v246, s[18:19] offset:64
	global_load_dword v187, v246, s[18:19] offset:128
	global_load_dword v188, v246, s[18:19] offset:192
	s_add_u32 s18, s18, 0x1000
	s_addc_u32 s19, s19, 0
	global_load_dword v189, v246, s[18:19] offset:0
	global_load_dword v190, v246, s[18:19] offset:64
	global_load_dword v191, v246, s[18:19] offset:128
	global_load_dword v192, v246, s[18:19] offset:192
	s_add_u32 s18, s18, 0x1000
	s_addc_u32 s19, s19, 0
	global_load_dword v193, v246, s[18:19] offset:0
	global_load_dword v194, v246, s[18:19] offset:64
	global_load_dword v195, v246, s[18:19] offset:128
	global_load_dword v196, v246, s[18:19] offset:192
	s_add_u32 s18, s18, 0x1000
	s_addc_u32 s19, s19, 0
	global_load_dword v197, v246, s[18:19] offset:0
	global_load_dword v198, v246, s[18:19] offset:64
	global_load_dword v199, v246, s[18:19] offset:128
	global_load_dword v200, v246, s[18:19] offset:192
	s_lshl_b32 s12, s12, 12
	s_add_u32 m0, s12, 0x0
	v_mov_b32_e32 v0, 0
	global_load_lds_dwordx4 v248, s[8:9]
	v_mov_b32_e32 v1, 0
	s_add_u32 m0, s12, 0x400
	v_mov_b32_e32 v2, 0
	global_load_lds_dwordx4 v249, s[8:9]
	v_mov_b32_e32 v3, 0
	s_add_u32 m0, s12, 0x800
	v_mov_b32_e32 v4, 0
	global_load_lds_dwordx4 v250, s[8:9]
	v_mov_b32_e32 v5, 0
	s_add_u32 m0, s12, 0xc00
	v_mov_b32_e32 v6, 0
	global_load_lds_dwordx4 v251, s[8:9]
	v_mov_b32_e32 v7, 0
	s_add_u32 m0, s12, 0x8000
	v_mov_b32_e32 v8, 0
	global_load_lds_dwordx4 v248, s[10:11]
	v_mov_b32_e32 v9, 0
	s_add_u32 m0, s12, 0x8400
	v_mov_b32_e32 v10, 0
	global_load_lds_dwordx4 v249, s[10:11]
	v_mov_b32_e32 v11, 0
	s_add_u32 m0, s12, 0x8800
	v_mov_b32_e32 v12, 0
	global_load_lds_dwordx4 v250, s[10:11]
	v_mov_b32_e32 v13, 0
	s_add_u32 m0, s12, 0x8c00
	v_mov_b32_e32 v14, 0
	global_load_lds_dwordx4 v251, s[10:11]
	v_mov_b32_e32 v15, 0
	s_add_u32 s8, s8, 0x80
	s_addc_u32 s9, s9, 0
	s_add_u32 s10, s10, 0x80
	s_addc_u32 s11, s11, 0
	s_add_u32 m0, s12, 0x4000
	v_mov_b32_e32 v16, 0
	global_load_lds_dwordx4 v248, s[8:9]
	v_mov_b32_e32 v17, 0
	s_add_u32 m0, s12, 0x4400
	v_mov_b32_e32 v18, 0
	global_load_lds_dwordx4 v249, s[8:9]
	v_mov_b32_e32 v19, 0
	s_add_u32 m0, s12, 0x4800
	v_mov_b32_e32 v20, 0
	global_load_lds_dwordx4 v250, s[8:9]
	v_mov_b32_e32 v21, 0
	s_add_u32 m0, s12, 0x4c00
	v_mov_b32_e32 v22, 0
	global_load_lds_dwordx4 v251, s[8:9]
	v_mov_b32_e32 v23, 0
	s_add_u32 m0, s12, 0xc000
	v_mov_b32_e32 v24, 0
	global_load_lds_dwordx4 v248, s[10:11]
	v_mov_b32_e32 v25, 0
	s_add_u32 m0, s12, 0xc400
	v_mov_b32_e32 v26, 0
	global_load_lds_dwordx4 v249, s[10:11]
	v_mov_b32_e32 v27, 0
	s_add_u32 m0, s12, 0xc800
	v_mov_b32_e32 v28, 0
	global_load_lds_dwordx4 v250, s[10:11]
	v_mov_b32_e32 v29, 0
	s_add_u32 m0, s12, 0xcc00
	v_mov_b32_e32 v30, 0
	global_load_lds_dwordx4 v251, s[10:11]
	v_mov_b32_e32 v31, 0
	s_add_u32 s8, s8, 0x80
	s_addc_u32 s9, s9, 0
	s_add_u32 s10, s10, 0x80
	s_addc_u32 s11, s11, 0
	v_mov_b32_e32 v32, 0
	v_mov_b32_e32 v33, 0
	v_mov_b32_e32 v34, 0
	v_mov_b32_e32 v35, 0
	v_mov_b32_e32 v36, 0
	v_mov_b32_e32 v37, 0
	v_mov_b32_e32 v38, 0
	v_mov_b32_e32 v39, 0
	v_mov_b32_e32 v40, 0
	v_mov_b32_e32 v41, 0
	v_mov_b32_e32 v42, 0
	v_mov_b32_e32 v43, 0
	v_mov_b32_e32 v44, 0
	v_mov_b32_e32 v45, 0
	v_mov_b32_e32 v46, 0
	v_mov_b32_e32 v47, 0
	v_mov_b32_e32 v48, 0
	v_mov_b32_e32 v49, 0
	v_mov_b32_e32 v50, 0
	v_mov_b32_e32 v51, 0
	v_mov_b32_e32 v52, 0
	v_mov_b32_e32 v53, 0
	v_mov_b32_e32 v54, 0
	v_mov_b32_e32 v55, 0
	v_mov_b32_e32 v56, 0
	v_mov_b32_e32 v57, 0
	v_mov_b32_e32 v58, 0
	v_mov_b32_e32 v59, 0
	v_mov_b32_e32 v60, 0
	v_mov_b32_e32 v61, 0
	v_mov_b32_e32 v62, 0
	v_mov_b32_e32 v63, 0
	s_waitcnt vmcnt(8)
	s_barrier
	ds_read_b128 v[64:67], v252 offset:0
	ds_read_b128 v[96:99], v254 offset:32768
	ds_read_b128 v[100:103], v254 offset:34816
	ds_read_b128 v[104:107], v254 offset:36864
	ds_read_b128 v[108:111], v254 offset:38912
	ds_read_b128 v[68:71], v252 offset:2048
	ds_read_b128 v[72:75], v252 offset:4096
	ds_read_b128 v[76:79], v252 offset:6144
	ds_read_b128 v[80:83], v253 offset:0
	ds_read_b128 v[112:115], v255 offset:32768
	ds_read_b128 v[116:119], v255 offset:34816
	ds_read_b128 v[120:123], v255 offset:36864
	ds_read_b128 v[124:127], v255 offset:38912
	s_waitcnt lgkmcnt(11)
	v_mfma_f32_16x16x32_bf16 v[0:3], v[64:67], v[96:99], v[0:3]
	s_waitcnt lgkmcnt(10)
	v_mfma_f32_16x16x32_bf16 v[4:7], v[64:67], v[100:103], v[4:7]
	s_waitcnt lgkmcnt(9)
	v_mfma_f32_16x16x32_bf16 v[8:11], v[64:67], v[104:107], v[8:11]
	s_waitcnt lgkmcnt(8)
	v_mfma_f32_16x16x32_bf16 v[12:15], v[64:67], v[108:111], v[12:15]
	ds_read_b128 v[84:87], v253 offset:2048
	ds_read_b128 v[88:91], v253 offset:4096
	ds_read_b128 v[92:95], v253 offset:6144
	s_waitcnt lgkmcnt(10)
	v_mfma_f32_16x16x32_bf16 v[16:19], v[68:71], v[96:99], v[16:19]
	v_mfma_f32_16x16x32_bf16 v[20:23], v[68:71], v[100:103], v[20:23]
	v_mfma_f32_16x16x32_bf16 v[24:27], v[68:71], v[104:107], v[24:27]
	v_mfma_f32_16x16x32_bf16 v[28:31], v[68:71], v[108:111], v[28:31]
	s_waitcnt lgkmcnt(0)
	s_barrier
	s_add_u32 m0, s12, 0x0
	v_mfma_f32_16x16x32_bf16 v[32:35], v[72:75], v[96:99], v[32:35]
	global_load_lds_dwordx4 v248, s[8:9]
	s_add_u32 m0, s12, 0x400
	v_mfma_f32_16x16x32_bf16 v[36:39], v[72:75], v[100:103], v[36:39]
	global_load_lds_dwordx4 v249, s[8:9]
	s_add_u32 m0, s12, 0x800
	v_mfma_f32_16x16x32_bf16 v[40:43], v[72:75], v[104:107], v[40:43]
	global_load_lds_dwordx4 v250, s[8:9]
	s_add_u32 m0, s12, 0xc00
	v_mfma_f32_16x16x32_bf16 v[44:47], v[72:75], v[108:111], v[44:47]
	global_load_lds_dwordx4 v251, s[8:9]
	s_add_u32 m0, s12, 0x8000
	v_mfma_f32_16x16x32_bf16 v[48:51], v[76:79], v[96:99], v[48:51]
	global_load_lds_dwordx4 v248, s[10:11]
	s_add_u32 m0, s12, 0x8400
	v_mfma_f32_16x16x32_bf16 v[52:55], v[76:79], v[100:103], v[52:55]
	global_load_lds_dwordx4 v249, s[10:11]
	s_add_u32 m0, s12, 0x8800
	v_mfma_f32_16x16x32_bf16 v[56:59], v[76:79], v[104:107], v[56:59]
	global_load_lds_dwordx4 v250, s[10:11]
	s_add_u32 m0, s12, 0x8c00
	v_mfma_f32_16x16x32_bf16 v[60:63], v[76:79], v[108:111], v[60:63]
	global_load_lds_dwordx4 v251, s[10:11]
	s_add_u32 s8, s8, 0x80
	s_addc_u32 s9, s9, 0
	s_add_u32 s10, s10, 0x80
	s_addc_u32 s11, s11, 0
	s_waitcnt vmcnt(8)
	s_barrier
	ds_read_b128 v[64:67], v252 offset:16384
	ds_read_b128 v[96:99], v254 offset:49152
	ds_read_b128 v[100:103], v254 offset:51200
	ds_read_b128 v[104:107], v254 offset:53248
	ds_read_b128 v[108:111], v254 offset:55296
	ds_read_b128 v[68:71], v252 offset:18432
	ds_read_b128 v[72:75], v252 offset:20480
	ds_read_b128 v[76:79], v252 offset:22528
	v_mfma_f32_16x16x32_bf16 v[0:3], v[80:83], v[112:115], v[0:3]
	v_mfma_f32_16x16x32_bf16 v[4:7], v[80:83], v[116:119], v[4:7]
	v_mfma_f32_16x16x32_bf16 v[8:11], v[80:83], v[120:123], v[8:11]
	v_mfma_f32_16x16x32_bf16 v[12:15], v[80:83], v[124:127], v[12:15]
	v_mfma_f32_16x16x32_bf16 v[16:19], v[84:87], v[112:115], v[16:19]
	v_mfma_f32_16x16x32_bf16 v[20:23], v[84:87], v[116:119], v[20:23]
	v_mfma_f32_16x16x32_bf16 v[24:27], v[84:87], v[120:123], v[24:27]
	v_mfma_f32_16x16x32_bf16 v[28:31], v[84:87], v[124:127], v[28:31]
	v_mfma_f32_16x16x32_bf16 v[32:35], v[88:91], v[112:115], v[32:35]
	v_mfma_f32_16x16x32_bf16 v[36:39], v[88:91], v[116:119], v[36:39]
	v_mfma_f32_16x16x32_bf16 v[40:43], v[88:91], v[120:123], v[40:43]
	v_mfma_f32_16x16x32_bf16 v[44:47], v[88:91], v[124:127], v[44:47]
	v_mfma_f32_16x16x32_bf16 v[48:51], v[92:95], v[112:115], v[48:51]
	v_mfma_f32_16x16x32_bf16 v[52:55], v[92:95], v[116:119], v[52:55]
	v_mfma_f32_16x16x32_bf16 v[56:59], v[92:95], v[120:123], v[56:59]
	v_mfma_f32_16x16x32_bf16 v[60:63], v[92:95], v[124:127], v[60:63]
	ds_read_b128 v[80:83], v253 offset:16384
	ds_read_b128 v[112:115], v255 offset:49152
	ds_read_b128 v[116:119], v255 offset:51200
	ds_read_b128 v[120:123], v255 offset:53248
	ds_read_b128 v[124:127], v255 offset:55296
	ds_read_b128 v[84:87], v253 offset:18432
	ds_read_b128 v[88:91], v253 offset:20480
	ds_read_b128 v[92:95], v253 offset:22528
	s_waitcnt lgkmcnt(14)
	v_mfma_f32_16x16x32_bf16 v[0:3], v[64:67], v[96:99], v[0:3]
	s_waitcnt lgkmcnt(13)
	v_mfma_f32_16x16x32_bf16 v[4:7], v[64:67], v[100:103], v[4:7]
	s_waitcnt lgkmcnt(12)
	v_mfma_f32_16x16x32_bf16 v[8:11], v[64:67], v[104:107], v[8:11]
	s_waitcnt lgkmcnt(11)
	v_mfma_f32_16x16x32_bf16 v[12:15], v[64:67], v[108:111], v[12:15]
	s_waitcnt lgkmcnt(10)
	v_mfma_f32_16x16x32_bf16 v[16:19], v[68:71], v[96:99], v[16:19]
	v_mfma_f32_16x16x32_bf16 v[20:23], v[68:71], v[100:103], v[20:23]
	v_mfma_f32_16x16x32_bf16 v[24:27], v[68:71], v[104:107], v[24:27]
	v_mfma_f32_16x16x32_bf16 v[28:31], v[68:71], v[108:111], v[28:31]
	s_waitcnt lgkmcnt(0)
	s_barrier
	s_add_u32 m0, s12, 0x4000
	v_mfma_f32_16x16x32_bf16 v[32:35], v[72:75], v[96:99], v[32:35]
	global_load_lds_dwordx4 v248, s[8:9]
	s_add_u32 m0, s12, 0x4400
	v_mfma_f32_16x16x32_bf16 v[36:39], v[72:75], v[100:103], v[36:39]
	global_load_lds_dwordx4 v249, s[8:9]
	s_add_u32 m0, s12, 0x4800
	v_mfma_f32_16x16x32_bf16 v[40:43], v[72:75], v[104:107], v[40:43]
	global_load_lds_dwordx4 v250, s[8:9]
	s_add_u32 m0, s12, 0x4c00
	v_mfma_f32_16x16x32_bf16 v[44:47], v[72:75], v[108:111], v[44:47]
	global_load_lds_dwordx4 v251, s[8:9]
	s_add_u32 m0, s12, 0xc000
	v_mfma_f32_16x16x32_bf16 v[48:51], v[76:79], v[96:99], v[48:51]
	global_load_lds_dwordx4 v248, s[10:11]
	s_add_u32 m0, s12, 0xc400
	v_mfma_f32_16x16x32_bf16 v[52:55], v[76:79], v[100:103], v[52:55]
	global_load_lds_dwordx4 v249, s[10:11]
	s_add_u32 m0, s12, 0xc800
	v_mfma_f32_16x16x32_bf16 v[56:59], v[76:79], v[104:107], v[56:59]
	global_load_lds_dwordx4 v250, s[10:11]
	s_add_u32 m0, s12, 0xcc00
	v_mfma_f32_16x16x32_bf16 v[60:63], v[76:79], v[108:111], v[60:63]
	global_load_lds_dwordx4 v251, s[10:11]
	s_add_u32 s8, s8, 0x80
	s_addc_u32 s9, s9, 0
	s_add_u32 s10, s10, 0x80
	s_addc_u32 s11, s11, 0
	s_mov_b32 s13, 20

.Lr32_end:
.LBB0_2915:
	s_cmp_lt_i32 s61, 33
	s_cbranch_scc1 .LBB0_2969
	s_waitcnt vmcnt(0)
	s_waitcnt vmcnt(63) expcnt(7) lgkmcnt(15)
	s_barrier
	s_and_saveexec_b64 s[4:5], s[52:53]
	s_cbranch_execz .LBB0_2968
	v_mov_b32_e32 v0, 0x12000
	s_waitcnt vmcnt(0) expcnt(0) lgkmcnt(0)
	ds_read_b32 v2, v0
	v_mov_b32_e32 v0, 0x12004
	ds_read_b32 v0, v0
	s_waitcnt lgkmcnt(1)
	v_cmp_ne_u32_e32 vcc, 0, v2
	s_cbranch_vccnz .LBB0_2932
	s_load_dwordx2 s[2:3], s[0:1], 0xf0
	s_load_dword s9, s[0:1], 0xf8
	s_add_u32 s6, s56, 0x1457a300
	s_addc_u32 s7, s57, 0
	s_add_u32 s8, s56, 0x1457a500
	s_waitcnt lgkmcnt(0)
	s_mul_i32 s2, s3, s2
	s_mul_i32 s2, s2, s9
	s_addc_u32 s9, s57, 0
	s_add_u32 s10, s56, 0x1457a600
	s_addc_u32 s11, s57, 0
	s_add_u32 s12, s56, 0x1457a700
	s_addc_u32 s13, s57, 0
	s_add_u32 s14, s56, 0x1457a800
	s_addc_u32 s15, s57, 0
	s_add_u32 s16, s56, 0x1457a900
	s_addc_u32 s17, s57, 0
	s_add_u32 s18, s56, 0x1457aa00
	s_addc_u32 s19, s57, 0
	s_add_u32 s20, s56, 0x1457ab00
	s_addc_u32 s21, s57, 0
	s_add_u32 s22, s56, 0x1457ac00
	s_addc_u32 s23, s57, 0
	s_add_u32 s24, s56, 0x1457ad00
	s_addc_u32 s25, s57, 0
	s_add_u32 s26, s56, 0x1457ae00
	s_addc_u32 s27, s57, 0
	s_add_u32 s28, s56, 0x1457af00
	s_addc_u32 s29, s57, 0
	s_add_u32 s30, s56, 0x1457b000
	s_addc_u32 s31, s57, 0
	s_add_u32 s34, s56, 0x1457b100
	s_addc_u32 s35, s57, 0
	s_add_u32 s36, s56, 0x1457b200
	s_addc_u32 s37, s57, 0
	s_add_u32 s38, s56, 0x1457b300
	s_addc_u32 s39, s57, 0
	s_add_u32 s40, s56, 0x1457b400
	s_addc_u32 s41, s57, 0
	s_mov_b32 s3, 1
	v_mov_b32_e32 v16, 0
	s_branch .LBB0_2920
